# v92 with GEMM LDS-DMA issue positions 1,4,6,9,12,14 (uniform 2.7-MFMA spacing)
# baseline (speedup 1.0000x reference)
.LBB0_94:
	s_ashr_i32 s0, s2, 31
	s_lshr_b32 s0, s0, 29
	s_add_i32 s0, s2, s0
	v_mov_b32_e32 v78, v133
	s_and_b32 s1, s0, 0x1fffff8
	s_lshl_b32 s0, s0, 5
	s_and_b32 s22, s0, 0xffffff00
	v_ashrrev_i32_e32 v6, 6, v78
	v_bfe_u32 v7, v78, 3, 3
	v_lshl_or_b32 v8, v6, 5, v7
	v_add_u32_e32 v0, s22, v8
	s_waitcnt lgkmcnt(0)
	v_ashrrev_i32_e32 v1, 31, v0
	v_lshlrev_b64 v[2:3], 11, v[0:1]
	v_bfe_u32 v1, v78, 4, 2
	v_readlane_b32 s20, v214, 4
	v_xor_b32_e32 v1, v1, v78
	v_readlane_b32 s21, v214, 5
	v_lshlrev_b32_e32 v1, 4, v1
	v_and_b32_e32 v64, 0x70, v1
	v_lshl_add_u64 v[2:3], s[20:21], 0, v[2:3]
	v_or_b32_e32 v1, 8, v8
	v_lshl_add_u64 v[66:67], v[2:3], 0, v[64:65]
	v_add_u32_e32 v2, s22, v1
	v_lshrrev_b32_e32 v1, 1, v1
	v_xor_b32_e32 v1, v1, v78
	v_ashrrev_i32_e32 v3, 31, v2
	v_lshlrev_b32_e32 v1, 4, v1
	v_or_b32_e32 v0, 16, v0
	v_lshlrev_b64 v[2:3], 11, v[2:3]
	v_and_b32_e32 v4, 0x70, v1
	v_ashrrev_i32_e32 v1, 31, v0
	v_lshl_add_u64 v[2:3], s[20:21], 0, v[2:3]
	v_mov_b32_e32 v5, v65
	v_lshlrev_b64 v[0:1], 11, v[0:1]
	v_lshl_add_u64 v[68:69], v[2:3], 0, v[4:5]
	v_lshl_add_u64 v[0:1], s[20:21], 0, v[0:1]
	v_or_b32_e32 v2, 24, v8
	v_lshl_add_u64 v[70:71], v[0:1], 0, v[64:65]
	v_add_u32_e32 v0, s22, v2
	v_lshrrev_b32_e32 v2, 1, v2
	v_ashrrev_i32_e32 v1, 31, v0
	v_xor_b32_e32 v2, v2, v78
	v_lshlrev_b64 v[0:1], 11, v[0:1]
	v_lshlrev_b32_e32 v2, 4, v2
	s_sub_i32 s1, s2, s1
	v_lshl_add_u64 v[0:1], s[20:21], 0, v[0:1]
	v_and_b32_e32 v2, 0x70, v2
	v_mov_b32_e32 v3, v65
	s_lshl_b32 s0, s1, 7
	v_lshl_add_u64 v[72:73], v[0:1], 0, v[2:3]
	v_lshl_or_b32 v2, v6, 4, v7
	v_add_u32_e32 v0, s0, v2
	v_lshlrev_b32_e32 v3, 12, v6
	v_ashrrev_i32_e32 v1, 31, v0
	v_add_u32_e32 v126, 0, v3
	v_lshlrev_b64 v[0:1], 11, v[0:1]
	s_waitcnt vmcnt(0)
	v_readfirstlane_b32 s38, v126
	v_add_u32_e32 v127, 0x400, v126
	v_lshl_add_u64 v[0:1], s[40:41], 0, v[0:1]
	v_or_b32_e32 v2, 8, v2
	s_waitcnt lgkmcnt(0)
	s_barrier
	s_mov_b32 m0, s38
	v_readfirstlane_b32 s39, v127
	v_add_u32_e32 v128, 0x800, v126
	v_lshlrev_b32_e32 v5, 11, v6
	v_and_b32_e32 v80, 1, v6
	v_lshl_add_u64 v[74:75], v[0:1], 0, v[64:65]
	v_add_u32_e32 v0, s0, v2
	v_lshrrev_b32_e32 v2, 1, v2
	global_load_lds_dwordx4 v[66:67], off
	s_mov_b32 m0, s39
	v_readfirstlane_b32 s48, v128
	v_add_u32_e32 v129, 0xc00, v126
	v_add_u32_e32 v6, 0, v5
	v_ashrrev_i32_e32 v1, 31, v0
	v_xor_b32_e32 v2, v2, v78
	global_load_lds_dwordx4 v[68:69], off
	s_mov_b32 m0, s48
	v_readfirstlane_b32 s49, v129
	v_add_u32_e32 v131, 0x8000, v6
	v_lshlrev_b64 v[0:1], 11, v[0:1]
	v_lshlrev_b32_e32 v2, 4, v2
	global_load_lds_dwordx4 v[70:71], off
	s_mov_b32 m0, s49
	v_readfirstlane_b32 s53, v131
	v_add_u32_e32 v130, 0x8400, v6
	v_lshl_add_u64 v[0:1], s[40:41], 0, v[0:1]
	v_and_b32_e32 v64, 0x70, v2
	global_load_lds_dwordx4 v[72:73], off
	s_mov_b32 m0, s53
	v_readfirstlane_b32 s54, v130
	v_add_u32_e32 v120, 0xc000, v126
	v_lshl_add_u64 v[76:77], v[0:1], 0, v[64:65]
	global_load_lds_dwordx4 v[74:75], off
	s_mov_b32 m0, s54
	s_mov_b64 s[20:21], 0x80
	v_readfirstlane_b32 s29, v120
	v_add_u32_e32 v121, 0xc400, v126
	global_load_lds_dwordx4 v[76:77], off
	v_lshl_add_u64 v[0:1], v[66:67], 0, s[20:21]
	s_mov_b32 m0, s29
	v_readfirstlane_b32 s33, v121
	v_add_u32_e32 v122, 0xc800, v126
	global_load_lds_dwordx4 v[0:1], off
	v_lshl_add_u64 v[0:1], v[68:69], 0, s[20:21]
	s_mov_b32 m0, s33
	v_readfirstlane_b32 s34, v122
	v_add_u32_e32 v123, 0xcc00, v126
	global_load_lds_dwordx4 v[0:1], off
	v_lshl_add_u64 v[0:1], v[70:71], 0, s[20:21]
	s_mov_b32 m0, s34
	v_readfirstlane_b32 s35, v123
	v_add_u32_e32 v124, s85, v5
	global_load_lds_dwordx4 v[0:1], off
	v_lshl_add_u64 v[0:1], v[72:73], 0, s[20:21]
	s_mov_b32 m0, s35
	v_readfirstlane_b32 s36, v124
	v_add_u32_e32 v125, 0x14400, v6
	global_load_lds_dwordx4 v[0:1], off
	v_lshl_add_u64 v[0:1], v[74:75], 0, s[20:21]
	s_mov_b32 m0, s36
	v_readfirstlane_b32 s37, v125
	global_load_lds_dwordx4 v[0:1], off
	v_lshl_add_u64 v[0:1], v[76:77], 0, s[20:21]
	s_mov_b32 m0, s37
	v_lshrrev_b32_e32 v2, 1, v78
	v_bfe_u32 v64, v78, 5, 1
	global_load_lds_dwordx4 v[0:1], off
	v_add_u32_e32 v114, s3, v3
	v_bitop3_b32 v0, v2, v64, 7 bitop3:0x6c
	s_waitcnt vmcnt(6)
	s_mov_b64 s[30:31], 0x100
	v_readfirstlane_b32 s1, v114
	v_add_u32_e32 v115, 0x400, v114
	v_lshlrev_b32_e32 v132, 4, v0
	s_waitcnt lgkmcnt(0)
	s_barrier
	v_lshl_add_u64 v[0:1], v[66:67], 0, s[30:31]
	s_mov_b32 m0, s1
	v_readfirstlane_b32 s20, v115
	v_add_u32_e32 v116, 0x800, v114
	global_load_lds_dwordx4 v[0:1], off
	v_lshl_add_u64 v[0:1], v[68:69], 0, s[30:31]
	s_mov_b32 m0, s20
	v_readfirstlane_b32 s21, v116
	v_add_u32_e32 v117, 0xc00, v114
	v_readlane_b32 s24, v212, 31
	v_and_b32_e32 v79, 31, v78
	global_load_lds_dwordx4 v[0:1], off
	v_lshl_add_u64 v[0:1], v[70:71], 0, s[30:31]
	s_mov_b32 m0, s21
	v_readfirstlane_b32 s23, v117
	v_add_u32_e32 v118, s24, v5
	v_add_u32_e32 v2, s3, v5
	v_lshlrev_b32_e32 v4, 7, v79
	global_load_lds_dwordx4 v[0:1], off
	v_lshl_add_u64 v[0:1], v[72:73], 0, s[30:31]
	s_mov_b32 m0, s23
	v_readfirstlane_b32 s24, v118
	v_add_u32_e32 v119, 0x8400, v2
	v_lshl_or_b32 v102, v80, 13, v4
	global_load_lds_dwordx4 v[0:1], off
	v_lshl_add_u64 v[0:1], v[74:75], 0, s[30:31]
	s_mov_b32 m0, s24
	v_readfirstlane_b32 s28, v119
	global_load_lds_dwordx4 v[0:1], off
	v_lshl_add_u64 v[0:1], v[76:77], 0, s[30:31]
	s_mov_b32 m0, s28
	v_add_u32_e32 v100, 0, v102
	global_load_lds_dwordx4 v[0:1], off
	v_add_u32_e32 v83, v100, v132
	v_ashrrev_i32_e32 v81, 7, v78
	ds_read_b128 a[0:3], v83 offset:32768
	ds_read_b128 a[4:7], v83 offset:36864
	v_lshl_or_b32 v134, v81, 13, v4
	v_add_u32_e32 v101, 0, v134
	v_add_u32_e32 v82, v101, v132
	ds_read_b128 a[8:11], v82
	ds_read_b128 a[12:15], v82 offset:4096
	v_lshrrev_b32_e32 v182, 6, v133
	s_nop 0
	v_readfirstlane_b32 s32, v182
	s_waitcnt lgkmcnt(1)
	v_mfma_f32_32x32x16_bf16 v[48:63], a[0:3], a[8:11], 0
	v_bfe_u32 v103, v78, 1, 3
	s_mov_b64 s[30:31], 0x180
	s_nop 0
	v_or_b32_e32 v143, 0x8000, v102
	v_or_b32_e32 v144, 0x9000, v102
	v_add_u32_e32 v145, s3, v134
	v_lshl_or_b32 v81, v81, 6, v79
	s_waitcnt vmcnt(12)
	v_mfma_f32_32x32x16_bf16 v[32:47], a[4:7], a[8:11], 0
	v_mul_lo_u32 v81, v81, s26
	s_mov_b64 s[80:81], 0x200
	s_waitcnt lgkmcnt(0)
	v_mfma_f32_32x32x16_bf16 v[16:31], a[0:3], a[12:15], 0
	v_bitop3_b32 v0, v64, v103, 2 bitop3:0x36
	v_lshlrev_b32_e32 v138, 4, v0
	v_add_u32_e32 v84, v101, v138
	ds_read_b128 a[28:31], v84 offset:4096
	s_nop 0
	s_nop 0
	ds_read_b128 a[24:27], v84
	s_nop 0
	v_add_u32_e32 v85, v100, v138
	ds_read_b128 a[20:23], v85 offset:36864
	s_nop 0
	s_nop 0
	ds_read_b128 a[16:19], v85 offset:32768
	s_nop 0
	s_nop 0
	s_nop 0
	s_nop 0
	s_nop 0
	s_nop 0
	v_mfma_f32_32x32x16_bf16 v[0:15], a[4:7], a[12:15], 0
	s_nop 0
	s_waitcnt lgkmcnt(0)
	v_mfma_f32_32x32x16_bf16 v[48:63], a[16:19], a[24:27], v[48:63]
	v_mfma_f32_32x32x16_bf16 v[32:47], a[20:23], a[24:27], v[32:47]
	v_mfma_f32_32x32x16_bf16 v[16:31], a[16:19], a[28:31], v[16:31]
	v_bitop3_b32 v86, v64, v103, 4 bitop3:0x36
	v_lshlrev_b32_e32 v139, 4, v86
	v_add_u32_e32 v86, v101, v139
	ds_read_b128 a[12:15], v86 offset:4096
	s_nop 0
	s_nop 0
	ds_read_b128 a[8:11], v86
	s_nop 0
	v_add_u32_e32 v87, v100, v139
	ds_read_b128 a[4:7], v87 offset:36864
	s_nop 0
	s_nop 0
	ds_read_b128 a[0:3], v87 offset:32768
	s_nop 0
	s_nop 0
	s_nop 0
	v_mfma_f32_32x32x16_bf16 v[0:15], a[20:23], a[28:31], v[0:15]
	s_nop 0
	s_nop 0
	s_nop 0
	s_nop 0
	s_waitcnt lgkmcnt(0)
	v_mfma_f32_32x32x16_bf16 v[48:63], a[0:3], a[8:11], v[48:63]
	v_mfma_f32_32x32x16_bf16 v[32:47], a[4:7], a[8:11], v[32:47]
	v_mfma_f32_32x32x16_bf16 v[16:31], a[0:3], a[12:15], v[16:31]
	v_bitop3_b32 v88, v64, v103, 6 bitop3:0x36
	v_lshlrev_b32_e32 v142, 4, v88
	v_add_u32_e32 v88, v101, v142
	ds_read_b128 a[28:31], v88 offset:4096
	s_nop 0
	s_nop 0
	ds_read_b128 a[24:27], v88
	s_nop 0
	v_add_u32_e32 v89, v100, v142
	ds_read_b128 a[20:23], v89 offset:36864
	s_nop 0
	s_nop 0
	ds_read_b128 a[16:19], v89 offset:32768
	s_nop 0
	s_nop 0
	s_nop 0
	v_lshlrev_b32_e32 v64, 4, v64
	v_lshl_or_b32 v64, v80, 8, v64
	v_add3_u32 v64, 0, v81, v64
	v_mfma_f32_32x32x16_bf16 v[0:15], a[4:7], a[12:15], v[0:15]
	s_nop 0
	s_nop 0
	s_nop 0
	s_nop 0
	s_waitcnt lgkmcnt(0)
	v_mfma_f32_32x32x16_bf16 v[48:63], a[16:19], a[24:27], v[48:63]
	v_mfma_f32_32x32x16_bf16 v[32:47], a[20:23], a[24:27], v[32:47]
	s_waitcnt vmcnt(6)
	s_waitcnt lgkmcnt(0)
	s_barrier
	ds_read_b128 a[12:15], v82 offset:53248
	ds_read_b128 a[8:11], v82 offset:49152
	v_mfma_f32_32x32x16_bf16 v[16:31], a[16:19], a[28:31], v[16:31]
	v_lshl_add_u64 v[158:159], v[66:67], 0, s[30:31]
	s_nop 0
	v_lshl_add_u64 v[160:161], v[68:69], 0, s[30:31]
	s_nop 0
	s_nop 0
	s_nop 0
	v_lshl_add_u64 v[162:163], v[70:71], 0, s[30:31]
	s_nop 0
	v_mfma_f32_32x32x16_bf16 v[0:15], a[20:23], a[28:31], v[0:15]
	s_and_b32 m0, s32, 7
	s_lshl_b32 m0, m0, 12
	s_add_i32 m0, m0, 0x0
	s_nop 0
	global_load_lds_dwordx4 v[158:159], off
	s_nop 0
	v_lshl_add_u64 v[164:165], v[72:73], 0, s[30:31]
	s_nop 0
	s_nop 0
	s_nop 0
	v_lshl_add_u64 v[166:167], v[74:75], 0, s[30:31]
	s_nop 0
	s_nop 0
	s_nop 0
	v_lshl_add_u64 v[168:169], v[76:77], 0, s[30:31]
	s_nop 0
	s_add_i32 s30, 0, 0xc000
	v_add_u32_e32 v90, s30, v132
	v_add_u32_e32 v92, v90, v143
	v_add_u32_e32 v90, v90, v144
	ds_read_b128 a[4:7], v90
	ds_read_b128 a[0:3], v92
	s_nop 0
	s_nop 0
	s_nop 0
	s_nop 0
	s_nop 0
	s_nop 0
	s_nop 0
	s_nop 0
	v_add_u32_e32 v91, s30, v138
	v_add_u32_e32 v93, v91, v143
	ds_read_b128 a[16:19], v93
	v_add_u32_e32 v91, v91, v144
	ds_read_b128 a[20:23], v91
	ds_read_b128 a[24:27], v84 offset:49152
	ds_read_b128 a[28:31], v84 offset:53248
	s_waitcnt lgkmcnt(4)
	v_mfma_f32_32x32x16_bf16 v[48:63], a[0:3], a[8:11], v[48:63]
	s_nop 0
	s_nop 0
	s_nop 0
	s_nop 0
	v_mfma_f32_32x32x16_bf16 v[32:47], a[4:7], a[8:11], v[32:47]
	v_mfma_f32_32x32x16_bf16 v[16:31], a[0:3], a[12:15], v[16:31]
	s_and_b32 m0, s32, 7
	s_lshl_b32 m0, m0, 12
	s_add_i32 m0, m0, 0x400
	s_nop 0
	global_load_lds_dwordx4 v[160:161], off
	v_mfma_f32_32x32x16_bf16 v[0:15], a[4:7], a[12:15], v[0:15]
	s_nop 0
	s_nop 0
	s_nop 0
	s_nop 0
	v_add_u32_e32 v94, s30, v139
	v_add_u32_e32 v95, v94, v143
	ds_read_b128 a[0:3], v95
	v_add_u32_e32 v94, v94, v144
	ds_read_b128 a[4:7], v94
	ds_read_b128 a[8:11], v86 offset:49152
	ds_read_b128 a[12:15], v86 offset:53248
	s_waitcnt lgkmcnt(5)
	v_mfma_f32_32x32x16_bf16 v[48:63], a[16:19], a[24:27], v[48:63]
	s_and_b32 m0, s32, 7
	s_lshl_b32 m0, m0, 12
	s_add_i32 m0, m0, 0x800
	s_nop 0
	global_load_lds_dwordx4 v[162:163], off
	v_mfma_f32_32x32x16_bf16 v[32:47], a[20:23], a[24:27], v[32:47]
	s_waitcnt lgkmcnt(4)
	v_mfma_f32_32x32x16_bf16 v[16:31], a[16:19], a[28:31], v[16:31]
	s_nop 0
	s_nop 0
	s_nop 0
	v_mfma_f32_32x32x16_bf16 v[0:15], a[20:23], a[28:31], v[0:15]
	s_and_b32 m0, s32, 7
	s_lshl_b32 m0, m0, 12
	s_add_i32 m0, m0, 0xc00
	s_nop 0
	global_load_lds_dwordx4 v[164:165], off
	s_nop 0
	s_nop 0
	s_nop 0
	s_nop 0
	v_add_u32_e32 v96, s30, v142
	v_add_u32_e32 v97, v96, v143
	ds_read_b128 a[16:19], v97
	v_add_u32_e32 v96, v96, v144
	ds_read_b128 a[20:23], v96
	ds_read_b128 a[24:27], v88 offset:49152
	ds_read_b128 a[28:31], v88 offset:53248
	s_waitcnt lgkmcnt(5)
	v_mfma_f32_32x32x16_bf16 v[48:63], a[0:3], a[8:11], v[48:63]
	v_mfma_f32_32x32x16_bf16 v[32:47], a[4:7], a[8:11], v[32:47]
	s_waitcnt lgkmcnt(4)
	v_mfma_f32_32x32x16_bf16 v[16:31], a[0:3], a[12:15], v[16:31]
	s_and_b32 m0, s32, 7
	s_lshl_b32 m0, m0, 11
	s_add_i32 m0, m0, 0x8000
	s_nop 0
	global_load_lds_dwordx4 v[166:167], off
	s_nop 0
	s_nop 0
	s_nop 0
	s_mov_b64 s[30:31], 0x200
	v_mfma_f32_32x32x16_bf16 v[0:15], a[4:7], a[12:15], v[0:15]
	s_nop 0
	s_nop 0
	s_nop 0
	s_nop 0
	s_waitcnt lgkmcnt(1)
	v_mfma_f32_32x32x16_bf16 v[48:63], a[16:19], a[24:27], v[48:63]
	s_and_b32 m0, s32, 7
	s_lshl_b32 m0, m0, 11
	s_add_i32 m0, m0, 0x8400
	s_nop 0
	global_load_lds_dwordx4 v[168:169], off
	v_mfma_f32_32x32x16_bf16 v[32:47], a[20:23], a[24:27], v[32:47]
	s_waitcnt vmcnt(6)
	s_waitcnt lgkmcnt(0)
	s_barrier
	v_add_u32_e32 v100, v145, v132
	ds_read_b128 a[8:11], v100
	v_add_u32_e32 v101, s3, v132
	v_add_u32_e32 v99, v101, v144
	ds_read_b128 a[4:7], v99
	s_nop 0
	v_add_u32_e32 v98, v101, v143
	v_or_b32_e32 v132, 0x1000, v134
	v_add_u32_e32 v101, v101, v132
	ds_read_b128 a[12:15], v101
	ds_read_b128 a[0:3], v98
	v_mfma_f32_32x32x16_bf16 v[16:31], a[16:19], a[28:31], v[16:31]
	v_lshl_add_u64 v[170:171], v[66:67], 0, s[30:31]
	s_nop 0
	v_lshl_add_u64 v[172:173], v[68:69], 0, s[30:31]
	s_nop 0
	s_nop 0
	s_nop 0
	v_lshl_add_u64 v[174:175], v[70:71], 0, s[30:31]
	s_nop 0
	v_mfma_f32_32x32x16_bf16 v[0:15], a[20:23], a[28:31], v[0:15]
	s_and_b32 m0, s32, 7
	s_lshl_b32 m0, m0, 12
	s_add_i32 m0, m0, 0xc000
	s_nop 0
	global_load_lds_dwordx4 v[170:171], off
	s_nop 0
	v_lshl_add_u64 v[176:177], v[72:73], 0, s[30:31]
	s_nop 0
	s_nop 0
	s_nop 0
	v_lshl_add_u64 v[178:179], v[74:75], 0, s[30:31]
	s_nop 0
	s_nop 0
	s_nop 0
	v_lshl_add_u64 v[180:181], v[76:77], 0, s[30:31]
	s_nop 0
	s_mov_b64 s[30:31], 0x280
	s_nop 0
	s_nop 0
	s_nop 0
	s_nop 0
	s_nop 0
	s_nop 0
	s_nop 0
	s_nop 0
	v_add_u32_e32 v105, s3, v138
	v_add_u32_e32 v102, v105, v143
	ds_read_b128 a[16:19], v102
	v_add_u32_e32 v103, v105, v144
	ds_read_b128 a[20:23], v103
	v_add_u32_e32 v104, v145, v138
	ds_read_b128 a[24:27], v104
	v_add_u32_e32 v105, v105, v132
	ds_read_b128 a[28:31], v105
	s_waitcnt lgkmcnt(4)
	v_mfma_f32_32x32x16_bf16 v[48:63], a[0:3], a[8:11], v[48:63]
	s_nop 0
	v_mfma_f32_32x32x16_bf16 v[32:47], a[4:7], a[8:11], v[32:47]
	s_nop 0
	s_nop 0
	s_nop 0
	s_nop 0
	s_nop 0
	v_mfma_f32_32x32x16_bf16 v[16:31], a[0:3], a[12:15], v[16:31]
	s_and_b32 m0, s32, 7
	s_lshl_b32 m0, m0, 12
	s_add_i32 m0, m0, 0xc400
	s_nop 0
	global_load_lds_dwordx4 v[172:173], off
	s_nop 0
	v_mfma_f32_32x32x16_bf16 v[0:15], a[4:7], a[12:15], v[0:15]
	s_nop 0
	s_nop 0
	s_nop 0
	v_add_u32_e32 v109, s3, v139
	v_add_u32_e32 v106, v109, v143
	ds_read_b128 a[0:3], v106
	v_add_u32_e32 v107, v109, v144
	ds_read_b128 a[4:7], v107
	v_add_u32_e32 v108, v145, v139
	ds_read_b128 a[8:11], v108
	v_add_u32_e32 v109, v109, v132
	ds_read_b128 a[12:15], v109
	s_waitcnt lgkmcnt(5)
	v_mfma_f32_32x32x16_bf16 v[48:63], a[16:19], a[24:27], v[48:63]
	s_and_b32 m0, s32, 7
	s_lshl_b32 m0, m0, 12
	s_add_i32 m0, m0, 0xc800
	s_nop 0
	global_load_lds_dwordx4 v[174:175], off
	v_mfma_f32_32x32x16_bf16 v[32:47], a[20:23], a[24:27], v[32:47]
	s_waitcnt lgkmcnt(4)
	v_mfma_f32_32x32x16_bf16 v[16:31], a[16:19], a[28:31], v[16:31]
	s_nop 0
	s_nop 0
	s_nop 0
	s_nop 0
	s_nop 0
	s_nop 0
	v_mfma_f32_32x32x16_bf16 v[0:15], a[20:23], a[28:31], v[0:15]
	s_and_b32 m0, s32, 7
	s_lshl_b32 m0, m0, 12
	s_add_i32 m0, m0, 0xcc00
	s_nop 0
	global_load_lds_dwordx4 v[176:177], off
	s_nop 0
	s_nop 0
	s_nop 0
	v_add_u32_e32 v113, s3, v142
	v_add_u32_e32 v110, v113, v143
	ds_read_b128 a[16:19], v110
	v_add_u32_e32 v111, v113, v144
	ds_read_b128 a[20:23], v111
	v_add_u32_e32 v112, v145, v142
	ds_read_b128 a[24:27], v112
	v_add_u32_e32 v113, v113, v132
	ds_read_b128 a[28:31], v113
	s_waitcnt lgkmcnt(5)
	v_mfma_f32_32x32x16_bf16 v[48:63], a[0:3], a[8:11], v[48:63]
	v_mfma_f32_32x32x16_bf16 v[32:47], a[4:7], a[8:11], v[32:47]
	s_waitcnt lgkmcnt(4)
	v_mfma_f32_32x32x16_bf16 v[16:31], a[0:3], a[12:15], v[16:31]
	s_and_b32 m0, s32, 7
	s_lshl_b32 m0, m0, 11
	s_add_i32 m0, m0, 0x14000
	s_nop 0
	global_load_lds_dwordx4 v[178:179], off
	s_nop 0
	s_nop 0
	s_nop 0
	s_nop 0
	s_nop 0
	s_nop 0
	v_mfma_f32_32x32x16_bf16 v[0:15], a[4:7], a[12:15], v[0:15]
	s_nop 0
	s_nop 0
	s_nop 0
	s_waitcnt lgkmcnt(1)
	v_mfma_f32_32x32x16_bf16 v[48:63], a[16:19], a[24:27], v[48:63]
	s_and_b32 m0, s32, 7
	s_lshl_b32 m0, m0, 11
	s_add_i32 m0, m0, 0x14400
	s_nop 0
	global_load_lds_dwordx4 v[180:181], off
	v_mfma_f32_32x32x16_bf16 v[32:47], a[20:23], a[24:27], v[32:47]
	s_waitcnt vmcnt(6)
	s_waitcnt lgkmcnt(0)
	s_barrier
	ds_read_b128 a[12:15], v82 offset:4096
	ds_read_b128 a[8:11], v82
	ds_read_b128 a[4:7], v83 offset:36864
	ds_read_b128 a[0:3], v83 offset:32768
	v_mfma_f32_32x32x16_bf16 v[16:31], a[16:19], a[28:31], v[16:31]
	v_lshl_add_u64 v[158:159], v[66:67], 0, s[30:31]
	s_nop 0
	v_lshl_add_u64 v[160:161], v[68:69], 0, s[30:31]
	s_nop 0
	s_nop 0
	s_nop 0
	v_lshl_add_u64 v[162:163], v[70:71], 0, s[30:31]
	s_nop 0
	v_mfma_f32_32x32x16_bf16 v[0:15], a[20:23], a[28:31], v[0:15]
	s_and_b32 m0, s32, 7
	s_lshl_b32 m0, m0, 12
	s_add_i32 m0, m0, 0x18000
	s_nop 0
	global_load_lds_dwordx4 v[158:159], off
	s_nop 0
	v_lshl_add_u64 v[164:165], v[72:73], 0, s[30:31]
	s_nop 0
	s_nop 0
	s_nop 0
	v_lshl_add_u64 v[166:167], v[74:75], 0, s[30:31]
	s_nop 0
	s_nop 0
	s_nop 0
	v_lshl_add_u64 v[168:169], v[76:77], 0, s[30:31]
	s_nop 0
	s_mov_b64 s[30:31], 0x300
	s_nop 0
	s_nop 0
	s_nop 0
	s_nop 0
	s_nop 0
	ds_read_b128 a[16:19], v85 offset:32768
	ds_read_b128 a[20:23], v85 offset:36864
	ds_read_b128 a[24:27], v84
	ds_read_b128 a[28:31], v84 offset:4096
	s_waitcnt lgkmcnt(4)
	v_mfma_f32_32x32x16_bf16 v[48:63], a[0:3], a[8:11], v[48:63]
	s_nop 0
	v_readfirstlane_b32 s38, v114
	v_mfma_f32_32x32x16_bf16 v[32:47], a[4:7], a[8:11], v[32:47]
	v_mfma_f32_32x32x16_bf16 v[16:31], a[0:3], a[12:15], v[16:31]
	s_and_b32 m0, s32, 7
	s_lshl_b32 m0, m0, 12
	s_add_i32 m0, m0, 0x18400
	s_nop 0
	global_load_lds_dwordx4 v[160:161], off
	v_mfma_f32_32x32x16_bf16 v[0:15], a[4:7], a[12:15], v[0:15]
	s_nop 0
	s_nop 0
	s_nop 0
	s_nop 0
	ds_read_b128 a[0:3], v87 offset:32768
	ds_read_b128 a[4:7], v87 offset:36864
	ds_read_b128 a[8:11], v86
	ds_read_b128 a[12:15], v86 offset:4096
	s_waitcnt lgkmcnt(5)
	v_mfma_f32_32x32x16_bf16 v[48:63], a[16:19], a[24:27], v[48:63]
	s_and_b32 m0, s32, 7
	s_lshl_b32 m0, m0, 12
	s_add_i32 m0, m0, 0x18800
	s_nop 0
	global_load_lds_dwordx4 v[162:163], off
	v_mfma_f32_32x32x16_bf16 v[32:47], a[20:23], a[24:27], v[32:47]
	s_waitcnt lgkmcnt(4)
	v_mfma_f32_32x32x16_bf16 v[16:31], a[16:19], a[28:31], v[16:31]
	v_mfma_f32_32x32x16_bf16 v[0:15], a[20:23], a[28:31], v[0:15]
	s_and_b32 m0, s32, 7
	s_lshl_b32 m0, m0, 12
	s_add_i32 m0, m0, 0x18c00
	s_nop 0
	global_load_lds_dwordx4 v[164:165], off
	s_nop 0
	s_nop 0
	s_nop 0
	s_nop 0
	ds_read_b128 a[16:19], v89 offset:32768
	ds_read_b128 a[20:23], v89 offset:36864
	ds_read_b128 a[24:27], v88
	ds_read_b128 a[28:31], v88 offset:4096
	s_waitcnt lgkmcnt(5)
	v_mfma_f32_32x32x16_bf16 v[48:63], a[0:3], a[8:11], v[48:63]
	v_mfma_f32_32x32x16_bf16 v[32:47], a[4:7], a[8:11], v[32:47]
	s_waitcnt lgkmcnt(4)
	v_mfma_f32_32x32x16_bf16 v[16:31], a[0:3], a[12:15], v[16:31]
	s_and_b32 m0, s32, 7
	s_lshl_b32 m0, m0, 11
	s_add_i32 m0, m0, 0x20000
	s_nop 0
	global_load_lds_dwordx4 v[166:167], off
	v_mfma_f32_32x32x16_bf16 v[0:15], a[4:7], a[12:15], v[0:15]
	s_nop 0
	s_nop 0
	s_nop 0
	s_nop 0
	s_waitcnt lgkmcnt(1)
	v_mfma_f32_32x32x16_bf16 v[48:63], a[16:19], a[24:27], v[48:63]
	s_and_b32 m0, s32, 7
	s_lshl_b32 m0, m0, 11
	s_add_i32 m0, m0, 0x20400
	s_nop 0
	global_load_lds_dwordx4 v[168:169], off
	v_mfma_f32_32x32x16_bf16 v[32:47], a[20:23], a[24:27], v[32:47]
	s_waitcnt vmcnt(6)
	s_waitcnt lgkmcnt(0)
	s_barrier
	ds_read_b128 a[12:15], v82 offset:53248
	ds_read_b128 a[8:11], v82 offset:49152
	ds_read_b128 a[4:7], v90
	ds_read_b128 a[0:3], v92
	v_mfma_f32_32x32x16_bf16 v[16:31], a[16:19], a[28:31], v[16:31]
	v_lshl_add_u64 v[170:171], v[66:67], 0, s[30:31]
	s_nop 0
	v_lshl_add_u64 v[172:173], v[68:69], 0, s[30:31]
	s_nop 0
	v_readfirstlane_b32 s39, v115
	s_nop 0
	v_lshl_add_u64 v[174:175], v[70:71], 0, s[30:31]
	s_nop 0
	v_mfma_f32_32x32x16_bf16 v[0:15], a[20:23], a[28:31], v[0:15]
	s_and_b32 m0, s32, 7
	s_lshl_b32 m0, m0, 12
	s_add_i32 m0, m0, 0x0
	s_nop 0
	global_load_lds_dwordx4 v[170:171], off
	s_nop 0
	v_lshl_add_u64 v[176:177], v[72:73], 0, s[30:31]
	s_nop 0
	v_readfirstlane_b32 s48, v116
	s_nop 0
	v_lshl_add_u64 v[178:179], v[74:75], 0, s[30:31]
	s_nop 0
	v_readfirstlane_b32 s49, v117
	s_nop 0
	v_lshl_add_u64 v[180:181], v[76:77], 0, s[30:31]
	s_nop 0
	s_mov_b64 s[30:31], 0x380
	s_nop 0
	s_nop 0
	s_nop 0
	s_nop 0
	s_nop 0
	ds_read_b128 a[16:19], v93
	ds_read_b128 a[20:23], v91
	ds_read_b128 a[24:27], v84 offset:49152
	ds_read_b128 a[28:31], v84 offset:53248
	s_waitcnt lgkmcnt(4)
	v_mfma_f32_32x32x16_bf16 v[48:63], a[0:3], a[8:11], v[48:63]
	s_nop 0
	v_readfirstlane_b32 s53, v118
	v_readfirstlane_b32 s54, v119
	v_mfma_f32_32x32x16_bf16 v[32:47], a[4:7], a[8:11], v[32:47]
	v_mfma_f32_32x32x16_bf16 v[16:31], a[0:3], a[12:15], v[16:31]
	s_and_b32 m0, s32, 7
	s_lshl_b32 m0, m0, 12
	s_add_i32 m0, m0, 0x400
	s_nop 0
	global_load_lds_dwordx4 v[172:173], off
	v_mfma_f32_32x32x16_bf16 v[0:15], a[4:7], a[12:15], v[0:15]
	s_nop 0
	s_nop 0
	s_nop 0
	s_nop 0
	ds_read_b128 a[0:3], v95
	ds_read_b128 a[4:7], v94
	ds_read_b128 a[8:11], v86 offset:49152
	ds_read_b128 a[12:15], v86 offset:53248
	s_waitcnt lgkmcnt(5)
	v_mfma_f32_32x32x16_bf16 v[48:63], a[16:19], a[24:27], v[48:63]
	s_and_b32 m0, s32, 7
	s_lshl_b32 m0, m0, 12
	s_add_i32 m0, m0, 0x800
	s_nop 0
	global_load_lds_dwordx4 v[174:175], off
	v_mfma_f32_32x32x16_bf16 v[32:47], a[20:23], a[24:27], v[32:47]
	s_waitcnt lgkmcnt(4)
	v_mfma_f32_32x32x16_bf16 v[16:31], a[16:19], a[28:31], v[16:31]
	v_mfma_f32_32x32x16_bf16 v[0:15], a[20:23], a[28:31], v[0:15]
	s_and_b32 m0, s32, 7
	s_lshl_b32 m0, m0, 12
	s_add_i32 m0, m0, 0xc00
	s_nop 0
	global_load_lds_dwordx4 v[176:177], off
	s_nop 0
	s_nop 0
	s_nop 0
	s_nop 0
	ds_read_b128 a[16:19], v97
	ds_read_b128 a[20:23], v96
	ds_read_b128 a[24:27], v88 offset:49152
	ds_read_b128 a[28:31], v88 offset:53248
	s_waitcnt lgkmcnt(5)
	v_mfma_f32_32x32x16_bf16 v[48:63], a[0:3], a[8:11], v[48:63]
	v_mfma_f32_32x32x16_bf16 v[32:47], a[4:7], a[8:11], v[32:47]
	s_waitcnt lgkmcnt(4)
	v_mfma_f32_32x32x16_bf16 v[16:31], a[0:3], a[12:15], v[16:31]
	s_and_b32 m0, s32, 7
	s_lshl_b32 m0, m0, 11
	s_add_i32 m0, m0, 0x8000
	s_nop 0
	global_load_lds_dwordx4 v[178:179], off
	v_mfma_f32_32x32x16_bf16 v[0:15], a[4:7], a[12:15], v[0:15]
	s_nop 0
	s_nop 0
	s_nop 0
	s_nop 0
	s_waitcnt lgkmcnt(1)
	v_mfma_f32_32x32x16_bf16 v[48:63], a[16:19], a[24:27], v[48:63]
	s_and_b32 m0, s32, 7
	s_lshl_b32 m0, m0, 11
	s_add_i32 m0, m0, 0x8400
	s_nop 0
	global_load_lds_dwordx4 v[180:181], off
	v_mfma_f32_32x32x16_bf16 v[32:47], a[20:23], a[24:27], v[32:47]
	s_waitcnt vmcnt(6)
	s_waitcnt lgkmcnt(0)
	s_barrier
	ds_read_b128 a[12:15], v101
	ds_read_b128 a[8:11], v100
	ds_read_b128 a[4:7], v99
	ds_read_b128 a[0:3], v98
	v_mfma_f32_32x32x16_bf16 v[16:31], a[16:19], a[28:31], v[16:31]
	v_lshl_add_u64 v[158:159], v[66:67], 0, s[30:31]
	s_nop 0
	v_lshl_add_u64 v[160:161], v[68:69], 0, s[30:31]
	s_nop 0
	v_readfirstlane_b32 s33, v121
	s_nop 0
	v_lshl_add_u64 v[162:163], v[70:71], 0, s[30:31]
	s_nop 0
	v_mfma_f32_32x32x16_bf16 v[0:15], a[20:23], a[28:31], v[0:15]
	s_and_b32 m0, s32, 7
	s_lshl_b32 m0, m0, 12
	s_add_i32 m0, m0, 0xc000
	s_nop 0
	global_load_lds_dwordx4 v[158:159], off
	s_nop 0
	v_lshl_add_u64 v[164:165], v[72:73], 0, s[30:31]
	s_nop 0
	v_readfirstlane_b32 s34, v122
	s_nop 0
	v_lshl_add_u64 v[166:167], v[74:75], 0, s[30:31]
	s_nop 0
	v_readfirstlane_b32 s35, v123
	s_nop 0
	v_lshl_add_u64 v[168:169], v[76:77], 0, s[30:31]
	s_nop 0
	s_mov_b64 s[30:31], 0x400
	s_nop 0
	s_nop 0
	s_nop 0
	s_nop 0
	s_nop 0
	ds_read_b128 a[16:19], v102
	ds_read_b128 a[20:23], v103
	ds_read_b128 a[24:27], v104
	ds_read_b128 a[28:31], v105
	s_waitcnt lgkmcnt(4)
	v_mfma_f32_32x32x16_bf16 v[48:63], a[0:3], a[8:11], v[48:63]
	s_nop 0
	v_readfirstlane_b32 s1, v126
	v_readfirstlane_b32 s36, v124
	v_readfirstlane_b32 s37, v125
	v_mfma_f32_32x32x16_bf16 v[32:47], a[4:7], a[8:11], v[32:47]
	v_mfma_f32_32x32x16_bf16 v[16:31], a[0:3], a[12:15], v[16:31]
	s_and_b32 m0, s32, 7
	s_lshl_b32 m0, m0, 12
	s_add_i32 m0, m0, 0xc400
	s_nop 0
	global_load_lds_dwordx4 v[160:161], off
	v_mfma_f32_32x32x16_bf16 v[0:15], a[4:7], a[12:15], v[0:15]
	s_nop 0
	s_nop 0
	s_nop 0
	s_nop 0
	ds_read_b128 a[0:3], v106
	ds_read_b128 a[4:7], v107
	ds_read_b128 a[8:11], v108
	ds_read_b128 a[12:15], v109
	s_waitcnt lgkmcnt(5)
	v_mfma_f32_32x32x16_bf16 v[48:63], a[16:19], a[24:27], v[48:63]
	s_and_b32 m0, s32, 7
	s_lshl_b32 m0, m0, 12
	s_add_i32 m0, m0, 0xc800
	s_nop 0
	global_load_lds_dwordx4 v[162:163], off
	v_mfma_f32_32x32x16_bf16 v[32:47], a[20:23], a[24:27], v[32:47]
	s_waitcnt lgkmcnt(4)
	v_mfma_f32_32x32x16_bf16 v[16:31], a[16:19], a[28:31], v[16:31]
	v_mfma_f32_32x32x16_bf16 v[0:15], a[20:23], a[28:31], v[0:15]
	s_and_b32 m0, s32, 7
	s_lshl_b32 m0, m0, 12
	s_add_i32 m0, m0, 0xcc00
	s_nop 0
	global_load_lds_dwordx4 v[164:165], off
	s_nop 0
	s_nop 0
	s_nop 0
	s_nop 0
	ds_read_b128 a[16:19], v110
	ds_read_b128 a[20:23], v111
	ds_read_b128 a[24:27], v112
	ds_read_b128 a[28:31], v113
	s_waitcnt lgkmcnt(5)
	v_mfma_f32_32x32x16_bf16 v[48:63], a[0:3], a[8:11], v[48:63]
	v_mfma_f32_32x32x16_bf16 v[32:47], a[4:7], a[8:11], v[32:47]
	s_waitcnt lgkmcnt(4)
	v_mfma_f32_32x32x16_bf16 v[16:31], a[0:3], a[12:15], v[16:31]
	s_and_b32 m0, s32, 7
	s_lshl_b32 m0, m0, 11
	s_add_i32 m0, m0, 0x14000
	s_nop 0
	global_load_lds_dwordx4 v[166:167], off
	v_mfma_f32_32x32x16_bf16 v[0:15], a[4:7], a[12:15], v[0:15]
	s_nop 0
	s_nop 0
	s_nop 0
	s_nop 0
	s_waitcnt lgkmcnt(1)
	v_mfma_f32_32x32x16_bf16 v[48:63], a[16:19], a[24:27], v[48:63]
	s_and_b32 m0, s32, 7
	s_lshl_b32 m0, m0, 11
	s_add_i32 m0, m0, 0x14400
	s_nop 0
	global_load_lds_dwordx4 v[168:169], off
	v_mfma_f32_32x32x16_bf16 v[32:47], a[20:23], a[24:27], v[32:47]
	s_waitcnt vmcnt(6)
	s_waitcnt lgkmcnt(0)
	s_barrier
	ds_read_b128 a[12:15], v82 offset:4096
	ds_read_b128 a[8:11], v82
	ds_read_b128 a[4:7], v83 offset:36864
	ds_read_b128 a[0:3], v83 offset:32768
	v_mfma_f32_32x32x16_bf16 v[16:31], a[16:19], a[28:31], v[16:31]
	v_lshl_add_u64 v[170:171], v[66:67], 0, s[30:31]
	s_nop 0
	v_lshl_add_u64 v[172:173], v[68:69], 0, s[30:31]
	s_nop 0
	v_readfirstlane_b32 s20, v127
	s_nop 0
	v_lshl_add_u64 v[174:175], v[70:71], 0, s[30:31]
	s_nop 0
	v_mfma_f32_32x32x16_bf16 v[0:15], a[20:23], a[28:31], v[0:15]
	s_and_b32 m0, s32, 7
	s_lshl_b32 m0, m0, 12
	s_add_i32 m0, m0, 0x18000
	s_nop 0
	global_load_lds_dwordx4 v[170:171], off
	s_nop 0
	v_lshl_add_u64 v[176:177], v[72:73], 0, s[30:31]
	s_nop 0
	v_readfirstlane_b32 s21, v128
	s_nop 0
	v_lshl_add_u64 v[178:179], v[74:75], 0, s[30:31]
	s_nop 0
	v_readfirstlane_b32 s23, v129
	s_nop 0
	v_lshl_add_u64 v[180:181], v[76:77], 0, s[30:31]
	s_nop 0
	s_mov_b64 s[28:29], 0x480
	s_nop 0
	s_nop 0
	s_nop 0
	s_nop 0
	s_nop 0
	ds_read_b128 a[16:19], v85 offset:32768
	ds_read_b128 a[20:23], v85 offset:36864
	ds_read_b128 a[24:27], v84
	ds_read_b128 a[28:31], v84 offset:4096
	s_waitcnt lgkmcnt(4)
	v_mfma_f32_32x32x16_bf16 v[48:63], a[0:3], a[8:11], v[48:63]
	s_nop 0
	v_lshl_add_u64 v[162:163], v[70:71], 0, s[28:29]
	v_readfirstlane_b32 s24, v131
	s_mov_b64 s[30:31], 0x500
	v_mfma_f32_32x32x16_bf16 v[32:47], a[4:7], a[8:11], v[32:47]
	v_mfma_f32_32x32x16_bf16 v[16:31], a[0:3], a[12:15], v[16:31]
	s_and_b32 m0, s32, 7
	s_lshl_b32 m0, m0, 12
	s_add_i32 m0, m0, 0x18400
	s_nop 0
	global_load_lds_dwordx4 v[172:173], off
	v_mfma_f32_32x32x16_bf16 v[0:15], a[4:7], a[12:15], v[0:15]
	s_nop 0
	s_nop 0
	s_nop 0
	s_nop 0
	ds_read_b128 a[0:3], v87 offset:32768
	ds_read_b128 a[4:7], v87 offset:36864
	ds_read_b128 a[8:11], v86
	ds_read_b128 a[12:15], v86 offset:4096
	s_waitcnt lgkmcnt(5)
	v_mfma_f32_32x32x16_bf16 v[48:63], a[16:19], a[24:27], v[48:63]
	s_and_b32 m0, s32, 7
	s_lshl_b32 m0, m0, 12
	s_add_i32 m0, m0, 0x18800
	s_nop 0
	global_load_lds_dwordx4 v[174:175], off
	v_mfma_f32_32x32x16_bf16 v[32:47], a[20:23], a[24:27], v[32:47]
	s_waitcnt lgkmcnt(4)
	v_mfma_f32_32x32x16_bf16 v[16:31], a[16:19], a[28:31], v[16:31]
	v_mfma_f32_32x32x16_bf16 v[0:15], a[20:23], a[28:31], v[0:15]
	s_and_b32 m0, s32, 7
	s_lshl_b32 m0, m0, 12
	s_add_i32 m0, m0, 0x18c00
	s_nop 0
	global_load_lds_dwordx4 v[176:177], off
	s_nop 0
	s_nop 0
	s_nop 0
	s_nop 0
	ds_read_b128 a[16:19], v89 offset:32768
	ds_read_b128 a[20:23], v89 offset:36864
	ds_read_b128 a[24:27], v88
	ds_read_b128 a[28:31], v88 offset:4096
	s_waitcnt lgkmcnt(5)
	v_mfma_f32_32x32x16_bf16 v[48:63], a[0:3], a[8:11], v[48:63]
	v_mfma_f32_32x32x16_bf16 v[32:47], a[4:7], a[8:11], v[32:47]
	s_waitcnt lgkmcnt(4)
	v_mfma_f32_32x32x16_bf16 v[16:31], a[0:3], a[12:15], v[16:31]
	s_and_b32 m0, s32, 7
	s_lshl_b32 m0, m0, 11
	s_add_i32 m0, m0, 0x20000
	s_nop 0
	global_load_lds_dwordx4 v[178:179], off
	v_mfma_f32_32x32x16_bf16 v[0:15], a[4:7], a[12:15], v[0:15]
	s_nop 0
	s_nop 0
	s_nop 0
	s_nop 0
	s_waitcnt lgkmcnt(1)
	v_mfma_f32_32x32x16_bf16 v[48:63], a[16:19], a[24:27], v[48:63]
	s_and_b32 m0, s32, 7
	s_lshl_b32 m0, m0, 11
	s_add_i32 m0, m0, 0x20400
	s_nop 0
	global_load_lds_dwordx4 v[180:181], off
	v_mfma_f32_32x32x16_bf16 v[32:47], a[20:23], a[24:27], v[32:47]
	s_waitcnt vmcnt(6)
	s_waitcnt lgkmcnt(0)
	s_barrier
	ds_read_b128 a[12:15], v82 offset:53248
	ds_read_b128 a[8:11], v82 offset:49152
	ds_read_b128 a[4:7], v90
	ds_read_b128 a[0:3], v92
	v_mfma_f32_32x32x16_bf16 v[16:31], a[16:19], a[28:31], v[16:31]
	v_lshl_add_u64 v[158:159], v[66:67], 0, s[28:29]
	s_nop 0
	v_lshl_add_u64 v[160:161], v[68:69], 0, s[28:29]
	s_nop 0
	s_nop 0
	s_nop 0
	s_nop 0
	v_mfma_f32_32x32x16_bf16 v[0:15], a[20:23], a[28:31], v[0:15]
	s_and_b32 m0, s32, 7
	s_lshl_b32 m0, m0, 12
	s_add_i32 m0, m0, 0x0
	s_nop 0
	global_load_lds_dwordx4 v[158:159], off
	s_nop 0
	v_lshl_add_u64 v[164:165], v[72:73], 0, s[28:29]
	s_nop 0
	s_nop 0
	s_nop 0
	v_lshl_add_u64 v[166:167], v[74:75], 0, s[28:29]
	s_nop 0
	s_nop 0
	s_nop 0
	v_lshl_add_u64 v[168:169], v[76:77], 0, s[28:29]
	v_readfirstlane_b32 s28, v130
	s_nop 0
	v_readfirstlane_b32 s29, v120
	s_nop 0
	s_nop 0
	s_nop 0
	s_nop 0
	s_nop 0
	ds_read_b128 a[16:19], v93
	ds_read_b128 a[20:23], v91
	ds_read_b128 a[24:27], v84 offset:49152
	ds_read_b128 a[28:31], v84 offset:53248
	s_waitcnt lgkmcnt(4)
	v_mfma_f32_32x32x16_bf16 v[48:63], a[0:3], a[8:11], v[48:63]
	s_nop 0
	v_lshl_add_u64 v[174:175], v[70:71], 0, s[30:31]
	v_mfma_f32_32x32x16_bf16 v[32:47], a[4:7], a[8:11], v[32:47]
	v_mfma_f32_32x32x16_bf16 v[16:31], a[0:3], a[12:15], v[16:31]
	s_and_b32 m0, s32, 7
	s_lshl_b32 m0, m0, 12
	s_add_i32 m0, m0, 0x400
	s_nop 0
	global_load_lds_dwordx4 v[160:161], off
	v_mfma_f32_32x32x16_bf16 v[0:15], a[4:7], a[12:15], v[0:15]
	s_nop 0
	s_nop 0
	s_nop 0
	s_nop 0
	ds_read_b128 a[0:3], v95
	ds_read_b128 a[4:7], v94
	ds_read_b128 a[8:11], v86 offset:49152
	ds_read_b128 a[12:15], v86 offset:53248
	s_waitcnt lgkmcnt(5)
	v_mfma_f32_32x32x16_bf16 v[48:63], a[16:19], a[24:27], v[48:63]
	s_and_b32 m0, s32, 7
	s_lshl_b32 m0, m0, 12
	s_add_i32 m0, m0, 0x800
	s_nop 0
	global_load_lds_dwordx4 v[162:163], off
	v_mfma_f32_32x32x16_bf16 v[32:47], a[20:23], a[24:27], v[32:47]
	s_waitcnt lgkmcnt(4)
	v_mfma_f32_32x32x16_bf16 v[16:31], a[16:19], a[28:31], v[16:31]
	v_mfma_f32_32x32x16_bf16 v[0:15], a[20:23], a[28:31], v[0:15]
	s_and_b32 m0, s32, 7
	s_lshl_b32 m0, m0, 12
	s_add_i32 m0, m0, 0xc00
	s_nop 0
	global_load_lds_dwordx4 v[164:165], off
	s_nop 0
	s_nop 0
	s_nop 0
	s_nop 0
	ds_read_b128 a[16:19], v97
	ds_read_b128 a[20:23], v96
	ds_read_b128 a[24:27], v88 offset:49152
	ds_read_b128 a[28:31], v88 offset:53248
	s_waitcnt lgkmcnt(5)
	v_mfma_f32_32x32x16_bf16 v[48:63], a[0:3], a[8:11], v[48:63]
	v_mfma_f32_32x32x16_bf16 v[32:47], a[4:7], a[8:11], v[32:47]
	s_waitcnt lgkmcnt(4)
	v_mfma_f32_32x32x16_bf16 v[16:31], a[0:3], a[12:15], v[16:31]
	s_and_b32 m0, s32, 7
	s_lshl_b32 m0, m0, 11
	s_add_i32 m0, m0, 0x8000
	s_nop 0
	global_load_lds_dwordx4 v[166:167], off
	v_mfma_f32_32x32x16_bf16 v[0:15], a[4:7], a[12:15], v[0:15]
	s_nop 0
	s_nop 0
	s_nop 0
	s_nop 0
	s_waitcnt lgkmcnt(1)
	v_mfma_f32_32x32x16_bf16 v[48:63], a[16:19], a[24:27], v[48:63]
	s_and_b32 m0, s32, 7
	s_lshl_b32 m0, m0, 11
	s_add_i32 m0, m0, 0x8400
	s_nop 0
	global_load_lds_dwordx4 v[168:169], off
	v_mfma_f32_32x32x16_bf16 v[32:47], a[20:23], a[24:27], v[32:47]
	s_waitcnt vmcnt(6)
	s_waitcnt lgkmcnt(0)
	s_barrier
	ds_read_b128 a[12:15], v101
	ds_read_b128 a[8:11], v100
	ds_read_b128 a[4:7], v99
	ds_read_b128 a[0:3], v98
	v_mfma_f32_32x32x16_bf16 v[16:31], a[16:19], a[28:31], v[16:31]
	v_lshl_add_u64 v[170:171], v[66:67], 0, s[30:31]
	s_nop 0
	v_lshl_add_u64 v[172:173], v[68:69], 0, s[30:31]
	s_nop 0
	s_nop 0
	s_nop 0
	s_nop 0
	v_mfma_f32_32x32x16_bf16 v[0:15], a[20:23], a[28:31], v[0:15]
	s_and_b32 m0, s32, 7
	s_lshl_b32 m0, m0, 12
	s_add_i32 m0, m0, 0xc000
	s_nop 0
	global_load_lds_dwordx4 v[170:171], off
	s_nop 0
	v_lshl_add_u64 v[176:177], v[72:73], 0, s[30:31]
	s_nop 0
	s_nop 0
	s_nop 0
	v_lshl_add_u64 v[178:179], v[74:75], 0, s[30:31]
	s_nop 0
	s_nop 0
	s_nop 0
	v_lshl_add_u64 v[180:181], v[76:77], 0, s[30:31]
	s_nop 0
	s_mov_b64 s[30:31], 0x580
	s_nop 0
	s_nop 0
	s_nop 0
	s_nop 0
	s_nop 0
	ds_read_b128 a[16:19], v102
	ds_read_b128 a[20:23], v103
	ds_read_b128 a[24:27], v104
	ds_read_b128 a[28:31], v105
	s_waitcnt lgkmcnt(4)
	v_mfma_f32_32x32x16_bf16 v[48:63], a[0:3], a[8:11], v[48:63]
	s_nop 0
	v_lshl_add_u64 v[162:163], v[70:71], 0, s[30:31]
	v_mfma_f32_32x32x16_bf16 v[32:47], a[4:7], a[8:11], v[32:47]
	v_mfma_f32_32x32x16_bf16 v[16:31], a[0:3], a[12:15], v[16:31]
	s_and_b32 m0, s32, 7
	s_lshl_b32 m0, m0, 12
	s_add_i32 m0, m0, 0xc400
	s_nop 0
	global_load_lds_dwordx4 v[172:173], off
	v_mfma_f32_32x32x16_bf16 v[0:15], a[4:7], a[12:15], v[0:15]
	s_nop 0
	s_nop 0
	s_nop 0
	s_nop 0
	ds_read_b128 a[0:3], v106
	ds_read_b128 a[4:7], v107
	ds_read_b128 a[8:11], v108
	ds_read_b128 a[12:15], v109
	s_waitcnt lgkmcnt(5)
	v_mfma_f32_32x32x16_bf16 v[48:63], a[16:19], a[24:27], v[48:63]
	s_and_b32 m0, s32, 7
	s_lshl_b32 m0, m0, 12
	s_add_i32 m0, m0, 0xc800
	s_nop 0
	global_load_lds_dwordx4 v[174:175], off
	v_mfma_f32_32x32x16_bf16 v[32:47], a[20:23], a[24:27], v[32:47]
	s_waitcnt lgkmcnt(4)
	v_mfma_f32_32x32x16_bf16 v[16:31], a[16:19], a[28:31], v[16:31]
	v_mfma_f32_32x32x16_bf16 v[0:15], a[20:23], a[28:31], v[0:15]
	s_and_b32 m0, s32, 7
	s_lshl_b32 m0, m0, 12
	s_add_i32 m0, m0, 0xcc00
	s_nop 0
	global_load_lds_dwordx4 v[176:177], off
	s_nop 0
	s_nop 0
	s_nop 0
	s_nop 0
	ds_read_b128 a[16:19], v110
	ds_read_b128 a[20:23], v111
	ds_read_b128 a[24:27], v112
	ds_read_b128 a[28:31], v113
	s_waitcnt lgkmcnt(5)
	v_mfma_f32_32x32x16_bf16 v[48:63], a[0:3], a[8:11], v[48:63]
	v_mfma_f32_32x32x16_bf16 v[32:47], a[4:7], a[8:11], v[32:47]
	s_waitcnt lgkmcnt(4)
	v_mfma_f32_32x32x16_bf16 v[16:31], a[0:3], a[12:15], v[16:31]
	s_and_b32 m0, s32, 7
	s_lshl_b32 m0, m0, 11
	s_add_i32 m0, m0, 0x14000
	s_nop 0
	global_load_lds_dwordx4 v[178:179], off
	v_mfma_f32_32x32x16_bf16 v[0:15], a[4:7], a[12:15], v[0:15]
	s_nop 0
	s_nop 0
	s_nop 0
	s_nop 0
	s_waitcnt lgkmcnt(1)
	v_mfma_f32_32x32x16_bf16 v[48:63], a[16:19], a[24:27], v[48:63]
	s_and_b32 m0, s32, 7
	s_lshl_b32 m0, m0, 11
	s_add_i32 m0, m0, 0x14400
	s_nop 0
	global_load_lds_dwordx4 v[180:181], off
	v_mfma_f32_32x32x16_bf16 v[32:47], a[20:23], a[24:27], v[32:47]
	s_waitcnt vmcnt(6)
	s_waitcnt lgkmcnt(0)
	s_barrier
	ds_read_b128 a[12:15], v82 offset:4096
	ds_read_b128 a[8:11], v82
	ds_read_b128 a[4:7], v83 offset:36864
	ds_read_b128 a[0:3], v83 offset:32768
	v_mfma_f32_32x32x16_bf16 v[16:31], a[16:19], a[28:31], v[16:31]
	v_lshl_add_u64 v[158:159], v[66:67], 0, s[30:31]
	s_nop 0
	v_lshl_add_u64 v[160:161], v[68:69], 0, s[30:31]
	s_nop 0
	s_nop 0
	s_nop 0
	s_nop 0
	v_mfma_f32_32x32x16_bf16 v[0:15], a[20:23], a[28:31], v[0:15]
	s_and_b32 m0, s32, 7
	s_lshl_b32 m0, m0, 12
	s_add_i32 m0, m0, 0x18000
	s_nop 0
	global_load_lds_dwordx4 v[158:159], off
	s_nop 0
	v_lshl_add_u64 v[164:165], v[72:73], 0, s[30:31]
	s_nop 0
	s_nop 0
	s_nop 0
	v_lshl_add_u64 v[166:167], v[74:75], 0, s[30:31]
	s_nop 0
	s_nop 0
	s_nop 0
	v_lshl_add_u64 v[168:169], v[76:77], 0, s[30:31]
	s_nop 0
	s_mov_b64 s[30:31], 0x600
	s_nop 0
	s_nop 0
	s_nop 0
	s_nop 0
	s_nop 0
	ds_read_b128 a[16:19], v85 offset:32768
	ds_read_b128 a[20:23], v85 offset:36864
	ds_read_b128 a[24:27], v84
	ds_read_b128 a[28:31], v84 offset:4096
	s_waitcnt lgkmcnt(4)
	v_mfma_f32_32x32x16_bf16 v[48:63], a[0:3], a[8:11], v[48:63]
	s_nop 0
	v_mfma_f32_32x32x16_bf16 v[32:47], a[4:7], a[8:11], v[32:47]
	v_mfma_f32_32x32x16_bf16 v[16:31], a[0:3], a[12:15], v[16:31]
	s_and_b32 m0, s32, 7
	s_lshl_b32 m0, m0, 12
	s_add_i32 m0, m0, 0x18400
	s_nop 0
	global_load_lds_dwordx4 v[160:161], off
	v_mfma_f32_32x32x16_bf16 v[0:15], a[4:7], a[12:15], v[0:15]
	s_nop 0
	s_nop 0
	s_nop 0
	s_nop 0
	ds_read_b128 a[0:3], v87 offset:32768
	ds_read_b128 a[4:7], v87 offset:36864
	ds_read_b128 a[8:11], v86
	ds_read_b128 a[12:15], v86 offset:4096
	s_waitcnt lgkmcnt(5)
	v_mfma_f32_32x32x16_bf16 v[48:63], a[16:19], a[24:27], v[48:63]
	s_and_b32 m0, s32, 7
	s_lshl_b32 m0, m0, 12
	s_add_i32 m0, m0, 0x18800
	s_nop 0
	global_load_lds_dwordx4 v[162:163], off
	v_mfma_f32_32x32x16_bf16 v[32:47], a[20:23], a[24:27], v[32:47]
	s_waitcnt lgkmcnt(4)
	v_mfma_f32_32x32x16_bf16 v[16:31], a[16:19], a[28:31], v[16:31]
	v_mfma_f32_32x32x16_bf16 v[0:15], a[20:23], a[28:31], v[0:15]
	s_and_b32 m0, s32, 7
	s_lshl_b32 m0, m0, 12
	s_add_i32 m0, m0, 0x18c00
	s_nop 0
	global_load_lds_dwordx4 v[164:165], off
	s_nop 0
	s_nop 0
	s_nop 0
	s_nop 0
	ds_read_b128 a[16:19], v89 offset:32768
	ds_read_b128 a[20:23], v89 offset:36864
	ds_read_b128 a[24:27], v88
	ds_read_b128 a[28:31], v88 offset:4096
	s_waitcnt lgkmcnt(5)
	v_mfma_f32_32x32x16_bf16 v[48:63], a[0:3], a[8:11], v[48:63]
	v_mfma_f32_32x32x16_bf16 v[32:47], a[4:7], a[8:11], v[32:47]
	s_waitcnt lgkmcnt(4)
	v_mfma_f32_32x32x16_bf16 v[16:31], a[0:3], a[12:15], v[16:31]
	s_and_b32 m0, s32, 7
	s_lshl_b32 m0, m0, 11
	s_add_i32 m0, m0, 0x20000
	s_nop 0
	global_load_lds_dwordx4 v[166:167], off
	v_mfma_f32_32x32x16_bf16 v[0:15], a[4:7], a[12:15], v[0:15]
	s_nop 0
	s_nop 0
	s_nop 0
	s_nop 0
	s_waitcnt lgkmcnt(1)
	v_mfma_f32_32x32x16_bf16 v[48:63], a[16:19], a[24:27], v[48:63]
	s_and_b32 m0, s32, 7
	s_lshl_b32 m0, m0, 11
	s_add_i32 m0, m0, 0x20400
	s_nop 0
	global_load_lds_dwordx4 v[168:169], off
	v_mfma_f32_32x32x16_bf16 v[32:47], a[20:23], a[24:27], v[32:47]
	s_waitcnt vmcnt(6)
	s_waitcnt lgkmcnt(0)
	s_barrier
	ds_read_b128 a[12:15], v82 offset:53248
	ds_read_b128 a[8:11], v82 offset:49152
	ds_read_b128 a[4:7], v90
	ds_read_b128 a[0:3], v92
	v_mfma_f32_32x32x16_bf16 v[16:31], a[16:19], a[28:31], v[16:31]
	v_lshl_add_u64 v[170:171], v[66:67], 0, s[30:31]
	s_nop 0
	v_lshl_add_u64 v[172:173], v[68:69], 0, s[30:31]
	s_nop 0
	s_nop 0
	s_nop 0
	v_lshl_add_u64 v[174:175], v[70:71], 0, s[30:31]
	s_nop 0
	v_mfma_f32_32x32x16_bf16 v[0:15], a[20:23], a[28:31], v[0:15]
	s_and_b32 m0, s32, 7
	s_lshl_b32 m0, m0, 12
	s_add_i32 m0, m0, 0x0
	s_nop 0
	global_load_lds_dwordx4 v[170:171], off
	s_nop 0
	v_lshl_add_u64 v[176:177], v[72:73], 0, s[30:31]
	s_nop 0
	s_nop 0
	s_nop 0
	v_lshl_add_u64 v[178:179], v[74:75], 0, s[30:31]
	s_nop 0
	s_nop 0
	s_nop 0
	v_lshl_add_u64 v[180:181], v[76:77], 0, s[30:31]
	s_nop 0
	s_mov_b64 s[30:31], 0x680
	s_nop 0
	s_nop 0
	s_nop 0
	s_nop 0
	s_nop 0
	ds_read_b128 a[16:19], v93
	ds_read_b128 a[20:23], v91
	ds_read_b128 a[24:27], v84 offset:49152
	ds_read_b128 a[28:31], v84 offset:53248
	s_waitcnt lgkmcnt(4)
	v_mfma_f32_32x32x16_bf16 v[48:63], a[0:3], a[8:11], v[48:63]
	s_nop 0
	v_mfma_f32_32x32x16_bf16 v[32:47], a[4:7], a[8:11], v[32:47]
	v_mfma_f32_32x32x16_bf16 v[16:31], a[0:3], a[12:15], v[16:31]
	s_and_b32 m0, s32, 7
	s_lshl_b32 m0, m0, 12
	s_add_i32 m0, m0, 0x400
	s_nop 0
	global_load_lds_dwordx4 v[172:173], off
	v_mfma_f32_32x32x16_bf16 v[0:15], a[4:7], a[12:15], v[0:15]
	s_nop 0
	s_nop 0
	s_nop 0
	s_nop 0
	ds_read_b128 a[0:3], v95
	ds_read_b128 a[4:7], v94
	ds_read_b128 a[8:11], v86 offset:49152
	ds_read_b128 a[12:15], v86 offset:53248
	s_waitcnt lgkmcnt(5)
	v_mfma_f32_32x32x16_bf16 v[48:63], a[16:19], a[24:27], v[48:63]
	s_and_b32 m0, s32, 7
	s_lshl_b32 m0, m0, 12
	s_add_i32 m0, m0, 0x800
	s_nop 0
	global_load_lds_dwordx4 v[174:175], off
	v_mfma_f32_32x32x16_bf16 v[32:47], a[20:23], a[24:27], v[32:47]
	s_waitcnt lgkmcnt(4)
	v_mfma_f32_32x32x16_bf16 v[16:31], a[16:19], a[28:31], v[16:31]
	v_mfma_f32_32x32x16_bf16 v[0:15], a[20:23], a[28:31], v[0:15]
	s_and_b32 m0, s32, 7
	s_lshl_b32 m0, m0, 12
	s_add_i32 m0, m0, 0xc00
	s_nop 0
	global_load_lds_dwordx4 v[176:177], off
	s_nop 0
	s_nop 0
	s_nop 0
	s_nop 0
	ds_read_b128 a[16:19], v97
	ds_read_b128 a[20:23], v96
	ds_read_b128 a[24:27], v88 offset:49152
	ds_read_b128 a[28:31], v88 offset:53248
	s_waitcnt lgkmcnt(5)
	v_mfma_f32_32x32x16_bf16 v[48:63], a[0:3], a[8:11], v[48:63]
	v_mfma_f32_32x32x16_bf16 v[32:47], a[4:7], a[8:11], v[32:47]
	s_waitcnt lgkmcnt(4)
	v_mfma_f32_32x32x16_bf16 v[16:31], a[0:3], a[12:15], v[16:31]
	s_and_b32 m0, s32, 7
	s_lshl_b32 m0, m0, 11
	s_add_i32 m0, m0, 0x8000
	s_nop 0
	global_load_lds_dwordx4 v[178:179], off
	v_mfma_f32_32x32x16_bf16 v[0:15], a[4:7], a[12:15], v[0:15]
	s_nop 0
	s_nop 0
	s_nop 0
	s_nop 0
	s_waitcnt lgkmcnt(1)
	v_mfma_f32_32x32x16_bf16 v[48:63], a[16:19], a[24:27], v[48:63]
	s_and_b32 m0, s32, 7
	s_lshl_b32 m0, m0, 11
	s_add_i32 m0, m0, 0x8400
	s_nop 0
	global_load_lds_dwordx4 v[180:181], off
	v_mfma_f32_32x32x16_bf16 v[32:47], a[20:23], a[24:27], v[32:47]
	s_waitcnt vmcnt(6)
	s_waitcnt lgkmcnt(0)
	s_barrier
	ds_read_b128 a[12:15], v101
	ds_read_b128 a[8:11], v100
	ds_read_b128 a[4:7], v99
	ds_read_b128 a[0:3], v98
	v_mfma_f32_32x32x16_bf16 v[16:31], a[16:19], a[28:31], v[16:31]
	v_lshl_add_u64 v[158:159], v[66:67], 0, s[30:31]
	s_nop 0
	v_lshl_add_u64 v[160:161], v[68:69], 0, s[30:31]
	s_nop 0
	s_nop 0
	s_nop 0
	v_lshl_add_u64 v[162:163], v[70:71], 0, s[30:31]
	s_nop 0
	v_mfma_f32_32x32x16_bf16 v[0:15], a[20:23], a[28:31], v[0:15]
	s_and_b32 m0, s32, 7
	s_lshl_b32 m0, m0, 12
	s_add_i32 m0, m0, 0xc000
	s_nop 0
	global_load_lds_dwordx4 v[158:159], off
	s_nop 0
	v_lshl_add_u64 v[164:165], v[72:73], 0, s[30:31]
	s_nop 0
	s_nop 0
	s_nop 0
	v_lshl_add_u64 v[166:167], v[74:75], 0, s[30:31]
	s_nop 0
	s_nop 0
	s_nop 0
	v_lshl_add_u64 v[168:169], v[76:77], 0, s[30:31]
	s_nop 0
	s_mov_b64 s[30:31], 0x700
	s_nop 0
	s_nop 0
	s_nop 0
	s_nop 0
	s_nop 0
	ds_read_b128 a[16:19], v102
	ds_read_b128 a[20:23], v103
	ds_read_b128 a[24:27], v104
	ds_read_b128 a[28:31], v105
	s_waitcnt lgkmcnt(4)
	v_mfma_f32_32x32x16_bf16 v[48:63], a[0:3], a[8:11], v[48:63]
	s_nop 0
	v_mfma_f32_32x32x16_bf16 v[32:47], a[4:7], a[8:11], v[32:47]
	v_mfma_f32_32x32x16_bf16 v[16:31], a[0:3], a[12:15], v[16:31]
	s_and_b32 m0, s32, 7
	s_lshl_b32 m0, m0, 12
	s_add_i32 m0, m0, 0xc400
	s_nop 0
	global_load_lds_dwordx4 v[160:161], off
	v_mfma_f32_32x32x16_bf16 v[0:15], a[4:7], a[12:15], v[0:15]
	s_nop 0
	s_nop 0
	s_nop 0
	s_nop 0
	ds_read_b128 a[0:3], v106
	ds_read_b128 a[4:7], v107
	ds_read_b128 a[8:11], v108
	ds_read_b128 a[12:15], v109
	s_waitcnt lgkmcnt(5)
	v_mfma_f32_32x32x16_bf16 v[48:63], a[16:19], a[24:27], v[48:63]
	s_and_b32 m0, s32, 7
	s_lshl_b32 m0, m0, 12
	s_add_i32 m0, m0, 0xc800
	s_nop 0
	global_load_lds_dwordx4 v[162:163], off
	v_mfma_f32_32x32x16_bf16 v[32:47], a[20:23], a[24:27], v[32:47]
	s_waitcnt lgkmcnt(4)
	v_mfma_f32_32x32x16_bf16 v[16:31], a[16:19], a[28:31], v[16:31]
	v_mfma_f32_32x32x16_bf16 v[0:15], a[20:23], a[28:31], v[0:15]
	s_and_b32 m0, s32, 7
	s_lshl_b32 m0, m0, 12
	s_add_i32 m0, m0, 0xcc00
	s_nop 0
	global_load_lds_dwordx4 v[164:165], off
	s_nop 0
	s_nop 0
	s_nop 0
	s_nop 0
	ds_read_b128 a[16:19], v110
	ds_read_b128 a[20:23], v111
	ds_read_b128 a[24:27], v112
	ds_read_b128 a[28:31], v113
	s_waitcnt lgkmcnt(5)
	v_mfma_f32_32x32x16_bf16 v[48:63], a[0:3], a[8:11], v[48:63]
	v_mfma_f32_32x32x16_bf16 v[32:47], a[4:7], a[8:11], v[32:47]
	s_waitcnt lgkmcnt(4)
	v_mfma_f32_32x32x16_bf16 v[16:31], a[0:3], a[12:15], v[16:31]
	s_and_b32 m0, s32, 7
	s_lshl_b32 m0, m0, 11
	s_add_i32 m0, m0, 0x14000
	s_nop 0
	global_load_lds_dwordx4 v[166:167], off
	v_mfma_f32_32x32x16_bf16 v[0:15], a[4:7], a[12:15], v[0:15]
	s_nop 0
	s_nop 0
	s_nop 0
	s_nop 0
	s_waitcnt lgkmcnt(1)
	v_mfma_f32_32x32x16_bf16 v[48:63], a[16:19], a[24:27], v[48:63]
	s_and_b32 m0, s32, 7
	s_lshl_b32 m0, m0, 11
	s_add_i32 m0, m0, 0x14400
	s_nop 0
	global_load_lds_dwordx4 v[168:169], off
	v_mfma_f32_32x32x16_bf16 v[32:47], a[20:23], a[24:27], v[32:47]
	s_waitcnt vmcnt(6)
	s_waitcnt lgkmcnt(0)
	s_barrier
	ds_read_b128 a[12:15], v82 offset:4096
	ds_read_b128 a[8:11], v82
	ds_read_b128 a[4:7], v83 offset:36864
	ds_read_b128 a[0:3], v83 offset:32768
	v_mfma_f32_32x32x16_bf16 v[16:31], a[16:19], a[28:31], v[16:31]
	v_lshl_add_u64 v[170:171], v[66:67], 0, s[30:31]
	s_nop 0
	v_lshl_add_u64 v[172:173], v[68:69], 0, s[30:31]
	s_nop 0
	s_nop 0
	s_nop 0
	v_lshl_add_u64 v[174:175], v[70:71], 0, s[30:31]
	s_nop 0
	v_mfma_f32_32x32x16_bf16 v[0:15], a[20:23], a[28:31], v[0:15]
	s_and_b32 m0, s32, 7
	s_lshl_b32 m0, m0, 12
	s_add_i32 m0, m0, 0x18000
	s_nop 0
	global_load_lds_dwordx4 v[170:171], off
	s_nop 0
	v_lshl_add_u64 v[176:177], v[72:73], 0, s[30:31]
	s_nop 0
	s_nop 0
	s_nop 0
	v_lshl_add_u64 v[178:179], v[74:75], 0, s[30:31]
	s_nop 0
	s_nop 0
	s_nop 0
	v_lshl_add_u64 v[180:181], v[76:77], 0, s[30:31]
	s_nop 0
	s_mov_b64 s[30:31], 0x780
	s_nop 0
	s_nop 0
	s_nop 0
	s_nop 0
	s_nop 0
	ds_read_b128 a[16:19], v85 offset:32768
	ds_read_b128 a[20:23], v85 offset:36864
	ds_read_b128 a[24:27], v84
	ds_read_b128 a[28:31], v84 offset:4096
	s_waitcnt lgkmcnt(4)
	v_mfma_f32_32x32x16_bf16 v[48:63], a[0:3], a[8:11], v[48:63]
	v_lshl_add_u64 v[158:159], v[66:67], 0, s[30:31]
	s_nop 0
	v_mfma_f32_32x32x16_bf16 v[32:47], a[4:7], a[8:11], v[32:47]
	v_mfma_f32_32x32x16_bf16 v[16:31], a[0:3], a[12:15], v[16:31]
	s_and_b32 m0, s32, 7
	s_lshl_b32 m0, m0, 12
	s_add_i32 m0, m0, 0x18400
	s_nop 0
	global_load_lds_dwordx4 v[172:173], off
	v_mfma_f32_32x32x16_bf16 v[0:15], a[4:7], a[12:15], v[0:15]
	s_nop 0
	s_nop 0
	s_nop 0
	s_nop 0
	ds_read_b128 a[0:3], v87 offset:32768
	ds_read_b128 a[4:7], v87 offset:36864
	ds_read_b128 a[8:11], v86
	ds_read_b128 a[12:15], v86 offset:4096
	s_waitcnt lgkmcnt(5)
	v_mfma_f32_32x32x16_bf16 v[48:63], a[16:19], a[24:27], v[48:63]
	s_and_b32 m0, s32, 7
	s_lshl_b32 m0, m0, 12
	s_add_i32 m0, m0, 0x18800
	s_nop 0
	global_load_lds_dwordx4 v[174:175], off
	v_mfma_f32_32x32x16_bf16 v[32:47], a[20:23], a[24:27], v[32:47]
	s_waitcnt lgkmcnt(4)
	v_mfma_f32_32x32x16_bf16 v[16:31], a[16:19], a[28:31], v[16:31]
	v_mfma_f32_32x32x16_bf16 v[0:15], a[20:23], a[28:31], v[0:15]
	s_and_b32 m0, s32, 7
	s_lshl_b32 m0, m0, 12
	s_add_i32 m0, m0, 0x18c00
	s_nop 0
	global_load_lds_dwordx4 v[176:177], off
	s_nop 0
	s_nop 0
	s_nop 0
	s_nop 0
	ds_read_b128 a[16:19], v89 offset:32768
	ds_read_b128 a[20:23], v89 offset:36864
	ds_read_b128 a[24:27], v88
	ds_read_b128 a[28:31], v88 offset:4096
	s_waitcnt lgkmcnt(5)
	v_mfma_f32_32x32x16_bf16 v[48:63], a[0:3], a[8:11], v[48:63]
	v_mfma_f32_32x32x16_bf16 v[32:47], a[4:7], a[8:11], v[32:47]
	s_waitcnt lgkmcnt(4)
	v_mfma_f32_32x32x16_bf16 v[16:31], a[0:3], a[12:15], v[16:31]
	s_and_b32 m0, s32, 7
	s_lshl_b32 m0, m0, 11
	s_add_i32 m0, m0, 0x20000
	s_nop 0
	global_load_lds_dwordx4 v[178:179], off
	v_mfma_f32_32x32x16_bf16 v[0:15], a[4:7], a[12:15], v[0:15]
	s_nop 0
	s_nop 0
	s_nop 0
	s_nop 0
	s_waitcnt lgkmcnt(1)
	v_mfma_f32_32x32x16_bf16 v[48:63], a[16:19], a[24:27], v[48:63]
	s_and_b32 m0, s32, 7
	s_lshl_b32 m0, m0, 11
	s_add_i32 m0, m0, 0x20400
	s_nop 0
	global_load_lds_dwordx4 v[180:181], off
	v_mfma_f32_32x32x16_bf16 v[32:47], a[20:23], a[24:27], v[32:47]
	s_waitcnt vmcnt(6)
	s_waitcnt lgkmcnt(0)
	s_barrier
	ds_read_b128 a[12:15], v82 offset:53248
	ds_read_b128 a[8:11], v82 offset:49152
	ds_read_b128 a[4:7], v90
	ds_read_b128 a[0:3], v92
	s_nop 0
	v_lshl_add_u64 v[160:161], v[68:69], 0, s[30:31]
	s_nop 0
	v_mfma_f32_32x32x16_bf16 v[16:31], a[16:19], a[28:31], v[16:31]
	s_nop 0
	v_lshl_add_u64 v[162:163], v[70:71], 0, s[30:31]
	s_nop 0
	v_readlane_b32 s20, v215, 52
	s_nop 0
	v_lshl_add_u64 v[164:165], v[72:73], 0, s[30:31]
	s_nop 0
	v_mfma_f32_32x32x16_bf16 v[0:15], a[20:23], a[28:31], v[0:15]
	s_and_b32 m0, s32, 7
	s_lshl_b32 m0, m0, 12
	s_add_i32 m0, m0, 0x0
	s_nop 0
	global_load_lds_dwordx4 v[158:159], off
	s_nop 0
	v_lshl_add_u64 v[166:167], v[74:75], 0, s[30:31]
	s_nop 0
	v_readlane_b32 s21, v215, 53
	s_nop 0
	v_lshl_add_u64 v[168:169], v[76:77], 0, s[30:31]
	s_nop 0
	s_mov_b32 s23, 0
	s_nop 0
	s_nop 0
	s_nop 0
	s_nop 0
	s_nop 0
	ds_read_b128 a[16:19], v93
	ds_read_b128 a[20:23], v91
	ds_read_b128 a[24:27], v84 offset:49152
	ds_read_b128 a[28:31], v84 offset:53248
	s_waitcnt lgkmcnt(4)
	v_mfma_f32_32x32x16_bf16 v[48:63], a[0:3], a[8:11], v[48:63]
	v_mfma_f32_32x32x16_bf16 v[32:47], a[4:7], a[8:11], v[32:47]
	v_mfma_f32_32x32x16_bf16 v[16:31], a[0:3], a[12:15], v[16:31]
	s_and_b32 m0, s32, 7
	s_lshl_b32 m0, m0, 12
	s_add_i32 m0, m0, 0x400
	s_nop 0
	global_load_lds_dwordx4 v[160:161], off
	v_mfma_f32_32x32x16_bf16 v[0:15], a[4:7], a[12:15], v[0:15]
	s_nop 0
	s_nop 0
	s_nop 0
	s_nop 0
	ds_read_b128 a[0:3], v95
	ds_read_b128 a[4:7], v94
	ds_read_b128 a[8:11], v86 offset:49152
	ds_read_b128 a[12:15], v86 offset:53248
	s_waitcnt lgkmcnt(5)
	v_mfma_f32_32x32x16_bf16 v[48:63], a[16:19], a[24:27], v[48:63]
	s_and_b32 m0, s32, 7
	s_lshl_b32 m0, m0, 12
	s_add_i32 m0, m0, 0x800
	s_nop 0
	global_load_lds_dwordx4 v[162:163], off
	v_mfma_f32_32x32x16_bf16 v[32:47], a[20:23], a[24:27], v[32:47]
	s_waitcnt lgkmcnt(4)
	v_mfma_f32_32x32x16_bf16 v[16:31], a[16:19], a[28:31], v[16:31]
	v_mfma_f32_32x32x16_bf16 v[0:15], a[20:23], a[28:31], v[0:15]
	s_and_b32 m0, s32, 7
	s_lshl_b32 m0, m0, 12
	s_add_i32 m0, m0, 0xc00
	s_nop 0
	global_load_lds_dwordx4 v[164:165], off
	s_nop 0
	s_nop 0
	s_nop 0
	s_nop 0
	ds_read_b128 a[16:19], v97
	ds_read_b128 a[20:23], v96
	ds_read_b128 a[24:27], v88 offset:49152
	ds_read_b128 a[28:31], v88 offset:53248
	s_waitcnt lgkmcnt(5)
	v_mfma_f32_32x32x16_bf16 v[48:63], a[0:3], a[8:11], v[48:63]
	v_mfma_f32_32x32x16_bf16 v[32:47], a[4:7], a[8:11], v[32:47]
	s_waitcnt lgkmcnt(4)
	v_mfma_f32_32x32x16_bf16 v[16:31], a[0:3], a[12:15], v[16:31]
	s_and_b32 m0, s32, 7
	s_lshl_b32 m0, m0, 11
	s_add_i32 m0, m0, 0x8000
	s_nop 0
	global_load_lds_dwordx4 v[166:167], off
	v_mfma_f32_32x32x16_bf16 v[0:15], a[4:7], a[12:15], v[0:15]
	s_nop 0
	s_nop 0
	s_nop 0
	s_nop 0
	s_waitcnt lgkmcnt(1)
	v_mfma_f32_32x32x16_bf16 v[48:63], a[16:19], a[24:27], v[48:63]
	s_and_b32 m0, s32, 7
	s_lshl_b32 m0, m0, 11
	s_add_i32 m0, m0, 0x8400
	s_nop 0
	global_load_lds_dwordx4 v[168:169], off
	v_mfma_f32_32x32x16_bf16 v[32:47], a[20:23], a[24:27], v[32:47]
	s_waitcnt vmcnt(6)
	s_waitcnt lgkmcnt(0)
	s_barrier
	ds_read_b128 a[12:15], v101
	ds_read_b128 a[8:11], v100
	ds_read_b128 a[4:7], v99
	ds_read_b128 a[0:3], v98
	v_mfma_f32_32x32x16_bf16 v[16:31], a[16:19], a[28:31], v[16:31]
	v_mfma_f32_32x32x16_bf16 v[0:15], a[20:23], a[28:31], v[0:15]
	s_nop 0
	s_nop 0
	s_nop 0
	s_nop 0
	ds_read_b128 a[16:19], v102
	ds_read_b128 a[20:23], v103
	ds_read_b128 a[24:27], v104
	ds_read_b128 a[28:31], v105
	s_waitcnt lgkmcnt(4)
	v_mfma_f32_32x32x16_bf16 v[48:63], a[0:3], a[8:11], v[48:63]
	v_mfma_f32_32x32x16_bf16 v[32:47], a[4:7], a[8:11], v[32:47]
	v_mfma_f32_32x32x16_bf16 v[16:31], a[0:3], a[12:15], v[16:31]
	v_mfma_f32_32x32x16_bf16 v[0:15], a[4:7], a[12:15], v[0:15]
	s_nop 0
	s_nop 0
	s_nop 0
	s_nop 0
	ds_read_b128 a[0:3], v106
	ds_read_b128 a[4:7], v107
	ds_read_b128 a[8:11], v108
	ds_read_b128 a[12:15], v109
	s_waitcnt lgkmcnt(5)
	v_mfma_f32_32x32x16_bf16 v[48:63], a[16:19], a[24:27], v[48:63]
	v_mfma_f32_32x32x16_bf16 v[32:47], a[20:23], a[24:27], v[32:47]
	s_waitcnt lgkmcnt(4)
	v_mfma_f32_32x32x16_bf16 v[16:31], a[16:19], a[28:31], v[16:31]
	v_mfma_f32_32x32x16_bf16 v[0:15], a[20:23], a[28:31], v[0:15]
	s_nop 0
	s_nop 0
	s_nop 0
	s_nop 0
	ds_read_b128 a[16:19], v110
	ds_read_b128 a[20:23], v111
	ds_read_b128 a[24:27], v112
	ds_read_b128 a[28:31], v113
	s_waitcnt lgkmcnt(5)
	v_mfma_f32_32x32x16_bf16 v[48:63], a[0:3], a[8:11], v[48:63]
	v_mfma_f32_32x32x16_bf16 v[32:47], a[4:7], a[8:11], v[32:47]
	s_waitcnt lgkmcnt(4)
	v_mfma_f32_32x32x16_bf16 v[16:31], a[0:3], a[12:15], v[16:31]
	v_mfma_f32_32x32x16_bf16 v[0:15], a[4:7], a[12:15], v[0:15]
	s_nop 0
	s_nop 0
	s_nop 0
	s_nop 0
	s_waitcnt lgkmcnt(1)
	v_mfma_f32_32x32x16_bf16 v[48:63], a[16:19], a[24:27], v[48:63]
	v_mfma_f32_32x32x16_bf16 v[32:47], a[20:23], a[24:27], v[32:47]
	s_waitcnt vmcnt(0)
	s_waitcnt lgkmcnt(0)
	s_barrier
	ds_read_b128 a[12:15], v82 offset:4096
	ds_read_b128 a[8:11], v82
	ds_read_b128 a[4:7], v83 offset:36864
	ds_read_b128 a[0:3], v83 offset:32768
	v_mfma_f32_32x32x16_bf16 v[16:31], a[16:19], a[28:31], v[16:31]
	v_mfma_f32_32x32x16_bf16 v[0:15], a[20:23], a[28:31], v[0:15]
	s_nop 0
	s_nop 0
	s_nop 0
	s_nop 0
	ds_read_b128 a[16:19], v85 offset:32768
	ds_read_b128 a[20:23], v85 offset:36864
	ds_read_b128 a[24:27], v84
	ds_read_b128 a[28:31], v84 offset:4096
	s_waitcnt lgkmcnt(4)
	v_mfma_f32_32x32x16_bf16 v[48:63], a[0:3], a[8:11], v[48:63]
	v_mfma_f32_32x32x16_bf16 v[32:47], a[4:7], a[8:11], v[32:47]
	v_mfma_f32_32x32x16_bf16 v[16:31], a[0:3], a[12:15], v[16:31]
	v_mfma_f32_32x32x16_bf16 v[0:15], a[4:7], a[12:15], v[0:15]
	s_nop 0
	s_nop 0
	s_nop 0
	s_nop 0
	ds_read_b128 a[0:3], v87 offset:32768
	ds_read_b128 a[4:7], v87 offset:36864
	ds_read_b128 a[8:11], v86
	ds_read_b128 a[12:15], v86 offset:4096
	s_waitcnt lgkmcnt(5)
	v_mfma_f32_32x32x16_bf16 v[48:63], a[16:19], a[24:27], v[48:63]
	v_mfma_f32_32x32x16_bf16 v[32:47], a[20:23], a[24:27], v[32:47]
	s_waitcnt lgkmcnt(4)
	v_mfma_f32_32x32x16_bf16 v[16:31], a[16:19], a[28:31], v[16:31]
	v_mfma_f32_32x32x16_bf16 v[0:15], a[20:23], a[28:31], v[0:15]
	s_nop 0
	s_nop 0
	s_nop 0
	s_waitcnt lgkmcnt(1)
	v_mfma_f32_32x32x16_bf16 v[48:63], a[0:3], a[8:11], v[48:63]
	v_mfma_f32_32x32x16_bf16 v[32:47], a[4:7], a[8:11], v[32:47]
	s_nop 0
	s_waitcnt lgkmcnt(0)
	v_mfma_f32_32x32x16_bf16 v[0:15], a[4:7], a[12:15], v[0:15]
	v_mfma_f32_32x32x16_bf16 v[16:31], a[0:3], a[12:15], v[16:31]
	ds_read_b128 v[66:69], v89 offset:32768
	ds_read_b128 v[70:73], v88
	ds_read_b128 v[74:77], v89 offset:36864
	ds_read_b128 v[82:85], v88 offset:4096
	s_waitcnt lgkmcnt(0)
	s_barrier
	s_waitcnt lgkmcnt(0)
	v_mfma_f32_32x32x16_bf16 v[48:63], v[66:69], v[70:73], v[48:63]
	v_mfma_f32_32x32x16_bf16 v[32:47], v[74:77], v[70:73], v[32:47]
	s_nop 10
	ds_write_b128 v64, v[48:51]
	ds_write_b128 v64, v[52:55] offset:32
	ds_write_b128 v64, v[56:59] offset:64
	ds_write_b128 v64, v[60:63] offset:96
	ds_write_b128 v64, v[32:35] offset:128
	v_mfma_f32_32x32x16_bf16 v[0:15], v[74:77], v[82:85], v[0:15]
	v_mfma_f32_32x32x16_bf16 v[16:31], v[66:69], v[82:85], v[16:31]
	ds_write_b128 v64, v[36:39] offset:160
	ds_write_b128 v64, v[40:43] offset:192
	ds_write_b128 v64, v[44:47] offset:224
	s_nop 8
	ds_write_b128 v64, v[16:19] offset:16896
	ds_write_b128 v64, v[20:23] offset:16928
	ds_write_b128 v64, v[24:27] offset:16960
	ds_write_b128 v64, v[28:31] offset:16992
	ds_write_b128 v64, v[0:3] offset:17024
	ds_write_b128 v64, v[4:7] offset:17056
	ds_write_b128 v64, v[8:11] offset:17088
	ds_write_b128 v64, v[12:15] offset:17120
	s_waitcnt lgkmcnt(0)
	s_barrier
	v_lshl_or_b32 v0, v79, 2, s0
	v_ashrrev_i32_e32 v1, 31, v0
	v_lshl_add_u32 v4, v79, 4, 0
	v_cmp_eq_u32_e64 s[0:1], 0, v79
	v_lshl_add_u64 v[6:7], v[0:1], 2, s[92:93]
	v_lshl_add_u64 v[8:9], v[0:1], 1, s[20:21]
	s_branch .LBB0_96

.LBB0_159:
	v_mov_b32_e32 v78, v133
	s_lshl_b32 s22, s2, 8
	v_ashrrev_i32_e32 v6, 6, v78
	v_bfe_u32 v7, v78, 3, 3
	v_lshl_or_b32 v8, v6, 5, v7
	v_add_u32_e32 v0, s22, v8
	s_waitcnt lgkmcnt(0)
	v_ashrrev_i32_e32 v1, 31, v0
	v_lshlrev_b64 v[2:3], 11, v[0:1]
	v_bfe_u32 v1, v78, 4, 2
	v_readlane_b32 s0, v214, 4
	v_xor_b32_e32 v1, v1, v78
	v_readlane_b32 s1, v214, 5
	v_lshlrev_b32_e32 v1, 4, v1
	v_and_b32_e32 v64, 0x70, v1
	v_lshl_add_u64 v[2:3], s[0:1], 0, v[2:3]
	v_or_b32_e32 v1, 8, v8
	v_lshl_add_u64 v[66:67], v[2:3], 0, v[64:65]
	v_add_u32_e32 v2, s22, v1
	v_lshrrev_b32_e32 v1, 1, v1
	v_xor_b32_e32 v1, v1, v78
	v_ashrrev_i32_e32 v3, 31, v2
	v_lshlrev_b32_e32 v1, 4, v1
	v_or_b32_e32 v0, 16, v0
	v_lshlrev_b64 v[2:3], 11, v[2:3]
	v_and_b32_e32 v4, 0x70, v1
	v_ashrrev_i32_e32 v1, 31, v0
	v_lshl_add_u64 v[2:3], s[0:1], 0, v[2:3]
	v_mov_b32_e32 v5, v65
	v_lshlrev_b64 v[0:1], 11, v[0:1]
	v_lshl_add_u64 v[68:69], v[2:3], 0, v[4:5]
	v_lshl_add_u64 v[0:1], s[0:1], 0, v[0:1]
	v_or_b32_e32 v2, 24, v8
	v_lshl_add_u64 v[70:71], v[0:1], 0, v[64:65]
	v_add_u32_e32 v0, s22, v2
	v_lshrrev_b32_e32 v2, 1, v2
	v_ashrrev_i32_e32 v1, 31, v0
	v_xor_b32_e32 v2, v2, v78
	v_lshlrev_b64 v[0:1], 11, v[0:1]
	v_lshlrev_b32_e32 v2, 4, v2
	v_lshl_add_u64 v[0:1], s[0:1], 0, v[0:1]
	v_and_b32_e32 v2, 0x70, v2
	v_mov_b32_e32 v3, v65
	v_lshl_add_u64 v[72:73], v[0:1], 0, v[2:3]
	v_lshl_or_b32 v2, v6, 4, v7
	v_readlane_b32 s31, v214, 58
	v_lshlrev_b32_e32 v3, 12, v6
	v_add_u32_e32 v126, 0, v3
	v_add_u32_e32 v0, s31, v2
	v_ashrrev_i32_e32 v1, 31, v0
	v_lshlrev_b64 v[0:1], 11, v[0:1]
	s_waitcnt vmcnt(0)
	v_readfirstlane_b32 s37, v126
	v_add_u32_e32 v127, 0x400, v126
	v_lshl_add_u64 v[0:1], s[40:41], 0, v[0:1]
	v_or_b32_e32 v2, 8, v2
	s_waitcnt lgkmcnt(0)
	s_barrier
	s_mov_b32 m0, s37
	v_readfirstlane_b32 s38, v127
	v_add_u32_e32 v128, 0x800, v126
	v_lshlrev_b32_e32 v5, 11, v6
	v_and_b32_e32 v80, 1, v6
	v_lshl_add_u64 v[74:75], v[0:1], 0, v[64:65]
	v_add_u32_e32 v0, s31, v2
	v_lshrrev_b32_e32 v2, 1, v2
	global_load_lds_dwordx4 v[66:67], off
	s_mov_b32 m0, s38
	v_readfirstlane_b32 s39, v128
	v_add_u32_e32 v129, 0xc00, v126
	v_add_u32_e32 v6, 0, v5
	v_ashrrev_i32_e32 v1, 31, v0
	v_xor_b32_e32 v2, v2, v78
	global_load_lds_dwordx4 v[68:69], off
	s_mov_b32 m0, s39
	v_readfirstlane_b32 s48, v129
	v_add_u32_e32 v131, 0x8000, v6
	v_lshlrev_b64 v[0:1], 11, v[0:1]
	v_lshlrev_b32_e32 v2, 4, v2
	global_load_lds_dwordx4 v[70:71], off
	s_mov_b32 m0, s48
	v_readfirstlane_b32 s49, v131
	v_add_u32_e32 v130, 0x8400, v6
	v_lshl_add_u64 v[0:1], s[40:41], 0, v[0:1]
	v_and_b32_e32 v64, 0x70, v2
	global_load_lds_dwordx4 v[72:73], off
	s_mov_b32 m0, s49
	v_readfirstlane_b32 s53, v130
	v_add_u32_e32 v120, 0xc000, v126
	v_lshl_add_u64 v[76:77], v[0:1], 0, v[64:65]
	global_load_lds_dwordx4 v[74:75], off
	s_mov_b32 m0, s53
	s_mov_b64 s[0:1], 0x80
	v_readfirstlane_b32 s28, v120
	v_add_u32_e32 v121, 0xc400, v126
	global_load_lds_dwordx4 v[76:77], off
	v_lshl_add_u64 v[0:1], v[66:67], 0, s[0:1]
	s_mov_b32 m0, s28
	v_readfirstlane_b32 s29, v121
	v_add_u32_e32 v122, 0xc800, v126
	global_load_lds_dwordx4 v[0:1], off
	v_lshl_add_u64 v[0:1], v[68:69], 0, s[0:1]
	s_mov_b32 m0, s29
	v_readfirstlane_b32 s33, v122
	v_add_u32_e32 v123, 0xcc00, v126
	global_load_lds_dwordx4 v[0:1], off
	v_lshl_add_u64 v[0:1], v[70:71], 0, s[0:1]
	s_mov_b32 m0, s33
	v_readfirstlane_b32 s34, v123
	v_add_u32_e32 v124, s85, v5
	global_load_lds_dwordx4 v[0:1], off
	v_lshl_add_u64 v[0:1], v[72:73], 0, s[0:1]
	s_mov_b32 m0, s34
	v_readfirstlane_b32 s35, v124
	v_add_u32_e32 v125, 0x14400, v6
	global_load_lds_dwordx4 v[0:1], off
	v_lshl_add_u64 v[0:1], v[74:75], 0, s[0:1]
	s_mov_b32 m0, s35
	v_readfirstlane_b32 s36, v125
	global_load_lds_dwordx4 v[0:1], off
	v_lshl_add_u64 v[0:1], v[76:77], 0, s[0:1]
	s_mov_b32 m0, s36
	v_lshrrev_b32_e32 v2, 1, v78
	v_bfe_u32 v64, v78, 5, 1
	global_load_lds_dwordx4 v[0:1], off
	v_add_u32_e32 v114, s3, v3
	v_bitop3_b32 v0, v2, v64, 7 bitop3:0x6c
	s_waitcnt vmcnt(6)
	s_mov_b64 s[46:47], 0x100
	v_readfirstlane_b32 s0, v114
	v_add_u32_e32 v115, 0x400, v114
	v_lshlrev_b32_e32 v132, 4, v0
	s_waitcnt lgkmcnt(0)
	s_barrier
	v_lshl_add_u64 v[0:1], v[66:67], 0, s[46:47]
	s_mov_b32 m0, s0
	v_readfirstlane_b32 s1, v115
	v_add_u32_e32 v116, 0x800, v114
	global_load_lds_dwordx4 v[0:1], off
	v_lshl_add_u64 v[0:1], v[68:69], 0, s[46:47]
	s_mov_b32 m0, s1
	v_readfirstlane_b32 s20, v116
	v_add_u32_e32 v117, 0xc00, v114
	v_readlane_b32 s23, v212, 31
	v_and_b32_e32 v79, 31, v78
	global_load_lds_dwordx4 v[0:1], off
	v_lshl_add_u64 v[0:1], v[70:71], 0, s[46:47]
	s_mov_b32 m0, s20
	v_readfirstlane_b32 s21, v117
	v_add_u32_e32 v118, s23, v5
	v_add_u32_e32 v2, s3, v5
	v_lshlrev_b32_e32 v4, 7, v79
	global_load_lds_dwordx4 v[0:1], off
	v_lshl_add_u64 v[0:1], v[72:73], 0, s[46:47]
	s_mov_b32 m0, s21
	v_readfirstlane_b32 s23, v118
	v_add_u32_e32 v119, 0x8400, v2
	v_lshl_or_b32 v102, v80, 13, v4
	global_load_lds_dwordx4 v[0:1], off
	v_lshl_add_u64 v[0:1], v[74:75], 0, s[46:47]
	s_mov_b32 m0, s23
	v_readfirstlane_b32 s24, v119
	global_load_lds_dwordx4 v[0:1], off
	v_lshl_add_u64 v[0:1], v[76:77], 0, s[46:47]
	s_mov_b32 m0, s24
	v_add_u32_e32 v100, 0, v102
	global_load_lds_dwordx4 v[0:1], off
	v_add_u32_e32 v83, v100, v132
	v_ashrrev_i32_e32 v81, 7, v78
	ds_read_b128 a[0:3], v83 offset:32768
	ds_read_b128 a[4:7], v83 offset:36864
	v_lshl_or_b32 v134, v81, 13, v4
	v_add_u32_e32 v101, 0, v134
	v_add_u32_e32 v82, v101, v132
	ds_read_b128 a[8:11], v82
	ds_read_b128 a[12:15], v82 offset:4096
	v_lshrrev_b32_e32 v182, 6, v133
	s_nop 0
	v_readfirstlane_b32 s32, v182
	s_waitcnt lgkmcnt(1)
	v_mfma_f32_32x32x16_bf16 v[48:63], a[0:3], a[8:11], 0
	v_bfe_u32 v103, v78, 1, 3
	s_mov_b64 s[46:47], 0x180
	s_nop 0
	s_add_i32 s30, 0, 0xc000
	v_or_b32_e32 v143, 0x8000, v102
	v_or_b32_e32 v144, 0x9000, v102
	v_add_u32_e32 v145, s3, v134
	s_waitcnt vmcnt(12)
	v_mfma_f32_32x32x16_bf16 v[32:47], a[4:7], a[8:11], 0
	v_lshl_or_b32 v81, v81, 6, v79
	v_mul_lo_u32 v81, v81, s26
	s_mov_b64 s[80:81], 0x200
	s_waitcnt lgkmcnt(0)
	v_mfma_f32_32x32x16_bf16 v[16:31], a[0:3], a[12:15], 0
	v_bitop3_b32 v0, v64, v103, 2 bitop3:0x36
	v_lshlrev_b32_e32 v138, 4, v0
	v_add_u32_e32 v84, v101, v138
	ds_read_b128 a[28:31], v84 offset:4096
	s_nop 0
	s_nop 0
	ds_read_b128 a[24:27], v84
	s_nop 0
	v_add_u32_e32 v85, v100, v138
	ds_read_b128 a[20:23], v85 offset:36864
	s_nop 0
	s_nop 0
	ds_read_b128 a[16:19], v85 offset:32768
	s_nop 0
	s_nop 0
	s_nop 0
	s_nop 0
	s_nop 0
	s_nop 0
	v_mfma_f32_32x32x16_bf16 v[0:15], a[4:7], a[12:15], 0
	s_nop 0
	s_waitcnt lgkmcnt(0)
	v_mfma_f32_32x32x16_bf16 v[48:63], a[16:19], a[24:27], v[48:63]
	v_mfma_f32_32x32x16_bf16 v[32:47], a[20:23], a[24:27], v[32:47]
	v_mfma_f32_32x32x16_bf16 v[16:31], a[16:19], a[28:31], v[16:31]
	v_bitop3_b32 v86, v64, v103, 4 bitop3:0x36
	v_lshlrev_b32_e32 v139, 4, v86
	v_add_u32_e32 v86, v101, v139
	ds_read_b128 a[12:15], v86 offset:4096
	s_nop 0
	s_nop 0
	ds_read_b128 a[8:11], v86
	s_nop 0
	v_add_u32_e32 v87, v100, v139
	ds_read_b128 a[4:7], v87 offset:36864
	s_nop 0
	s_nop 0
	ds_read_b128 a[0:3], v87 offset:32768
	s_nop 0
	s_nop 0
	s_nop 0
	v_mfma_f32_32x32x16_bf16 v[0:15], a[20:23], a[28:31], v[0:15]
	s_nop 0
	s_nop 0
	s_nop 0
	s_nop 0
	s_waitcnt lgkmcnt(0)
	v_mfma_f32_32x32x16_bf16 v[48:63], a[0:3], a[8:11], v[48:63]
	v_mfma_f32_32x32x16_bf16 v[32:47], a[4:7], a[8:11], v[32:47]
	v_mfma_f32_32x32x16_bf16 v[16:31], a[0:3], a[12:15], v[16:31]
	v_bitop3_b32 v88, v64, v103, 6 bitop3:0x36
	v_lshlrev_b32_e32 v142, 4, v88
	v_add_u32_e32 v88, v101, v142
	ds_read_b128 a[28:31], v88 offset:4096
	s_nop 0
	s_nop 0
	ds_read_b128 a[24:27], v88
	s_nop 0
	v_add_u32_e32 v89, v100, v142
	ds_read_b128 a[20:23], v89 offset:36864
	s_nop 0
	s_nop 0
	ds_read_b128 a[16:19], v89 offset:32768
	s_nop 0
	s_nop 0
	s_nop 0
	v_lshlrev_b32_e32 v64, 4, v64
	v_lshl_or_b32 v64, v80, 8, v64
	v_add3_u32 v64, 0, v81, v64
	v_mfma_f32_32x32x16_bf16 v[0:15], a[4:7], a[12:15], v[0:15]
	s_nop 0
	s_nop 0
	s_nop 0
	s_nop 0
	s_waitcnt lgkmcnt(0)
	v_mfma_f32_32x32x16_bf16 v[48:63], a[16:19], a[24:27], v[48:63]
	v_mfma_f32_32x32x16_bf16 v[32:47], a[20:23], a[24:27], v[32:47]
	s_waitcnt vmcnt(6)
	s_waitcnt lgkmcnt(0)
	s_barrier
	ds_read_b128 a[12:15], v82 offset:53248
	ds_read_b128 a[8:11], v82 offset:49152
	v_add_u32_e32 v90, s30, v132
	v_add_u32_e32 v92, v90, v143
	v_add_u32_e32 v90, v90, v144
	ds_read_b128 a[4:7], v90
	ds_read_b128 a[0:3], v92
	v_mfma_f32_32x32x16_bf16 v[16:31], a[16:19], a[28:31], v[16:31]
	v_lshl_add_u64 v[158:159], v[66:67], 0, s[46:47]
	s_nop 0
	v_lshl_add_u64 v[160:161], v[68:69], 0, s[46:47]
	s_nop 0
	s_nop 0
	s_nop 0
	v_lshl_add_u64 v[162:163], v[70:71], 0, s[46:47]
	s_nop 0
	v_mfma_f32_32x32x16_bf16 v[0:15], a[20:23], a[28:31], v[0:15]
	s_and_b32 m0, s32, 7
	s_lshl_b32 m0, m0, 12
	s_add_i32 m0, m0, 0x0
	s_nop 0
	global_load_lds_dwordx4 v[158:159], off
	s_nop 0
	v_lshl_add_u64 v[164:165], v[72:73], 0, s[46:47]
	s_nop 0
	s_nop 0
	s_nop 0
	v_lshl_add_u64 v[166:167], v[74:75], 0, s[46:47]
	s_nop 0
	s_nop 0
	s_nop 0
	v_lshl_add_u64 v[168:169], v[76:77], 0, s[46:47]
	s_nop 0
	s_mov_b64 s[46:47], 0x200
	s_nop 0
	s_nop 0
	s_nop 0
	s_nop 0
	s_nop 0
	s_nop 0
	s_nop 0
	s_nop 0
	v_add_u32_e32 v91, s30, v138
	v_add_u32_e32 v93, v91, v143
	ds_read_b128 a[16:19], v93
	v_add_u32_e32 v91, v91, v144
	ds_read_b128 a[20:23], v91
	ds_read_b128 a[24:27], v84 offset:49152
	ds_read_b128 a[28:31], v84 offset:53248
	s_waitcnt lgkmcnt(4)
	v_mfma_f32_32x32x16_bf16 v[48:63], a[0:3], a[8:11], v[48:63]
	s_nop 0
	s_nop 0
	s_nop 0
	s_nop 0
	v_mfma_f32_32x32x16_bf16 v[32:47], a[4:7], a[8:11], v[32:47]
	v_mfma_f32_32x32x16_bf16 v[16:31], a[0:3], a[12:15], v[16:31]
	s_and_b32 m0, s32, 7
	s_lshl_b32 m0, m0, 12
	s_add_i32 m0, m0, 0x400
	s_nop 0
	global_load_lds_dwordx4 v[160:161], off
	v_mfma_f32_32x32x16_bf16 v[0:15], a[4:7], a[12:15], v[0:15]
	s_nop 0
	s_nop 0
	s_nop 0
	s_nop 0
	v_add_u32_e32 v94, s30, v139
	v_add_u32_e32 v95, v94, v143
	ds_read_b128 a[0:3], v95
	v_add_u32_e32 v94, v94, v144
	ds_read_b128 a[4:7], v94
	ds_read_b128 a[8:11], v86 offset:49152
	ds_read_b128 a[12:15], v86 offset:53248
	s_waitcnt lgkmcnt(5)
	v_mfma_f32_32x32x16_bf16 v[48:63], a[16:19], a[24:27], v[48:63]
	s_and_b32 m0, s32, 7
	s_lshl_b32 m0, m0, 12
	s_add_i32 m0, m0, 0x800
	s_nop 0
	global_load_lds_dwordx4 v[162:163], off
	v_mfma_f32_32x32x16_bf16 v[32:47], a[20:23], a[24:27], v[32:47]
	s_waitcnt lgkmcnt(4)
	v_mfma_f32_32x32x16_bf16 v[16:31], a[16:19], a[28:31], v[16:31]
	s_nop 0
	s_nop 0
	s_nop 0
	v_mfma_f32_32x32x16_bf16 v[0:15], a[20:23], a[28:31], v[0:15]
	s_and_b32 m0, s32, 7
	s_lshl_b32 m0, m0, 12
	s_add_i32 m0, m0, 0xc00
	s_nop 0
	global_load_lds_dwordx4 v[164:165], off
	s_nop 0
	s_nop 0
	s_nop 0
	s_nop 0
	v_add_u32_e32 v96, s30, v142
	v_add_u32_e32 v97, v96, v143
	ds_read_b128 a[16:19], v97
	v_add_u32_e32 v96, v96, v144
	ds_read_b128 a[20:23], v96
	ds_read_b128 a[24:27], v88 offset:49152
	ds_read_b128 a[28:31], v88 offset:53248
	s_waitcnt lgkmcnt(5)
	v_mfma_f32_32x32x16_bf16 v[48:63], a[0:3], a[8:11], v[48:63]
	v_mfma_f32_32x32x16_bf16 v[32:47], a[4:7], a[8:11], v[32:47]
	s_waitcnt lgkmcnt(4)
	v_mfma_f32_32x32x16_bf16 v[16:31], a[0:3], a[12:15], v[16:31]
	s_and_b32 m0, s32, 7
	s_lshl_b32 m0, m0, 11
	s_add_i32 m0, m0, 0x8000
	s_nop 0
	global_load_lds_dwordx4 v[166:167], off
	s_nop 0
	s_nop 0
	s_nop 0
	v_mfma_f32_32x32x16_bf16 v[0:15], a[4:7], a[12:15], v[0:15]
	s_nop 0
	s_nop 0
	s_nop 0
	s_nop 0
	s_waitcnt lgkmcnt(1)
	v_mfma_f32_32x32x16_bf16 v[48:63], a[16:19], a[24:27], v[48:63]
	s_and_b32 m0, s32, 7
	s_lshl_b32 m0, m0, 11
	s_add_i32 m0, m0, 0x8400
	s_nop 0
	global_load_lds_dwordx4 v[168:169], off
	v_mfma_f32_32x32x16_bf16 v[32:47], a[20:23], a[24:27], v[32:47]
	s_waitcnt vmcnt(6)
	s_waitcnt lgkmcnt(0)
	s_barrier
	v_add_u32_e32 v100, v145, v132
	ds_read_b128 a[8:11], v100
	v_add_u32_e32 v101, s3, v132
	v_add_u32_e32 v99, v101, v144
	ds_read_b128 a[4:7], v99
	s_nop 0
	v_add_u32_e32 v98, v101, v143
	v_or_b32_e32 v132, 0x1000, v134
	v_add_u32_e32 v101, v101, v132
	ds_read_b128 a[12:15], v101
	ds_read_b128 a[0:3], v98
	v_mfma_f32_32x32x16_bf16 v[16:31], a[16:19], a[28:31], v[16:31]
	v_lshl_add_u64 v[170:171], v[66:67], 0, s[46:47]
	s_nop 0
	v_lshl_add_u64 v[172:173], v[68:69], 0, s[46:47]
	s_nop 0
	s_nop 0
	s_nop 0
	v_lshl_add_u64 v[174:175], v[70:71], 0, s[46:47]
	s_nop 0
	v_mfma_f32_32x32x16_bf16 v[0:15], a[20:23], a[28:31], v[0:15]
	s_and_b32 m0, s32, 7
	s_lshl_b32 m0, m0, 12
	s_add_i32 m0, m0, 0xc000
	s_nop 0
	global_load_lds_dwordx4 v[170:171], off
	s_nop 0
	v_lshl_add_u64 v[176:177], v[72:73], 0, s[46:47]
	s_nop 0
	s_nop 0
	s_nop 0
	v_lshl_add_u64 v[178:179], v[74:75], 0, s[46:47]
	s_nop 0
	s_nop 0
	s_nop 0
	v_lshl_add_u64 v[180:181], v[76:77], 0, s[46:47]
	s_nop 0
	s_mov_b64 s[46:47], 0x280
	s_nop 0
	s_nop 0
	s_nop 0
	s_nop 0
	s_nop 0
	s_nop 0
	s_nop 0
	s_nop 0
	v_add_u32_e32 v105, s3, v138
	v_add_u32_e32 v102, v105, v143
	ds_read_b128 a[16:19], v102
	v_add_u32_e32 v103, v105, v144
	ds_read_b128 a[20:23], v103
	v_add_u32_e32 v104, v145, v138
	ds_read_b128 a[24:27], v104
	v_add_u32_e32 v105, v105, v132
	ds_read_b128 a[28:31], v105
	s_waitcnt lgkmcnt(4)
	v_mfma_f32_32x32x16_bf16 v[48:63], a[0:3], a[8:11], v[48:63]
	s_nop 0
	v_mfma_f32_32x32x16_bf16 v[32:47], a[4:7], a[8:11], v[32:47]
	s_nop 0
	s_nop 0
	s_nop 0
	s_nop 0
	s_nop 0
	v_mfma_f32_32x32x16_bf16 v[16:31], a[0:3], a[12:15], v[16:31]
	s_and_b32 m0, s32, 7
	s_lshl_b32 m0, m0, 12
	s_add_i32 m0, m0, 0xc400
	s_nop 0
	global_load_lds_dwordx4 v[172:173], off
	s_nop 0
	v_mfma_f32_32x32x16_bf16 v[0:15], a[4:7], a[12:15], v[0:15]
	s_nop 0
	s_nop 0
	s_nop 0
	v_add_u32_e32 v109, s3, v139
	v_add_u32_e32 v106, v109, v143
	ds_read_b128 a[0:3], v106
	v_add_u32_e32 v107, v109, v144
	ds_read_b128 a[4:7], v107
	v_add_u32_e32 v108, v145, v139
	ds_read_b128 a[8:11], v108
	v_add_u32_e32 v109, v109, v132
	ds_read_b128 a[12:15], v109
	s_waitcnt lgkmcnt(5)
	v_mfma_f32_32x32x16_bf16 v[48:63], a[16:19], a[24:27], v[48:63]
	s_and_b32 m0, s32, 7
	s_lshl_b32 m0, m0, 12
	s_add_i32 m0, m0, 0xc800
	s_nop 0
	global_load_lds_dwordx4 v[174:175], off
	v_mfma_f32_32x32x16_bf16 v[32:47], a[20:23], a[24:27], v[32:47]
	s_waitcnt lgkmcnt(4)
	v_mfma_f32_32x32x16_bf16 v[16:31], a[16:19], a[28:31], v[16:31]
	s_nop 0
	s_nop 0
	s_nop 0
	s_nop 0
	s_nop 0
	s_nop 0
	v_mfma_f32_32x32x16_bf16 v[0:15], a[20:23], a[28:31], v[0:15]
	s_and_b32 m0, s32, 7
	s_lshl_b32 m0, m0, 12
	s_add_i32 m0, m0, 0xcc00
	s_nop 0
	global_load_lds_dwordx4 v[176:177], off
	s_nop 0
	s_nop 0
	s_nop 0
	v_add_u32_e32 v113, s3, v142
	v_add_u32_e32 v110, v113, v143
	ds_read_b128 a[16:19], v110
	v_add_u32_e32 v111, v113, v144
	ds_read_b128 a[20:23], v111
	v_add_u32_e32 v112, v145, v142
	ds_read_b128 a[24:27], v112
	v_add_u32_e32 v113, v113, v132
	ds_read_b128 a[28:31], v113
	s_waitcnt lgkmcnt(5)
	v_mfma_f32_32x32x16_bf16 v[48:63], a[0:3], a[8:11], v[48:63]
	v_mfma_f32_32x32x16_bf16 v[32:47], a[4:7], a[8:11], v[32:47]
	s_waitcnt lgkmcnt(4)
	v_mfma_f32_32x32x16_bf16 v[16:31], a[0:3], a[12:15], v[16:31]
	s_and_b32 m0, s32, 7
	s_lshl_b32 m0, m0, 11
	s_add_i32 m0, m0, 0x14000
	s_nop 0
	global_load_lds_dwordx4 v[178:179], off
	s_nop 0
	s_nop 0
	s_nop 0
	s_nop 0
	s_nop 0
	s_nop 0
	v_mfma_f32_32x32x16_bf16 v[0:15], a[4:7], a[12:15], v[0:15]
	s_nop 0
	s_nop 0
	s_nop 0
	s_waitcnt lgkmcnt(1)
	v_mfma_f32_32x32x16_bf16 v[48:63], a[16:19], a[24:27], v[48:63]
	s_and_b32 m0, s32, 7
	s_lshl_b32 m0, m0, 11
	s_add_i32 m0, m0, 0x14400
	s_nop 0
	global_load_lds_dwordx4 v[180:181], off
	v_mfma_f32_32x32x16_bf16 v[32:47], a[20:23], a[24:27], v[32:47]
	s_waitcnt vmcnt(6)
	s_waitcnt lgkmcnt(0)
	s_barrier
	ds_read_b128 a[12:15], v82 offset:4096
	ds_read_b128 a[8:11], v82
	ds_read_b128 a[4:7], v83 offset:36864
	ds_read_b128 a[0:3], v83 offset:32768
	v_mfma_f32_32x32x16_bf16 v[16:31], a[16:19], a[28:31], v[16:31]
	v_lshl_add_u64 v[158:159], v[66:67], 0, s[46:47]
	s_nop 0
	v_lshl_add_u64 v[160:161], v[68:69], 0, s[46:47]
	s_nop 0
	s_nop 0
	s_nop 0
	v_lshl_add_u64 v[162:163], v[70:71], 0, s[46:47]
	s_nop 0
	v_mfma_f32_32x32x16_bf16 v[0:15], a[20:23], a[28:31], v[0:15]
	s_and_b32 m0, s32, 7
	s_lshl_b32 m0, m0, 12
	s_add_i32 m0, m0, 0x18000
	s_nop 0
	global_load_lds_dwordx4 v[158:159], off
	s_nop 0
	v_lshl_add_u64 v[164:165], v[72:73], 0, s[46:47]
	s_nop 0
	s_nop 0
	s_nop 0
	v_lshl_add_u64 v[166:167], v[74:75], 0, s[46:47]
	s_nop 0
	s_nop 0
	s_nop 0
	v_lshl_add_u64 v[168:169], v[76:77], 0, s[46:47]
	s_nop 0
	s_mov_b64 s[46:47], 0x300
	s_nop 0
	s_nop 0
	s_nop 0
	s_nop 0
	s_nop 0
	ds_read_b128 a[16:19], v85 offset:32768
	ds_read_b128 a[20:23], v85 offset:36864
	ds_read_b128 a[24:27], v84
	ds_read_b128 a[28:31], v84 offset:4096
	s_waitcnt lgkmcnt(4)
	v_mfma_f32_32x32x16_bf16 v[48:63], a[0:3], a[8:11], v[48:63]
	s_nop 0
	v_mfma_f32_32x32x16_bf16 v[32:47], a[4:7], a[8:11], v[32:47]
	v_mfma_f32_32x32x16_bf16 v[16:31], a[0:3], a[12:15], v[16:31]
	s_and_b32 m0, s32, 7
	s_lshl_b32 m0, m0, 12
	s_add_i32 m0, m0, 0x18400
	s_nop 0
	global_load_lds_dwordx4 v[160:161], off
	v_mfma_f32_32x32x16_bf16 v[0:15], a[4:7], a[12:15], v[0:15]
	s_nop 0
	s_nop 0
	s_nop 0
	s_nop 0
	ds_read_b128 a[0:3], v87 offset:32768
	ds_read_b128 a[4:7], v87 offset:36864
	ds_read_b128 a[8:11], v86
	ds_read_b128 a[12:15], v86 offset:4096
	s_waitcnt lgkmcnt(5)
	v_mfma_f32_32x32x16_bf16 v[48:63], a[16:19], a[24:27], v[48:63]
	s_and_b32 m0, s32, 7
	s_lshl_b32 m0, m0, 12
	s_add_i32 m0, m0, 0x18800
	s_nop 0
	global_load_lds_dwordx4 v[162:163], off
	v_mfma_f32_32x32x16_bf16 v[32:47], a[20:23], a[24:27], v[32:47]
	s_waitcnt lgkmcnt(4)
	v_mfma_f32_32x32x16_bf16 v[16:31], a[16:19], a[28:31], v[16:31]
	v_mfma_f32_32x32x16_bf16 v[0:15], a[20:23], a[28:31], v[0:15]
	s_and_b32 m0, s32, 7
	s_lshl_b32 m0, m0, 12
	s_add_i32 m0, m0, 0x18c00
	s_nop 0
	global_load_lds_dwordx4 v[164:165], off
	s_nop 0
	s_nop 0
	s_nop 0
	s_nop 0
	ds_read_b128 a[16:19], v89 offset:32768
	ds_read_b128 a[20:23], v89 offset:36864
	ds_read_b128 a[24:27], v88
	ds_read_b128 a[28:31], v88 offset:4096
	s_waitcnt lgkmcnt(5)
	v_mfma_f32_32x32x16_bf16 v[48:63], a[0:3], a[8:11], v[48:63]
	v_mfma_f32_32x32x16_bf16 v[32:47], a[4:7], a[8:11], v[32:47]
	s_waitcnt lgkmcnt(4)
	v_mfma_f32_32x32x16_bf16 v[16:31], a[0:3], a[12:15], v[16:31]
	s_and_b32 m0, s32, 7
	s_lshl_b32 m0, m0, 11
	s_add_i32 m0, m0, 0x20000
	s_nop 0
	global_load_lds_dwordx4 v[166:167], off
	v_mfma_f32_32x32x16_bf16 v[0:15], a[4:7], a[12:15], v[0:15]
	s_nop 0
	s_nop 0
	s_nop 0
	s_nop 0
	s_waitcnt lgkmcnt(1)
	v_mfma_f32_32x32x16_bf16 v[48:63], a[16:19], a[24:27], v[48:63]
	s_and_b32 m0, s32, 7
	s_lshl_b32 m0, m0, 11
	s_add_i32 m0, m0, 0x20400
	s_nop 0
	global_load_lds_dwordx4 v[168:169], off
	v_mfma_f32_32x32x16_bf16 v[32:47], a[20:23], a[24:27], v[32:47]
	s_waitcnt vmcnt(6)
	s_waitcnt lgkmcnt(0)
	s_barrier
	ds_read_b128 a[12:15], v82 offset:53248
	ds_read_b128 a[8:11], v82 offset:49152
	ds_read_b128 a[4:7], v90
	ds_read_b128 a[0:3], v92
	v_mfma_f32_32x32x16_bf16 v[16:31], a[16:19], a[28:31], v[16:31]
	v_lshl_add_u64 v[170:171], v[66:67], 0, s[46:47]
	s_nop 0
	v_lshl_add_u64 v[172:173], v[68:69], 0, s[46:47]
	s_nop 0
	s_nop 0
	s_nop 0
	v_lshl_add_u64 v[174:175], v[70:71], 0, s[46:47]
	s_nop 0
	v_mfma_f32_32x32x16_bf16 v[0:15], a[20:23], a[28:31], v[0:15]
	s_and_b32 m0, s32, 7
	s_lshl_b32 m0, m0, 12
	s_add_i32 m0, m0, 0x0
	s_nop 0
	global_load_lds_dwordx4 v[170:171], off
	s_nop 0
	v_lshl_add_u64 v[176:177], v[72:73], 0, s[46:47]
	s_nop 0
	s_mov_b64 s[38:39], 0x380
	s_nop 0
	v_lshl_add_u64 v[178:179], v[74:75], 0, s[46:47]
	s_nop 0
	v_readfirstlane_b32 s48, v117
	s_nop 0
	v_lshl_add_u64 v[180:181], v[76:77], 0, s[46:47]
	s_nop 0
	s_mov_b64 s[46:47], 0x580
	s_nop 0
	s_nop 0
	s_nop 0
	s_nop 0
	s_nop 0
	ds_read_b128 a[16:19], v93
	ds_read_b128 a[20:23], v91
	ds_read_b128 a[24:27], v84 offset:49152
	ds_read_b128 a[28:31], v84 offset:53248
	s_waitcnt lgkmcnt(4)
	v_mfma_f32_32x32x16_bf16 v[48:63], a[0:3], a[8:11], v[48:63]
	s_nop 0
	v_readfirstlane_b32 s49, v118
	v_readfirstlane_b32 s53, v119
	v_mfma_f32_32x32x16_bf16 v[32:47], a[4:7], a[8:11], v[32:47]
	v_mfma_f32_32x32x16_bf16 v[16:31], a[0:3], a[12:15], v[16:31]
	s_and_b32 m0, s32, 7
	s_lshl_b32 m0, m0, 12
	s_add_i32 m0, m0, 0x400
	s_nop 0
	global_load_lds_dwordx4 v[172:173], off
	v_mfma_f32_32x32x16_bf16 v[0:15], a[4:7], a[12:15], v[0:15]
	s_nop 0
	s_nop 0
	s_nop 0
	s_nop 0
	ds_read_b128 a[0:3], v95
	ds_read_b128 a[4:7], v94
	ds_read_b128 a[8:11], v86 offset:49152
	ds_read_b128 a[12:15], v86 offset:53248
	s_waitcnt lgkmcnt(5)
	v_mfma_f32_32x32x16_bf16 v[48:63], a[16:19], a[24:27], v[48:63]
	s_and_b32 m0, s32, 7
	s_lshl_b32 m0, m0, 12
	s_add_i32 m0, m0, 0x800
	s_nop 0
	global_load_lds_dwordx4 v[174:175], off
	v_mfma_f32_32x32x16_bf16 v[32:47], a[20:23], a[24:27], v[32:47]
	s_waitcnt lgkmcnt(4)
	v_mfma_f32_32x32x16_bf16 v[16:31], a[16:19], a[28:31], v[16:31]
	v_mfma_f32_32x32x16_bf16 v[0:15], a[20:23], a[28:31], v[0:15]
	s_and_b32 m0, s32, 7
	s_lshl_b32 m0, m0, 12
	s_add_i32 m0, m0, 0xc00
	s_nop 0
	global_load_lds_dwordx4 v[176:177], off
	s_nop 0
	s_nop 0
	s_nop 0
	s_nop 0
	ds_read_b128 a[16:19], v97
	ds_read_b128 a[20:23], v96
	ds_read_b128 a[24:27], v88 offset:49152
	ds_read_b128 a[28:31], v88 offset:53248
	s_waitcnt lgkmcnt(5)
	v_mfma_f32_32x32x16_bf16 v[48:63], a[0:3], a[8:11], v[48:63]
	v_mfma_f32_32x32x16_bf16 v[32:47], a[4:7], a[8:11], v[32:47]
	s_waitcnt lgkmcnt(4)
	v_mfma_f32_32x32x16_bf16 v[16:31], a[0:3], a[12:15], v[16:31]
	s_and_b32 m0, s32, 7
	s_lshl_b32 m0, m0, 11
	s_add_i32 m0, m0, 0x8000
	s_nop 0
	global_load_lds_dwordx4 v[178:179], off
	v_mfma_f32_32x32x16_bf16 v[0:15], a[4:7], a[12:15], v[0:15]
	s_nop 0
	s_nop 0
	s_nop 0
	s_nop 0
	s_waitcnt lgkmcnt(1)
	v_mfma_f32_32x32x16_bf16 v[48:63], a[16:19], a[24:27], v[48:63]
	s_and_b32 m0, s32, 7
	s_lshl_b32 m0, m0, 11
	s_add_i32 m0, m0, 0x8400
	s_nop 0
	global_load_lds_dwordx4 v[180:181], off
	v_mfma_f32_32x32x16_bf16 v[32:47], a[20:23], a[24:27], v[32:47]
	s_waitcnt vmcnt(6)
	s_waitcnt lgkmcnt(0)
	s_barrier
	ds_read_b128 a[12:15], v101
	ds_read_b128 a[8:11], v100
	ds_read_b128 a[4:7], v99
	ds_read_b128 a[0:3], v98
	v_mfma_f32_32x32x16_bf16 v[16:31], a[16:19], a[28:31], v[16:31]
	v_lshl_add_u64 v[158:159], v[66:67], 0, s[38:39]
	s_nop 0
	v_lshl_add_u64 v[160:161], v[68:69], 0, s[38:39]
	s_nop 0
	s_mov_b64 s[28:29], 0x400
	s_nop 0
	v_lshl_add_u64 v[162:163], v[70:71], 0, s[38:39]
	s_nop 0
	v_mfma_f32_32x32x16_bf16 v[0:15], a[20:23], a[28:31], v[0:15]
	s_and_b32 m0, s32, 7
	s_lshl_b32 m0, m0, 12
	s_add_i32 m0, m0, 0xc000
	s_nop 0
	global_load_lds_dwordx4 v[158:159], off
	s_nop 0
	v_lshl_add_u64 v[164:165], v[72:73], 0, s[38:39]
	s_nop 0
	v_readfirstlane_b32 s33, v122
	s_nop 0
	v_lshl_add_u64 v[166:167], v[74:75], 0, s[38:39]
	s_nop 0
	v_readfirstlane_b32 s34, v123
	s_nop 0
	v_lshl_add_u64 v[168:169], v[76:77], 0, s[38:39]
	s_nop 0
	s_mov_b64 s[36:37], 0x500
	s_nop 0
	s_nop 0
	s_nop 0
	s_nop 0
	s_nop 0
	ds_read_b128 a[16:19], v102
	ds_read_b128 a[20:23], v103
	ds_read_b128 a[24:27], v104
	ds_read_b128 a[28:31], v105
	s_waitcnt lgkmcnt(4)
	v_mfma_f32_32x32x16_bf16 v[48:63], a[0:3], a[8:11], v[48:63]
	s_nop 0
	v_readfirstlane_b32 s0, v126
	v_readfirstlane_b32 s35, v124
	v_readfirstlane_b32 s38, v115
	v_readfirstlane_b32 s39, v116
	v_mfma_f32_32x32x16_bf16 v[32:47], a[4:7], a[8:11], v[32:47]
	v_mfma_f32_32x32x16_bf16 v[16:31], a[0:3], a[12:15], v[16:31]
	s_and_b32 m0, s32, 7
	s_lshl_b32 m0, m0, 12
	s_add_i32 m0, m0, 0xc400
	s_nop 0
	global_load_lds_dwordx4 v[160:161], off
	v_mfma_f32_32x32x16_bf16 v[0:15], a[4:7], a[12:15], v[0:15]
	s_nop 0
	s_nop 0
	s_nop 0
	s_nop 0
	ds_read_b128 a[0:3], v106
	ds_read_b128 a[4:7], v107
	ds_read_b128 a[8:11], v108
	ds_read_b128 a[12:15], v109
	s_waitcnt lgkmcnt(5)
	v_mfma_f32_32x32x16_bf16 v[48:63], a[16:19], a[24:27], v[48:63]
	s_and_b32 m0, s32, 7
	s_lshl_b32 m0, m0, 12
	s_add_i32 m0, m0, 0xc800
	s_nop 0
	global_load_lds_dwordx4 v[162:163], off
	v_mfma_f32_32x32x16_bf16 v[32:47], a[20:23], a[24:27], v[32:47]
	s_waitcnt lgkmcnt(4)
	v_mfma_f32_32x32x16_bf16 v[16:31], a[16:19], a[28:31], v[16:31]
	v_mfma_f32_32x32x16_bf16 v[0:15], a[20:23], a[28:31], v[0:15]
	s_and_b32 m0, s32, 7
	s_lshl_b32 m0, m0, 12
	s_add_i32 m0, m0, 0xcc00
	s_nop 0
	global_load_lds_dwordx4 v[164:165], off
	s_nop 0
	s_nop 0
	s_nop 0
	s_nop 0
	ds_read_b128 a[16:19], v110
	ds_read_b128 a[20:23], v111
	ds_read_b128 a[24:27], v112
	ds_read_b128 a[28:31], v113
	s_waitcnt lgkmcnt(5)
	v_mfma_f32_32x32x16_bf16 v[48:63], a[0:3], a[8:11], v[48:63]
	v_mfma_f32_32x32x16_bf16 v[32:47], a[4:7], a[8:11], v[32:47]
	s_waitcnt lgkmcnt(4)
	v_mfma_f32_32x32x16_bf16 v[16:31], a[0:3], a[12:15], v[16:31]
	s_and_b32 m0, s32, 7
	s_lshl_b32 m0, m0, 11
	s_add_i32 m0, m0, 0x14000
	s_nop 0
	global_load_lds_dwordx4 v[166:167], off
	v_mfma_f32_32x32x16_bf16 v[0:15], a[4:7], a[12:15], v[0:15]
	s_nop 0
	s_nop 0
	s_nop 0
	s_nop 0
	s_waitcnt lgkmcnt(1)
	v_mfma_f32_32x32x16_bf16 v[48:63], a[16:19], a[24:27], v[48:63]
	s_and_b32 m0, s32, 7
	s_lshl_b32 m0, m0, 11
	s_add_i32 m0, m0, 0x14400
	s_nop 0
	global_load_lds_dwordx4 v[168:169], off
	v_mfma_f32_32x32x16_bf16 v[32:47], a[20:23], a[24:27], v[32:47]
	s_waitcnt vmcnt(6)
	s_waitcnt lgkmcnt(0)
	s_barrier
	ds_read_b128 a[12:15], v82 offset:4096
	ds_read_b128 a[8:11], v82
	ds_read_b128 a[4:7], v83 offset:36864
	ds_read_b128 a[0:3], v83 offset:32768
	v_mfma_f32_32x32x16_bf16 v[16:31], a[16:19], a[28:31], v[16:31]
	v_lshl_add_u64 v[170:171], v[66:67], 0, s[28:29]
	s_nop 0
	v_lshl_add_u64 v[172:173], v[68:69], 0, s[28:29]
	s_nop 0
	v_readfirstlane_b32 s1, v127
	s_nop 0
	v_lshl_add_u64 v[174:175], v[70:71], 0, s[28:29]
	s_nop 0
	v_mfma_f32_32x32x16_bf16 v[0:15], a[20:23], a[28:31], v[0:15]
	s_and_b32 m0, s32, 7
	s_lshl_b32 m0, m0, 12
	s_add_i32 m0, m0, 0x18000
	s_nop 0
	global_load_lds_dwordx4 v[170:171], off
	s_nop 0
	v_lshl_add_u64 v[176:177], v[72:73], 0, s[28:29]
	s_nop 0
	v_readfirstlane_b32 s20, v128
	s_nop 0
	v_lshl_add_u64 v[178:179], v[74:75], 0, s[28:29]
	s_nop 0
	v_readfirstlane_b32 s21, v129
	s_nop 0
	v_lshl_add_u64 v[180:181], v[76:77], 0, s[28:29]
	s_nop 0
	s_mov_b64 s[28:29], 0x480
	s_nop 0
	s_nop 0
	s_nop 0
	s_nop 0
	s_nop 0
	ds_read_b128 a[16:19], v85 offset:32768
	ds_read_b128 a[20:23], v85 offset:36864
	ds_read_b128 a[24:27], v84
	ds_read_b128 a[28:31], v84 offset:4096
	s_waitcnt lgkmcnt(4)
	v_mfma_f32_32x32x16_bf16 v[48:63], a[0:3], a[8:11], v[48:63]
	s_nop 0
	v_lshl_add_u64 v[162:163], v[70:71], 0, s[28:29]
	v_readfirstlane_b32 s23, v131
	v_readfirstlane_b32 s24, v130
	v_mfma_f32_32x32x16_bf16 v[32:47], a[4:7], a[8:11], v[32:47]
	v_mfma_f32_32x32x16_bf16 v[16:31], a[0:3], a[12:15], v[16:31]
	s_and_b32 m0, s32, 7
	s_lshl_b32 m0, m0, 12
	s_add_i32 m0, m0, 0x18400
	s_nop 0
	global_load_lds_dwordx4 v[172:173], off
	v_mfma_f32_32x32x16_bf16 v[0:15], a[4:7], a[12:15], v[0:15]
	s_nop 0
	s_nop 0
	s_nop 0
	s_nop 0
	ds_read_b128 a[0:3], v87 offset:32768
	ds_read_b128 a[4:7], v87 offset:36864
	ds_read_b128 a[8:11], v86
	ds_read_b128 a[12:15], v86 offset:4096
	s_waitcnt lgkmcnt(5)
	v_mfma_f32_32x32x16_bf16 v[48:63], a[16:19], a[24:27], v[48:63]
	s_and_b32 m0, s32, 7
	s_lshl_b32 m0, m0, 12
	s_add_i32 m0, m0, 0x18800
	s_nop 0
	global_load_lds_dwordx4 v[174:175], off
	v_mfma_f32_32x32x16_bf16 v[32:47], a[20:23], a[24:27], v[32:47]
	s_waitcnt lgkmcnt(4)
	v_mfma_f32_32x32x16_bf16 v[16:31], a[16:19], a[28:31], v[16:31]
	v_mfma_f32_32x32x16_bf16 v[0:15], a[20:23], a[28:31], v[0:15]
	s_and_b32 m0, s32, 7
	s_lshl_b32 m0, m0, 12
	s_add_i32 m0, m0, 0x18c00
	s_nop 0
	global_load_lds_dwordx4 v[176:177], off
	s_nop 0
	s_nop 0
	s_nop 0
	s_nop 0
	ds_read_b128 a[16:19], v89 offset:32768
	ds_read_b128 a[20:23], v89 offset:36864
	ds_read_b128 a[24:27], v88
	ds_read_b128 a[28:31], v88 offset:4096
	s_waitcnt lgkmcnt(5)
	v_mfma_f32_32x32x16_bf16 v[48:63], a[0:3], a[8:11], v[48:63]
	v_mfma_f32_32x32x16_bf16 v[32:47], a[4:7], a[8:11], v[32:47]
	s_waitcnt lgkmcnt(4)
	v_mfma_f32_32x32x16_bf16 v[16:31], a[0:3], a[12:15], v[16:31]
	s_and_b32 m0, s32, 7
	s_lshl_b32 m0, m0, 11
	s_add_i32 m0, m0, 0x20000
	s_nop 0
	global_load_lds_dwordx4 v[178:179], off
	v_mfma_f32_32x32x16_bf16 v[0:15], a[4:7], a[12:15], v[0:15]
	s_nop 0
	s_nop 0
	s_nop 0
	s_nop 0
	s_waitcnt lgkmcnt(1)
	v_mfma_f32_32x32x16_bf16 v[48:63], a[16:19], a[24:27], v[48:63]
	s_and_b32 m0, s32, 7
	s_lshl_b32 m0, m0, 11
	s_add_i32 m0, m0, 0x20400
	s_nop 0
	global_load_lds_dwordx4 v[180:181], off
	v_mfma_f32_32x32x16_bf16 v[32:47], a[20:23], a[24:27], v[32:47]
	s_waitcnt vmcnt(6)
	s_waitcnt lgkmcnt(0)
	s_barrier
	ds_read_b128 a[12:15], v82 offset:53248
	ds_read_b128 a[8:11], v82 offset:49152
	ds_read_b128 a[4:7], v90
	ds_read_b128 a[0:3], v92
	v_mfma_f32_32x32x16_bf16 v[16:31], a[16:19], a[28:31], v[16:31]
	v_lshl_add_u64 v[158:159], v[66:67], 0, s[28:29]
	s_nop 0
	v_lshl_add_u64 v[160:161], v[68:69], 0, s[28:29]
	s_nop 0
	s_nop 0
	s_nop 0
	s_nop 0
	v_mfma_f32_32x32x16_bf16 v[0:15], a[20:23], a[28:31], v[0:15]
	s_and_b32 m0, s32, 7
	s_lshl_b32 m0, m0, 12
	s_add_i32 m0, m0, 0x0
	s_nop 0
	global_load_lds_dwordx4 v[158:159], off
	s_nop 0
	v_lshl_add_u64 v[164:165], v[72:73], 0, s[28:29]
	s_nop 0
	s_nop 0
	s_nop 0
	v_lshl_add_u64 v[166:167], v[74:75], 0, s[28:29]
	s_nop 0
	s_nop 0
	s_nop 0
	v_lshl_add_u64 v[168:169], v[76:77], 0, s[28:29]
	s_nop 0
	v_readfirstlane_b32 s28, v120
	s_nop 0
	s_nop 0
	s_nop 0
	s_nop 0
	s_nop 0
	ds_read_b128 a[16:19], v93
	ds_read_b128 a[20:23], v91
	ds_read_b128 a[24:27], v84 offset:49152
	ds_read_b128 a[28:31], v84 offset:53248
	s_waitcnt lgkmcnt(4)
	v_mfma_f32_32x32x16_bf16 v[48:63], a[0:3], a[8:11], v[48:63]
	s_nop 0
	v_readfirstlane_b32 s29, v121
	v_lshl_add_u64 v[174:175], v[70:71], 0, s[36:37]
	v_mfma_f32_32x32x16_bf16 v[32:47], a[4:7], a[8:11], v[32:47]
	v_mfma_f32_32x32x16_bf16 v[16:31], a[0:3], a[12:15], v[16:31]
	s_and_b32 m0, s32, 7
	s_lshl_b32 m0, m0, 12
	s_add_i32 m0, m0, 0x400
	s_nop 0
	global_load_lds_dwordx4 v[160:161], off
	v_mfma_f32_32x32x16_bf16 v[0:15], a[4:7], a[12:15], v[0:15]
	s_nop 0
	s_nop 0
	s_nop 0
	s_nop 0
	ds_read_b128 a[0:3], v95
	ds_read_b128 a[4:7], v94
	ds_read_b128 a[8:11], v86 offset:49152
	ds_read_b128 a[12:15], v86 offset:53248
	s_waitcnt lgkmcnt(5)
	v_mfma_f32_32x32x16_bf16 v[48:63], a[16:19], a[24:27], v[48:63]
	s_and_b32 m0, s32, 7
	s_lshl_b32 m0, m0, 12
	s_add_i32 m0, m0, 0x800
	s_nop 0
	global_load_lds_dwordx4 v[162:163], off
	v_mfma_f32_32x32x16_bf16 v[32:47], a[20:23], a[24:27], v[32:47]
	s_waitcnt lgkmcnt(4)
	v_mfma_f32_32x32x16_bf16 v[16:31], a[16:19], a[28:31], v[16:31]
	v_mfma_f32_32x32x16_bf16 v[0:15], a[20:23], a[28:31], v[0:15]
	s_and_b32 m0, s32, 7
	s_lshl_b32 m0, m0, 12
	s_add_i32 m0, m0, 0xc00
	s_nop 0
	global_load_lds_dwordx4 v[164:165], off
	s_nop 0
	s_nop 0
	s_nop 0
	s_nop 0
	ds_read_b128 a[16:19], v97
	ds_read_b128 a[20:23], v96
	ds_read_b128 a[24:27], v88 offset:49152
	ds_read_b128 a[28:31], v88 offset:53248
	s_waitcnt lgkmcnt(5)
	v_mfma_f32_32x32x16_bf16 v[48:63], a[0:3], a[8:11], v[48:63]
	v_mfma_f32_32x32x16_bf16 v[32:47], a[4:7], a[8:11], v[32:47]
	s_waitcnt lgkmcnt(4)
	v_mfma_f32_32x32x16_bf16 v[16:31], a[0:3], a[12:15], v[16:31]
	s_and_b32 m0, s32, 7
	s_lshl_b32 m0, m0, 11
	s_add_i32 m0, m0, 0x8000
	s_nop 0
	global_load_lds_dwordx4 v[166:167], off
	v_mfma_f32_32x32x16_bf16 v[0:15], a[4:7], a[12:15], v[0:15]
	s_nop 0
	s_nop 0
	s_nop 0
	s_nop 0
	s_waitcnt lgkmcnt(1)
	v_mfma_f32_32x32x16_bf16 v[48:63], a[16:19], a[24:27], v[48:63]
	s_and_b32 m0, s32, 7
	s_lshl_b32 m0, m0, 11
	s_add_i32 m0, m0, 0x8400
	s_nop 0
	global_load_lds_dwordx4 v[168:169], off
	v_mfma_f32_32x32x16_bf16 v[32:47], a[20:23], a[24:27], v[32:47]
	s_waitcnt vmcnt(6)
	s_waitcnt lgkmcnt(0)
	s_barrier
	ds_read_b128 a[12:15], v101
	ds_read_b128 a[8:11], v100
	ds_read_b128 a[4:7], v99
	ds_read_b128 a[0:3], v98
	v_mfma_f32_32x32x16_bf16 v[16:31], a[16:19], a[28:31], v[16:31]
	v_lshl_add_u64 v[170:171], v[66:67], 0, s[36:37]
	s_nop 0
	v_lshl_add_u64 v[172:173], v[68:69], 0, s[36:37]
	s_nop 0
	s_nop 0
	s_nop 0
	s_nop 0
	v_mfma_f32_32x32x16_bf16 v[0:15], a[20:23], a[28:31], v[0:15]
	s_and_b32 m0, s32, 7
	s_lshl_b32 m0, m0, 12
	s_add_i32 m0, m0, 0xc000
	s_nop 0
	global_load_lds_dwordx4 v[170:171], off
	s_nop 0
	v_lshl_add_u64 v[176:177], v[72:73], 0, s[36:37]
	s_nop 0
	s_nop 0
	s_nop 0
	v_lshl_add_u64 v[178:179], v[74:75], 0, s[36:37]
	s_nop 0
	s_nop 0
	s_nop 0
	v_lshl_add_u64 v[180:181], v[76:77], 0, s[36:37]
	v_readfirstlane_b32 s36, v125
	s_nop 0
	v_readfirstlane_b32 s37, v114
	s_nop 0
	s_nop 0
	s_nop 0
	s_nop 0
	s_nop 0
	ds_read_b128 a[16:19], v102
	ds_read_b128 a[20:23], v103
	ds_read_b128 a[24:27], v104
	ds_read_b128 a[28:31], v105
	s_waitcnt lgkmcnt(4)
	v_mfma_f32_32x32x16_bf16 v[48:63], a[0:3], a[8:11], v[48:63]
	s_nop 0
	v_lshl_add_u64 v[162:163], v[70:71], 0, s[46:47]
	v_mfma_f32_32x32x16_bf16 v[32:47], a[4:7], a[8:11], v[32:47]
	v_mfma_f32_32x32x16_bf16 v[16:31], a[0:3], a[12:15], v[16:31]
	s_and_b32 m0, s32, 7
	s_lshl_b32 m0, m0, 12
	s_add_i32 m0, m0, 0xc400
	s_nop 0
	global_load_lds_dwordx4 v[172:173], off
	v_mfma_f32_32x32x16_bf16 v[0:15], a[4:7], a[12:15], v[0:15]
	s_nop 0
	s_nop 0
	s_nop 0
	s_nop 0
	ds_read_b128 a[0:3], v106
	ds_read_b128 a[4:7], v107
	ds_read_b128 a[8:11], v108
	ds_read_b128 a[12:15], v109
	s_waitcnt lgkmcnt(5)
	v_mfma_f32_32x32x16_bf16 v[48:63], a[16:19], a[24:27], v[48:63]
	s_and_b32 m0, s32, 7
	s_lshl_b32 m0, m0, 12
	s_add_i32 m0, m0, 0xc800
	s_nop 0
	global_load_lds_dwordx4 v[174:175], off
	v_mfma_f32_32x32x16_bf16 v[32:47], a[20:23], a[24:27], v[32:47]
	s_waitcnt lgkmcnt(4)
	v_mfma_f32_32x32x16_bf16 v[16:31], a[16:19], a[28:31], v[16:31]
	v_mfma_f32_32x32x16_bf16 v[0:15], a[20:23], a[28:31], v[0:15]
	s_and_b32 m0, s32, 7
	s_lshl_b32 m0, m0, 12
	s_add_i32 m0, m0, 0xcc00
	s_nop 0
	global_load_lds_dwordx4 v[176:177], off
	s_nop 0
	s_nop 0
	s_nop 0
	s_nop 0
	ds_read_b128 a[16:19], v110
	ds_read_b128 a[20:23], v111
	ds_read_b128 a[24:27], v112
	ds_read_b128 a[28:31], v113
	s_waitcnt lgkmcnt(5)
	v_mfma_f32_32x32x16_bf16 v[48:63], a[0:3], a[8:11], v[48:63]
	v_mfma_f32_32x32x16_bf16 v[32:47], a[4:7], a[8:11], v[32:47]
	s_waitcnt lgkmcnt(4)
	v_mfma_f32_32x32x16_bf16 v[16:31], a[0:3], a[12:15], v[16:31]
	s_and_b32 m0, s32, 7
	s_lshl_b32 m0, m0, 11
	s_add_i32 m0, m0, 0x14000
	s_nop 0
	global_load_lds_dwordx4 v[178:179], off
	v_mfma_f32_32x32x16_bf16 v[0:15], a[4:7], a[12:15], v[0:15]
	s_nop 0
	s_nop 0
	s_nop 0
	s_nop 0
	s_waitcnt lgkmcnt(1)
	v_mfma_f32_32x32x16_bf16 v[48:63], a[16:19], a[24:27], v[48:63]
	s_and_b32 m0, s32, 7
	s_lshl_b32 m0, m0, 11
	s_add_i32 m0, m0, 0x14400
	s_nop 0
	global_load_lds_dwordx4 v[180:181], off
	v_mfma_f32_32x32x16_bf16 v[32:47], a[20:23], a[24:27], v[32:47]
	s_waitcnt vmcnt(6)
	s_waitcnt lgkmcnt(0)
	s_barrier
	ds_read_b128 a[12:15], v82 offset:4096
	ds_read_b128 a[8:11], v82
	ds_read_b128 a[4:7], v83 offset:36864
	ds_read_b128 a[0:3], v83 offset:32768
	v_mfma_f32_32x32x16_bf16 v[16:31], a[16:19], a[28:31], v[16:31]
	v_lshl_add_u64 v[158:159], v[66:67], 0, s[46:47]
	s_nop 0
	v_lshl_add_u64 v[160:161], v[68:69], 0, s[46:47]
	s_nop 0
	s_nop 0
	s_nop 0
	s_nop 0
	v_mfma_f32_32x32x16_bf16 v[0:15], a[20:23], a[28:31], v[0:15]
	s_and_b32 m0, s32, 7
	s_lshl_b32 m0, m0, 12
	s_add_i32 m0, m0, 0x18000
	s_nop 0
	global_load_lds_dwordx4 v[158:159], off
	s_nop 0
	v_lshl_add_u64 v[164:165], v[72:73], 0, s[46:47]
	s_nop 0
	s_nop 0
	s_nop 0
	v_lshl_add_u64 v[166:167], v[74:75], 0, s[46:47]
	s_nop 0
	s_nop 0
	s_nop 0
	v_lshl_add_u64 v[168:169], v[76:77], 0, s[46:47]
	s_nop 0
	s_mov_b64 s[46:47], 0x600
	s_nop 0
	s_nop 0
	s_nop 0
	s_nop 0
	s_nop 0
	ds_read_b128 a[16:19], v85 offset:32768
	ds_read_b128 a[20:23], v85 offset:36864
	ds_read_b128 a[24:27], v84
	ds_read_b128 a[28:31], v84 offset:4096
	s_waitcnt lgkmcnt(4)
	v_mfma_f32_32x32x16_bf16 v[48:63], a[0:3], a[8:11], v[48:63]
	s_nop 0
	v_mfma_f32_32x32x16_bf16 v[32:47], a[4:7], a[8:11], v[32:47]
	v_mfma_f32_32x32x16_bf16 v[16:31], a[0:3], a[12:15], v[16:31]
	s_and_b32 m0, s32, 7
	s_lshl_b32 m0, m0, 12
	s_add_i32 m0, m0, 0x18400
	s_nop 0
	global_load_lds_dwordx4 v[160:161], off
	v_mfma_f32_32x32x16_bf16 v[0:15], a[4:7], a[12:15], v[0:15]
	s_nop 0
	s_nop 0
	s_nop 0
	s_nop 0
	ds_read_b128 a[0:3], v87 offset:32768
	ds_read_b128 a[4:7], v87 offset:36864
	ds_read_b128 a[8:11], v86
	ds_read_b128 a[12:15], v86 offset:4096
	s_waitcnt lgkmcnt(5)
	v_mfma_f32_32x32x16_bf16 v[48:63], a[16:19], a[24:27], v[48:63]
	s_and_b32 m0, s32, 7
	s_lshl_b32 m0, m0, 12
	s_add_i32 m0, m0, 0x18800
	s_nop 0
	global_load_lds_dwordx4 v[162:163], off
	v_mfma_f32_32x32x16_bf16 v[32:47], a[20:23], a[24:27], v[32:47]
	s_waitcnt lgkmcnt(4)
	v_mfma_f32_32x32x16_bf16 v[16:31], a[16:19], a[28:31], v[16:31]
	v_mfma_f32_32x32x16_bf16 v[0:15], a[20:23], a[28:31], v[0:15]
	s_and_b32 m0, s32, 7
	s_lshl_b32 m0, m0, 12
	s_add_i32 m0, m0, 0x18c00
	s_nop 0
	global_load_lds_dwordx4 v[164:165], off
	s_nop 0
	s_nop 0
	s_nop 0
	s_nop 0
	ds_read_b128 a[16:19], v89 offset:32768
	ds_read_b128 a[20:23], v89 offset:36864
	ds_read_b128 a[24:27], v88
	ds_read_b128 a[28:31], v88 offset:4096
	s_waitcnt lgkmcnt(5)
	v_mfma_f32_32x32x16_bf16 v[48:63], a[0:3], a[8:11], v[48:63]
	v_mfma_f32_32x32x16_bf16 v[32:47], a[4:7], a[8:11], v[32:47]
	s_waitcnt lgkmcnt(4)
	v_mfma_f32_32x32x16_bf16 v[16:31], a[0:3], a[12:15], v[16:31]
	s_and_b32 m0, s32, 7
	s_lshl_b32 m0, m0, 11
	s_add_i32 m0, m0, 0x20000
	s_nop 0
	global_load_lds_dwordx4 v[166:167], off
	v_mfma_f32_32x32x16_bf16 v[0:15], a[4:7], a[12:15], v[0:15]
	s_nop 0
	s_nop 0
	s_nop 0
	s_nop 0
	s_waitcnt lgkmcnt(1)
	v_mfma_f32_32x32x16_bf16 v[48:63], a[16:19], a[24:27], v[48:63]
	s_and_b32 m0, s32, 7
	s_lshl_b32 m0, m0, 11
	s_add_i32 m0, m0, 0x20400
	s_nop 0
	global_load_lds_dwordx4 v[168:169], off
	v_mfma_f32_32x32x16_bf16 v[32:47], a[20:23], a[24:27], v[32:47]
	s_waitcnt vmcnt(6)
	s_waitcnt lgkmcnt(0)
	s_barrier
	ds_read_b128 a[12:15], v82 offset:53248
	ds_read_b128 a[8:11], v82 offset:49152
	ds_read_b128 a[4:7], v90
	ds_read_b128 a[0:3], v92
	v_mfma_f32_32x32x16_bf16 v[16:31], a[16:19], a[28:31], v[16:31]
	v_lshl_add_u64 v[170:171], v[66:67], 0, s[46:47]
	s_nop 0
	v_lshl_add_u64 v[172:173], v[68:69], 0, s[46:47]
	s_nop 0
	s_nop 0
	s_nop 0
	v_lshl_add_u64 v[174:175], v[70:71], 0, s[46:47]
	s_nop 0
	v_mfma_f32_32x32x16_bf16 v[0:15], a[20:23], a[28:31], v[0:15]
	s_and_b32 m0, s32, 7
	s_lshl_b32 m0, m0, 12
	s_add_i32 m0, m0, 0x0
	s_nop 0
	global_load_lds_dwordx4 v[170:171], off
	s_nop 0
	v_lshl_add_u64 v[176:177], v[72:73], 0, s[46:47]
	s_nop 0
	s_nop 0
	s_nop 0
	v_lshl_add_u64 v[178:179], v[74:75], 0, s[46:47]
	s_nop 0
	s_nop 0
	s_nop 0
	v_lshl_add_u64 v[180:181], v[76:77], 0, s[46:47]
	s_nop 0
	s_mov_b64 s[46:47], 0x680
	s_nop 0
	s_nop 0
	s_nop 0
	s_nop 0
	s_nop 0
	ds_read_b128 a[16:19], v93
	ds_read_b128 a[20:23], v91
	ds_read_b128 a[24:27], v84 offset:49152
	ds_read_b128 a[28:31], v84 offset:53248
	s_waitcnt lgkmcnt(4)
	v_mfma_f32_32x32x16_bf16 v[48:63], a[0:3], a[8:11], v[48:63]
	s_nop 0
	v_mfma_f32_32x32x16_bf16 v[32:47], a[4:7], a[8:11], v[32:47]
	v_mfma_f32_32x32x16_bf16 v[16:31], a[0:3], a[12:15], v[16:31]
	s_and_b32 m0, s32, 7
	s_lshl_b32 m0, m0, 12
	s_add_i32 m0, m0, 0x400
	s_nop 0
	global_load_lds_dwordx4 v[172:173], off
	v_mfma_f32_32x32x16_bf16 v[0:15], a[4:7], a[12:15], v[0:15]
	s_nop 0
	s_nop 0
	s_nop 0
	s_nop 0
	ds_read_b128 a[0:3], v95
	ds_read_b128 a[4:7], v94
	ds_read_b128 a[8:11], v86 offset:49152
	ds_read_b128 a[12:15], v86 offset:53248
	s_waitcnt lgkmcnt(5)
	v_mfma_f32_32x32x16_bf16 v[48:63], a[16:19], a[24:27], v[48:63]
	s_and_b32 m0, s32, 7
	s_lshl_b32 m0, m0, 12
	s_add_i32 m0, m0, 0x800
	s_nop 0
	global_load_lds_dwordx4 v[174:175], off
	v_mfma_f32_32x32x16_bf16 v[32:47], a[20:23], a[24:27], v[32:47]
	s_waitcnt lgkmcnt(4)
	v_mfma_f32_32x32x16_bf16 v[16:31], a[16:19], a[28:31], v[16:31]
	v_mfma_f32_32x32x16_bf16 v[0:15], a[20:23], a[28:31], v[0:15]
	s_and_b32 m0, s32, 7
	s_lshl_b32 m0, m0, 12
	s_add_i32 m0, m0, 0xc00
	s_nop 0
	global_load_lds_dwordx4 v[176:177], off
	s_nop 0
	s_nop 0
	s_nop 0
	s_nop 0
	ds_read_b128 a[16:19], v97
	ds_read_b128 a[20:23], v96
	ds_read_b128 a[24:27], v88 offset:49152
	ds_read_b128 a[28:31], v88 offset:53248
	s_waitcnt lgkmcnt(5)
	v_mfma_f32_32x32x16_bf16 v[48:63], a[0:3], a[8:11], v[48:63]
	v_mfma_f32_32x32x16_bf16 v[32:47], a[4:7], a[8:11], v[32:47]
	s_waitcnt lgkmcnt(4)
	v_mfma_f32_32x32x16_bf16 v[16:31], a[0:3], a[12:15], v[16:31]
	s_and_b32 m0, s32, 7
	s_lshl_b32 m0, m0, 11
	s_add_i32 m0, m0, 0x8000
	s_nop 0
	global_load_lds_dwordx4 v[178:179], off
	v_mfma_f32_32x32x16_bf16 v[0:15], a[4:7], a[12:15], v[0:15]
	s_nop 0
	s_nop 0
	s_nop 0
	s_nop 0
	s_waitcnt lgkmcnt(1)
	v_mfma_f32_32x32x16_bf16 v[48:63], a[16:19], a[24:27], v[48:63]
	s_and_b32 m0, s32, 7
	s_lshl_b32 m0, m0, 11
	s_add_i32 m0, m0, 0x8400
	s_nop 0
	global_load_lds_dwordx4 v[180:181], off
	v_mfma_f32_32x32x16_bf16 v[32:47], a[20:23], a[24:27], v[32:47]
	s_waitcnt vmcnt(6)
	s_waitcnt lgkmcnt(0)
	s_barrier
	ds_read_b128 a[12:15], v101
	ds_read_b128 a[8:11], v100
	ds_read_b128 a[4:7], v99
	ds_read_b128 a[0:3], v98
	v_mfma_f32_32x32x16_bf16 v[16:31], a[16:19], a[28:31], v[16:31]
	v_lshl_add_u64 v[158:159], v[66:67], 0, s[46:47]
	s_nop 0
	v_lshl_add_u64 v[160:161], v[68:69], 0, s[46:47]
	s_nop 0
	s_mov_b64 s[28:29], 0x700
	s_nop 0
	v_lshl_add_u64 v[162:163], v[70:71], 0, s[46:47]
	s_nop 0
	v_mfma_f32_32x32x16_bf16 v[0:15], a[20:23], a[28:31], v[0:15]
	s_and_b32 m0, s32, 7
	s_lshl_b32 m0, m0, 12
	s_add_i32 m0, m0, 0xc000
	s_nop 0
	global_load_lds_dwordx4 v[158:159], off
	s_nop 0
	v_lshl_add_u64 v[164:165], v[72:73], 0, s[46:47]
	s_nop 0
	s_nop 0
	s_nop 0
	v_lshl_add_u64 v[166:167], v[74:75], 0, s[46:47]
	s_nop 0
	s_nop 0
	s_nop 0
	v_lshl_add_u64 v[168:169], v[76:77], 0, s[46:47]
	s_nop 0
	s_nop 0
	s_nop 0
	s_nop 0
	s_nop 0
	s_nop 0
	s_nop 0
	ds_read_b128 a[16:19], v102
	ds_read_b128 a[20:23], v103
	ds_read_b128 a[24:27], v104
	ds_read_b128 a[28:31], v105
	s_waitcnt lgkmcnt(4)
	v_mfma_f32_32x32x16_bf16 v[48:63], a[0:3], a[8:11], v[48:63]
	s_nop 0
	v_mfma_f32_32x32x16_bf16 v[32:47], a[4:7], a[8:11], v[32:47]
	v_mfma_f32_32x32x16_bf16 v[16:31], a[0:3], a[12:15], v[16:31]
	s_and_b32 m0, s32, 7
	s_lshl_b32 m0, m0, 12
	s_add_i32 m0, m0, 0xc400
	s_nop 0
	global_load_lds_dwordx4 v[160:161], off
	v_mfma_f32_32x32x16_bf16 v[0:15], a[4:7], a[12:15], v[0:15]
	s_nop 0
	s_nop 0
	s_nop 0
	s_nop 0
	ds_read_b128 a[0:3], v106
	ds_read_b128 a[4:7], v107
	ds_read_b128 a[8:11], v108
	ds_read_b128 a[12:15], v109
	s_waitcnt lgkmcnt(5)
	v_mfma_f32_32x32x16_bf16 v[48:63], a[16:19], a[24:27], v[48:63]
	s_and_b32 m0, s32, 7
	s_lshl_b32 m0, m0, 12
	s_add_i32 m0, m0, 0xc800
	s_nop 0
	global_load_lds_dwordx4 v[162:163], off
	v_mfma_f32_32x32x16_bf16 v[32:47], a[20:23], a[24:27], v[32:47]
	s_waitcnt lgkmcnt(4)
	v_mfma_f32_32x32x16_bf16 v[16:31], a[16:19], a[28:31], v[16:31]
	v_mfma_f32_32x32x16_bf16 v[0:15], a[20:23], a[28:31], v[0:15]
	s_and_b32 m0, s32, 7
	s_lshl_b32 m0, m0, 12
	s_add_i32 m0, m0, 0xcc00
	s_nop 0
	global_load_lds_dwordx4 v[164:165], off
	s_nop 0
	s_nop 0
	s_nop 0
	s_nop 0
	ds_read_b128 a[16:19], v110
	ds_read_b128 a[20:23], v111
	ds_read_b128 a[24:27], v112
	ds_read_b128 a[28:31], v113
	s_waitcnt lgkmcnt(5)
	v_mfma_f32_32x32x16_bf16 v[48:63], a[0:3], a[8:11], v[48:63]
	v_mfma_f32_32x32x16_bf16 v[32:47], a[4:7], a[8:11], v[32:47]
	s_waitcnt lgkmcnt(4)
	v_mfma_f32_32x32x16_bf16 v[16:31], a[0:3], a[12:15], v[16:31]
	s_and_b32 m0, s32, 7
	s_lshl_b32 m0, m0, 11
	s_add_i32 m0, m0, 0x14000
	s_nop 0
	global_load_lds_dwordx4 v[166:167], off
	v_mfma_f32_32x32x16_bf16 v[0:15], a[4:7], a[12:15], v[0:15]
	s_nop 0
	s_nop 0
	s_nop 0
	s_nop 0
	s_waitcnt lgkmcnt(1)
	v_mfma_f32_32x32x16_bf16 v[48:63], a[16:19], a[24:27], v[48:63]
	s_and_b32 m0, s32, 7
	s_lshl_b32 m0, m0, 11
	s_add_i32 m0, m0, 0x14400
	s_nop 0
	global_load_lds_dwordx4 v[168:169], off
	v_mfma_f32_32x32x16_bf16 v[32:47], a[20:23], a[24:27], v[32:47]
	s_waitcnt vmcnt(6)
	s_waitcnt lgkmcnt(0)
	s_barrier
	ds_read_b128 a[12:15], v82 offset:4096
	ds_read_b128 a[8:11], v82
	ds_read_b128 a[4:7], v83 offset:36864
	ds_read_b128 a[0:3], v83 offset:32768
	v_mfma_f32_32x32x16_bf16 v[16:31], a[16:19], a[28:31], v[16:31]
	v_lshl_add_u64 v[170:171], v[66:67], 0, s[28:29]
	s_nop 0
	v_lshl_add_u64 v[172:173], v[68:69], 0, s[28:29]
	s_nop 0
	s_nop 0
	s_nop 0
	v_lshl_add_u64 v[174:175], v[70:71], 0, s[28:29]
	s_nop 0
	v_mfma_f32_32x32x16_bf16 v[0:15], a[20:23], a[28:31], v[0:15]
	s_and_b32 m0, s32, 7
	s_lshl_b32 m0, m0, 12
	s_add_i32 m0, m0, 0x18000
	s_nop 0
	global_load_lds_dwordx4 v[170:171], off
	s_nop 0
	v_lshl_add_u64 v[176:177], v[72:73], 0, s[28:29]
	s_nop 0
	s_nop 0
	s_nop 0
	v_lshl_add_u64 v[178:179], v[74:75], 0, s[28:29]
	s_nop 0
	s_nop 0
	s_nop 0
	v_lshl_add_u64 v[180:181], v[76:77], 0, s[28:29]
	s_nop 0
	s_mov_b64 s[28:29], 0x780
	s_nop 0
	s_nop 0
	s_nop 0
	s_nop 0
	s_nop 0
	ds_read_b128 a[16:19], v85 offset:32768
	ds_read_b128 a[20:23], v85 offset:36864
	ds_read_b128 a[24:27], v84
	ds_read_b128 a[28:31], v84 offset:4096
	s_waitcnt lgkmcnt(4)
	v_mfma_f32_32x32x16_bf16 v[48:63], a[0:3], a[8:11], v[48:63]
	v_lshl_add_u64 v[158:159], v[66:67], 0, s[28:29]
	s_nop 0
	v_mfma_f32_32x32x16_bf16 v[32:47], a[4:7], a[8:11], v[32:47]
	v_mfma_f32_32x32x16_bf16 v[16:31], a[0:3], a[12:15], v[16:31]
	s_and_b32 m0, s32, 7
	s_lshl_b32 m0, m0, 12
	s_add_i32 m0, m0, 0x18400
	s_nop 0
	global_load_lds_dwordx4 v[172:173], off
	v_mfma_f32_32x32x16_bf16 v[0:15], a[4:7], a[12:15], v[0:15]
	s_nop 0
	s_nop 0
	s_nop 0
	s_nop 0
	ds_read_b128 a[0:3], v87 offset:32768
	ds_read_b128 a[4:7], v87 offset:36864
	ds_read_b128 a[8:11], v86
	ds_read_b128 a[12:15], v86 offset:4096
	s_waitcnt lgkmcnt(5)
	v_mfma_f32_32x32x16_bf16 v[48:63], a[16:19], a[24:27], v[48:63]
	s_and_b32 m0, s32, 7
	s_lshl_b32 m0, m0, 12
	s_add_i32 m0, m0, 0x18800
	s_nop 0
	global_load_lds_dwordx4 v[174:175], off
	v_mfma_f32_32x32x16_bf16 v[32:47], a[20:23], a[24:27], v[32:47]
	s_waitcnt lgkmcnt(4)
	v_mfma_f32_32x32x16_bf16 v[16:31], a[16:19], a[28:31], v[16:31]
	v_mfma_f32_32x32x16_bf16 v[0:15], a[20:23], a[28:31], v[0:15]
	s_and_b32 m0, s32, 7
	s_lshl_b32 m0, m0, 12
	s_add_i32 m0, m0, 0x18c00
	s_nop 0
	global_load_lds_dwordx4 v[176:177], off
	s_nop 0
	s_nop 0
	s_nop 0
	s_nop 0
	ds_read_b128 a[16:19], v89 offset:32768
	ds_read_b128 a[20:23], v89 offset:36864
	ds_read_b128 a[24:27], v88
	ds_read_b128 a[28:31], v88 offset:4096
	s_waitcnt lgkmcnt(5)
	v_mfma_f32_32x32x16_bf16 v[48:63], a[0:3], a[8:11], v[48:63]
	v_mfma_f32_32x32x16_bf16 v[32:47], a[4:7], a[8:11], v[32:47]
	s_waitcnt lgkmcnt(4)
	v_mfma_f32_32x32x16_bf16 v[16:31], a[0:3], a[12:15], v[16:31]
	s_and_b32 m0, s32, 7
	s_lshl_b32 m0, m0, 11
	s_add_i32 m0, m0, 0x20000
	s_nop 0
	global_load_lds_dwordx4 v[178:179], off
	v_mfma_f32_32x32x16_bf16 v[0:15], a[4:7], a[12:15], v[0:15]
	s_nop 0
	s_nop 0
	s_nop 0
	s_nop 0
	s_waitcnt lgkmcnt(1)
	v_mfma_f32_32x32x16_bf16 v[48:63], a[16:19], a[24:27], v[48:63]
	s_and_b32 m0, s32, 7
	s_lshl_b32 m0, m0, 11
	s_add_i32 m0, m0, 0x20400
	s_nop 0
	global_load_lds_dwordx4 v[180:181], off
	v_mfma_f32_32x32x16_bf16 v[32:47], a[20:23], a[24:27], v[32:47]
	s_waitcnt vmcnt(6)
	s_waitcnt lgkmcnt(0)
	s_barrier
	ds_read_b128 a[12:15], v82 offset:53248
	ds_read_b128 a[8:11], v82 offset:49152
	ds_read_b128 a[4:7], v90
	ds_read_b128 a[0:3], v92
	s_nop 0
	v_lshl_add_u64 v[160:161], v[68:69], 0, s[28:29]
	s_nop 0
	v_mfma_f32_32x32x16_bf16 v[16:31], a[16:19], a[28:31], v[16:31]
	s_nop 0
	v_lshl_add_u64 v[162:163], v[70:71], 0, s[28:29]
	s_nop 0
	v_cmp_eq_u32_e64 s[0:1], 0, v79
	s_nop 0
	v_lshl_add_u64 v[164:165], v[72:73], 0, s[28:29]
	s_nop 0
	v_mfma_f32_32x32x16_bf16 v[0:15], a[20:23], a[28:31], v[0:15]
	s_and_b32 m0, s32, 7
	s_lshl_b32 m0, m0, 12
	s_add_i32 m0, m0, 0x0
	s_nop 0
	global_load_lds_dwordx4 v[158:159], off
	s_nop 0
	v_lshl_add_u64 v[166:167], v[74:75], 0, s[28:29]
	s_nop 0
	v_readlane_b32 s20, v215, 52
	s_nop 0
	v_lshl_add_u64 v[168:169], v[76:77], 0, s[28:29]
	s_nop 0
	v_readlane_b32 s21, v215, 53
	s_nop 0
	s_nop 0
	s_nop 0
	s_nop 0
	s_nop 0
	ds_read_b128 a[16:19], v93
	ds_read_b128 a[20:23], v91
	ds_read_b128 a[24:27], v84 offset:49152
	ds_read_b128 a[28:31], v84 offset:53248
	s_waitcnt lgkmcnt(4)
	v_mfma_f32_32x32x16_bf16 v[48:63], a[0:3], a[8:11], v[48:63]
	s_mov_b32 s23, 0
	v_mfma_f32_32x32x16_bf16 v[32:47], a[4:7], a[8:11], v[32:47]
	v_mfma_f32_32x32x16_bf16 v[16:31], a[0:3], a[12:15], v[16:31]
	s_and_b32 m0, s32, 7
	s_lshl_b32 m0, m0, 12
	s_add_i32 m0, m0, 0x400
	s_nop 0
	global_load_lds_dwordx4 v[160:161], off
	v_mfma_f32_32x32x16_bf16 v[0:15], a[4:7], a[12:15], v[0:15]
	s_nop 0
	s_nop 0
	s_nop 0
	s_nop 0
	ds_read_b128 a[0:3], v95
	ds_read_b128 a[4:7], v94
	ds_read_b128 a[8:11], v86 offset:49152
	ds_read_b128 a[12:15], v86 offset:53248
	s_waitcnt lgkmcnt(5)
	v_mfma_f32_32x32x16_bf16 v[48:63], a[16:19], a[24:27], v[48:63]
	s_and_b32 m0, s32, 7
	s_lshl_b32 m0, m0, 12
	s_add_i32 m0, m0, 0x800
	s_nop 0
	global_load_lds_dwordx4 v[162:163], off
	v_mfma_f32_32x32x16_bf16 v[32:47], a[20:23], a[24:27], v[32:47]
	s_waitcnt lgkmcnt(4)
	v_mfma_f32_32x32x16_bf16 v[16:31], a[16:19], a[28:31], v[16:31]
	v_mfma_f32_32x32x16_bf16 v[0:15], a[20:23], a[28:31], v[0:15]
	s_and_b32 m0, s32, 7
	s_lshl_b32 m0, m0, 12
	s_add_i32 m0, m0, 0xc00
	s_nop 0
	global_load_lds_dwordx4 v[164:165], off
	s_nop 0
	s_nop 0
	s_nop 0
	s_nop 0
	ds_read_b128 a[16:19], v97
	ds_read_b128 a[20:23], v96
	ds_read_b128 a[24:27], v88 offset:49152
	ds_read_b128 a[28:31], v88 offset:53248
	s_waitcnt lgkmcnt(5)
	v_mfma_f32_32x32x16_bf16 v[48:63], a[0:3], a[8:11], v[48:63]
	v_mfma_f32_32x32x16_bf16 v[32:47], a[4:7], a[8:11], v[32:47]
	s_waitcnt lgkmcnt(4)
	v_mfma_f32_32x32x16_bf16 v[16:31], a[0:3], a[12:15], v[16:31]
	s_and_b32 m0, s32, 7
	s_lshl_b32 m0, m0, 11
	s_add_i32 m0, m0, 0x8000
	s_nop 0
	global_load_lds_dwordx4 v[166:167], off
	v_mfma_f32_32x32x16_bf16 v[0:15], a[4:7], a[12:15], v[0:15]
	s_nop 0
	s_nop 0
	s_nop 0
	s_nop 0
	s_waitcnt lgkmcnt(1)
	v_mfma_f32_32x32x16_bf16 v[48:63], a[16:19], a[24:27], v[48:63]
	s_and_b32 m0, s32, 7
	s_lshl_b32 m0, m0, 11
	s_add_i32 m0, m0, 0x8400
	s_nop 0
	global_load_lds_dwordx4 v[168:169], off
	v_mfma_f32_32x32x16_bf16 v[32:47], a[20:23], a[24:27], v[32:47]
	s_waitcnt vmcnt(6)
	s_waitcnt lgkmcnt(0)
	s_barrier
	ds_read_b128 a[12:15], v101
	ds_read_b128 a[8:11], v100
	ds_read_b128 a[4:7], v99
	ds_read_b128 a[0:3], v98
	v_mfma_f32_32x32x16_bf16 v[16:31], a[16:19], a[28:31], v[16:31]
	v_mfma_f32_32x32x16_bf16 v[0:15], a[20:23], a[28:31], v[0:15]
	s_nop 0
	s_nop 0
	s_nop 0
	s_nop 0
	ds_read_b128 a[16:19], v102
	ds_read_b128 a[20:23], v103
	ds_read_b128 a[24:27], v104
	ds_read_b128 a[28:31], v105
	s_waitcnt lgkmcnt(4)
	v_mfma_f32_32x32x16_bf16 v[48:63], a[0:3], a[8:11], v[48:63]
	v_mfma_f32_32x32x16_bf16 v[32:47], a[4:7], a[8:11], v[32:47]
	v_mfma_f32_32x32x16_bf16 v[16:31], a[0:3], a[12:15], v[16:31]
	v_mfma_f32_32x32x16_bf16 v[0:15], a[4:7], a[12:15], v[0:15]
	s_nop 0
	s_nop 0
	s_nop 0
	s_nop 0
	ds_read_b128 a[0:3], v106
	ds_read_b128 a[4:7], v107
	ds_read_b128 a[8:11], v108
	ds_read_b128 a[12:15], v109
	s_waitcnt lgkmcnt(5)
	v_mfma_f32_32x32x16_bf16 v[48:63], a[16:19], a[24:27], v[48:63]
	v_mfma_f32_32x32x16_bf16 v[32:47], a[20:23], a[24:27], v[32:47]
	s_waitcnt lgkmcnt(4)
	v_mfma_f32_32x32x16_bf16 v[16:31], a[16:19], a[28:31], v[16:31]
	v_mfma_f32_32x32x16_bf16 v[0:15], a[20:23], a[28:31], v[0:15]
	s_nop 0
	s_nop 0
	s_nop 0
	s_nop 0
	ds_read_b128 a[16:19], v110
	ds_read_b128 a[20:23], v111
	ds_read_b128 a[24:27], v112
	ds_read_b128 a[28:31], v113
	s_waitcnt lgkmcnt(5)
	v_mfma_f32_32x32x16_bf16 v[48:63], a[0:3], a[8:11], v[48:63]
	v_mfma_f32_32x32x16_bf16 v[32:47], a[4:7], a[8:11], v[32:47]
	s_waitcnt lgkmcnt(4)
	v_mfma_f32_32x32x16_bf16 v[16:31], a[0:3], a[12:15], v[16:31]
	v_mfma_f32_32x32x16_bf16 v[0:15], a[4:7], a[12:15], v[0:15]
	s_nop 0
	s_nop 0
	s_nop 0
	s_nop 0
	s_waitcnt lgkmcnt(1)
	v_mfma_f32_32x32x16_bf16 v[48:63], a[16:19], a[24:27], v[48:63]
	v_mfma_f32_32x32x16_bf16 v[32:47], a[20:23], a[24:27], v[32:47]
	s_waitcnt vmcnt(0)
	s_waitcnt lgkmcnt(0)
	s_barrier
	ds_read_b128 a[12:15], v82 offset:4096
	ds_read_b128 a[8:11], v82
	ds_read_b128 a[4:7], v83 offset:36864
	ds_read_b128 a[0:3], v83 offset:32768
	v_mfma_f32_32x32x16_bf16 v[16:31], a[16:19], a[28:31], v[16:31]
	v_mfma_f32_32x32x16_bf16 v[0:15], a[20:23], a[28:31], v[0:15]
	s_nop 0
	s_nop 0
	s_nop 0
	s_nop 0
	ds_read_b128 a[16:19], v85 offset:32768
	ds_read_b128 a[20:23], v85 offset:36864
	ds_read_b128 a[24:27], v84
	ds_read_b128 a[28:31], v84 offset:4096
	s_waitcnt lgkmcnt(4)
	v_mfma_f32_32x32x16_bf16 v[48:63], a[0:3], a[8:11], v[48:63]
	v_mfma_f32_32x32x16_bf16 v[32:47], a[4:7], a[8:11], v[32:47]
	v_mfma_f32_32x32x16_bf16 v[16:31], a[0:3], a[12:15], v[16:31]
	v_mfma_f32_32x32x16_bf16 v[0:15], a[4:7], a[12:15], v[0:15]
	s_nop 0
	s_nop 0
	s_nop 0
	s_nop 0
	ds_read_b128 a[0:3], v87 offset:32768
	ds_read_b128 a[4:7], v87 offset:36864
	ds_read_b128 a[8:11], v86
	ds_read_b128 a[12:15], v86 offset:4096
	s_waitcnt lgkmcnt(5)
	v_mfma_f32_32x32x16_bf16 v[48:63], a[16:19], a[24:27], v[48:63]
	v_mfma_f32_32x32x16_bf16 v[32:47], a[20:23], a[24:27], v[32:47]
	s_waitcnt lgkmcnt(4)
	v_mfma_f32_32x32x16_bf16 v[16:31], a[16:19], a[28:31], v[16:31]
	v_mfma_f32_32x32x16_bf16 v[0:15], a[20:23], a[28:31], v[0:15]
	s_nop 0
	s_nop 0
	s_nop 0
	s_waitcnt lgkmcnt(1)
	v_mfma_f32_32x32x16_bf16 v[48:63], a[0:3], a[8:11], v[48:63]
	v_mfma_f32_32x32x16_bf16 v[32:47], a[4:7], a[8:11], v[32:47]
	s_nop 0
	s_waitcnt lgkmcnt(0)
	v_mfma_f32_32x32x16_bf16 v[0:15], a[4:7], a[12:15], v[0:15]
	v_mfma_f32_32x32x16_bf16 v[16:31], a[0:3], a[12:15], v[16:31]
	ds_read_b128 v[66:69], v89 offset:32768
	ds_read_b128 v[70:73], v88
	ds_read_b128 v[74:77], v89 offset:36864
	ds_read_b128 v[82:85], v88 offset:4096
	s_waitcnt lgkmcnt(0)
	s_barrier
	s_waitcnt lgkmcnt(0)
	v_mfma_f32_32x32x16_bf16 v[48:63], v[66:69], v[70:73], v[48:63]
	v_mfma_f32_32x32x16_bf16 v[32:47], v[74:77], v[70:73], v[32:47]
	s_nop 10
	ds_write_b128 v64, v[48:51]
	ds_write_b128 v64, v[52:55] offset:32
	ds_write_b128 v64, v[56:59] offset:64
	ds_write_b128 v64, v[60:63] offset:96
	ds_write_b128 v64, v[32:35] offset:128
	v_mfma_f32_32x32x16_bf16 v[0:15], v[74:77], v[82:85], v[0:15]
	v_mfma_f32_32x32x16_bf16 v[16:31], v[66:69], v[82:85], v[16:31]
	ds_write_b128 v64, v[36:39] offset:160
	ds_write_b128 v64, v[40:43] offset:192
	ds_write_b128 v64, v[44:47] offset:224
	s_nop 8
	ds_write_b128 v64, v[16:19] offset:16896
	ds_write_b128 v64, v[20:23] offset:16928
	ds_write_b128 v64, v[24:27] offset:16960
	ds_write_b128 v64, v[28:31] offset:16992
	ds_write_b128 v64, v[0:3] offset:17024
	ds_write_b128 v64, v[4:7] offset:17056
	ds_write_b128 v64, v[8:11] offset:17088
	ds_write_b128 v64, v[12:15] offset:17120
	s_waitcnt lgkmcnt(0)
	s_barrier
	v_lshl_or_b32 v0, v79, 2, s31
	v_ashrrev_i32_e32 v1, 31, v0
	v_lshl_add_u32 v4, v79, 4, 0
	v_lshl_add_u64 v[6:7], v[0:1], 2, s[92:93]
	v_lshl_add_u64 v[8:9], v[0:1], 1, s[20:21]
	s_branch .LBB0_161

.LBB0_585:
	s_and_b64 vcc, exec, s[0:1]
	s_cbranch_vccz .LBB0_518
	s_mul_hi_i32 s0, s33, 0x51eb851f
	s_lshr_b32 s1, s0, 31
	s_ashr_i32 s0, s0, 3
	v_mov_b32_e32 v78, v133
	s_add_i32 s21, s0, s1
	s_lshl_b32 s20, s21, 8
	v_ashrrev_i32_e32 v6, 6, v78
	v_bfe_u32 v7, v78, 3, 3
	v_lshl_or_b32 v8, v6, 5, v7
	v_add_u32_e32 v0, s20, v8
	s_waitcnt lgkmcnt(0)
	v_ashrrev_i32_e32 v1, 31, v0
	v_lshlrev_b64 v[2:3], 11, v[0:1]
	v_bfe_u32 v1, v78, 4, 2
	v_readlane_b32 s0, v215, 52
	v_xor_b32_e32 v1, v1, v78
	v_readlane_b32 s1, v215, 53
	v_lshlrev_b32_e32 v1, 4, v1
	v_and_b32_e32 v64, 0x70, v1
	v_lshl_add_u64 v[2:3], s[0:1], 0, v[2:3]
	v_or_b32_e32 v1, 8, v8
	v_lshl_add_u64 v[66:67], v[2:3], 0, v[64:65]
	v_add_u32_e32 v2, s20, v1
	v_lshrrev_b32_e32 v1, 1, v1
	v_xor_b32_e32 v1, v1, v78
	v_ashrrev_i32_e32 v3, 31, v2
	v_lshlrev_b32_e32 v1, 4, v1
	v_or_b32_e32 v0, 16, v0
	v_lshlrev_b64 v[2:3], 11, v[2:3]
	v_and_b32_e32 v4, 0x70, v1
	v_ashrrev_i32_e32 v1, 31, v0
	v_lshl_add_u64 v[2:3], s[0:1], 0, v[2:3]
	v_mov_b32_e32 v5, v65
	v_lshlrev_b64 v[0:1], 11, v[0:1]
	v_lshl_add_u64 v[68:69], v[2:3], 0, v[4:5]
	v_lshl_add_u64 v[0:1], s[0:1], 0, v[0:1]
	v_or_b32_e32 v2, 24, v8
	v_lshl_add_u64 v[70:71], v[0:1], 0, v[64:65]
	v_add_u32_e32 v0, s20, v2
	v_lshrrev_b32_e32 v2, 1, v2
	v_ashrrev_i32_e32 v1, 31, v0
	v_xor_b32_e32 v2, v2, v78
	v_lshlrev_b64 v[0:1], 11, v[0:1]
	v_lshlrev_b32_e32 v2, 4, v2
	v_lshl_add_u64 v[0:1], s[0:1], 0, v[0:1]
	v_and_b32_e32 v2, 0x70, v2
	v_mov_b32_e32 v3, v65
	v_lshl_or_b32 v4, v6, 4, v7
	s_mulk_i32 s21, 0xc80
	v_lshl_add_u64 v[72:73], v[0:1], 0, v[2:3]
	v_subrev_u32_e32 v0, s21, v4
	v_add_u32_e32 v0, s23, v0
	v_ashrrev_i32_e32 v1, 31, v0
	v_lshlrev_b64 v[2:3], 11, v[0:1]
	v_lshl_add_u64 v[2:3], s[96:97], 0, v[2:3]
	v_lshl_add_u64 v[74:75], v[2:3], 0, v[64:65]
	v_lshlrev_b32_e32 v3, 12, v6
	v_add_u32_e32 v126, 0, v3
	s_waitcnt vmcnt(0)
	v_add_u32_e32 v127, 0x400, v126
	v_readfirstlane_b32 s41, v126
	v_or_b32_e32 v2, 8, v4
	s_waitcnt lgkmcnt(0)
	s_barrier
	s_mov_b32 m0, s41
	v_readfirstlane_b32 s42, v127
	v_add_u32_e32 v128, 0x800, v126
	v_lshlrev_b32_e32 v5, 11, v6
	v_and_b32_e32 v79, 1, v6
	v_add_u32_e32 v0, 8, v0
	v_lshrrev_b32_e32 v2, 1, v2
	global_load_lds_dwordx4 v[66:67], off
	s_mov_b32 m0, s42
	v_readfirstlane_b32 s43, v128
	v_add_u32_e32 v129, 0xc00, v126
	v_add_u32_e32 v6, 0, v5
	v_ashrrev_i32_e32 v1, 31, v0
	v_xor_b32_e32 v2, v2, v78
	global_load_lds_dwordx4 v[68:69], off
	s_mov_b32 m0, s43
	v_readfirstlane_b32 s44, v129
	v_add_u32_e32 v131, 0x8000, v6
	v_lshlrev_b64 v[0:1], 11, v[0:1]
	v_lshlrev_b32_e32 v2, 4, v2
	global_load_lds_dwordx4 v[70:71], off
	s_mov_b32 m0, s44
	v_readfirstlane_b32 s45, v131
	v_add_u32_e32 v130, 0x8400, v6
	v_lshl_add_u64 v[0:1], s[96:97], 0, v[0:1]
	v_and_b32_e32 v64, 0x70, v2
	global_load_lds_dwordx4 v[72:73], off
	s_mov_b32 m0, s45
	v_readfirstlane_b32 s46, v130
	v_add_u32_e32 v120, 0xc000, v126
	v_lshl_add_u64 v[76:77], v[0:1], 0, v[64:65]
	global_load_lds_dwordx4 v[74:75], off
	s_mov_b32 m0, s46
	s_mov_b64 s[0:1], 0x80
	v_readfirstlane_b32 s35, v120
	v_add_u32_e32 v121, 0xc400, v126
	global_load_lds_dwordx4 v[76:77], off
	v_lshl_add_u64 v[0:1], v[66:67], 0, s[0:1]
	s_mov_b32 m0, s35
	v_readfirstlane_b32 s36, v121
	v_add_u32_e32 v122, 0xc800, v126
	global_load_lds_dwordx4 v[0:1], off
	v_lshl_add_u64 v[0:1], v[68:69], 0, s[0:1]
	s_mov_b32 m0, s36
	v_readfirstlane_b32 s37, v122
	v_add_u32_e32 v123, 0xcc00, v126
	global_load_lds_dwordx4 v[0:1], off
	v_lshl_add_u64 v[0:1], v[70:71], 0, s[0:1]
	s_mov_b32 m0, s37
	v_readfirstlane_b32 s38, v123
	v_add_u32_e32 v124, s85, v5
	global_load_lds_dwordx4 v[0:1], off
	v_lshl_add_u64 v[0:1], v[72:73], 0, s[0:1]
	s_mov_b32 m0, s38
	v_readfirstlane_b32 s39, v124
	v_add_u32_e32 v125, 0x14400, v6
	global_load_lds_dwordx4 v[0:1], off
	v_lshl_add_u64 v[0:1], v[74:75], 0, s[0:1]
	s_mov_b32 m0, s39
	v_readfirstlane_b32 s40, v125
	global_load_lds_dwordx4 v[0:1], off
	v_lshl_add_u64 v[0:1], v[76:77], 0, s[0:1]
	s_mov_b32 m0, s40
	v_lshrrev_b32_e32 v2, 1, v78
	v_bfe_u32 v64, v78, 5, 1
	global_load_lds_dwordx4 v[0:1], off
	v_add_u32_e32 v114, s3, v3
	v_bitop3_b32 v0, v2, v64, 7 bitop3:0x6c
	s_waitcnt vmcnt(6)
	s_mov_b64 s[30:31], 0x100
	v_readfirstlane_b32 s0, v114
	v_add_u32_e32 v115, 0x400, v114
	v_lshlrev_b32_e32 v132, 4, v0
	s_waitcnt lgkmcnt(0)
	s_barrier
	v_lshl_add_u64 v[0:1], v[66:67], 0, s[30:31]
	s_mov_b32 m0, s0
	v_readfirstlane_b32 s1, v115
	v_add_u32_e32 v116, 0x800, v114
	global_load_lds_dwordx4 v[0:1], off
	v_lshl_add_u64 v[0:1], v[68:69], 0, s[30:31]
	s_mov_b32 m0, s1
	v_readfirstlane_b32 s24, v116
	v_add_u32_e32 v117, 0xc00, v114
	v_readlane_b32 s29, v212, 31
	v_and_b32_e32 v81, 31, v78
	global_load_lds_dwordx4 v[0:1], off
	v_lshl_add_u64 v[0:1], v[70:71], 0, s[30:31]
	s_mov_b32 m0, s24
	v_readfirstlane_b32 s28, v117
	v_add_u32_e32 v118, s29, v5
	v_add_u32_e32 v2, s3, v5
	v_lshlrev_b32_e32 v4, 7, v81
	global_load_lds_dwordx4 v[0:1], off
	v_lshl_add_u64 v[0:1], v[72:73], 0, s[30:31]
	s_mov_b32 m0, s28
	v_readfirstlane_b32 s29, v118
	v_add_u32_e32 v119, 0x8400, v2
	v_lshl_or_b32 v102, v79, 13, v4
	global_load_lds_dwordx4 v[0:1], off
	v_lshl_add_u64 v[0:1], v[74:75], 0, s[30:31]
	s_mov_b32 m0, s29
	v_readfirstlane_b32 s34, v119
	global_load_lds_dwordx4 v[0:1], off
	v_lshl_add_u64 v[0:1], v[76:77], 0, s[30:31]
	s_mov_b32 m0, s34
	v_add_u32_e32 v100, 0, v102
	global_load_lds_dwordx4 v[0:1], off
	v_add_u32_e32 v83, v100, v132
	v_ashrrev_i32_e32 v80, 7, v78
	ds_read_b128 a[0:3], v83 offset:32768
	ds_read_b128 a[4:7], v83 offset:36864
	v_lshl_or_b32 v134, v80, 13, v4
	v_add_u32_e32 v101, 0, v134
	v_add_u32_e32 v82, v101, v132
	ds_read_b128 a[8:11], v82
	ds_read_b128 a[12:15], v82 offset:4096
	v_lshrrev_b32_e32 v182, 6, v133
	s_nop 0
	v_readfirstlane_b32 s32, v182
	s_waitcnt lgkmcnt(1)
	v_mfma_f32_32x32x16_bf16 v[48:63], a[0:3], a[8:11], 0
	v_bfe_u32 v103, v78, 1, 3
	s_mov_b64 s[30:31], 0x180
	s_nop 0
	v_or_b32_e32 v143, 0x8000, v102
	v_or_b32_e32 v144, 0x9000, v102
	v_add_u32_e32 v145, s3, v134
	s_mov_b64 s[80:81], 0x200
	s_waitcnt vmcnt(12)
	v_mfma_f32_32x32x16_bf16 v[32:47], a[4:7], a[8:11], 0
	s_waitcnt lgkmcnt(0)
	v_mfma_f32_32x32x16_bf16 v[16:31], a[0:3], a[12:15], 0
	v_bitop3_b32 v0, v64, v103, 2 bitop3:0x36
	v_lshlrev_b32_e32 v138, 4, v0
	v_add_u32_e32 v84, v101, v138
	ds_read_b128 a[28:31], v84 offset:4096
	s_nop 0
	s_nop 0
	ds_read_b128 a[24:27], v84
	s_nop 0
	v_add_u32_e32 v85, v100, v138
	ds_read_b128 a[20:23], v85 offset:36864
	s_nop 0
	s_nop 0
	ds_read_b128 a[16:19], v85 offset:32768
	s_nop 0
	s_nop 0
	s_nop 0
	s_nop 0
	s_nop 0
	s_nop 0
	v_mfma_f32_32x32x16_bf16 v[0:15], a[4:7], a[12:15], 0
	s_nop 0
	s_waitcnt lgkmcnt(0)
	v_mfma_f32_32x32x16_bf16 v[48:63], a[16:19], a[24:27], v[48:63]
	v_mfma_f32_32x32x16_bf16 v[32:47], a[20:23], a[24:27], v[32:47]
	v_mfma_f32_32x32x16_bf16 v[16:31], a[16:19], a[28:31], v[16:31]
	v_bitop3_b32 v86, v64, v103, 4 bitop3:0x36
	v_lshlrev_b32_e32 v139, 4, v86
	v_add_u32_e32 v86, v101, v139
	ds_read_b128 a[12:15], v86 offset:4096
	s_nop 0
	s_nop 0
	ds_read_b128 a[8:11], v86
	s_nop 0
	v_add_u32_e32 v87, v100, v139
	ds_read_b128 a[4:7], v87 offset:36864
	s_nop 0
	s_nop 0
	ds_read_b128 a[0:3], v87 offset:32768
	s_nop 0
	s_nop 0
	s_nop 0
	v_mfma_f32_32x32x16_bf16 v[0:15], a[20:23], a[28:31], v[0:15]
	s_nop 0
	s_nop 0
	s_nop 0
	s_waitcnt lgkmcnt(0)
	v_mfma_f32_32x32x16_bf16 v[48:63], a[0:3], a[8:11], v[48:63]
	v_mfma_f32_32x32x16_bf16 v[32:47], a[4:7], a[8:11], v[32:47]
	s_nop 0
	v_mfma_f32_32x32x16_bf16 v[16:31], a[0:3], a[12:15], v[16:31]
	v_bitop3_b32 v88, v64, v103, 6 bitop3:0x36
	v_lshlrev_b32_e32 v142, 4, v88
	v_add_u32_e32 v88, v101, v142
	ds_read_b128 a[28:31], v88 offset:4096
	s_nop 0
	s_nop 0
	ds_read_b128 a[24:27], v88
	s_nop 0
	v_add_u32_e32 v89, v100, v142
	ds_read_b128 a[20:23], v89 offset:36864
	s_nop 0
	s_nop 0
	ds_read_b128 a[16:19], v89 offset:32768
	s_nop 0
	s_nop 0
	s_nop 0
	v_mfma_f32_32x32x16_bf16 v[0:15], a[4:7], a[12:15], v[0:15]
	s_nop 0
	s_nop 0
	s_nop 0
	s_waitcnt lgkmcnt(0)
	v_mfma_f32_32x32x16_bf16 v[48:63], a[16:19], a[24:27], v[48:63]
	v_mfma_f32_32x32x16_bf16 v[32:47], a[20:23], a[24:27], v[32:47]
	s_nop 0
	s_waitcnt vmcnt(6)
	s_waitcnt lgkmcnt(0)
	s_barrier
	ds_read_b128 a[12:15], v82 offset:53248
	ds_read_b128 a[8:11], v82 offset:49152
	v_mfma_f32_32x32x16_bf16 v[16:31], a[16:19], a[28:31], v[16:31]
	v_lshl_add_u64 v[158:159], v[66:67], 0, s[30:31]
	s_nop 0
	v_lshl_add_u64 v[160:161], v[68:69], 0, s[30:31]
	s_nop 0
	s_nop 0
	s_nop 0
	v_lshl_add_u64 v[162:163], v[70:71], 0, s[30:31]
	s_nop 0
	v_mfma_f32_32x32x16_bf16 v[0:15], a[20:23], a[28:31], v[0:15]
	s_and_b32 m0, s32, 7
	s_lshl_b32 m0, m0, 12
	s_add_i32 m0, m0, 0x0
	s_nop 0
	global_load_lds_dwordx4 v[158:159], off
	s_nop 0
	v_lshl_add_u64 v[164:165], v[72:73], 0, s[30:31]
	s_nop 0
	s_nop 0
	s_nop 0
	v_lshl_add_u64 v[166:167], v[74:75], 0, s[30:31]
	s_nop 0
	s_nop 0
	s_nop 0
	v_lshl_add_u64 v[168:169], v[76:77], 0, s[30:31]
	s_nop 0
	s_add_i32 s30, 0, 0xc000
	v_add_u32_e32 v90, s30, v132
	v_add_u32_e32 v92, v90, v143
	v_add_u32_e32 v90, v90, v144
	ds_read_b128 a[4:7], v90
	ds_read_b128 a[0:3], v92
	s_nop 0
	s_nop 0
	s_nop 0
	s_nop 0
	s_nop 0
	s_nop 0
	s_nop 0
	s_nop 0
	v_add_u32_e32 v91, s30, v138
	v_add_u32_e32 v93, v91, v143
	ds_read_b128 a[16:19], v93
	v_add_u32_e32 v91, v91, v144
	ds_read_b128 a[20:23], v91
	ds_read_b128 a[24:27], v84 offset:49152
	ds_read_b128 a[28:31], v84 offset:53248
	s_waitcnt lgkmcnt(4)
	v_mfma_f32_32x32x16_bf16 v[48:63], a[0:3], a[8:11], v[48:63]
	s_nop 0
	s_nop 0
	s_nop 0
	s_nop 0
	v_mfma_f32_32x32x16_bf16 v[32:47], a[4:7], a[8:11], v[32:47]
	v_mfma_f32_32x32x16_bf16 v[16:31], a[0:3], a[12:15], v[16:31]
	s_and_b32 m0, s32, 7
	s_lshl_b32 m0, m0, 12
	s_add_i32 m0, m0, 0x400
	s_nop 0
	global_load_lds_dwordx4 v[160:161], off
	v_mfma_f32_32x32x16_bf16 v[0:15], a[4:7], a[12:15], v[0:15]
	s_nop 0
	s_nop 0
	s_nop 0
	s_nop 0
	v_add_u32_e32 v94, s30, v139
	v_add_u32_e32 v95, v94, v143
	ds_read_b128 a[0:3], v95
	v_add_u32_e32 v94, v94, v144
	ds_read_b128 a[4:7], v94
	ds_read_b128 a[8:11], v86 offset:49152
	ds_read_b128 a[12:15], v86 offset:53248
	s_waitcnt lgkmcnt(5)
	v_mfma_f32_32x32x16_bf16 v[48:63], a[16:19], a[24:27], v[48:63]
	s_and_b32 m0, s32, 7
	s_lshl_b32 m0, m0, 12
	s_add_i32 m0, m0, 0x800
	s_nop 0
	global_load_lds_dwordx4 v[162:163], off
	v_mfma_f32_32x32x16_bf16 v[32:47], a[20:23], a[24:27], v[32:47]
	s_waitcnt lgkmcnt(4)
	v_mfma_f32_32x32x16_bf16 v[16:31], a[16:19], a[28:31], v[16:31]
	s_nop 0
	s_nop 0
	s_nop 0
	v_mfma_f32_32x32x16_bf16 v[0:15], a[20:23], a[28:31], v[0:15]
	s_and_b32 m0, s32, 7
	s_lshl_b32 m0, m0, 12
	s_add_i32 m0, m0, 0xc00
	s_nop 0
	global_load_lds_dwordx4 v[164:165], off
	s_nop 0
	s_nop 0
	s_nop 0
	s_nop 0
	v_add_u32_e32 v96, s30, v142
	v_add_u32_e32 v97, v96, v143
	ds_read_b128 a[16:19], v97
	v_add_u32_e32 v96, v96, v144
	ds_read_b128 a[20:23], v96
	ds_read_b128 a[24:27], v88 offset:49152
	ds_read_b128 a[28:31], v88 offset:53248
	s_waitcnt lgkmcnt(5)
	v_mfma_f32_32x32x16_bf16 v[48:63], a[0:3], a[8:11], v[48:63]
	v_mfma_f32_32x32x16_bf16 v[32:47], a[4:7], a[8:11], v[32:47]
	s_waitcnt lgkmcnt(4)
	v_mfma_f32_32x32x16_bf16 v[16:31], a[0:3], a[12:15], v[16:31]
	s_and_b32 m0, s32, 7
	s_lshl_b32 m0, m0, 11
	s_add_i32 m0, m0, 0x8000
	s_nop 0
	global_load_lds_dwordx4 v[166:167], off
	s_nop 0
	s_nop 0
	s_nop 0
	s_mov_b64 s[30:31], 0x200
	v_mfma_f32_32x32x16_bf16 v[0:15], a[4:7], a[12:15], v[0:15]
	s_nop 0
	s_nop 0
	s_nop 0
	s_nop 0
	s_waitcnt lgkmcnt(1)
	v_mfma_f32_32x32x16_bf16 v[48:63], a[16:19], a[24:27], v[48:63]
	s_and_b32 m0, s32, 7
	s_lshl_b32 m0, m0, 11
	s_add_i32 m0, m0, 0x8400
	s_nop 0
	global_load_lds_dwordx4 v[168:169], off
	v_mfma_f32_32x32x16_bf16 v[32:47], a[20:23], a[24:27], v[32:47]
	s_waitcnt vmcnt(6)
	s_waitcnt lgkmcnt(0)
	s_barrier
	v_add_u32_e32 v100, v145, v132
	ds_read_b128 a[8:11], v100
	v_add_u32_e32 v101, s3, v132
	v_add_u32_e32 v99, v101, v144
	ds_read_b128 a[4:7], v99
	s_nop 0
	v_add_u32_e32 v98, v101, v143
	v_or_b32_e32 v132, 0x1000, v134
	v_add_u32_e32 v101, v101, v132
	ds_read_b128 a[12:15], v101
	ds_read_b128 a[0:3], v98
	v_mfma_f32_32x32x16_bf16 v[16:31], a[16:19], a[28:31], v[16:31]
	v_lshl_add_u64 v[170:171], v[66:67], 0, s[30:31]
	s_nop 0
	v_lshl_add_u64 v[172:173], v[68:69], 0, s[30:31]
	s_nop 0
	s_nop 0
	s_nop 0
	v_lshl_add_u64 v[174:175], v[70:71], 0, s[30:31]
	s_nop 0
	v_mfma_f32_32x32x16_bf16 v[0:15], a[20:23], a[28:31], v[0:15]
	s_and_b32 m0, s32, 7
	s_lshl_b32 m0, m0, 12
	s_add_i32 m0, m0, 0xc000
	s_nop 0
	global_load_lds_dwordx4 v[170:171], off
	s_nop 0
	v_lshl_add_u64 v[176:177], v[72:73], 0, s[30:31]
	s_nop 0
	s_nop 0
	s_nop 0
	v_lshl_add_u64 v[178:179], v[74:75], 0, s[30:31]
	s_nop 0
	s_nop 0
	s_nop 0
	v_lshl_add_u64 v[180:181], v[76:77], 0, s[30:31]
	s_nop 0
	s_mov_b64 s[30:31], 0x280
	s_nop 0
	s_nop 0
	s_nop 0
	s_nop 0
	s_nop 0
	s_nop 0
	s_nop 0
	s_nop 0
	v_add_u32_e32 v105, s3, v138
	v_add_u32_e32 v102, v105, v143
	ds_read_b128 a[16:19], v102
	v_add_u32_e32 v103, v105, v144
	ds_read_b128 a[20:23], v103
	v_add_u32_e32 v104, v145, v138
	ds_read_b128 a[24:27], v104
	v_add_u32_e32 v105, v105, v132
	ds_read_b128 a[28:31], v105
	s_waitcnt lgkmcnt(4)
	v_mfma_f32_32x32x16_bf16 v[48:63], a[0:3], a[8:11], v[48:63]
	s_nop 0
	v_mfma_f32_32x32x16_bf16 v[32:47], a[4:7], a[8:11], v[32:47]
	s_nop 0
	s_nop 0
	s_nop 0
	s_nop 0
	s_nop 0
	v_mfma_f32_32x32x16_bf16 v[16:31], a[0:3], a[12:15], v[16:31]
	s_and_b32 m0, s32, 7
	s_lshl_b32 m0, m0, 12
	s_add_i32 m0, m0, 0xc400
	s_nop 0
	global_load_lds_dwordx4 v[172:173], off
	s_nop 0
	v_mfma_f32_32x32x16_bf16 v[0:15], a[4:7], a[12:15], v[0:15]
	s_nop 0
	s_nop 0
	s_nop 0
	v_add_u32_e32 v109, s3, v139
	v_add_u32_e32 v106, v109, v143
	ds_read_b128 a[0:3], v106
	v_add_u32_e32 v107, v109, v144
	ds_read_b128 a[4:7], v107
	v_add_u32_e32 v108, v145, v139
	ds_read_b128 a[8:11], v108
	v_add_u32_e32 v109, v109, v132
	ds_read_b128 a[12:15], v109
	s_waitcnt lgkmcnt(5)
	v_mfma_f32_32x32x16_bf16 v[48:63], a[16:19], a[24:27], v[48:63]
	s_and_b32 m0, s32, 7
	s_lshl_b32 m0, m0, 12
	s_add_i32 m0, m0, 0xc800
	s_nop 0
	global_load_lds_dwordx4 v[174:175], off
	v_mfma_f32_32x32x16_bf16 v[32:47], a[20:23], a[24:27], v[32:47]
	s_waitcnt lgkmcnt(4)
	v_mfma_f32_32x32x16_bf16 v[16:31], a[16:19], a[28:31], v[16:31]
	s_nop 0
	s_nop 0
	s_nop 0
	s_nop 0
	s_nop 0
	s_nop 0
	v_mfma_f32_32x32x16_bf16 v[0:15], a[20:23], a[28:31], v[0:15]
	s_and_b32 m0, s32, 7
	s_lshl_b32 m0, m0, 12
	s_add_i32 m0, m0, 0xcc00
	s_nop 0
	global_load_lds_dwordx4 v[176:177], off
	s_nop 0
	s_nop 0
	s_nop 0
	v_add_u32_e32 v113, s3, v142
	v_add_u32_e32 v110, v113, v143
	ds_read_b128 a[16:19], v110
	v_add_u32_e32 v111, v113, v144
	ds_read_b128 a[20:23], v111
	v_add_u32_e32 v112, v145, v142
	ds_read_b128 a[24:27], v112
	v_add_u32_e32 v113, v113, v132
	ds_read_b128 a[28:31], v113
	s_waitcnt lgkmcnt(5)
	v_mfma_f32_32x32x16_bf16 v[48:63], a[0:3], a[8:11], v[48:63]
	v_mfma_f32_32x32x16_bf16 v[32:47], a[4:7], a[8:11], v[32:47]
	s_waitcnt lgkmcnt(4)
	v_mfma_f32_32x32x16_bf16 v[16:31], a[0:3], a[12:15], v[16:31]
	s_and_b32 m0, s32, 7
	s_lshl_b32 m0, m0, 11
	s_add_i32 m0, m0, 0x14000
	s_nop 0
	global_load_lds_dwordx4 v[178:179], off
	s_nop 0
	s_nop 0
	s_nop 0
	s_nop 0
	s_nop 0
	s_nop 0
	v_mfma_f32_32x32x16_bf16 v[0:15], a[4:7], a[12:15], v[0:15]
	s_nop 0
	s_nop 0
	s_nop 0
	s_waitcnt lgkmcnt(1)
	v_mfma_f32_32x32x16_bf16 v[48:63], a[16:19], a[24:27], v[48:63]
	s_and_b32 m0, s32, 7
	s_lshl_b32 m0, m0, 11
	s_add_i32 m0, m0, 0x14400
	s_nop 0
	global_load_lds_dwordx4 v[180:181], off
	v_mfma_f32_32x32x16_bf16 v[32:47], a[20:23], a[24:27], v[32:47]
	s_waitcnt vmcnt(6)
	s_waitcnt lgkmcnt(0)
	s_barrier
	ds_read_b128 a[12:15], v82 offset:4096
	ds_read_b128 a[8:11], v82
	ds_read_b128 a[4:7], v83 offset:36864
	ds_read_b128 a[0:3], v83 offset:32768
	v_mfma_f32_32x32x16_bf16 v[16:31], a[16:19], a[28:31], v[16:31]
	v_lshl_add_u64 v[158:159], v[66:67], 0, s[30:31]
	s_nop 0
	v_lshl_add_u64 v[160:161], v[68:69], 0, s[30:31]
	s_nop 0
	s_nop 0
	s_nop 0
	v_lshl_add_u64 v[162:163], v[70:71], 0, s[30:31]
	s_nop 0
	v_mfma_f32_32x32x16_bf16 v[0:15], a[20:23], a[28:31], v[0:15]
	s_and_b32 m0, s32, 7
	s_lshl_b32 m0, m0, 12
	s_add_i32 m0, m0, 0x18000
	s_nop 0
	global_load_lds_dwordx4 v[158:159], off
	s_nop 0
	v_lshl_add_u64 v[164:165], v[72:73], 0, s[30:31]
	s_nop 0
	s_nop 0
	s_nop 0
	v_lshl_add_u64 v[166:167], v[74:75], 0, s[30:31]
	s_nop 0
	s_nop 0
	s_nop 0
	v_lshl_add_u64 v[168:169], v[76:77], 0, s[30:31]
	s_nop 0
	s_mov_b64 s[30:31], 0x300
	s_nop 0
	s_nop 0
	s_nop 0
	s_nop 0
	s_nop 0
	ds_read_b128 a[16:19], v85 offset:32768
	ds_read_b128 a[20:23], v85 offset:36864
	ds_read_b128 a[24:27], v84
	ds_read_b128 a[28:31], v84 offset:4096
	s_waitcnt lgkmcnt(4)
	v_mfma_f32_32x32x16_bf16 v[48:63], a[0:3], a[8:11], v[48:63]
	s_nop 0
	v_readfirstlane_b32 s41, v114
	v_mfma_f32_32x32x16_bf16 v[32:47], a[4:7], a[8:11], v[32:47]
	v_mfma_f32_32x32x16_bf16 v[16:31], a[0:3], a[12:15], v[16:31]
	s_and_b32 m0, s32, 7
	s_lshl_b32 m0, m0, 12
	s_add_i32 m0, m0, 0x18400
	s_nop 0
	global_load_lds_dwordx4 v[160:161], off
	v_mfma_f32_32x32x16_bf16 v[0:15], a[4:7], a[12:15], v[0:15]
	s_nop 0
	s_nop 0
	s_nop 0
	s_nop 0
	ds_read_b128 a[0:3], v87 offset:32768
	ds_read_b128 a[4:7], v87 offset:36864
	ds_read_b128 a[8:11], v86
	ds_read_b128 a[12:15], v86 offset:4096
	s_waitcnt lgkmcnt(5)
	v_mfma_f32_32x32x16_bf16 v[48:63], a[16:19], a[24:27], v[48:63]
	s_and_b32 m0, s32, 7
	s_lshl_b32 m0, m0, 12
	s_add_i32 m0, m0, 0x18800
	s_nop 0
	global_load_lds_dwordx4 v[162:163], off
	v_mfma_f32_32x32x16_bf16 v[32:47], a[20:23], a[24:27], v[32:47]
	s_waitcnt lgkmcnt(4)
	v_mfma_f32_32x32x16_bf16 v[16:31], a[16:19], a[28:31], v[16:31]
	v_mfma_f32_32x32x16_bf16 v[0:15], a[20:23], a[28:31], v[0:15]
	s_and_b32 m0, s32, 7
	s_lshl_b32 m0, m0, 12
	s_add_i32 m0, m0, 0x18c00
	s_nop 0
	global_load_lds_dwordx4 v[164:165], off
	s_nop 0
	s_nop 0
	s_nop 0
	s_nop 0
	ds_read_b128 a[16:19], v89 offset:32768
	ds_read_b128 a[20:23], v89 offset:36864
	ds_read_b128 a[24:27], v88
	ds_read_b128 a[28:31], v88 offset:4096
	s_waitcnt lgkmcnt(5)
	v_mfma_f32_32x32x16_bf16 v[48:63], a[0:3], a[8:11], v[48:63]
	v_mfma_f32_32x32x16_bf16 v[32:47], a[4:7], a[8:11], v[32:47]
	s_waitcnt lgkmcnt(4)
	v_mfma_f32_32x32x16_bf16 v[16:31], a[0:3], a[12:15], v[16:31]
	s_and_b32 m0, s32, 7
	s_lshl_b32 m0, m0, 11
	s_add_i32 m0, m0, 0x20000
	s_nop 0
	global_load_lds_dwordx4 v[166:167], off
	v_mfma_f32_32x32x16_bf16 v[0:15], a[4:7], a[12:15], v[0:15]
	s_nop 0
	s_nop 0
	s_nop 0
	s_nop 0
	s_waitcnt lgkmcnt(1)
	v_mfma_f32_32x32x16_bf16 v[48:63], a[16:19], a[24:27], v[48:63]
	s_and_b32 m0, s32, 7
	s_lshl_b32 m0, m0, 11
	s_add_i32 m0, m0, 0x20400
	s_nop 0
	global_load_lds_dwordx4 v[168:169], off
	v_mfma_f32_32x32x16_bf16 v[32:47], a[20:23], a[24:27], v[32:47]
	s_waitcnt vmcnt(6)
	s_waitcnt lgkmcnt(0)
	s_barrier
	ds_read_b128 a[12:15], v82 offset:53248
	ds_read_b128 a[8:11], v82 offset:49152
	ds_read_b128 a[4:7], v90
	ds_read_b128 a[0:3], v92
	v_mfma_f32_32x32x16_bf16 v[16:31], a[16:19], a[28:31], v[16:31]
	v_lshl_add_u64 v[170:171], v[66:67], 0, s[30:31]
	s_nop 0
	v_lshl_add_u64 v[172:173], v[68:69], 0, s[30:31]
	s_nop 0
	v_readfirstlane_b32 s42, v115
	s_nop 0
	v_lshl_add_u64 v[174:175], v[70:71], 0, s[30:31]
	s_nop 0
	v_mfma_f32_32x32x16_bf16 v[0:15], a[20:23], a[28:31], v[0:15]
	s_and_b32 m0, s32, 7
	s_lshl_b32 m0, m0, 12
	s_add_i32 m0, m0, 0x0
	s_nop 0
	global_load_lds_dwordx4 v[170:171], off
	s_nop 0
	v_lshl_add_u64 v[176:177], v[72:73], 0, s[30:31]
	s_nop 0
	v_readfirstlane_b32 s43, v116
	s_nop 0
	v_lshl_add_u64 v[178:179], v[74:75], 0, s[30:31]
	s_nop 0
	v_readfirstlane_b32 s44, v117
	s_nop 0
	v_lshl_add_u64 v[180:181], v[76:77], 0, s[30:31]
	s_nop 0
	s_mov_b64 s[30:31], 0x380
	s_nop 0
	s_nop 0
	s_nop 0
	s_nop 0
	s_nop 0
	ds_read_b128 a[16:19], v93
	ds_read_b128 a[20:23], v91
	ds_read_b128 a[24:27], v84 offset:49152
	ds_read_b128 a[28:31], v84 offset:53248
	s_waitcnt lgkmcnt(4)
	v_mfma_f32_32x32x16_bf16 v[48:63], a[0:3], a[8:11], v[48:63]
	s_nop 0
	v_readfirstlane_b32 s35, v120
	v_readfirstlane_b32 s45, v118
	v_readfirstlane_b32 s46, v119
	v_mfma_f32_32x32x16_bf16 v[32:47], a[4:7], a[8:11], v[32:47]
	v_mfma_f32_32x32x16_bf16 v[16:31], a[0:3], a[12:15], v[16:31]
	s_and_b32 m0, s32, 7
	s_lshl_b32 m0, m0, 12
	s_add_i32 m0, m0, 0x400
	s_nop 0
	global_load_lds_dwordx4 v[172:173], off
	v_mfma_f32_32x32x16_bf16 v[0:15], a[4:7], a[12:15], v[0:15]
	s_nop 0
	s_nop 0
	s_nop 0
	s_nop 0
	ds_read_b128 a[0:3], v95
	ds_read_b128 a[4:7], v94
	ds_read_b128 a[8:11], v86 offset:49152
	ds_read_b128 a[12:15], v86 offset:53248
	s_waitcnt lgkmcnt(5)
	v_mfma_f32_32x32x16_bf16 v[48:63], a[16:19], a[24:27], v[48:63]
	s_and_b32 m0, s32, 7
	s_lshl_b32 m0, m0, 12
	s_add_i32 m0, m0, 0x800
	s_nop 0
	global_load_lds_dwordx4 v[174:175], off
	v_mfma_f32_32x32x16_bf16 v[32:47], a[20:23], a[24:27], v[32:47]
	s_waitcnt lgkmcnt(4)
	v_mfma_f32_32x32x16_bf16 v[16:31], a[16:19], a[28:31], v[16:31]
	v_mfma_f32_32x32x16_bf16 v[0:15], a[20:23], a[28:31], v[0:15]
	s_and_b32 m0, s32, 7
	s_lshl_b32 m0, m0, 12
	s_add_i32 m0, m0, 0xc00
	s_nop 0
	global_load_lds_dwordx4 v[176:177], off
	s_nop 0
	s_nop 0
	s_nop 0
	s_nop 0
	ds_read_b128 a[16:19], v97
	ds_read_b128 a[20:23], v96
	ds_read_b128 a[24:27], v88 offset:49152
	ds_read_b128 a[28:31], v88 offset:53248
	s_waitcnt lgkmcnt(5)
	v_mfma_f32_32x32x16_bf16 v[48:63], a[0:3], a[8:11], v[48:63]
	v_mfma_f32_32x32x16_bf16 v[32:47], a[4:7], a[8:11], v[32:47]
	s_waitcnt lgkmcnt(4)
	v_mfma_f32_32x32x16_bf16 v[16:31], a[0:3], a[12:15], v[16:31]
	s_and_b32 m0, s32, 7
	s_lshl_b32 m0, m0, 11
	s_add_i32 m0, m0, 0x8000
	s_nop 0
	global_load_lds_dwordx4 v[178:179], off
	v_mfma_f32_32x32x16_bf16 v[0:15], a[4:7], a[12:15], v[0:15]
	s_nop 0
	s_nop 0
	s_nop 0
	s_nop 0
	s_waitcnt lgkmcnt(1)
	v_mfma_f32_32x32x16_bf16 v[48:63], a[16:19], a[24:27], v[48:63]
	s_and_b32 m0, s32, 7
	s_lshl_b32 m0, m0, 11
	s_add_i32 m0, m0, 0x8400
	s_nop 0
	global_load_lds_dwordx4 v[180:181], off
	v_mfma_f32_32x32x16_bf16 v[32:47], a[20:23], a[24:27], v[32:47]
	s_waitcnt vmcnt(6)
	s_waitcnt lgkmcnt(0)
	s_barrier
	ds_read_b128 a[12:15], v101
	ds_read_b128 a[8:11], v100
	ds_read_b128 a[4:7], v99
	ds_read_b128 a[0:3], v98
	v_mfma_f32_32x32x16_bf16 v[16:31], a[16:19], a[28:31], v[16:31]
	v_lshl_add_u64 v[158:159], v[66:67], 0, s[30:31]
	s_nop 0
	v_lshl_add_u64 v[160:161], v[68:69], 0, s[30:31]
	s_nop 0
	v_readfirstlane_b32 s36, v121
	s_nop 0
	v_lshl_add_u64 v[162:163], v[70:71], 0, s[30:31]
	s_nop 0
	v_mfma_f32_32x32x16_bf16 v[0:15], a[20:23], a[28:31], v[0:15]
	s_and_b32 m0, s32, 7
	s_lshl_b32 m0, m0, 12
	s_add_i32 m0, m0, 0xc000
	s_nop 0
	global_load_lds_dwordx4 v[158:159], off
	s_nop 0
	v_lshl_add_u64 v[164:165], v[72:73], 0, s[30:31]
	s_nop 0
	v_readfirstlane_b32 s37, v122
	s_nop 0
	v_lshl_add_u64 v[166:167], v[74:75], 0, s[30:31]
	s_nop 0
	v_readfirstlane_b32 s38, v123
	s_nop 0
	v_lshl_add_u64 v[168:169], v[76:77], 0, s[30:31]
	s_nop 0
	s_mov_b64 s[30:31], 0x400
	s_nop 0
	s_nop 0
	s_nop 0
	s_nop 0
	s_nop 0
	ds_read_b128 a[16:19], v102
	ds_read_b128 a[20:23], v103
	ds_read_b128 a[24:27], v104
	ds_read_b128 a[28:31], v105
	s_waitcnt lgkmcnt(4)
	v_mfma_f32_32x32x16_bf16 v[48:63], a[0:3], a[8:11], v[48:63]
	s_nop 0
	v_readfirstlane_b32 s0, v126
	v_readfirstlane_b32 s39, v124
	v_readfirstlane_b32 s40, v125
	v_mfma_f32_32x32x16_bf16 v[32:47], a[4:7], a[8:11], v[32:47]
	v_mfma_f32_32x32x16_bf16 v[16:31], a[0:3], a[12:15], v[16:31]
	s_and_b32 m0, s32, 7
	s_lshl_b32 m0, m0, 12
	s_add_i32 m0, m0, 0xc400
	s_nop 0
	global_load_lds_dwordx4 v[160:161], off
	v_mfma_f32_32x32x16_bf16 v[0:15], a[4:7], a[12:15], v[0:15]
	s_nop 0
	s_nop 0
	s_nop 0
	s_nop 0
	ds_read_b128 a[0:3], v106
	ds_read_b128 a[4:7], v107
	ds_read_b128 a[8:11], v108
	ds_read_b128 a[12:15], v109
	s_waitcnt lgkmcnt(5)
	v_mfma_f32_32x32x16_bf16 v[48:63], a[16:19], a[24:27], v[48:63]
	s_and_b32 m0, s32, 7
	s_lshl_b32 m0, m0, 12
	s_add_i32 m0, m0, 0xc800
	s_nop 0
	global_load_lds_dwordx4 v[162:163], off
	v_mfma_f32_32x32x16_bf16 v[32:47], a[20:23], a[24:27], v[32:47]
	s_waitcnt lgkmcnt(4)
	v_mfma_f32_32x32x16_bf16 v[16:31], a[16:19], a[28:31], v[16:31]
	v_mfma_f32_32x32x16_bf16 v[0:15], a[20:23], a[28:31], v[0:15]
	s_and_b32 m0, s32, 7
	s_lshl_b32 m0, m0, 12
	s_add_i32 m0, m0, 0xcc00
	s_nop 0
	global_load_lds_dwordx4 v[164:165], off
	s_nop 0
	s_nop 0
	s_nop 0
	s_nop 0
	ds_read_b128 a[16:19], v110
	ds_read_b128 a[20:23], v111
	ds_read_b128 a[24:27], v112
	ds_read_b128 a[28:31], v113
	s_waitcnt lgkmcnt(5)
	v_mfma_f32_32x32x16_bf16 v[48:63], a[0:3], a[8:11], v[48:63]
	v_mfma_f32_32x32x16_bf16 v[32:47], a[4:7], a[8:11], v[32:47]
	s_waitcnt lgkmcnt(4)
	v_mfma_f32_32x32x16_bf16 v[16:31], a[0:3], a[12:15], v[16:31]
	s_and_b32 m0, s32, 7
	s_lshl_b32 m0, m0, 11
	s_add_i32 m0, m0, 0x14000
	s_nop 0
	global_load_lds_dwordx4 v[166:167], off
	v_mfma_f32_32x32x16_bf16 v[0:15], a[4:7], a[12:15], v[0:15]
	s_nop 0
	s_nop 0
	s_nop 0
	s_nop 0
	s_waitcnt lgkmcnt(1)
	v_mfma_f32_32x32x16_bf16 v[48:63], a[16:19], a[24:27], v[48:63]
	s_and_b32 m0, s32, 7
	s_lshl_b32 m0, m0, 11
	s_add_i32 m0, m0, 0x14400
	s_nop 0
	global_load_lds_dwordx4 v[168:169], off
	v_mfma_f32_32x32x16_bf16 v[32:47], a[20:23], a[24:27], v[32:47]
	s_waitcnt vmcnt(6)
	s_waitcnt lgkmcnt(0)
	s_barrier
	ds_read_b128 a[12:15], v82 offset:4096
	ds_read_b128 a[8:11], v82
	ds_read_b128 a[4:7], v83 offset:36864
	ds_read_b128 a[0:3], v83 offset:32768
	v_mfma_f32_32x32x16_bf16 v[16:31], a[16:19], a[28:31], v[16:31]
	v_lshl_add_u64 v[170:171], v[66:67], 0, s[30:31]
	s_nop 0
	v_lshl_add_u64 v[172:173], v[68:69], 0, s[30:31]
	s_nop 0
	v_readfirstlane_b32 s1, v127
	s_nop 0
	v_lshl_add_u64 v[174:175], v[70:71], 0, s[30:31]
	s_nop 0
	v_mfma_f32_32x32x16_bf16 v[0:15], a[20:23], a[28:31], v[0:15]
	s_and_b32 m0, s32, 7
	s_lshl_b32 m0, m0, 12
	s_add_i32 m0, m0, 0x18000
	s_nop 0
	global_load_lds_dwordx4 v[170:171], off
	s_nop 0
	v_lshl_add_u64 v[176:177], v[72:73], 0, s[30:31]
	s_nop 0
	v_readfirstlane_b32 s24, v128
	s_nop 0
	v_lshl_add_u64 v[178:179], v[74:75], 0, s[30:31]
	s_nop 0
	v_readfirstlane_b32 s28, v129
	s_nop 0
	v_lshl_add_u64 v[180:181], v[76:77], 0, s[30:31]
	s_nop 0
	s_mov_b64 s[30:31], 0x480
	s_nop 0
	s_nop 0
	s_nop 0
	s_nop 0
	s_nop 0
	ds_read_b128 a[16:19], v85 offset:32768
	ds_read_b128 a[20:23], v85 offset:36864
	ds_read_b128 a[24:27], v84
	ds_read_b128 a[28:31], v84 offset:4096
	s_waitcnt lgkmcnt(4)
	v_mfma_f32_32x32x16_bf16 v[48:63], a[0:3], a[8:11], v[48:63]
	s_nop 0
	v_lshl_add_u64 v[162:163], v[70:71], 0, s[30:31]
	v_readfirstlane_b32 s29, v131
	v_readfirstlane_b32 s34, v130
	v_mfma_f32_32x32x16_bf16 v[32:47], a[4:7], a[8:11], v[32:47]
	v_mfma_f32_32x32x16_bf16 v[16:31], a[0:3], a[12:15], v[16:31]
	s_and_b32 m0, s32, 7
	s_lshl_b32 m0, m0, 12
	s_add_i32 m0, m0, 0x18400
	s_nop 0
	global_load_lds_dwordx4 v[172:173], off
	v_mfma_f32_32x32x16_bf16 v[0:15], a[4:7], a[12:15], v[0:15]
	s_nop 0
	s_nop 0
	s_nop 0
	s_nop 0
	ds_read_b128 a[0:3], v87 offset:32768
	ds_read_b128 a[4:7], v87 offset:36864
	ds_read_b128 a[8:11], v86
	ds_read_b128 a[12:15], v86 offset:4096
	s_waitcnt lgkmcnt(5)
	v_mfma_f32_32x32x16_bf16 v[48:63], a[16:19], a[24:27], v[48:63]
	s_and_b32 m0, s32, 7
	s_lshl_b32 m0, m0, 12
	s_add_i32 m0, m0, 0x18800
	s_nop 0
	global_load_lds_dwordx4 v[174:175], off
	v_mfma_f32_32x32x16_bf16 v[32:47], a[20:23], a[24:27], v[32:47]
	s_waitcnt lgkmcnt(4)
	v_mfma_f32_32x32x16_bf16 v[16:31], a[16:19], a[28:31], v[16:31]
	v_mfma_f32_32x32x16_bf16 v[0:15], a[20:23], a[28:31], v[0:15]
	s_and_b32 m0, s32, 7
	s_lshl_b32 m0, m0, 12
	s_add_i32 m0, m0, 0x18c00
	s_nop 0
	global_load_lds_dwordx4 v[176:177], off
	s_nop 0
	s_nop 0
	s_nop 0
	s_nop 0
	ds_read_b128 a[16:19], v89 offset:32768
	ds_read_b128 a[20:23], v89 offset:36864
	ds_read_b128 a[24:27], v88
	ds_read_b128 a[28:31], v88 offset:4096
	s_waitcnt lgkmcnt(5)
	v_mfma_f32_32x32x16_bf16 v[48:63], a[0:3], a[8:11], v[48:63]
	v_mfma_f32_32x32x16_bf16 v[32:47], a[4:7], a[8:11], v[32:47]
	s_waitcnt lgkmcnt(4)
	v_mfma_f32_32x32x16_bf16 v[16:31], a[0:3], a[12:15], v[16:31]
	s_and_b32 m0, s32, 7
	s_lshl_b32 m0, m0, 11
	s_add_i32 m0, m0, 0x20000
	s_nop 0
	global_load_lds_dwordx4 v[178:179], off
	v_mfma_f32_32x32x16_bf16 v[0:15], a[4:7], a[12:15], v[0:15]
	s_nop 0
	s_nop 0
	s_nop 0
	s_nop 0
	s_waitcnt lgkmcnt(1)
	v_mfma_f32_32x32x16_bf16 v[48:63], a[16:19], a[24:27], v[48:63]
	s_and_b32 m0, s32, 7
	s_lshl_b32 m0, m0, 11
	s_add_i32 m0, m0, 0x20400
	s_nop 0
	global_load_lds_dwordx4 v[180:181], off
	v_mfma_f32_32x32x16_bf16 v[32:47], a[20:23], a[24:27], v[32:47]
	s_waitcnt vmcnt(6)
	s_waitcnt lgkmcnt(0)
	s_barrier
	ds_read_b128 a[12:15], v82 offset:53248
	ds_read_b128 a[8:11], v82 offset:49152
	ds_read_b128 a[4:7], v90
	ds_read_b128 a[0:3], v92
	v_mfma_f32_32x32x16_bf16 v[16:31], a[16:19], a[28:31], v[16:31]
	v_lshl_add_u64 v[158:159], v[66:67], 0, s[30:31]
	s_nop 0
	v_lshl_add_u64 v[160:161], v[68:69], 0, s[30:31]
	s_nop 0
	s_nop 0
	s_nop 0
	s_nop 0
	v_mfma_f32_32x32x16_bf16 v[0:15], a[20:23], a[28:31], v[0:15]
	s_and_b32 m0, s32, 7
	s_lshl_b32 m0, m0, 12
	s_add_i32 m0, m0, 0x0
	s_nop 0
	global_load_lds_dwordx4 v[158:159], off
	s_nop 0
	v_lshl_add_u64 v[164:165], v[72:73], 0, s[30:31]
	s_nop 0
	s_nop 0
	s_nop 0
	v_lshl_add_u64 v[166:167], v[74:75], 0, s[30:31]
	s_nop 0
	s_nop 0
	s_nop 0
	v_lshl_add_u64 v[168:169], v[76:77], 0, s[30:31]
	s_nop 0
	s_mov_b64 s[30:31], 0x500
	s_nop 0
	s_nop 0
	s_nop 0
	s_nop 0
	s_nop 0
	ds_read_b128 a[16:19], v93
	ds_read_b128 a[20:23], v91
	ds_read_b128 a[24:27], v84 offset:49152
	ds_read_b128 a[28:31], v84 offset:53248
	s_waitcnt lgkmcnt(4)
	v_mfma_f32_32x32x16_bf16 v[48:63], a[0:3], a[8:11], v[48:63]
	s_nop 0
	v_lshl_add_u64 v[174:175], v[70:71], 0, s[30:31]
	v_mfma_f32_32x32x16_bf16 v[32:47], a[4:7], a[8:11], v[32:47]
	v_mfma_f32_32x32x16_bf16 v[16:31], a[0:3], a[12:15], v[16:31]
	s_and_b32 m0, s32, 7
	s_lshl_b32 m0, m0, 12
	s_add_i32 m0, m0, 0x400
	s_nop 0
	global_load_lds_dwordx4 v[160:161], off
	v_mfma_f32_32x32x16_bf16 v[0:15], a[4:7], a[12:15], v[0:15]
	s_nop 0
	s_nop 0
	s_nop 0
	s_nop 0
	ds_read_b128 a[0:3], v95
	ds_read_b128 a[4:7], v94
	ds_read_b128 a[8:11], v86 offset:49152
	ds_read_b128 a[12:15], v86 offset:53248
	s_waitcnt lgkmcnt(5)
	v_mfma_f32_32x32x16_bf16 v[48:63], a[16:19], a[24:27], v[48:63]
	s_and_b32 m0, s32, 7
	s_lshl_b32 m0, m0, 12
	s_add_i32 m0, m0, 0x800
	s_nop 0
	global_load_lds_dwordx4 v[162:163], off
	v_mfma_f32_32x32x16_bf16 v[32:47], a[20:23], a[24:27], v[32:47]
	s_waitcnt lgkmcnt(4)
	v_mfma_f32_32x32x16_bf16 v[16:31], a[16:19], a[28:31], v[16:31]
	v_mfma_f32_32x32x16_bf16 v[0:15], a[20:23], a[28:31], v[0:15]
	s_and_b32 m0, s32, 7
	s_lshl_b32 m0, m0, 12
	s_add_i32 m0, m0, 0xc00
	s_nop 0
	global_load_lds_dwordx4 v[164:165], off
	s_nop 0
	s_nop 0
	s_nop 0
	s_nop 0
	ds_read_b128 a[16:19], v97
	ds_read_b128 a[20:23], v96
	ds_read_b128 a[24:27], v88 offset:49152
	ds_read_b128 a[28:31], v88 offset:53248
	s_waitcnt lgkmcnt(5)
	v_mfma_f32_32x32x16_bf16 v[48:63], a[0:3], a[8:11], v[48:63]
	v_mfma_f32_32x32x16_bf16 v[32:47], a[4:7], a[8:11], v[32:47]
	s_waitcnt lgkmcnt(4)
	v_mfma_f32_32x32x16_bf16 v[16:31], a[0:3], a[12:15], v[16:31]
	s_and_b32 m0, s32, 7
	s_lshl_b32 m0, m0, 11
	s_add_i32 m0, m0, 0x8000
	s_nop 0
	global_load_lds_dwordx4 v[166:167], off
	v_mfma_f32_32x32x16_bf16 v[0:15], a[4:7], a[12:15], v[0:15]
	s_nop 0
	s_nop 0
	s_nop 0
	s_nop 0
	s_waitcnt lgkmcnt(1)
	v_mfma_f32_32x32x16_bf16 v[48:63], a[16:19], a[24:27], v[48:63]
	s_and_b32 m0, s32, 7
	s_lshl_b32 m0, m0, 11
	s_add_i32 m0, m0, 0x8400
	s_nop 0
	global_load_lds_dwordx4 v[168:169], off
	v_mfma_f32_32x32x16_bf16 v[32:47], a[20:23], a[24:27], v[32:47]
	s_waitcnt vmcnt(6)
	s_waitcnt lgkmcnt(0)
	s_barrier
	ds_read_b128 a[12:15], v101
	ds_read_b128 a[8:11], v100
	ds_read_b128 a[4:7], v99
	ds_read_b128 a[0:3], v98
	v_mfma_f32_32x32x16_bf16 v[16:31], a[16:19], a[28:31], v[16:31]
	v_lshl_add_u64 v[170:171], v[66:67], 0, s[30:31]
	s_nop 0
	v_lshl_add_u64 v[172:173], v[68:69], 0, s[30:31]
	s_nop 0
	s_nop 0
	s_nop 0
	s_nop 0
	v_mfma_f32_32x32x16_bf16 v[0:15], a[20:23], a[28:31], v[0:15]
	s_and_b32 m0, s32, 7
	s_lshl_b32 m0, m0, 12
	s_add_i32 m0, m0, 0xc000
	s_nop 0
	global_load_lds_dwordx4 v[170:171], off
	s_nop 0
	v_lshl_add_u64 v[176:177], v[72:73], 0, s[30:31]
	s_nop 0
	s_nop 0
	s_nop 0
	v_lshl_add_u64 v[178:179], v[74:75], 0, s[30:31]
	s_nop 0
	s_nop 0
	s_nop 0
	v_lshl_add_u64 v[180:181], v[76:77], 0, s[30:31]
	s_nop 0
	s_mov_b64 s[30:31], 0x580
	s_nop 0
	s_nop 0
	s_nop 0
	s_nop 0
	s_nop 0
	ds_read_b128 a[16:19], v102
	ds_read_b128 a[20:23], v103
	ds_read_b128 a[24:27], v104
	ds_read_b128 a[28:31], v105
	s_waitcnt lgkmcnt(4)
	v_mfma_f32_32x32x16_bf16 v[48:63], a[0:3], a[8:11], v[48:63]
	s_nop 0
	v_lshl_add_u64 v[162:163], v[70:71], 0, s[30:31]
	v_mfma_f32_32x32x16_bf16 v[32:47], a[4:7], a[8:11], v[32:47]
	v_mfma_f32_32x32x16_bf16 v[16:31], a[0:3], a[12:15], v[16:31]
	s_and_b32 m0, s32, 7
	s_lshl_b32 m0, m0, 12
	s_add_i32 m0, m0, 0xc400
	s_nop 0
	global_load_lds_dwordx4 v[172:173], off
	v_mfma_f32_32x32x16_bf16 v[0:15], a[4:7], a[12:15], v[0:15]
	s_nop 0
	s_nop 0
	s_nop 0
	s_nop 0
	ds_read_b128 a[0:3], v106
	ds_read_b128 a[4:7], v107
	ds_read_b128 a[8:11], v108
	ds_read_b128 a[12:15], v109
	s_waitcnt lgkmcnt(5)
	v_mfma_f32_32x32x16_bf16 v[48:63], a[16:19], a[24:27], v[48:63]
	s_and_b32 m0, s32, 7
	s_lshl_b32 m0, m0, 12
	s_add_i32 m0, m0, 0xc800
	s_nop 0
	global_load_lds_dwordx4 v[174:175], off
	v_mfma_f32_32x32x16_bf16 v[32:47], a[20:23], a[24:27], v[32:47]
	s_waitcnt lgkmcnt(4)
	v_mfma_f32_32x32x16_bf16 v[16:31], a[16:19], a[28:31], v[16:31]
	v_mfma_f32_32x32x16_bf16 v[0:15], a[20:23], a[28:31], v[0:15]
	s_and_b32 m0, s32, 7
	s_lshl_b32 m0, m0, 12
	s_add_i32 m0, m0, 0xcc00
	s_nop 0
	global_load_lds_dwordx4 v[176:177], off
	s_nop 0
	s_nop 0
	s_nop 0
	s_nop 0
	ds_read_b128 a[16:19], v110
	ds_read_b128 a[20:23], v111
	ds_read_b128 a[24:27], v112
	ds_read_b128 a[28:31], v113
	s_waitcnt lgkmcnt(5)
	v_mfma_f32_32x32x16_bf16 v[48:63], a[0:3], a[8:11], v[48:63]
	v_mfma_f32_32x32x16_bf16 v[32:47], a[4:7], a[8:11], v[32:47]
	s_waitcnt lgkmcnt(4)
	v_mfma_f32_32x32x16_bf16 v[16:31], a[0:3], a[12:15], v[16:31]
	s_and_b32 m0, s32, 7
	s_lshl_b32 m0, m0, 11
	s_add_i32 m0, m0, 0x14000
	s_nop 0
	global_load_lds_dwordx4 v[178:179], off
	v_mfma_f32_32x32x16_bf16 v[0:15], a[4:7], a[12:15], v[0:15]
	s_nop 0
	s_nop 0
	s_nop 0
	s_nop 0
	s_waitcnt lgkmcnt(1)
	v_mfma_f32_32x32x16_bf16 v[48:63], a[16:19], a[24:27], v[48:63]
	s_and_b32 m0, s32, 7
	s_lshl_b32 m0, m0, 11
	s_add_i32 m0, m0, 0x14400
	s_nop 0
	global_load_lds_dwordx4 v[180:181], off
	v_mfma_f32_32x32x16_bf16 v[32:47], a[20:23], a[24:27], v[32:47]
	s_waitcnt vmcnt(6)
	s_waitcnt lgkmcnt(0)
	s_barrier
	ds_read_b128 a[12:15], v82 offset:4096
	ds_read_b128 a[8:11], v82
	ds_read_b128 a[4:7], v83 offset:36864
	ds_read_b128 a[0:3], v83 offset:32768
	v_mfma_f32_32x32x16_bf16 v[16:31], a[16:19], a[28:31], v[16:31]
	v_lshl_add_u64 v[158:159], v[66:67], 0, s[30:31]
	s_nop 0
	v_lshl_add_u64 v[160:161], v[68:69], 0, s[30:31]
	s_nop 0
	s_nop 0
	s_nop 0
	s_nop 0
	v_mfma_f32_32x32x16_bf16 v[0:15], a[20:23], a[28:31], v[0:15]
	s_and_b32 m0, s32, 7
	s_lshl_b32 m0, m0, 12
	s_add_i32 m0, m0, 0x18000
	s_nop 0
	global_load_lds_dwordx4 v[158:159], off
	s_nop 0
	v_lshl_add_u64 v[164:165], v[72:73], 0, s[30:31]
	s_nop 0
	s_nop 0
	s_nop 0
	v_lshl_add_u64 v[166:167], v[74:75], 0, s[30:31]
	s_nop 0
	s_nop 0
	s_nop 0
	v_lshl_add_u64 v[168:169], v[76:77], 0, s[30:31]
	s_nop 0
	s_mov_b64 s[30:31], 0x600
	s_nop 0
	s_nop 0
	s_nop 0
	s_nop 0
	s_nop 0
	ds_read_b128 a[16:19], v85 offset:32768
	ds_read_b128 a[20:23], v85 offset:36864
	ds_read_b128 a[24:27], v84
	ds_read_b128 a[28:31], v84 offset:4096
	s_waitcnt lgkmcnt(4)
	v_mfma_f32_32x32x16_bf16 v[48:63], a[0:3], a[8:11], v[48:63]
	s_nop 0
	v_mfma_f32_32x32x16_bf16 v[32:47], a[4:7], a[8:11], v[32:47]
	v_mfma_f32_32x32x16_bf16 v[16:31], a[0:3], a[12:15], v[16:31]
	s_and_b32 m0, s32, 7
	s_lshl_b32 m0, m0, 12
	s_add_i32 m0, m0, 0x18400
	s_nop 0
	global_load_lds_dwordx4 v[160:161], off
	v_mfma_f32_32x32x16_bf16 v[0:15], a[4:7], a[12:15], v[0:15]
	s_nop 0
	s_nop 0
	s_nop 0
	s_nop 0
	ds_read_b128 a[0:3], v87 offset:32768
	ds_read_b128 a[4:7], v87 offset:36864
	ds_read_b128 a[8:11], v86
	ds_read_b128 a[12:15], v86 offset:4096
	s_waitcnt lgkmcnt(5)
	v_mfma_f32_32x32x16_bf16 v[48:63], a[16:19], a[24:27], v[48:63]
	s_and_b32 m0, s32, 7
	s_lshl_b32 m0, m0, 12
	s_add_i32 m0, m0, 0x18800
	s_nop 0
	global_load_lds_dwordx4 v[162:163], off
	v_mfma_f32_32x32x16_bf16 v[32:47], a[20:23], a[24:27], v[32:47]
	s_waitcnt lgkmcnt(4)
	v_mfma_f32_32x32x16_bf16 v[16:31], a[16:19], a[28:31], v[16:31]
	v_mfma_f32_32x32x16_bf16 v[0:15], a[20:23], a[28:31], v[0:15]
	s_and_b32 m0, s32, 7
	s_lshl_b32 m0, m0, 12
	s_add_i32 m0, m0, 0x18c00
	s_nop 0
	global_load_lds_dwordx4 v[164:165], off
	s_nop 0
	s_nop 0
	s_nop 0
	s_nop 0
	ds_read_b128 a[16:19], v89 offset:32768
	ds_read_b128 a[20:23], v89 offset:36864
	ds_read_b128 a[24:27], v88
	ds_read_b128 a[28:31], v88 offset:4096
	s_waitcnt lgkmcnt(5)
	v_mfma_f32_32x32x16_bf16 v[48:63], a[0:3], a[8:11], v[48:63]
	v_mfma_f32_32x32x16_bf16 v[32:47], a[4:7], a[8:11], v[32:47]
	s_waitcnt lgkmcnt(4)
	v_mfma_f32_32x32x16_bf16 v[16:31], a[0:3], a[12:15], v[16:31]
	s_and_b32 m0, s32, 7
	s_lshl_b32 m0, m0, 11
	s_add_i32 m0, m0, 0x20000
	s_nop 0
	global_load_lds_dwordx4 v[166:167], off
	v_mfma_f32_32x32x16_bf16 v[0:15], a[4:7], a[12:15], v[0:15]
	s_nop 0
	s_nop 0
	s_nop 0
	s_nop 0
	s_waitcnt lgkmcnt(1)
	v_mfma_f32_32x32x16_bf16 v[48:63], a[16:19], a[24:27], v[48:63]
	s_and_b32 m0, s32, 7
	s_lshl_b32 m0, m0, 11
	s_add_i32 m0, m0, 0x20400
	s_nop 0
	global_load_lds_dwordx4 v[168:169], off
	v_mfma_f32_32x32x16_bf16 v[32:47], a[20:23], a[24:27], v[32:47]
	s_waitcnt vmcnt(6)
	s_waitcnt lgkmcnt(0)
	s_barrier
	ds_read_b128 a[12:15], v82 offset:53248
	ds_read_b128 a[8:11], v82 offset:49152
	ds_read_b128 a[4:7], v90
	ds_read_b128 a[0:3], v92
	v_mfma_f32_32x32x16_bf16 v[16:31], a[16:19], a[28:31], v[16:31]
	v_lshl_add_u64 v[170:171], v[66:67], 0, s[30:31]
	s_nop 0
	v_lshl_add_u64 v[172:173], v[68:69], 0, s[30:31]
	s_nop 0
	s_nop 0
	s_nop 0
	v_lshl_add_u64 v[174:175], v[70:71], 0, s[30:31]
	s_nop 0
	v_mfma_f32_32x32x16_bf16 v[0:15], a[20:23], a[28:31], v[0:15]
	s_and_b32 m0, s32, 7
	s_lshl_b32 m0, m0, 12
	s_add_i32 m0, m0, 0x0
	s_nop 0
	global_load_lds_dwordx4 v[170:171], off
	s_nop 0
	v_lshl_add_u64 v[176:177], v[72:73], 0, s[30:31]
	s_nop 0
	s_nop 0
	s_nop 0
	v_lshl_add_u64 v[178:179], v[74:75], 0, s[30:31]
	s_nop 0
	s_nop 0
	s_nop 0
	v_lshl_add_u64 v[180:181], v[76:77], 0, s[30:31]
	s_nop 0
	s_mov_b64 s[30:31], 0x680
	s_nop 0
	s_nop 0
	s_nop 0
	s_nop 0
	s_nop 0
	ds_read_b128 a[16:19], v93
	ds_read_b128 a[20:23], v91
	ds_read_b128 a[24:27], v84 offset:49152
	ds_read_b128 a[28:31], v84 offset:53248
	s_waitcnt lgkmcnt(4)
	v_mfma_f32_32x32x16_bf16 v[48:63], a[0:3], a[8:11], v[48:63]
	s_nop 0
	v_mfma_f32_32x32x16_bf16 v[32:47], a[4:7], a[8:11], v[32:47]
	v_mfma_f32_32x32x16_bf16 v[16:31], a[0:3], a[12:15], v[16:31]
	s_and_b32 m0, s32, 7
	s_lshl_b32 m0, m0, 12
	s_add_i32 m0, m0, 0x400
	s_nop 0
	global_load_lds_dwordx4 v[172:173], off
	v_mfma_f32_32x32x16_bf16 v[0:15], a[4:7], a[12:15], v[0:15]
	s_nop 0
	s_nop 0
	s_nop 0
	s_nop 0
	ds_read_b128 a[0:3], v95
	ds_read_b128 a[4:7], v94
	ds_read_b128 a[8:11], v86 offset:49152
	ds_read_b128 a[12:15], v86 offset:53248
	s_waitcnt lgkmcnt(5)
	v_mfma_f32_32x32x16_bf16 v[48:63], a[16:19], a[24:27], v[48:63]
	s_and_b32 m0, s32, 7
	s_lshl_b32 m0, m0, 12
	s_add_i32 m0, m0, 0x800
	s_nop 0
	global_load_lds_dwordx4 v[174:175], off
	v_mfma_f32_32x32x16_bf16 v[32:47], a[20:23], a[24:27], v[32:47]
	s_waitcnt lgkmcnt(4)
	v_mfma_f32_32x32x16_bf16 v[16:31], a[16:19], a[28:31], v[16:31]
	v_mfma_f32_32x32x16_bf16 v[0:15], a[20:23], a[28:31], v[0:15]
	s_and_b32 m0, s32, 7
	s_lshl_b32 m0, m0, 12
	s_add_i32 m0, m0, 0xc00
	s_nop 0
	global_load_lds_dwordx4 v[176:177], off
	s_nop 0
	s_nop 0
	s_nop 0
	s_nop 0
	ds_read_b128 a[16:19], v97
	ds_read_b128 a[20:23], v96
	ds_read_b128 a[24:27], v88 offset:49152
	ds_read_b128 a[28:31], v88 offset:53248
	s_waitcnt lgkmcnt(5)
	v_mfma_f32_32x32x16_bf16 v[48:63], a[0:3], a[8:11], v[48:63]
	v_mfma_f32_32x32x16_bf16 v[32:47], a[4:7], a[8:11], v[32:47]
	s_waitcnt lgkmcnt(4)
	v_mfma_f32_32x32x16_bf16 v[16:31], a[0:3], a[12:15], v[16:31]
	s_and_b32 m0, s32, 7
	s_lshl_b32 m0, m0, 11
	s_add_i32 m0, m0, 0x8000
	s_nop 0
	global_load_lds_dwordx4 v[178:179], off
	v_mfma_f32_32x32x16_bf16 v[0:15], a[4:7], a[12:15], v[0:15]
	s_nop 0
	s_nop 0
	s_nop 0
	s_nop 0
	s_waitcnt lgkmcnt(1)
	v_mfma_f32_32x32x16_bf16 v[48:63], a[16:19], a[24:27], v[48:63]
	s_and_b32 m0, s32, 7
	s_lshl_b32 m0, m0, 11
	s_add_i32 m0, m0, 0x8400
	s_nop 0
	global_load_lds_dwordx4 v[180:181], off
	v_mfma_f32_32x32x16_bf16 v[32:47], a[20:23], a[24:27], v[32:47]
	s_waitcnt vmcnt(6)
	s_waitcnt lgkmcnt(0)
	s_barrier
	ds_read_b128 a[12:15], v101
	ds_read_b128 a[8:11], v100
	ds_read_b128 a[4:7], v99
	ds_read_b128 a[0:3], v98
	v_mfma_f32_32x32x16_bf16 v[16:31], a[16:19], a[28:31], v[16:31]
	v_lshl_add_u64 v[158:159], v[66:67], 0, s[30:31]
	s_nop 0
	v_lshl_add_u64 v[160:161], v[68:69], 0, s[30:31]
	s_nop 0
	s_nop 0
	s_nop 0
	v_lshl_add_u64 v[162:163], v[70:71], 0, s[30:31]
	s_nop 0
	v_mfma_f32_32x32x16_bf16 v[0:15], a[20:23], a[28:31], v[0:15]
	s_and_b32 m0, s32, 7
	s_lshl_b32 m0, m0, 12
	s_add_i32 m0, m0, 0xc000
	s_nop 0
	global_load_lds_dwordx4 v[158:159], off
	s_nop 0
	v_lshl_add_u64 v[164:165], v[72:73], 0, s[30:31]
	s_nop 0
	s_nop 0
	s_nop 0
	v_lshl_add_u64 v[166:167], v[74:75], 0, s[30:31]
	s_nop 0
	s_nop 0
	s_nop 0
	v_lshl_add_u64 v[168:169], v[76:77], 0, s[30:31]
	s_nop 0
	s_mov_b64 s[30:31], 0x700
	s_nop 0
	s_nop 0
	s_nop 0
	s_nop 0
	s_nop 0
	ds_read_b128 a[16:19], v102
	ds_read_b128 a[20:23], v103
	ds_read_b128 a[24:27], v104
	ds_read_b128 a[28:31], v105
	s_waitcnt lgkmcnt(4)
	v_mfma_f32_32x32x16_bf16 v[48:63], a[0:3], a[8:11], v[48:63]
	s_nop 0
	v_mfma_f32_32x32x16_bf16 v[32:47], a[4:7], a[8:11], v[32:47]
	v_mfma_f32_32x32x16_bf16 v[16:31], a[0:3], a[12:15], v[16:31]
	s_and_b32 m0, s32, 7
	s_lshl_b32 m0, m0, 12
	s_add_i32 m0, m0, 0xc400
	s_nop 0
	global_load_lds_dwordx4 v[160:161], off
	v_mfma_f32_32x32x16_bf16 v[0:15], a[4:7], a[12:15], v[0:15]
	s_nop 0
	s_nop 0
	s_nop 0
	s_nop 0
	ds_read_b128 a[0:3], v106
	ds_read_b128 a[4:7], v107
	ds_read_b128 a[8:11], v108
	ds_read_b128 a[12:15], v109
	s_waitcnt lgkmcnt(5)
	v_mfma_f32_32x32x16_bf16 v[48:63], a[16:19], a[24:27], v[48:63]
	s_and_b32 m0, s32, 7
	s_lshl_b32 m0, m0, 12
	s_add_i32 m0, m0, 0xc800
	s_nop 0
	global_load_lds_dwordx4 v[162:163], off
	v_mfma_f32_32x32x16_bf16 v[32:47], a[20:23], a[24:27], v[32:47]
	s_waitcnt lgkmcnt(4)
	v_mfma_f32_32x32x16_bf16 v[16:31], a[16:19], a[28:31], v[16:31]
	v_mfma_f32_32x32x16_bf16 v[0:15], a[20:23], a[28:31], v[0:15]
	s_and_b32 m0, s32, 7
	s_lshl_b32 m0, m0, 12
	s_add_i32 m0, m0, 0xcc00
	s_nop 0
	global_load_lds_dwordx4 v[164:165], off
	s_nop 0
	s_nop 0
	s_nop 0
	s_nop 0
	ds_read_b128 a[16:19], v110
	ds_read_b128 a[20:23], v111
	ds_read_b128 a[24:27], v112
	ds_read_b128 a[28:31], v113
	s_waitcnt lgkmcnt(5)
	v_mfma_f32_32x32x16_bf16 v[48:63], a[0:3], a[8:11], v[48:63]
	v_mfma_f32_32x32x16_bf16 v[32:47], a[4:7], a[8:11], v[32:47]
	s_waitcnt lgkmcnt(4)
	v_mfma_f32_32x32x16_bf16 v[16:31], a[0:3], a[12:15], v[16:31]
	s_and_b32 m0, s32, 7
	s_lshl_b32 m0, m0, 11
	s_add_i32 m0, m0, 0x14000
	s_nop 0
	global_load_lds_dwordx4 v[166:167], off
	v_mfma_f32_32x32x16_bf16 v[0:15], a[4:7], a[12:15], v[0:15]
	s_nop 0
	s_nop 0
	s_nop 0
	s_nop 0
	s_waitcnt lgkmcnt(1)
	v_mfma_f32_32x32x16_bf16 v[48:63], a[16:19], a[24:27], v[48:63]
	s_and_b32 m0, s32, 7
	s_lshl_b32 m0, m0, 11
	s_add_i32 m0, m0, 0x14400
	s_nop 0
	global_load_lds_dwordx4 v[168:169], off
	v_mfma_f32_32x32x16_bf16 v[32:47], a[20:23], a[24:27], v[32:47]
	s_waitcnt vmcnt(6)
	s_waitcnt lgkmcnt(0)
	s_barrier
	ds_read_b128 a[12:15], v82 offset:4096
	ds_read_b128 a[8:11], v82
	ds_read_b128 a[4:7], v83 offset:36864
	ds_read_b128 a[0:3], v83 offset:32768
	v_mfma_f32_32x32x16_bf16 v[16:31], a[16:19], a[28:31], v[16:31]
	v_lshl_add_u64 v[170:171], v[66:67], 0, s[30:31]
	s_nop 0
	v_lshl_add_u64 v[172:173], v[68:69], 0, s[30:31]
	s_nop 0
	s_nop 0
	s_nop 0
	v_lshl_add_u64 v[174:175], v[70:71], 0, s[30:31]
	s_nop 0
	v_mfma_f32_32x32x16_bf16 v[0:15], a[20:23], a[28:31], v[0:15]
	s_and_b32 m0, s32, 7
	s_lshl_b32 m0, m0, 12
	s_add_i32 m0, m0, 0x18000
	s_nop 0
	global_load_lds_dwordx4 v[170:171], off
	s_nop 0
	v_lshl_add_u64 v[176:177], v[72:73], 0, s[30:31]
	s_nop 0
	s_nop 0
	s_nop 0
	v_lshl_add_u64 v[178:179], v[74:75], 0, s[30:31]
	s_nop 0
	s_nop 0
	s_nop 0
	v_lshl_add_u64 v[180:181], v[76:77], 0, s[30:31]
	s_nop 0
	s_mov_b64 s[30:31], 0x780
	s_nop 0
	s_nop 0
	s_nop 0
	s_nop 0
	s_nop 0
	ds_read_b128 a[16:19], v85 offset:32768
	ds_read_b128 a[20:23], v85 offset:36864
	ds_read_b128 a[24:27], v84
	ds_read_b128 a[28:31], v84 offset:4096
	s_waitcnt lgkmcnt(4)
	v_mfma_f32_32x32x16_bf16 v[48:63], a[0:3], a[8:11], v[48:63]
	v_lshl_add_u64 v[158:159], v[66:67], 0, s[30:31]
	s_nop 0
	v_mfma_f32_32x32x16_bf16 v[32:47], a[4:7], a[8:11], v[32:47]
	v_mfma_f32_32x32x16_bf16 v[16:31], a[0:3], a[12:15], v[16:31]
	s_and_b32 m0, s32, 7
	s_lshl_b32 m0, m0, 12
	s_add_i32 m0, m0, 0x18400
	s_nop 0
	global_load_lds_dwordx4 v[172:173], off
	v_mfma_f32_32x32x16_bf16 v[0:15], a[4:7], a[12:15], v[0:15]
	s_nop 0
	s_nop 0
	s_nop 0
	s_nop 0
	ds_read_b128 a[0:3], v87 offset:32768
	ds_read_b128 a[4:7], v87 offset:36864
	ds_read_b128 a[8:11], v86
	ds_read_b128 a[12:15], v86 offset:4096
	s_waitcnt lgkmcnt(5)
	v_mfma_f32_32x32x16_bf16 v[48:63], a[16:19], a[24:27], v[48:63]
	s_and_b32 m0, s32, 7
	s_lshl_b32 m0, m0, 12
	s_add_i32 m0, m0, 0x18800
	s_nop 0
	global_load_lds_dwordx4 v[174:175], off
	v_mfma_f32_32x32x16_bf16 v[32:47], a[20:23], a[24:27], v[32:47]
	s_waitcnt lgkmcnt(4)
	v_mfma_f32_32x32x16_bf16 v[16:31], a[16:19], a[28:31], v[16:31]
	v_mfma_f32_32x32x16_bf16 v[0:15], a[20:23], a[28:31], v[0:15]
	s_and_b32 m0, s32, 7
	s_lshl_b32 m0, m0, 12
	s_add_i32 m0, m0, 0x18c00
	s_nop 0
	global_load_lds_dwordx4 v[176:177], off
	s_nop 0
	s_nop 0
	s_nop 0
	s_nop 0
	ds_read_b128 a[16:19], v89 offset:32768
	ds_read_b128 a[20:23], v89 offset:36864
	ds_read_b128 a[24:27], v88
	ds_read_b128 a[28:31], v88 offset:4096
	s_waitcnt lgkmcnt(5)
	v_mfma_f32_32x32x16_bf16 v[48:63], a[0:3], a[8:11], v[48:63]
	v_mfma_f32_32x32x16_bf16 v[32:47], a[4:7], a[8:11], v[32:47]
	s_waitcnt lgkmcnt(4)
	v_mfma_f32_32x32x16_bf16 v[16:31], a[0:3], a[12:15], v[16:31]
	s_and_b32 m0, s32, 7
	s_lshl_b32 m0, m0, 11
	s_add_i32 m0, m0, 0x20000
	s_nop 0
	global_load_lds_dwordx4 v[178:179], off
	v_mfma_f32_32x32x16_bf16 v[0:15], a[4:7], a[12:15], v[0:15]
	s_nop 0
	s_nop 0
	s_nop 0
	s_nop 0
	s_waitcnt lgkmcnt(1)
	v_mfma_f32_32x32x16_bf16 v[48:63], a[16:19], a[24:27], v[48:63]
	s_and_b32 m0, s32, 7
	s_lshl_b32 m0, m0, 11
	s_add_i32 m0, m0, 0x20400
	s_nop 0
	global_load_lds_dwordx4 v[180:181], off
	v_mfma_f32_32x32x16_bf16 v[32:47], a[20:23], a[24:27], v[32:47]
	s_waitcnt vmcnt(6)
	s_waitcnt lgkmcnt(0)
	s_barrier
	ds_read_b128 a[12:15], v82 offset:53248
	ds_read_b128 a[8:11], v82 offset:49152
	ds_read_b128 a[4:7], v90
	ds_read_b128 a[0:3], v92
	s_nop 0
	v_lshl_add_u64 v[160:161], v[68:69], 0, s[30:31]
	s_nop 0
	v_mfma_f32_32x32x16_bf16 v[16:31], a[16:19], a[28:31], v[16:31]
	s_nop 0
	v_lshl_add_u64 v[162:163], v[70:71], 0, s[30:31]
	s_nop 0
	s_nop 0
	s_nop 0
	v_lshl_add_u64 v[164:165], v[72:73], 0, s[30:31]
	s_nop 0
	v_mfma_f32_32x32x16_bf16 v[0:15], a[20:23], a[28:31], v[0:15]
	s_and_b32 m0, s32, 7
	s_lshl_b32 m0, m0, 12
	s_add_i32 m0, m0, 0x0
	s_nop 0
	global_load_lds_dwordx4 v[158:159], off
	s_nop 0
	v_lshl_add_u64 v[166:167], v[74:75], 0, s[30:31]
	s_nop 0
	s_nop 0
	s_nop 0
	v_lshl_add_u64 v[168:169], v[76:77], 0, s[30:31]
	s_nop 0
	s_nop 0
	s_nop 0
	s_nop 0
	s_nop 0
	s_nop 0
	s_nop 0
	ds_read_b128 a[16:19], v93
	ds_read_b128 a[20:23], v91
	ds_read_b128 a[24:27], v84 offset:49152
	ds_read_b128 a[28:31], v84 offset:53248
	s_waitcnt lgkmcnt(4)
	v_mfma_f32_32x32x16_bf16 v[48:63], a[0:3], a[8:11], v[48:63]
	v_mfma_f32_32x32x16_bf16 v[32:47], a[4:7], a[8:11], v[32:47]
	v_mfma_f32_32x32x16_bf16 v[16:31], a[0:3], a[12:15], v[16:31]
	s_and_b32 m0, s32, 7
	s_lshl_b32 m0, m0, 12
	s_add_i32 m0, m0, 0x400
	s_nop 0
	global_load_lds_dwordx4 v[160:161], off
	v_mfma_f32_32x32x16_bf16 v[0:15], a[4:7], a[12:15], v[0:15]
	s_nop 0
	s_nop 0
	s_nop 0
	s_nop 0
	ds_read_b128 a[0:3], v95
	ds_read_b128 a[4:7], v94
	ds_read_b128 a[8:11], v86 offset:49152
	ds_read_b128 a[12:15], v86 offset:53248
	s_waitcnt lgkmcnt(5)
	v_mfma_f32_32x32x16_bf16 v[48:63], a[16:19], a[24:27], v[48:63]
	s_and_b32 m0, s32, 7
	s_lshl_b32 m0, m0, 12
	s_add_i32 m0, m0, 0x800
	s_nop 0
	global_load_lds_dwordx4 v[162:163], off
	v_mfma_f32_32x32x16_bf16 v[32:47], a[20:23], a[24:27], v[32:47]
	s_waitcnt lgkmcnt(4)
	v_mfma_f32_32x32x16_bf16 v[16:31], a[16:19], a[28:31], v[16:31]
	v_mfma_f32_32x32x16_bf16 v[0:15], a[20:23], a[28:31], v[0:15]
	s_and_b32 m0, s32, 7
	s_lshl_b32 m0, m0, 12
	s_add_i32 m0, m0, 0xc00
	s_nop 0
	global_load_lds_dwordx4 v[164:165], off
	s_nop 0
	s_nop 0
	s_nop 0
	s_nop 0
	ds_read_b128 a[16:19], v97
	ds_read_b128 a[20:23], v96
	ds_read_b128 a[24:27], v88 offset:49152
	ds_read_b128 a[28:31], v88 offset:53248
	s_waitcnt lgkmcnt(5)
	v_mfma_f32_32x32x16_bf16 v[48:63], a[0:3], a[8:11], v[48:63]
	v_mfma_f32_32x32x16_bf16 v[32:47], a[4:7], a[8:11], v[32:47]
	s_waitcnt lgkmcnt(4)
	v_mfma_f32_32x32x16_bf16 v[16:31], a[0:3], a[12:15], v[16:31]
	s_and_b32 m0, s32, 7
	s_lshl_b32 m0, m0, 11
	s_add_i32 m0, m0, 0x8000
	s_nop 0
	global_load_lds_dwordx4 v[166:167], off
	v_mfma_f32_32x32x16_bf16 v[0:15], a[4:7], a[12:15], v[0:15]
	s_nop 0
	s_nop 0
	s_nop 0
	s_nop 0
	s_waitcnt lgkmcnt(1)
	v_mfma_f32_32x32x16_bf16 v[48:63], a[16:19], a[24:27], v[48:63]
	s_and_b32 m0, s32, 7
	s_lshl_b32 m0, m0, 11
	s_add_i32 m0, m0, 0x8400
	s_nop 0
	global_load_lds_dwordx4 v[168:169], off
	v_mfma_f32_32x32x16_bf16 v[32:47], a[20:23], a[24:27], v[32:47]
	s_waitcnt vmcnt(6)
	s_waitcnt lgkmcnt(0)
	s_barrier
	ds_read_b128 a[12:15], v101
	ds_read_b128 a[8:11], v100
	ds_read_b128 a[4:7], v99
	ds_read_b128 a[0:3], v98
	v_mfma_f32_32x32x16_bf16 v[16:31], a[16:19], a[28:31], v[16:31]
	v_mfma_f32_32x32x16_bf16 v[0:15], a[20:23], a[28:31], v[0:15]
	s_nop 0
	s_nop 0
	s_nop 0
	s_nop 0
	ds_read_b128 a[16:19], v102
	ds_read_b128 a[20:23], v103
	ds_read_b128 a[24:27], v104
	ds_read_b128 a[28:31], v105
	s_waitcnt lgkmcnt(4)
	v_mfma_f32_32x32x16_bf16 v[48:63], a[0:3], a[8:11], v[48:63]
	v_mfma_f32_32x32x16_bf16 v[32:47], a[4:7], a[8:11], v[32:47]
	v_mfma_f32_32x32x16_bf16 v[16:31], a[0:3], a[12:15], v[16:31]
	v_mfma_f32_32x32x16_bf16 v[0:15], a[4:7], a[12:15], v[0:15]
	s_nop 0
	s_nop 0
	s_nop 0
	s_nop 0
	ds_read_b128 a[0:3], v106
	ds_read_b128 a[4:7], v107
	ds_read_b128 a[8:11], v108
	ds_read_b128 a[12:15], v109
	s_waitcnt lgkmcnt(5)
	v_mfma_f32_32x32x16_bf16 v[48:63], a[16:19], a[24:27], v[48:63]
	v_mfma_f32_32x32x16_bf16 v[32:47], a[20:23], a[24:27], v[32:47]
	s_waitcnt lgkmcnt(4)
	v_mfma_f32_32x32x16_bf16 v[16:31], a[16:19], a[28:31], v[16:31]
	v_mfma_f32_32x32x16_bf16 v[0:15], a[20:23], a[28:31], v[0:15]
	s_nop 0
	s_nop 0
	s_nop 0
	s_nop 0
	ds_read_b128 a[16:19], v110
	ds_read_b128 a[20:23], v111
	ds_read_b128 a[24:27], v112
	ds_read_b128 a[28:31], v113
	s_waitcnt lgkmcnt(5)
	v_mfma_f32_32x32x16_bf16 v[48:63], a[0:3], a[8:11], v[48:63]
	v_mfma_f32_32x32x16_bf16 v[32:47], a[4:7], a[8:11], v[32:47]
	s_waitcnt lgkmcnt(4)
	v_mfma_f32_32x32x16_bf16 v[16:31], a[0:3], a[12:15], v[16:31]
	v_mfma_f32_32x32x16_bf16 v[0:15], a[4:7], a[12:15], v[0:15]
	s_nop 0
	s_nop 0
	s_nop 0
	s_nop 0
	s_waitcnt lgkmcnt(1)
	v_mfma_f32_32x32x16_bf16 v[48:63], a[16:19], a[24:27], v[48:63]
	v_mfma_f32_32x32x16_bf16 v[32:47], a[20:23], a[24:27], v[32:47]
	s_waitcnt vmcnt(0)
	s_waitcnt lgkmcnt(0)
	s_barrier
	ds_read_b128 a[12:15], v82 offset:4096
	ds_read_b128 a[8:11], v82
	ds_read_b128 a[4:7], v83 offset:36864
	ds_read_b128 a[0:3], v83 offset:32768
	v_mfma_f32_32x32x16_bf16 v[16:31], a[16:19], a[28:31], v[16:31]
	v_mfma_f32_32x32x16_bf16 v[0:15], a[20:23], a[28:31], v[0:15]
	s_nop 0
	s_nop 0
	s_nop 0
	s_nop 0
	ds_read_b128 a[16:19], v85 offset:32768
	ds_read_b128 a[20:23], v85 offset:36864
	ds_read_b128 a[24:27], v84
	ds_read_b128 a[28:31], v84 offset:4096
	s_waitcnt lgkmcnt(4)
	v_mfma_f32_32x32x16_bf16 v[48:63], a[0:3], a[8:11], v[48:63]
	v_mfma_f32_32x32x16_bf16 v[32:47], a[4:7], a[8:11], v[32:47]
	v_mfma_f32_32x32x16_bf16 v[16:31], a[0:3], a[12:15], v[16:31]
	v_mfma_f32_32x32x16_bf16 v[0:15], a[4:7], a[12:15], v[0:15]
	s_nop 0
	s_nop 0
	s_nop 0
	s_nop 0
	ds_read_b128 a[0:3], v87 offset:32768
	ds_read_b128 a[4:7], v87 offset:36864
	ds_read_b128 a[8:11], v86
	ds_read_b128 a[12:15], v86 offset:4096
	s_waitcnt lgkmcnt(5)
	v_mfma_f32_32x32x16_bf16 v[48:63], a[16:19], a[24:27], v[48:63]
	v_mfma_f32_32x32x16_bf16 v[32:47], a[20:23], a[24:27], v[32:47]
	s_waitcnt lgkmcnt(4)
	v_mfma_f32_32x32x16_bf16 v[16:31], a[16:19], a[28:31], v[16:31]
	v_mfma_f32_32x32x16_bf16 v[0:15], a[20:23], a[28:31], v[0:15]
	s_nop 0
	s_nop 0
	s_nop 0
	s_nop 0
	s_waitcnt lgkmcnt(1)
	v_mfma_f32_32x32x16_bf16 v[48:63], a[0:3], a[8:11], v[48:63]
	v_mfma_f32_32x32x16_bf16 v[32:47], a[4:7], a[8:11], v[32:47]
	s_waitcnt lgkmcnt(0)
	v_mfma_f32_32x32x16_bf16 v[16:31], a[0:3], a[12:15], v[16:31]
	v_mfma_f32_32x32x16_bf16 v[0:15], a[4:7], a[12:15], v[0:15]
	ds_read_b128 v[66:69], v89 offset:32768
	ds_read_b128 v[70:73], v88
	ds_read_b128 v[74:77], v89 offset:36864
	ds_read_b128 v[82:85], v88 offset:4096
	s_waitcnt lgkmcnt(0)
	s_barrier
	s_waitcnt lgkmcnt(0)
	v_mfma_f32_32x32x16_bf16 v[48:63], v[66:69], v[70:73], v[48:63]
	v_mfma_f32_32x32x16_bf16 v[32:47], v[74:77], v[70:73], v[32:47]
	v_mov_b32_e32 v70, 0
	v_mfma_f32_32x32x16_bf16 v[16:31], v[66:69], v[82:85], v[16:31]
	v_lshl_or_b32 v69, v80, 6, v81
	v_add_u32_e32 v66, s20, v69
	v_cmp_gt_i32_e32 vcc, s69, v66
	v_mov_b32_e32 v68, 0
	v_ashrrev_i32_e32 v67, 31, v66
	v_mfma_f32_32x32x16_bf16 v[0:15], v[74:77], v[82:85], v[0:15]
	s_and_saveexec_b64 s[0:1], vcc
	s_cbranch_execz .LBB0_588
	v_lshl_add_u64 v[70:71], v[66:67], 2, s[76:77]
	global_load_dword v70, v[70:71], off
	s_waitcnt vmcnt(0)
	v_fmamk_f32 v70, v70, 0x3a800000, v188
	v_mul_f32_e32 v71, 0x4b800000, v70
	v_cmp_gt_f32_e32 vcc, s82, v70
	s_nop 1
	v_cndmask_b32_e32 v70, v70, v71, vcc
	v_rsq_f32_e32 v70, v70
	s_nop 0
	v_mul_f32_e32 v71, 0x45800000, v70
	v_cndmask_b32_e32 v70, v70, v71, vcc

.LBB0_612:
	v_readlane_b32 s0, v212, 1
	s_cmp_ge_i32 s56, s0
	s_mov_b64 s[0:1], -1
	s_cbranch_scc0 .LBB0_742
	s_ashr_i32 s1, s52, 31
	s_lshr_b32 s0, s1, 27
	s_add_i32 s2, s52, s0
	s_ashr_i32 s0, s2, 5
	s_and_b32 s2, s2, 0xffe0
	s_sub_i32 s2, s52, s2
	s_lshr_b32 s1, s1, 30
	s_bfe_i32 s20, s2, 0x80000
	s_add_i32 s1, s52, s1
	s_bfe_u32 s20, s20, 0x2000d
	s_and_b32 s1, s1, 0x1fffffc
	s_add_i32 s2, s2, s20
	s_sub_i32 s23, s52, s1
	s_ashr_i32 s1, s0, 31
	s_bfe_i32 s2, s2, 0x80000
	s_lshl_b64 s[20:21], s[0:1], 20
	v_readlane_b32 s22, v215, 46
	s_sext_i32_i16 s2, s2
	s_add_u32 s20, s22, s20
	v_readlane_b32 s22, v215, 47
	v_mov_b32_e32 v12, v133
	s_addc_u32 s21, s22, s21
	s_lshl_b32 s2, s2, 6
	s_and_b32 s22, s2, 0xffffff00
	v_ashrrev_i32_e32 v6, 6, v12
	v_bfe_u32 v7, v12, 3, 3
	v_lshl_or_b32 v8, v6, 5, v7
	v_add_u32_e32 v0, s22, v8
	s_waitcnt lgkmcnt(0)
	v_ashrrev_i32_e32 v1, 31, v0
	v_lshlrev_b64 v[2:3], 11, v[0:1]
	v_bfe_u32 v1, v12, 4, 2
	v_readlane_b32 s28, v215, 50
	v_xor_b32_e32 v1, v1, v12
	v_readlane_b32 s29, v215, 51
	v_lshlrev_b32_e32 v1, 4, v1
	v_and_b32_e32 v64, 0x70, v1
	v_lshl_add_u64 v[2:3], s[28:29], 0, v[2:3]
	v_or_b32_e32 v1, 8, v8
	v_lshl_add_u64 v[66:67], v[2:3], 0, v[64:65]
	v_add_u32_e32 v2, s22, v1
	v_lshrrev_b32_e32 v1, 1, v1
	v_xor_b32_e32 v1, v1, v12
	v_ashrrev_i32_e32 v3, 31, v2
	v_lshlrev_b32_e32 v1, 4, v1
	v_or_b32_e32 v0, 16, v0
	v_lshlrev_b64 v[2:3], 11, v[2:3]
	v_and_b32_e32 v4, 0x70, v1
	v_ashrrev_i32_e32 v1, 31, v0
	v_lshl_add_u64 v[2:3], s[28:29], 0, v[2:3]
	v_mov_b32_e32 v5, v65
	v_lshlrev_b64 v[0:1], 11, v[0:1]
	v_lshl_add_u64 v[68:69], v[2:3], 0, v[4:5]
	v_lshl_add_u64 v[0:1], s[28:29], 0, v[0:1]
	v_or_b32_e32 v2, 24, v8
	v_lshl_add_u64 v[70:71], v[0:1], 0, v[64:65]
	v_add_u32_e32 v0, s22, v2
	v_lshrrev_b32_e32 v2, 1, v2
	v_ashrrev_i32_e32 v1, 31, v0
	v_xor_b32_e32 v2, v2, v12
	v_lshlrev_b64 v[0:1], 11, v[0:1]
	v_lshlrev_b32_e32 v2, 4, v2
	v_lshl_add_u64 v[0:1], s[28:29], 0, v[0:1]
	v_and_b32_e32 v2, 0x70, v2
	v_mov_b32_e32 v3, v65
	s_lshl_b32 s2, s23, 7
	v_lshl_add_u64 v[72:73], v[0:1], 0, v[2:3]
	v_lshl_or_b32 v2, v6, 4, v7
	v_add_u32_e32 v0, s2, v2
	v_lshlrev_b32_e32 v3, 12, v6
	v_ashrrev_i32_e32 v1, 31, v0
	v_add_u32_e32 v125, 0, v3
	v_lshlrev_b64 v[0:1], 11, v[0:1]
	s_waitcnt vmcnt(0)
	v_readfirstlane_b32 s42, v125
	v_add_u32_e32 v126, 0x400, v125
	v_lshl_add_u64 v[0:1], s[20:21], 0, v[0:1]
	v_or_b32_e32 v2, 8, v2
	s_waitcnt lgkmcnt(0)
	s_barrier
	s_mov_b32 m0, s42
	v_readfirstlane_b32 s43, v126
	v_add_u32_e32 v127, 0x800, v125
	v_lshlrev_b32_e32 v5, 11, v6
	v_and_b32_e32 v79, 1, v6
	v_lshl_add_u64 v[74:75], v[0:1], 0, v[64:65]
	v_add_u32_e32 v0, s2, v2
	v_lshrrev_b32_e32 v2, 1, v2
	global_load_lds_dwordx4 v[66:67], off
	s_mov_b32 m0, s43
	v_readfirstlane_b32 s44, v127
	v_add_u32_e32 v128, 0xc00, v125
	v_add_u32_e32 v6, 0, v5
	v_ashrrev_i32_e32 v1, 31, v0
	v_xor_b32_e32 v2, v2, v12
	global_load_lds_dwordx4 v[68:69], off
	s_mov_b32 m0, s44
	v_readfirstlane_b32 s45, v128
	v_add_u32_e32 v130, 0x8000, v6
	v_lshlrev_b64 v[0:1], 11, v[0:1]
	v_lshlrev_b32_e32 v2, 4, v2
	global_load_lds_dwordx4 v[70:71], off
	s_mov_b32 m0, s45
	v_readfirstlane_b32 s46, v130
	v_add_u32_e32 v129, 0x8400, v6
	v_lshl_add_u64 v[0:1], s[20:21], 0, v[0:1]
	v_and_b32_e32 v64, 0x70, v2
	global_load_lds_dwordx4 v[72:73], off
	s_mov_b32 m0, s46
	v_readfirstlane_b32 s47, v129
	v_add_u32_e32 v119, 0xc000, v125
	v_lshl_add_u64 v[76:77], v[0:1], 0, v[64:65]
	global_load_lds_dwordx4 v[74:75], off
	s_mov_b32 m0, s47
	s_mov_b64 s[20:21], 0x80
	v_readfirstlane_b32 s36, v119
	v_add_u32_e32 v120, 0xc400, v125
	global_load_lds_dwordx4 v[76:77], off
	v_lshl_add_u64 v[0:1], v[66:67], 0, s[20:21]
	s_mov_b32 m0, s36
	v_readfirstlane_b32 s37, v120
	v_add_u32_e32 v121, 0xc800, v125
	global_load_lds_dwordx4 v[0:1], off
	v_lshl_add_u64 v[0:1], v[68:69], 0, s[20:21]
	s_mov_b32 m0, s37
	v_readfirstlane_b32 s38, v121
	v_add_u32_e32 v122, 0xcc00, v125
	global_load_lds_dwordx4 v[0:1], off
	v_lshl_add_u64 v[0:1], v[70:71], 0, s[20:21]
	s_mov_b32 m0, s38
	v_readfirstlane_b32 s39, v122
	v_add_u32_e32 v123, s85, v5
	global_load_lds_dwordx4 v[0:1], off
	v_lshl_add_u64 v[0:1], v[72:73], 0, s[20:21]
	s_mov_b32 m0, s39
	v_readfirstlane_b32 s40, v123
	v_add_u32_e32 v124, 0x14400, v6
	global_load_lds_dwordx4 v[0:1], off
	v_lshl_add_u64 v[0:1], v[74:75], 0, s[20:21]
	s_mov_b32 m0, s40
	v_readfirstlane_b32 s41, v124
	global_load_lds_dwordx4 v[0:1], off
	v_lshl_add_u64 v[0:1], v[76:77], 0, s[20:21]
	s_mov_b32 m0, s41
	v_lshrrev_b32_e32 v2, 1, v12
	v_bfe_u32 v64, v12, 5, 1
	global_load_lds_dwordx4 v[0:1], off
	v_add_u32_e32 v113, s3, v3
	v_bitop3_b32 v0, v2, v64, 7 bitop3:0x6c
	s_waitcnt vmcnt(6)
	s_mov_b64 s[30:31], 0x100
	v_readfirstlane_b32 s20, v113
	v_add_u32_e32 v114, 0x400, v113
	v_lshlrev_b32_e32 v110, 4, v0
	s_waitcnt lgkmcnt(0)
	s_barrier
	v_lshl_add_u64 v[0:1], v[66:67], 0, s[30:31]
	s_mov_b32 m0, s20
	v_readfirstlane_b32 s21, v114
	v_add_u32_e32 v115, 0x800, v113
	global_load_lds_dwordx4 v[0:1], off
	v_lshl_add_u64 v[0:1], v[68:69], 0, s[30:31]
	s_mov_b32 m0, s21
	v_readfirstlane_b32 s23, v115
	v_add_u32_e32 v116, 0xc00, v113
	v_readlane_b32 s29, v212, 31
	v_and_b32_e32 v80, 31, v12
	global_load_lds_dwordx4 v[0:1], off
	v_lshl_add_u64 v[0:1], v[70:71], 0, s[30:31]
	s_mov_b32 m0, s23
	v_readfirstlane_b32 s28, v116
	v_add_u32_e32 v117, s29, v5
	v_add_u32_e32 v2, s3, v5
	v_lshlrev_b32_e32 v4, 7, v80
	global_load_lds_dwordx4 v[0:1], off
	v_lshl_add_u64 v[0:1], v[72:73], 0, s[30:31]
	s_mov_b32 m0, s28
	v_readfirstlane_b32 s29, v117
	v_add_u32_e32 v118, 0x8400, v2
	v_lshl_or_b32 v102, v79, 13, v4
	global_load_lds_dwordx4 v[0:1], off
	v_lshl_add_u64 v[0:1], v[74:75], 0, s[30:31]
	s_mov_b32 m0, s29
	v_readfirstlane_b32 s33, v118
	global_load_lds_dwordx4 v[0:1], off
	v_lshl_add_u64 v[0:1], v[76:77], 0, s[30:31]
	s_mov_b32 m0, s33
	v_add_u32_e32 v100, 0, v102
	global_load_lds_dwordx4 v[0:1], off
	v_add_u32_e32 v82, v100, v110
	v_ashrrev_i32_e32 v78, 7, v12
	ds_read_b128 a[0:3], v82 offset:32768
	ds_read_b128 a[4:7], v82 offset:36864
	v_lshl_or_b32 v111, v78, 13, v4
	v_add_u32_e32 v101, 0, v111
	v_add_u32_e32 v81, v101, v110
	ds_read_b128 a[8:11], v81
	ds_read_b128 a[12:15], v81 offset:4096
	v_lshrrev_b32_e32 v182, 6, v133
	s_nop 0
	v_readfirstlane_b32 s32, v182
	s_waitcnt lgkmcnt(1)
	v_mfma_f32_32x32x16_bf16 v[48:63], a[0:3], a[8:11], 0
	v_bfe_u32 v103, v12, 1, 3
	v_bitop3_b32 v85, v64, v103, 4 bitop3:0x36
	v_lshlrev_b32_e32 v131, 4, v85
	v_add_u32_e32 v85, v101, v131
	s_mov_b64 s[30:31], 0x180
	s_nop 0
	v_or_b32_e32 v146, 0x8000, v102
	s_waitcnt vmcnt(12)
	v_mfma_f32_32x32x16_bf16 v[32:47], a[4:7], a[8:11], 0
	v_or_b32_e32 v147, 0x9000, v102
	v_add_u32_e32 v138, s3, v110
	v_add_u32_e32 v148, s3, v111
	v_or_b32_e32 v149, 0x1000, v111
	s_mov_b64 s[60:61], 0x80
	s_mov_b64 s[80:81], 0x200
	s_waitcnt lgkmcnt(0)
	v_mfma_f32_32x32x16_bf16 v[16:31], a[0:3], a[12:15], 0
	v_bitop3_b32 v0, v64, v103, 2 bitop3:0x36
	v_lshlrev_b32_e32 v112, 4, v0
	v_add_u32_e32 v83, v101, v112
	ds_read_b128 a[28:31], v83 offset:4096
	s_nop 0
	s_nop 0
	ds_read_b128 a[24:27], v83
	s_nop 0
	v_add_u32_e32 v84, v100, v112
	ds_read_b128 a[20:23], v84 offset:36864
	s_nop 0
	s_nop 0
	ds_read_b128 a[16:19], v84 offset:32768
	s_nop 0
	s_nop 0
	s_nop 0
	s_nop 0
	s_nop 0
	s_nop 0
	v_mfma_f32_32x32x16_bf16 v[0:15], a[4:7], a[12:15], 0
	v_add_u32_e32 v142, s3, v112
	s_nop 0
	v_add_u32_e32 v86, v100, v131
	ds_read_b128 a[0:3], v86 offset:32768
	ds_read_b128 a[4:7], v86 offset:36864
	ds_read_b128 a[8:11], v85
	ds_read_b128 a[12:15], v85 offset:4096
	s_waitcnt lgkmcnt(4)
	v_mfma_f32_32x32x16_bf16 v[48:63], a[16:19], a[24:27], v[48:63]
	v_mfma_f32_32x32x16_bf16 v[32:47], a[20:23], a[24:27], v[32:47]
	v_mfma_f32_32x32x16_bf16 v[16:31], a[16:19], a[28:31], v[16:31]
	s_nop 0
	v_bitop3_b32 v87, v64, v103, 6 bitop3:0x36
	v_lshlrev_b32_e32 v132, 4, v87
	v_add_u32_e32 v87, v101, v132
	v_lshlrev_b32_e32 v64, 2, v64
	v_mfma_f32_32x32x16_bf16 v[0:15], a[20:23], a[28:31], v[0:15]
	s_nop 0
	s_nop 0
	s_nop 0
	v_add_u32_e32 v88, v100, v132
	ds_read_b128 a[16:19], v88 offset:32768
	ds_read_b128 a[20:23], v88 offset:36864
	ds_read_b128 a[24:27], v87
	ds_read_b128 a[28:31], v87 offset:4096
	s_waitcnt lgkmcnt(5)
	v_mfma_f32_32x32x16_bf16 v[48:63], a[0:3], a[8:11], v[48:63]
	v_mfma_f32_32x32x16_bf16 v[32:47], a[4:7], a[8:11], v[32:47]
	s_nop 0
	s_waitcnt lgkmcnt(4)
	v_mfma_f32_32x32x16_bf16 v[16:31], a[0:3], a[12:15], v[16:31]
	s_nop 0
	v_mfma_f32_32x32x16_bf16 v[0:15], a[4:7], a[12:15], v[0:15]
	s_nop 0
	s_nop 0
	s_nop 0
	s_waitcnt lgkmcnt(1)
	v_mfma_f32_32x32x16_bf16 v[48:63], a[16:19], a[24:27], v[48:63]
	v_mfma_f32_32x32x16_bf16 v[32:47], a[20:23], a[24:27], v[32:47]
	s_nop 0
	s_waitcnt vmcnt(6)
	s_waitcnt lgkmcnt(0)
	s_barrier
	ds_read_b128 a[12:15], v81 offset:53248
	ds_read_b128 a[8:11], v81 offset:49152
	v_mfma_f32_32x32x16_bf16 v[16:31], a[16:19], a[28:31], v[16:31]
	v_lshl_add_u64 v[158:159], v[66:67], 0, s[30:31]
	s_nop 0
	v_lshl_add_u64 v[160:161], v[68:69], 0, s[30:31]
	s_nop 0
	s_nop 0
	s_nop 0
	v_lshl_add_u64 v[162:163], v[70:71], 0, s[30:31]
	s_nop 0
	v_mfma_f32_32x32x16_bf16 v[0:15], a[20:23], a[28:31], v[0:15]
	s_and_b32 m0, s32, 7
	s_lshl_b32 m0, m0, 12
	s_add_i32 m0, m0, 0x0
	s_nop 0
	global_load_lds_dwordx4 v[158:159], off
	s_nop 0
	v_lshl_add_u64 v[164:165], v[72:73], 0, s[30:31]
	s_nop 0
	s_nop 0
	s_nop 0
	v_lshl_add_u64 v[166:167], v[74:75], 0, s[30:31]
	s_nop 0
	s_nop 0
	s_nop 0
	v_lshl_add_u64 v[168:169], v[76:77], 0, s[30:31]
	s_add_i32 s30, 0, 0xc000
	v_add_u32_e32 v89, s30, v110
	v_add_u32_e32 v91, v89, v146
	v_add_u32_e32 v89, v89, v147
	ds_read_b128 a[4:7], v89
	ds_read_b128 a[0:3], v91
	s_nop 0
	s_nop 0
	s_nop 0
	s_nop 0
	s_nop 0
	s_nop 0
	s_nop 0
	s_nop 0
	s_nop 0
	v_add_u32_e32 v90, s30, v112
	v_add_u32_e32 v92, v90, v146
	ds_read_b128 a[16:19], v92
	v_add_u32_e32 v90, v90, v147
	ds_read_b128 a[20:23], v90
	ds_read_b128 a[24:27], v83 offset:49152
	ds_read_b128 a[28:31], v83 offset:53248
	s_waitcnt lgkmcnt(4)
	v_mfma_f32_32x32x16_bf16 v[48:63], a[0:3], a[8:11], v[48:63]
	s_nop 0
	s_nop 0
	v_mfma_f32_32x32x16_bf16 v[32:47], a[4:7], a[8:11], v[32:47]
	v_mfma_f32_32x32x16_bf16 v[16:31], a[0:3], a[12:15], v[16:31]
	s_and_b32 m0, s32, 7
	s_lshl_b32 m0, m0, 12
	s_add_i32 m0, m0, 0x400
	s_nop 0
	global_load_lds_dwordx4 v[160:161], off
	s_nop 0
	s_nop 0
	v_add_u32_e32 v93, s30, v131
	v_mfma_f32_32x32x16_bf16 v[0:15], a[4:7], a[12:15], v[0:15]
	s_nop 0
	s_nop 0
	s_nop 0
	s_nop 0
	v_add_u32_e32 v94, v93, v146
	ds_read_b128 a[0:3], v94
	v_add_u32_e32 v93, v93, v147
	ds_read_b128 a[4:7], v93
	ds_read_b128 a[8:11], v85 offset:49152
	ds_read_b128 a[12:15], v85 offset:53248
	s_waitcnt lgkmcnt(5)
	v_mfma_f32_32x32x16_bf16 v[48:63], a[16:19], a[24:27], v[48:63]
	s_and_b32 m0, s32, 7
	s_lshl_b32 m0, m0, 12
	s_add_i32 m0, m0, 0x800
	s_nop 0
	global_load_lds_dwordx4 v[162:163], off
	v_mfma_f32_32x32x16_bf16 v[32:47], a[20:23], a[24:27], v[32:47]
	s_waitcnt lgkmcnt(4)
	v_mfma_f32_32x32x16_bf16 v[16:31], a[16:19], a[28:31], v[16:31]
	s_nop 0
	s_nop 0
	v_add_u32_e32 v95, s30, v132
	s_mov_b64 s[30:31], 0x200
	v_mfma_f32_32x32x16_bf16 v[0:15], a[20:23], a[28:31], v[0:15]
	s_and_b32 m0, s32, 7
	s_lshl_b32 m0, m0, 12
	s_add_i32 m0, m0, 0xc00
	s_nop 0
	global_load_lds_dwordx4 v[164:165], off
	s_nop 0
	s_nop 0
	s_nop 0
	s_nop 0
	v_add_u32_e32 v96, v95, v146
	ds_read_b128 a[16:19], v96
	v_add_u32_e32 v95, v95, v147
	ds_read_b128 a[20:23], v95
	ds_read_b128 a[24:27], v87 offset:49152
	ds_read_b128 a[28:31], v87 offset:53248
	s_waitcnt lgkmcnt(5)
	v_mfma_f32_32x32x16_bf16 v[48:63], a[0:3], a[8:11], v[48:63]
	v_mfma_f32_32x32x16_bf16 v[32:47], a[4:7], a[8:11], v[32:47]
	s_waitcnt lgkmcnt(4)
	v_mfma_f32_32x32x16_bf16 v[16:31], a[0:3], a[12:15], v[16:31]
	s_and_b32 m0, s32, 7
	s_lshl_b32 m0, m0, 11
	s_add_i32 m0, m0, 0x8000
	s_nop 0
	global_load_lds_dwordx4 v[166:167], off
	s_nop 0
	s_nop 0
	v_add_u32_e32 v97, v138, v146
	v_mfma_f32_32x32x16_bf16 v[0:15], a[4:7], a[12:15], v[0:15]
	s_nop 0
	s_nop 0
	s_nop 0
	s_nop 0
	s_waitcnt lgkmcnt(1)
	v_mfma_f32_32x32x16_bf16 v[48:63], a[16:19], a[24:27], v[48:63]
	s_and_b32 m0, s32, 7
	s_lshl_b32 m0, m0, 11
	s_add_i32 m0, m0, 0x8400
	s_nop 0
	global_load_lds_dwordx4 v[168:169], off
	v_mfma_f32_32x32x16_bf16 v[32:47], a[20:23], a[24:27], v[32:47]
	s_waitcnt vmcnt(6)
	s_waitcnt lgkmcnt(0)
	s_barrier
	v_add_u32_e32 v100, v138, v149
	ds_read_b128 a[12:15], v100
	v_add_u32_e32 v99, v148, v110
	ds_read_b128 a[8:11], v99
	v_add_u32_e32 v98, v138, v147
	ds_read_b128 a[4:7], v98
	ds_read_b128 a[0:3], v97
	v_mfma_f32_32x32x16_bf16 v[16:31], a[16:19], a[28:31], v[16:31]
	v_lshl_add_u64 v[170:171], v[66:67], 0, s[30:31]
	s_nop 0
	v_lshl_add_u64 v[172:173], v[68:69], 0, s[30:31]
	s_nop 0
	s_nop 0
	s_nop 0
	v_lshl_add_u64 v[174:175], v[70:71], 0, s[30:31]
	s_nop 0
	v_mfma_f32_32x32x16_bf16 v[0:15], a[20:23], a[28:31], v[0:15]
	s_and_b32 m0, s32, 7
	s_lshl_b32 m0, m0, 12
	s_add_i32 m0, m0, 0xc000
	s_nop 0
	global_load_lds_dwordx4 v[170:171], off
	s_nop 0
	v_lshl_add_u64 v[176:177], v[72:73], 0, s[30:31]
	s_nop 0
	s_nop 0
	s_nop 0
	v_lshl_add_u64 v[178:179], v[74:75], 0, s[30:31]
	s_nop 0
	s_nop 0
	s_nop 0
	v_lshl_add_u64 v[180:181], v[76:77], 0, s[30:31]
	s_nop 0
	s_mov_b64 s[30:31], 0x280
	s_nop 0
	s_nop 0
	s_nop 0
	s_nop 0
	s_nop 0
	s_nop 0
	v_add_u32_e32 v101, v142, v146
	ds_read_b128 a[16:19], v101
	v_add_u32_e32 v102, v142, v147
	ds_read_b128 a[20:23], v102
	v_add_u32_e32 v103, v148, v112
	ds_read_b128 a[24:27], v103
	v_add_u32_e32 v104, v142, v149
	ds_read_b128 a[28:31], v104
	s_waitcnt lgkmcnt(4)
	v_mfma_f32_32x32x16_bf16 v[48:63], a[0:3], a[8:11], v[48:63]
	s_nop 0
	v_mfma_f32_32x32x16_bf16 v[32:47], a[4:7], a[8:11], v[32:47]
	s_nop 0
	s_nop 0
	s_nop 0
	s_nop 0
	s_nop 0
	s_nop 0
	v_add_u32_e32 v112, s3, v131
	v_mfma_f32_32x32x16_bf16 v[16:31], a[0:3], a[12:15], v[16:31]
	s_and_b32 m0, s32, 7
	s_lshl_b32 m0, m0, 12
	s_add_i32 m0, m0, 0xc400
	s_nop 0
	global_load_lds_dwordx4 v[172:173], off
	s_nop 0
	v_mfma_f32_32x32x16_bf16 v[0:15], a[4:7], a[12:15], v[0:15]
	s_nop 0
	s_nop 0
	v_add_u32_e32 v105, v112, v146
	s_nop 0
	ds_read_b128 a[0:3], v105
	v_add_u32_e32 v106, v112, v147
	ds_read_b128 a[4:7], v106
	v_add_u32_e32 v107, v148, v131
	ds_read_b128 a[8:11], v107
	v_add_u32_e32 v108, v112, v149
	ds_read_b128 a[12:15], v108
	s_waitcnt lgkmcnt(5)
	v_mfma_f32_32x32x16_bf16 v[48:63], a[16:19], a[24:27], v[48:63]
	s_and_b32 m0, s32, 7
	s_lshl_b32 m0, m0, 12
	s_add_i32 m0, m0, 0xc800
	s_nop 0
	global_load_lds_dwordx4 v[174:175], off
	v_mfma_f32_32x32x16_bf16 v[32:47], a[20:23], a[24:27], v[32:47]
	s_waitcnt lgkmcnt(4)
	v_mfma_f32_32x32x16_bf16 v[16:31], a[16:19], a[28:31], v[16:31]
	s_nop 0
	s_nop 0
	s_nop 0
	v_mfma_f32_32x32x16_bf16 v[0:15], a[20:23], a[28:31], v[0:15]
	s_and_b32 m0, s32, 7
	s_lshl_b32 m0, m0, 12
	s_add_i32 m0, m0, 0xcc00
	s_nop 0
	global_load_lds_dwordx4 v[176:177], off
	s_nop 0
	s_nop 0
	v_add_u32_e32 v112, s3, v132
	v_add_u32_e32 v109, v112, v146
	ds_read_b128 a[16:19], v109
	v_add_u32_e32 v110, v112, v147
	ds_read_b128 a[20:23], v110
	v_add_u32_e32 v111, v148, v132
	ds_read_b128 a[24:27], v111
	v_add_u32_e32 v112, v112, v149
	ds_read_b128 a[28:31], v112
	s_waitcnt lgkmcnt(5)
	v_mfma_f32_32x32x16_bf16 v[48:63], a[0:3], a[8:11], v[48:63]
	v_mfma_f32_32x32x16_bf16 v[32:47], a[4:7], a[8:11], v[32:47]
	s_nop 0
	s_nop 0
	s_nop 0
	s_nop 0
	s_nop 0
	s_nop 0
	s_nop 0
	s_waitcnt lgkmcnt(4)
	v_mfma_f32_32x32x16_bf16 v[16:31], a[0:3], a[12:15], v[16:31]
	s_and_b32 m0, s32, 7
	s_lshl_b32 m0, m0, 11
	s_add_i32 m0, m0, 0x14000
	s_nop 0
	global_load_lds_dwordx4 v[178:179], off
	s_nop 0
	v_mfma_f32_32x32x16_bf16 v[0:15], a[4:7], a[12:15], v[0:15]
	s_nop 0
	s_nop 0
	s_nop 0
	s_waitcnt lgkmcnt(1)
	v_mfma_f32_32x32x16_bf16 v[48:63], a[16:19], a[24:27], v[48:63]
	s_and_b32 m0, s32, 7
	s_lshl_b32 m0, m0, 11
	s_add_i32 m0, m0, 0x14400
	s_nop 0
	global_load_lds_dwordx4 v[180:181], off
	v_mfma_f32_32x32x16_bf16 v[32:47], a[20:23], a[24:27], v[32:47]
	s_waitcnt vmcnt(6)
	s_waitcnt lgkmcnt(0)
	s_barrier
	ds_read_b128 a[12:15], v81 offset:4096
	ds_read_b128 a[8:11], v81
	ds_read_b128 a[4:7], v82 offset:36864
	ds_read_b128 a[0:3], v82 offset:32768
	v_mfma_f32_32x32x16_bf16 v[16:31], a[16:19], a[28:31], v[16:31]
	v_lshl_add_u64 v[158:159], v[66:67], 0, s[30:31]
	s_nop 0
	v_lshl_add_u64 v[160:161], v[68:69], 0, s[30:31]
	s_nop 0
	s_nop 0
	s_nop 0
	v_lshl_add_u64 v[162:163], v[70:71], 0, s[30:31]
	s_nop 0
	v_mfma_f32_32x32x16_bf16 v[0:15], a[20:23], a[28:31], v[0:15]
	s_and_b32 m0, s32, 7
	s_lshl_b32 m0, m0, 12
	s_add_i32 m0, m0, 0x18000
	s_nop 0
	global_load_lds_dwordx4 v[158:159], off
	s_nop 0
	v_lshl_add_u64 v[164:165], v[72:73], 0, s[30:31]
	s_nop 0
	s_nop 0
	s_nop 0
	v_lshl_add_u64 v[166:167], v[74:75], 0, s[30:31]
	s_nop 0
	s_nop 0
	s_nop 0
	v_lshl_add_u64 v[168:169], v[76:77], 0, s[30:31]
	s_nop 0
	s_mov_b64 s[30:31], 0x300
	s_nop 0
	s_nop 0
	s_nop 0
	s_nop 0
	s_nop 0
	ds_read_b128 a[16:19], v84 offset:32768
	ds_read_b128 a[20:23], v84 offset:36864
	ds_read_b128 a[24:27], v83
	ds_read_b128 a[28:31], v83 offset:4096
	s_waitcnt lgkmcnt(4)
	v_mfma_f32_32x32x16_bf16 v[48:63], a[0:3], a[8:11], v[48:63]
	s_nop 0
	v_readfirstlane_b32 s42, v113
	v_mfma_f32_32x32x16_bf16 v[32:47], a[4:7], a[8:11], v[32:47]
	v_mfma_f32_32x32x16_bf16 v[16:31], a[0:3], a[12:15], v[16:31]
	s_and_b32 m0, s32, 7
	s_lshl_b32 m0, m0, 12
	s_add_i32 m0, m0, 0x18400
	s_nop 0
	global_load_lds_dwordx4 v[160:161], off
	v_mfma_f32_32x32x16_bf16 v[0:15], a[4:7], a[12:15], v[0:15]
	s_nop 0
	s_nop 0
	s_nop 0
	s_nop 0
	ds_read_b128 a[0:3], v86 offset:32768
	ds_read_b128 a[4:7], v86 offset:36864
	ds_read_b128 a[8:11], v85
	ds_read_b128 a[12:15], v85 offset:4096
	s_waitcnt lgkmcnt(5)
	v_mfma_f32_32x32x16_bf16 v[48:63], a[16:19], a[24:27], v[48:63]
	s_and_b32 m0, s32, 7
	s_lshl_b32 m0, m0, 12
	s_add_i32 m0, m0, 0x18800
	s_nop 0
	global_load_lds_dwordx4 v[162:163], off
	v_mfma_f32_32x32x16_bf16 v[32:47], a[20:23], a[24:27], v[32:47]
	s_waitcnt lgkmcnt(4)
	v_mfma_f32_32x32x16_bf16 v[16:31], a[16:19], a[28:31], v[16:31]
	v_mfma_f32_32x32x16_bf16 v[0:15], a[20:23], a[28:31], v[0:15]
	s_and_b32 m0, s32, 7
	s_lshl_b32 m0, m0, 12
	s_add_i32 m0, m0, 0x18c00
	s_nop 0
	global_load_lds_dwordx4 v[164:165], off
	s_nop 0
	s_nop 0
	s_nop 0
	s_nop 0
	ds_read_b128 a[16:19], v88 offset:32768
	ds_read_b128 a[20:23], v88 offset:36864
	ds_read_b128 a[24:27], v87
	ds_read_b128 a[28:31], v87 offset:4096
	s_waitcnt lgkmcnt(5)
	v_mfma_f32_32x32x16_bf16 v[48:63], a[0:3], a[8:11], v[48:63]
	v_mfma_f32_32x32x16_bf16 v[32:47], a[4:7], a[8:11], v[32:47]
	s_waitcnt lgkmcnt(4)
	v_mfma_f32_32x32x16_bf16 v[16:31], a[0:3], a[12:15], v[16:31]
	s_and_b32 m0, s32, 7
	s_lshl_b32 m0, m0, 11
	s_add_i32 m0, m0, 0x20000
	s_nop 0
	global_load_lds_dwordx4 v[166:167], off
	v_mfma_f32_32x32x16_bf16 v[0:15], a[4:7], a[12:15], v[0:15]
	s_nop 0
	s_nop 0
	s_nop 0
	s_nop 0
	s_waitcnt lgkmcnt(1)
	v_mfma_f32_32x32x16_bf16 v[48:63], a[16:19], a[24:27], v[48:63]
	s_and_b32 m0, s32, 7
	s_lshl_b32 m0, m0, 11
	s_add_i32 m0, m0, 0x20400
	s_nop 0
	global_load_lds_dwordx4 v[168:169], off
	v_mfma_f32_32x32x16_bf16 v[32:47], a[20:23], a[24:27], v[32:47]
	s_waitcnt vmcnt(6)
	s_waitcnt lgkmcnt(0)
	s_barrier
	ds_read_b128 a[12:15], v81 offset:53248
	ds_read_b128 a[8:11], v81 offset:49152
	ds_read_b128 a[4:7], v89
	ds_read_b128 a[0:3], v91
	v_mfma_f32_32x32x16_bf16 v[16:31], a[16:19], a[28:31], v[16:31]
	v_lshl_add_u64 v[170:171], v[66:67], 0, s[30:31]
	s_nop 0
	v_lshl_add_u64 v[172:173], v[68:69], 0, s[30:31]
	s_nop 0
	v_readfirstlane_b32 s43, v114
	s_nop 0
	v_lshl_add_u64 v[174:175], v[70:71], 0, s[30:31]
	s_nop 0
	v_mfma_f32_32x32x16_bf16 v[0:15], a[20:23], a[28:31], v[0:15]
	s_and_b32 m0, s32, 7
	s_lshl_b32 m0, m0, 12
	s_add_i32 m0, m0, 0x0
	s_nop 0
	global_load_lds_dwordx4 v[170:171], off
	s_nop 0
	v_lshl_add_u64 v[176:177], v[72:73], 0, s[30:31]
	s_nop 0
	v_readfirstlane_b32 s44, v115
	s_nop 0
	v_lshl_add_u64 v[178:179], v[74:75], 0, s[30:31]
	s_nop 0
	v_readfirstlane_b32 s45, v116
	s_nop 0
	v_lshl_add_u64 v[180:181], v[76:77], 0, s[30:31]
	s_nop 0
	s_mov_b64 s[30:31], 0x380
	s_nop 0
	s_nop 0
	s_nop 0
	s_nop 0
	s_nop 0
	ds_read_b128 a[16:19], v92
	ds_read_b128 a[20:23], v90
	ds_read_b128 a[24:27], v83 offset:49152
	ds_read_b128 a[28:31], v83 offset:53248
	s_waitcnt lgkmcnt(4)
	v_mfma_f32_32x32x16_bf16 v[48:63], a[0:3], a[8:11], v[48:63]
	s_nop 0
	v_readfirstlane_b32 s36, v119
	v_readfirstlane_b32 s46, v117
	v_readfirstlane_b32 s47, v118
	v_mfma_f32_32x32x16_bf16 v[32:47], a[4:7], a[8:11], v[32:47]
	v_mfma_f32_32x32x16_bf16 v[16:31], a[0:3], a[12:15], v[16:31]
	s_and_b32 m0, s32, 7
	s_lshl_b32 m0, m0, 12
	s_add_i32 m0, m0, 0x400
	s_nop 0
	global_load_lds_dwordx4 v[172:173], off
	v_mfma_f32_32x32x16_bf16 v[0:15], a[4:7], a[12:15], v[0:15]
	s_nop 0
	s_nop 0
	s_nop 0
	s_nop 0
	ds_read_b128 a[0:3], v94
	ds_read_b128 a[4:7], v93
	ds_read_b128 a[8:11], v85 offset:49152
	ds_read_b128 a[12:15], v85 offset:53248
	s_waitcnt lgkmcnt(5)
	v_mfma_f32_32x32x16_bf16 v[48:63], a[16:19], a[24:27], v[48:63]
	s_and_b32 m0, s32, 7
	s_lshl_b32 m0, m0, 12
	s_add_i32 m0, m0, 0x800
	s_nop 0
	global_load_lds_dwordx4 v[174:175], off
	v_mfma_f32_32x32x16_bf16 v[32:47], a[20:23], a[24:27], v[32:47]
	s_waitcnt lgkmcnt(4)
	v_mfma_f32_32x32x16_bf16 v[16:31], a[16:19], a[28:31], v[16:31]
	v_mfma_f32_32x32x16_bf16 v[0:15], a[20:23], a[28:31], v[0:15]
	s_and_b32 m0, s32, 7
	s_lshl_b32 m0, m0, 12
	s_add_i32 m0, m0, 0xc00
	s_nop 0
	global_load_lds_dwordx4 v[176:177], off
	s_nop 0
	s_nop 0
	s_nop 0
	s_nop 0
	ds_read_b128 a[16:19], v96
	ds_read_b128 a[20:23], v95
	ds_read_b128 a[24:27], v87 offset:49152
	ds_read_b128 a[28:31], v87 offset:53248
	s_waitcnt lgkmcnt(5)
	v_mfma_f32_32x32x16_bf16 v[48:63], a[0:3], a[8:11], v[48:63]
	v_mfma_f32_32x32x16_bf16 v[32:47], a[4:7], a[8:11], v[32:47]
	s_waitcnt lgkmcnt(4)
	v_mfma_f32_32x32x16_bf16 v[16:31], a[0:3], a[12:15], v[16:31]
	s_and_b32 m0, s32, 7
	s_lshl_b32 m0, m0, 11
	s_add_i32 m0, m0, 0x8000
	s_nop 0
	global_load_lds_dwordx4 v[178:179], off
	v_mfma_f32_32x32x16_bf16 v[0:15], a[4:7], a[12:15], v[0:15]
	s_nop 0
	s_nop 0
	s_nop 0
	s_nop 0
	s_waitcnt lgkmcnt(1)
	v_mfma_f32_32x32x16_bf16 v[48:63], a[16:19], a[24:27], v[48:63]
	s_and_b32 m0, s32, 7
	s_lshl_b32 m0, m0, 11
	s_add_i32 m0, m0, 0x8400
	s_nop 0
	global_load_lds_dwordx4 v[180:181], off
	v_mfma_f32_32x32x16_bf16 v[32:47], a[20:23], a[24:27], v[32:47]
	s_waitcnt vmcnt(6)
	s_waitcnt lgkmcnt(0)
	s_barrier
	ds_read_b128 a[12:15], v100
	ds_read_b128 a[8:11], v99
	ds_read_b128 a[4:7], v98
	ds_read_b128 a[0:3], v97
	v_mfma_f32_32x32x16_bf16 v[16:31], a[16:19], a[28:31], v[16:31]
	v_lshl_add_u64 v[158:159], v[66:67], 0, s[30:31]
	s_nop 0
	v_lshl_add_u64 v[160:161], v[68:69], 0, s[30:31]
	s_nop 0
	v_readfirstlane_b32 s37, v120
	s_nop 0
	v_lshl_add_u64 v[162:163], v[70:71], 0, s[30:31]
	s_nop 0
	v_mfma_f32_32x32x16_bf16 v[0:15], a[20:23], a[28:31], v[0:15]
	s_and_b32 m0, s32, 7
	s_lshl_b32 m0, m0, 12
	s_add_i32 m0, m0, 0xc000
	s_nop 0
	global_load_lds_dwordx4 v[158:159], off
	s_nop 0
	v_lshl_add_u64 v[164:165], v[72:73], 0, s[30:31]
	s_nop 0
	v_readfirstlane_b32 s38, v121
	s_nop 0
	v_lshl_add_u64 v[166:167], v[74:75], 0, s[30:31]
	s_nop 0
	v_readfirstlane_b32 s39, v122
	s_nop 0
	v_lshl_add_u64 v[168:169], v[76:77], 0, s[30:31]
	s_nop 0
	s_mov_b64 s[30:31], 0x400
	s_nop 0
	s_nop 0
	s_nop 0
	s_nop 0
	s_nop 0
	ds_read_b128 a[16:19], v101
	ds_read_b128 a[20:23], v102
	ds_read_b128 a[24:27], v103
	ds_read_b128 a[28:31], v104
	s_waitcnt lgkmcnt(4)
	v_mfma_f32_32x32x16_bf16 v[48:63], a[0:3], a[8:11], v[48:63]
	s_nop 0
	v_readfirstlane_b32 s20, v125
	v_readfirstlane_b32 s40, v123
	v_readfirstlane_b32 s41, v124
	v_mfma_f32_32x32x16_bf16 v[32:47], a[4:7], a[8:11], v[32:47]
	v_mfma_f32_32x32x16_bf16 v[16:31], a[0:3], a[12:15], v[16:31]
	s_and_b32 m0, s32, 7
	s_lshl_b32 m0, m0, 12
	s_add_i32 m0, m0, 0xc400
	s_nop 0
	global_load_lds_dwordx4 v[160:161], off
	v_mfma_f32_32x32x16_bf16 v[0:15], a[4:7], a[12:15], v[0:15]
	s_nop 0
	s_nop 0
	s_nop 0
	s_nop 0
	ds_read_b128 a[0:3], v105
	ds_read_b128 a[4:7], v106
	ds_read_b128 a[8:11], v107
	ds_read_b128 a[12:15], v108
	s_waitcnt lgkmcnt(5)
	v_mfma_f32_32x32x16_bf16 v[48:63], a[16:19], a[24:27], v[48:63]
	s_and_b32 m0, s32, 7
	s_lshl_b32 m0, m0, 12
	s_add_i32 m0, m0, 0xc800
	s_nop 0
	global_load_lds_dwordx4 v[162:163], off
	v_mfma_f32_32x32x16_bf16 v[32:47], a[20:23], a[24:27], v[32:47]
	s_waitcnt lgkmcnt(4)
	v_mfma_f32_32x32x16_bf16 v[16:31], a[16:19], a[28:31], v[16:31]
	v_mfma_f32_32x32x16_bf16 v[0:15], a[20:23], a[28:31], v[0:15]
	s_and_b32 m0, s32, 7
	s_lshl_b32 m0, m0, 12
	s_add_i32 m0, m0, 0xcc00
	s_nop 0
	global_load_lds_dwordx4 v[164:165], off
	s_nop 0
	s_nop 0
	s_nop 0
	s_nop 0
	ds_read_b128 a[16:19], v109
	ds_read_b128 a[20:23], v110
	ds_read_b128 a[24:27], v111
	ds_read_b128 a[28:31], v112
	s_waitcnt lgkmcnt(5)
	v_mfma_f32_32x32x16_bf16 v[48:63], a[0:3], a[8:11], v[48:63]
	v_mfma_f32_32x32x16_bf16 v[32:47], a[4:7], a[8:11], v[32:47]
	s_waitcnt lgkmcnt(4)
	v_mfma_f32_32x32x16_bf16 v[16:31], a[0:3], a[12:15], v[16:31]
	s_and_b32 m0, s32, 7
	s_lshl_b32 m0, m0, 11
	s_add_i32 m0, m0, 0x14000
	s_nop 0
	global_load_lds_dwordx4 v[166:167], off
	v_mfma_f32_32x32x16_bf16 v[0:15], a[4:7], a[12:15], v[0:15]
	s_nop 0
	s_nop 0
	s_nop 0
	s_nop 0
	s_waitcnt lgkmcnt(1)
	v_mfma_f32_32x32x16_bf16 v[48:63], a[16:19], a[24:27], v[48:63]
	s_and_b32 m0, s32, 7
	s_lshl_b32 m0, m0, 11
	s_add_i32 m0, m0, 0x14400
	s_nop 0
	global_load_lds_dwordx4 v[168:169], off
	v_mfma_f32_32x32x16_bf16 v[32:47], a[20:23], a[24:27], v[32:47]
	s_waitcnt vmcnt(6)
	s_waitcnt lgkmcnt(0)
	s_barrier
	ds_read_b128 a[12:15], v81 offset:4096
	ds_read_b128 a[8:11], v81
	ds_read_b128 a[4:7], v82 offset:36864
	ds_read_b128 a[0:3], v82 offset:32768
	v_mfma_f32_32x32x16_bf16 v[16:31], a[16:19], a[28:31], v[16:31]
	v_lshl_add_u64 v[170:171], v[66:67], 0, s[30:31]
	s_nop 0
	v_lshl_add_u64 v[172:173], v[68:69], 0, s[30:31]
	s_nop 0
	v_readfirstlane_b32 s21, v126
	s_nop 0
	v_lshl_add_u64 v[174:175], v[70:71], 0, s[30:31]
	s_nop 0
	v_mfma_f32_32x32x16_bf16 v[0:15], a[20:23], a[28:31], v[0:15]
	s_and_b32 m0, s32, 7
	s_lshl_b32 m0, m0, 12
	s_add_i32 m0, m0, 0x18000
	s_nop 0
	global_load_lds_dwordx4 v[170:171], off
	s_nop 0
	v_lshl_add_u64 v[176:177], v[72:73], 0, s[30:31]
	s_nop 0
	v_readfirstlane_b32 s23, v127
	s_nop 0
	v_lshl_add_u64 v[178:179], v[74:75], 0, s[30:31]
	s_nop 0
	v_readfirstlane_b32 s28, v128
	s_nop 0
	v_lshl_add_u64 v[180:181], v[76:77], 0, s[30:31]
	s_nop 0
	s_mov_b64 s[30:31], 0x480
	s_nop 0
	s_nop 0
	s_nop 0
	s_nop 0
	s_nop 0
	ds_read_b128 a[16:19], v84 offset:32768
	ds_read_b128 a[20:23], v84 offset:36864
	ds_read_b128 a[24:27], v83
	ds_read_b128 a[28:31], v83 offset:4096
	s_waitcnt lgkmcnt(4)
	v_mfma_f32_32x32x16_bf16 v[48:63], a[0:3], a[8:11], v[48:63]
	s_nop 0
	v_lshl_add_u64 v[164:165], v[72:73], 0, s[30:31]
	v_readfirstlane_b32 s29, v130
	v_readfirstlane_b32 s33, v129
	v_mfma_f32_32x32x16_bf16 v[32:47], a[4:7], a[8:11], v[32:47]
	v_mfma_f32_32x32x16_bf16 v[16:31], a[0:3], a[12:15], v[16:31]
	s_and_b32 m0, s32, 7
	s_lshl_b32 m0, m0, 12
	s_add_i32 m0, m0, 0x18400
	s_nop 0
	global_load_lds_dwordx4 v[172:173], off
	v_mfma_f32_32x32x16_bf16 v[0:15], a[4:7], a[12:15], v[0:15]
	s_nop 0
	s_nop 0
	s_nop 0
	s_nop 0
	ds_read_b128 a[0:3], v86 offset:32768
	ds_read_b128 a[4:7], v86 offset:36864
	ds_read_b128 a[8:11], v85
	ds_read_b128 a[12:15], v85 offset:4096
	s_waitcnt lgkmcnt(5)
	v_mfma_f32_32x32x16_bf16 v[48:63], a[16:19], a[24:27], v[48:63]
	s_and_b32 m0, s32, 7
	s_lshl_b32 m0, m0, 12
	s_add_i32 m0, m0, 0x18800
	s_nop 0
	global_load_lds_dwordx4 v[174:175], off
	v_mfma_f32_32x32x16_bf16 v[32:47], a[20:23], a[24:27], v[32:47]
	s_waitcnt lgkmcnt(4)
	v_mfma_f32_32x32x16_bf16 v[16:31], a[16:19], a[28:31], v[16:31]
	v_mfma_f32_32x32x16_bf16 v[0:15], a[20:23], a[28:31], v[0:15]
	s_and_b32 m0, s32, 7
	s_lshl_b32 m0, m0, 12
	s_add_i32 m0, m0, 0x18c00
	s_nop 0
	global_load_lds_dwordx4 v[176:177], off
	s_nop 0
	s_nop 0
	s_nop 0
	s_nop 0
	ds_read_b128 a[16:19], v88 offset:32768
	ds_read_b128 a[20:23], v88 offset:36864
	ds_read_b128 a[24:27], v87
	ds_read_b128 a[28:31], v87 offset:4096
	s_waitcnt lgkmcnt(5)
	v_mfma_f32_32x32x16_bf16 v[48:63], a[0:3], a[8:11], v[48:63]
	v_mfma_f32_32x32x16_bf16 v[32:47], a[4:7], a[8:11], v[32:47]
	s_waitcnt lgkmcnt(4)
	v_mfma_f32_32x32x16_bf16 v[16:31], a[0:3], a[12:15], v[16:31]
	s_and_b32 m0, s32, 7
	s_lshl_b32 m0, m0, 11
	s_add_i32 m0, m0, 0x20000
	s_nop 0
	global_load_lds_dwordx4 v[178:179], off
	v_mfma_f32_32x32x16_bf16 v[0:15], a[4:7], a[12:15], v[0:15]
	s_nop 0
	s_nop 0
	s_nop 0
	s_nop 0
	s_waitcnt lgkmcnt(1)
	v_mfma_f32_32x32x16_bf16 v[48:63], a[16:19], a[24:27], v[48:63]
	s_and_b32 m0, s32, 7
	s_lshl_b32 m0, m0, 11
	s_add_i32 m0, m0, 0x20400
	s_nop 0
	global_load_lds_dwordx4 v[180:181], off
	v_mfma_f32_32x32x16_bf16 v[32:47], a[20:23], a[24:27], v[32:47]
	s_waitcnt vmcnt(6)
	s_waitcnt lgkmcnt(0)
	s_barrier
	ds_read_b128 a[12:15], v81 offset:53248
	ds_read_b128 a[8:11], v81 offset:49152
	ds_read_b128 a[4:7], v89
	ds_read_b128 a[0:3], v91
	v_mfma_f32_32x32x16_bf16 v[16:31], a[16:19], a[28:31], v[16:31]
	v_lshl_add_u64 v[158:159], v[66:67], 0, s[30:31]
	s_nop 0
	v_lshl_add_u64 v[160:161], v[68:69], 0, s[30:31]
	s_nop 0
	s_nop 0
	s_nop 0
	v_lshl_add_u64 v[162:163], v[70:71], 0, s[30:31]
	s_nop 0
	v_mfma_f32_32x32x16_bf16 v[0:15], a[20:23], a[28:31], v[0:15]
	s_and_b32 m0, s32, 7
	s_lshl_b32 m0, m0, 12
	s_add_i32 m0, m0, 0x0
	s_nop 0
	global_load_lds_dwordx4 v[158:159], off
	s_nop 0
	s_nop 0
	s_nop 0
	s_nop 0
	v_lshl_add_u64 v[166:167], v[74:75], 0, s[30:31]
	s_nop 0
	s_nop 0
	s_nop 0
	v_lshl_add_u64 v[168:169], v[76:77], 0, s[30:31]
	s_nop 0
	s_mov_b64 s[30:31], 0x500
	s_nop 0
	s_nop 0
	s_nop 0
	s_nop 0
	s_nop 0
	ds_read_b128 a[16:19], v92
	ds_read_b128 a[20:23], v90
	ds_read_b128 a[24:27], v83 offset:49152
	ds_read_b128 a[28:31], v83 offset:53248
	s_waitcnt lgkmcnt(4)
	v_mfma_f32_32x32x16_bf16 v[48:63], a[0:3], a[8:11], v[48:63]
	s_nop 0
	v_lshl_add_u64 v[176:177], v[72:73], 0, s[30:31]
	v_mfma_f32_32x32x16_bf16 v[32:47], a[4:7], a[8:11], v[32:47]
	v_mfma_f32_32x32x16_bf16 v[16:31], a[0:3], a[12:15], v[16:31]
	s_and_b32 m0, s32, 7
	s_lshl_b32 m0, m0, 12
	s_add_i32 m0, m0, 0x400
	s_nop 0
	global_load_lds_dwordx4 v[160:161], off
	v_mfma_f32_32x32x16_bf16 v[0:15], a[4:7], a[12:15], v[0:15]
	s_nop 0
	s_nop 0
	s_nop 0
	s_nop 0
	ds_read_b128 a[0:3], v94
	ds_read_b128 a[4:7], v93
	ds_read_b128 a[8:11], v85 offset:49152
	ds_read_b128 a[12:15], v85 offset:53248
	s_waitcnt lgkmcnt(5)
	v_mfma_f32_32x32x16_bf16 v[48:63], a[16:19], a[24:27], v[48:63]
	s_and_b32 m0, s32, 7
	s_lshl_b32 m0, m0, 12
	s_add_i32 m0, m0, 0x800
	s_nop 0
	global_load_lds_dwordx4 v[162:163], off
	v_mfma_f32_32x32x16_bf16 v[32:47], a[20:23], a[24:27], v[32:47]
	s_waitcnt lgkmcnt(4)
	v_mfma_f32_32x32x16_bf16 v[16:31], a[16:19], a[28:31], v[16:31]
	v_mfma_f32_32x32x16_bf16 v[0:15], a[20:23], a[28:31], v[0:15]
	s_and_b32 m0, s32, 7
	s_lshl_b32 m0, m0, 12
	s_add_i32 m0, m0, 0xc00
	s_nop 0
	global_load_lds_dwordx4 v[164:165], off
	s_nop 0
	s_nop 0
	s_nop 0
	s_nop 0
	ds_read_b128 a[16:19], v96
	ds_read_b128 a[20:23], v95
	ds_read_b128 a[24:27], v87 offset:49152
	ds_read_b128 a[28:31], v87 offset:53248
	s_waitcnt lgkmcnt(5)
	v_mfma_f32_32x32x16_bf16 v[48:63], a[0:3], a[8:11], v[48:63]
	v_mfma_f32_32x32x16_bf16 v[32:47], a[4:7], a[8:11], v[32:47]
	s_waitcnt lgkmcnt(4)
	v_mfma_f32_32x32x16_bf16 v[16:31], a[0:3], a[12:15], v[16:31]
	s_and_b32 m0, s32, 7
	s_lshl_b32 m0, m0, 11
	s_add_i32 m0, m0, 0x8000
	s_nop 0
	global_load_lds_dwordx4 v[166:167], off
	v_mfma_f32_32x32x16_bf16 v[0:15], a[4:7], a[12:15], v[0:15]
	s_nop 0
	s_nop 0
	s_nop 0
	s_nop 0
	s_waitcnt lgkmcnt(1)
	v_mfma_f32_32x32x16_bf16 v[48:63], a[16:19], a[24:27], v[48:63]
	s_and_b32 m0, s32, 7
	s_lshl_b32 m0, m0, 11
	s_add_i32 m0, m0, 0x8400
	s_nop 0
	global_load_lds_dwordx4 v[168:169], off
	v_mfma_f32_32x32x16_bf16 v[32:47], a[20:23], a[24:27], v[32:47]
	s_waitcnt vmcnt(6)
	s_waitcnt lgkmcnt(0)
	s_barrier
	ds_read_b128 a[12:15], v100
	ds_read_b128 a[8:11], v99
	ds_read_b128 a[4:7], v98
	ds_read_b128 a[0:3], v97
	v_mfma_f32_32x32x16_bf16 v[16:31], a[16:19], a[28:31], v[16:31]
	v_lshl_add_u64 v[170:171], v[66:67], 0, s[30:31]
	s_nop 0
	v_lshl_add_u64 v[172:173], v[68:69], 0, s[30:31]
	s_nop 0
	s_nop 0
	s_nop 0
	v_lshl_add_u64 v[174:175], v[70:71], 0, s[30:31]
	s_nop 0
	v_mfma_f32_32x32x16_bf16 v[0:15], a[20:23], a[28:31], v[0:15]
	s_and_b32 m0, s32, 7
	s_lshl_b32 m0, m0, 12
	s_add_i32 m0, m0, 0xc000
	s_nop 0
	global_load_lds_dwordx4 v[170:171], off
	s_nop 0
	s_nop 0
	s_nop 0
	s_nop 0
	v_lshl_add_u64 v[178:179], v[74:75], 0, s[30:31]
	s_nop 0
	s_nop 0
	s_nop 0
	v_lshl_add_u64 v[180:181], v[76:77], 0, s[30:31]
	s_nop 0
	s_mov_b64 s[30:31], 0x580
	s_nop 0
	s_nop 0
	s_nop 0
	s_nop 0
	s_nop 0
	ds_read_b128 a[16:19], v101
	ds_read_b128 a[20:23], v102
	ds_read_b128 a[24:27], v103
	ds_read_b128 a[28:31], v104
	s_waitcnt lgkmcnt(4)
	v_mfma_f32_32x32x16_bf16 v[48:63], a[0:3], a[8:11], v[48:63]
	s_nop 0
	v_lshl_add_u64 v[164:165], v[72:73], 0, s[30:31]
	v_mfma_f32_32x32x16_bf16 v[32:47], a[4:7], a[8:11], v[32:47]
	v_mfma_f32_32x32x16_bf16 v[16:31], a[0:3], a[12:15], v[16:31]
	s_and_b32 m0, s32, 7
	s_lshl_b32 m0, m0, 12
	s_add_i32 m0, m0, 0xc400
	s_nop 0
	global_load_lds_dwordx4 v[172:173], off
	v_mfma_f32_32x32x16_bf16 v[0:15], a[4:7], a[12:15], v[0:15]
	s_nop 0
	s_nop 0
	s_nop 0
	s_nop 0
	ds_read_b128 a[0:3], v105
	ds_read_b128 a[4:7], v106
	ds_read_b128 a[8:11], v107
	ds_read_b128 a[12:15], v108
	s_waitcnt lgkmcnt(5)
	v_mfma_f32_32x32x16_bf16 v[48:63], a[16:19], a[24:27], v[48:63]
	s_and_b32 m0, s32, 7
	s_lshl_b32 m0, m0, 12
	s_add_i32 m0, m0, 0xc800
	s_nop 0
	global_load_lds_dwordx4 v[174:175], off
	v_mfma_f32_32x32x16_bf16 v[32:47], a[20:23], a[24:27], v[32:47]
	s_waitcnt lgkmcnt(4)
	v_mfma_f32_32x32x16_bf16 v[16:31], a[16:19], a[28:31], v[16:31]
	v_mfma_f32_32x32x16_bf16 v[0:15], a[20:23], a[28:31], v[0:15]
	s_and_b32 m0, s32, 7
	s_lshl_b32 m0, m0, 12
	s_add_i32 m0, m0, 0xcc00
	s_nop 0
	global_load_lds_dwordx4 v[176:177], off
	s_nop 0
	s_nop 0
	s_nop 0
	s_nop 0
	ds_read_b128 a[16:19], v109
	ds_read_b128 a[20:23], v110
	ds_read_b128 a[24:27], v111
	ds_read_b128 a[28:31], v112
	s_waitcnt lgkmcnt(5)
	v_mfma_f32_32x32x16_bf16 v[48:63], a[0:3], a[8:11], v[48:63]
	v_mfma_f32_32x32x16_bf16 v[32:47], a[4:7], a[8:11], v[32:47]
	s_waitcnt lgkmcnt(4)
	v_mfma_f32_32x32x16_bf16 v[16:31], a[0:3], a[12:15], v[16:31]
	s_and_b32 m0, s32, 7
	s_lshl_b32 m0, m0, 11
	s_add_i32 m0, m0, 0x14000
	s_nop 0
	global_load_lds_dwordx4 v[178:179], off
	v_mfma_f32_32x32x16_bf16 v[0:15], a[4:7], a[12:15], v[0:15]
	s_nop 0
	s_nop 0
	s_nop 0
	s_nop 0
	s_waitcnt lgkmcnt(1)
	v_mfma_f32_32x32x16_bf16 v[48:63], a[16:19], a[24:27], v[48:63]
	s_and_b32 m0, s32, 7
	s_lshl_b32 m0, m0, 11
	s_add_i32 m0, m0, 0x14400
	s_nop 0
	global_load_lds_dwordx4 v[180:181], off
	v_mfma_f32_32x32x16_bf16 v[32:47], a[20:23], a[24:27], v[32:47]
	s_waitcnt vmcnt(6)
	s_waitcnt lgkmcnt(0)
	s_barrier
	ds_read_b128 a[12:15], v81 offset:4096
	ds_read_b128 a[8:11], v81
	ds_read_b128 a[4:7], v82 offset:36864
	ds_read_b128 a[0:3], v82 offset:32768
	v_mfma_f32_32x32x16_bf16 v[16:31], a[16:19], a[28:31], v[16:31]
	v_lshl_add_u64 v[158:159], v[66:67], 0, s[30:31]
	s_nop 0
	v_lshl_add_u64 v[160:161], v[68:69], 0, s[30:31]
	s_nop 0
	s_nop 0
	s_nop 0
	v_lshl_add_u64 v[162:163], v[70:71], 0, s[30:31]
	s_nop 0
	v_mfma_f32_32x32x16_bf16 v[0:15], a[20:23], a[28:31], v[0:15]
	s_and_b32 m0, s32, 7
	s_lshl_b32 m0, m0, 12
	s_add_i32 m0, m0, 0x18000
	s_nop 0
	global_load_lds_dwordx4 v[158:159], off
	s_nop 0
	s_nop 0
	s_nop 0
	s_nop 0
	v_lshl_add_u64 v[166:167], v[74:75], 0, s[30:31]
	s_nop 0
	s_nop 0
	s_nop 0
	v_lshl_add_u64 v[168:169], v[76:77], 0, s[30:31]
	s_nop 0
	s_mov_b64 s[30:31], 0x600
	s_nop 0
	s_nop 0
	s_nop 0
	s_nop 0
	s_nop 0
	ds_read_b128 a[16:19], v84 offset:32768
	ds_read_b128 a[20:23], v84 offset:36864
	ds_read_b128 a[24:27], v83
	ds_read_b128 a[28:31], v83 offset:4096
	s_waitcnt lgkmcnt(4)
	v_mfma_f32_32x32x16_bf16 v[48:63], a[0:3], a[8:11], v[48:63]
	s_nop 0
	v_mfma_f32_32x32x16_bf16 v[32:47], a[4:7], a[8:11], v[32:47]
	v_mfma_f32_32x32x16_bf16 v[16:31], a[0:3], a[12:15], v[16:31]
	s_and_b32 m0, s32, 7
	s_lshl_b32 m0, m0, 12
	s_add_i32 m0, m0, 0x18400
	s_nop 0
	global_load_lds_dwordx4 v[160:161], off
	v_mfma_f32_32x32x16_bf16 v[0:15], a[4:7], a[12:15], v[0:15]
	s_nop 0
	s_nop 0
	s_nop 0
	s_nop 0
	ds_read_b128 a[0:3], v86 offset:32768
	ds_read_b128 a[4:7], v86 offset:36864
	ds_read_b128 a[8:11], v85
	ds_read_b128 a[12:15], v85 offset:4096
	s_waitcnt lgkmcnt(5)
	v_mfma_f32_32x32x16_bf16 v[48:63], a[16:19], a[24:27], v[48:63]
	s_and_b32 m0, s32, 7
	s_lshl_b32 m0, m0, 12
	s_add_i32 m0, m0, 0x18800
	s_nop 0
	global_load_lds_dwordx4 v[162:163], off
	v_mfma_f32_32x32x16_bf16 v[32:47], a[20:23], a[24:27], v[32:47]
	s_waitcnt lgkmcnt(4)
	v_mfma_f32_32x32x16_bf16 v[16:31], a[16:19], a[28:31], v[16:31]
	v_mfma_f32_32x32x16_bf16 v[0:15], a[20:23], a[28:31], v[0:15]
	s_and_b32 m0, s32, 7
	s_lshl_b32 m0, m0, 12
	s_add_i32 m0, m0, 0x18c00
	s_nop 0
	global_load_lds_dwordx4 v[164:165], off
	s_nop 0
	s_nop 0
	s_nop 0
	s_nop 0
	ds_read_b128 a[16:19], v88 offset:32768
	ds_read_b128 a[20:23], v88 offset:36864
	ds_read_b128 a[24:27], v87
	ds_read_b128 a[28:31], v87 offset:4096
	s_waitcnt lgkmcnt(5)
	v_mfma_f32_32x32x16_bf16 v[48:63], a[0:3], a[8:11], v[48:63]
	v_mfma_f32_32x32x16_bf16 v[32:47], a[4:7], a[8:11], v[32:47]
	s_waitcnt lgkmcnt(4)
	v_mfma_f32_32x32x16_bf16 v[16:31], a[0:3], a[12:15], v[16:31]
	s_and_b32 m0, s32, 7
	s_lshl_b32 m0, m0, 11
	s_add_i32 m0, m0, 0x20000
	s_nop 0
	global_load_lds_dwordx4 v[166:167], off
	v_mfma_f32_32x32x16_bf16 v[0:15], a[4:7], a[12:15], v[0:15]
	s_nop 0
	s_nop 0
	s_nop 0
	s_nop 0
	s_waitcnt lgkmcnt(1)
	v_mfma_f32_32x32x16_bf16 v[48:63], a[16:19], a[24:27], v[48:63]
	s_and_b32 m0, s32, 7
	s_lshl_b32 m0, m0, 11
	s_add_i32 m0, m0, 0x20400
	s_nop 0
	global_load_lds_dwordx4 v[168:169], off
	v_mfma_f32_32x32x16_bf16 v[32:47], a[20:23], a[24:27], v[32:47]
	s_waitcnt vmcnt(6)
	s_waitcnt lgkmcnt(0)
	s_barrier
	ds_read_b128 a[12:15], v81 offset:53248
	ds_read_b128 a[8:11], v81 offset:49152
	ds_read_b128 a[4:7], v89
	ds_read_b128 a[0:3], v91
	v_mfma_f32_32x32x16_bf16 v[16:31], a[16:19], a[28:31], v[16:31]
	v_lshl_add_u64 v[170:171], v[66:67], 0, s[30:31]
	s_nop 0
	v_lshl_add_u64 v[172:173], v[68:69], 0, s[30:31]
	s_nop 0
	s_nop 0
	s_nop 0
	v_lshl_add_u64 v[174:175], v[70:71], 0, s[30:31]
	s_nop 0
	v_mfma_f32_32x32x16_bf16 v[0:15], a[20:23], a[28:31], v[0:15]
	s_and_b32 m0, s32, 7
	s_lshl_b32 m0, m0, 12
	s_add_i32 m0, m0, 0x0
	s_nop 0
	global_load_lds_dwordx4 v[170:171], off
	s_nop 0
	v_lshl_add_u64 v[176:177], v[72:73], 0, s[30:31]
	s_nop 0
	s_nop 0
	s_nop 0
	v_lshl_add_u64 v[178:179], v[74:75], 0, s[30:31]
	s_nop 0
	s_nop 0
	s_nop 0
	v_lshl_add_u64 v[180:181], v[76:77], 0, s[30:31]
	s_nop 0
	s_mov_b64 s[30:31], 0x680
	s_nop 0
	s_nop 0
	s_nop 0
	s_nop 0
	s_nop 0
	ds_read_b128 a[16:19], v92
	ds_read_b128 a[20:23], v90
	ds_read_b128 a[24:27], v83 offset:49152
	ds_read_b128 a[28:31], v83 offset:53248
	s_waitcnt lgkmcnt(4)
	v_mfma_f32_32x32x16_bf16 v[48:63], a[0:3], a[8:11], v[48:63]
	s_nop 0
	v_mfma_f32_32x32x16_bf16 v[32:47], a[4:7], a[8:11], v[32:47]
	v_mfma_f32_32x32x16_bf16 v[16:31], a[0:3], a[12:15], v[16:31]
	s_and_b32 m0, s32, 7
	s_lshl_b32 m0, m0, 12
	s_add_i32 m0, m0, 0x400
	s_nop 0
	global_load_lds_dwordx4 v[172:173], off
	v_mfma_f32_32x32x16_bf16 v[0:15], a[4:7], a[12:15], v[0:15]
	s_nop 0
	s_nop 0
	s_nop 0
	s_nop 0
	ds_read_b128 a[0:3], v94
	ds_read_b128 a[4:7], v93
	ds_read_b128 a[8:11], v85 offset:49152
	ds_read_b128 a[12:15], v85 offset:53248
	s_waitcnt lgkmcnt(5)
	v_mfma_f32_32x32x16_bf16 v[48:63], a[16:19], a[24:27], v[48:63]
	s_and_b32 m0, s32, 7
	s_lshl_b32 m0, m0, 12
	s_add_i32 m0, m0, 0x800
	s_nop 0
	global_load_lds_dwordx4 v[174:175], off
	v_mfma_f32_32x32x16_bf16 v[32:47], a[20:23], a[24:27], v[32:47]
	s_waitcnt lgkmcnt(4)
	v_mfma_f32_32x32x16_bf16 v[16:31], a[16:19], a[28:31], v[16:31]
	v_mfma_f32_32x32x16_bf16 v[0:15], a[20:23], a[28:31], v[0:15]
	s_and_b32 m0, s32, 7
	s_lshl_b32 m0, m0, 12
	s_add_i32 m0, m0, 0xc00
	s_nop 0
	global_load_lds_dwordx4 v[176:177], off
	s_nop 0
	s_nop 0
	s_nop 0
	s_nop 0
	ds_read_b128 a[16:19], v96
	ds_read_b128 a[20:23], v95
	ds_read_b128 a[24:27], v87 offset:49152
	ds_read_b128 a[28:31], v87 offset:53248
	s_waitcnt lgkmcnt(5)
	v_mfma_f32_32x32x16_bf16 v[48:63], a[0:3], a[8:11], v[48:63]
	v_mfma_f32_32x32x16_bf16 v[32:47], a[4:7], a[8:11], v[32:47]
	s_waitcnt lgkmcnt(4)
	v_mfma_f32_32x32x16_bf16 v[16:31], a[0:3], a[12:15], v[16:31]
	s_and_b32 m0, s32, 7
	s_lshl_b32 m0, m0, 11
	s_add_i32 m0, m0, 0x8000
	s_nop 0
	global_load_lds_dwordx4 v[178:179], off
	v_mfma_f32_32x32x16_bf16 v[0:15], a[4:7], a[12:15], v[0:15]
	s_nop 0
	s_nop 0
	s_nop 0
	s_nop 0
	s_waitcnt lgkmcnt(1)
	v_mfma_f32_32x32x16_bf16 v[48:63], a[16:19], a[24:27], v[48:63]
	s_and_b32 m0, s32, 7
	s_lshl_b32 m0, m0, 11
	s_add_i32 m0, m0, 0x8400
	s_nop 0
	global_load_lds_dwordx4 v[180:181], off
	v_mfma_f32_32x32x16_bf16 v[32:47], a[20:23], a[24:27], v[32:47]
	s_waitcnt vmcnt(6)
	s_waitcnt lgkmcnt(0)
	s_barrier
	ds_read_b128 a[12:15], v100
	ds_read_b128 a[8:11], v99
	ds_read_b128 a[4:7], v98
	ds_read_b128 a[0:3], v97
	v_mfma_f32_32x32x16_bf16 v[16:31], a[16:19], a[28:31], v[16:31]
	v_lshl_add_u64 v[158:159], v[66:67], 0, s[30:31]
	s_nop 0
	v_lshl_add_u64 v[160:161], v[68:69], 0, s[30:31]
	s_nop 0
	s_nop 0
	s_nop 0
	v_lshl_add_u64 v[162:163], v[70:71], 0, s[30:31]
	s_nop 0
	v_mfma_f32_32x32x16_bf16 v[0:15], a[20:23], a[28:31], v[0:15]
	s_and_b32 m0, s32, 7
	s_lshl_b32 m0, m0, 12
	s_add_i32 m0, m0, 0xc000
	s_nop 0
	global_load_lds_dwordx4 v[158:159], off
	s_nop 0
	v_lshl_add_u64 v[164:165], v[72:73], 0, s[30:31]
	s_nop 0
	s_nop 0
	s_nop 0
	v_lshl_add_u64 v[166:167], v[74:75], 0, s[30:31]
	s_nop 0
	s_nop 0
	s_nop 0
	v_lshl_add_u64 v[168:169], v[76:77], 0, s[30:31]
	s_nop 0
	s_mov_b64 s[30:31], 0x700
	s_nop 0
	s_nop 0
	s_nop 0
	s_nop 0
	s_nop 0
	ds_read_b128 a[16:19], v101
	ds_read_b128 a[20:23], v102
	ds_read_b128 a[24:27], v103
	ds_read_b128 a[28:31], v104
	s_waitcnt lgkmcnt(4)
	v_mfma_f32_32x32x16_bf16 v[48:63], a[0:3], a[8:11], v[48:63]
	s_nop 0
	v_mfma_f32_32x32x16_bf16 v[32:47], a[4:7], a[8:11], v[32:47]
	v_mfma_f32_32x32x16_bf16 v[16:31], a[0:3], a[12:15], v[16:31]
	s_and_b32 m0, s32, 7
	s_lshl_b32 m0, m0, 12
	s_add_i32 m0, m0, 0xc400
	s_nop 0
	global_load_lds_dwordx4 v[160:161], off
	v_mfma_f32_32x32x16_bf16 v[0:15], a[4:7], a[12:15], v[0:15]
	s_nop 0
	s_nop 0
	s_nop 0
	s_nop 0
	ds_read_b128 a[0:3], v105
	ds_read_b128 a[4:7], v106
	ds_read_b128 a[8:11], v107
	ds_read_b128 a[12:15], v108
	s_waitcnt lgkmcnt(5)
	v_mfma_f32_32x32x16_bf16 v[48:63], a[16:19], a[24:27], v[48:63]
	s_and_b32 m0, s32, 7
	s_lshl_b32 m0, m0, 12
	s_add_i32 m0, m0, 0xc800
	s_nop 0
	global_load_lds_dwordx4 v[162:163], off
	v_mfma_f32_32x32x16_bf16 v[32:47], a[20:23], a[24:27], v[32:47]
	s_waitcnt lgkmcnt(4)
	v_mfma_f32_32x32x16_bf16 v[16:31], a[16:19], a[28:31], v[16:31]
	v_mfma_f32_32x32x16_bf16 v[0:15], a[20:23], a[28:31], v[0:15]
	s_and_b32 m0, s32, 7
	s_lshl_b32 m0, m0, 12
	s_add_i32 m0, m0, 0xcc00
	s_nop 0
	global_load_lds_dwordx4 v[164:165], off
	s_nop 0
	s_nop 0
	s_nop 0
	s_nop 0
	ds_read_b128 a[16:19], v109
	ds_read_b128 a[20:23], v110
	ds_read_b128 a[24:27], v111
	ds_read_b128 a[28:31], v112
	s_waitcnt lgkmcnt(5)
	v_mfma_f32_32x32x16_bf16 v[48:63], a[0:3], a[8:11], v[48:63]
	v_mfma_f32_32x32x16_bf16 v[32:47], a[4:7], a[8:11], v[32:47]
	s_waitcnt lgkmcnt(4)
	v_mfma_f32_32x32x16_bf16 v[16:31], a[0:3], a[12:15], v[16:31]
	s_and_b32 m0, s32, 7
	s_lshl_b32 m0, m0, 11
	s_add_i32 m0, m0, 0x14000
	s_nop 0
	global_load_lds_dwordx4 v[166:167], off
	v_mfma_f32_32x32x16_bf16 v[0:15], a[4:7], a[12:15], v[0:15]
	s_nop 0
	s_nop 0
	s_nop 0
	s_nop 0
	s_waitcnt lgkmcnt(1)
	v_mfma_f32_32x32x16_bf16 v[48:63], a[16:19], a[24:27], v[48:63]
	s_and_b32 m0, s32, 7
	s_lshl_b32 m0, m0, 11
	s_add_i32 m0, m0, 0x14400
	s_nop 0
	global_load_lds_dwordx4 v[168:169], off
	v_mfma_f32_32x32x16_bf16 v[32:47], a[20:23], a[24:27], v[32:47]
	s_waitcnt vmcnt(6)
	s_waitcnt lgkmcnt(0)
	s_barrier
	ds_read_b128 a[12:15], v81 offset:4096
	ds_read_b128 a[8:11], v81
	ds_read_b128 a[4:7], v82 offset:36864
	ds_read_b128 a[0:3], v82 offset:32768
	v_mfma_f32_32x32x16_bf16 v[16:31], a[16:19], a[28:31], v[16:31]
	v_lshl_add_u64 v[170:171], v[66:67], 0, s[30:31]
	s_nop 0
	v_lshl_add_u64 v[172:173], v[68:69], 0, s[30:31]
	s_nop 0
	s_nop 0
	s_nop 0
	v_lshl_add_u64 v[174:175], v[70:71], 0, s[30:31]
	s_nop 0
	v_mfma_f32_32x32x16_bf16 v[0:15], a[20:23], a[28:31], v[0:15]
	s_and_b32 m0, s32, 7
	s_lshl_b32 m0, m0, 12
	s_add_i32 m0, m0, 0x18000
	s_nop 0
	global_load_lds_dwordx4 v[170:171], off
	s_nop 0
	v_lshl_add_u64 v[176:177], v[72:73], 0, s[30:31]
	s_nop 0
	s_nop 0
	s_nop 0
	v_lshl_add_u64 v[178:179], v[74:75], 0, s[30:31]
	s_nop 0
	s_nop 0
	s_nop 0
	v_lshl_add_u64 v[180:181], v[76:77], 0, s[30:31]
	s_nop 0
	s_mov_b64 s[30:31], 0x780
	s_nop 0
	s_nop 0
	s_nop 0
	s_nop 0
	s_nop 0
	ds_read_b128 a[16:19], v84 offset:32768
	ds_read_b128 a[20:23], v84 offset:36864
	ds_read_b128 a[24:27], v83
	ds_read_b128 a[28:31], v83 offset:4096
	s_waitcnt lgkmcnt(4)
	v_mfma_f32_32x32x16_bf16 v[48:63], a[0:3], a[8:11], v[48:63]
	v_lshl_add_u64 v[158:159], v[66:67], 0, s[30:31]
	s_nop 0
	v_readlane_b32 s20, v214, 43
	v_mfma_f32_32x32x16_bf16 v[32:47], a[4:7], a[8:11], v[32:47]
	v_mfma_f32_32x32x16_bf16 v[16:31], a[0:3], a[12:15], v[16:31]
	s_and_b32 m0, s32, 7
	s_lshl_b32 m0, m0, 12
	s_add_i32 m0, m0, 0x18400
	s_nop 0
	global_load_lds_dwordx4 v[172:173], off
	v_mfma_f32_32x32x16_bf16 v[0:15], a[4:7], a[12:15], v[0:15]
	s_nop 0
	s_nop 0
	s_nop 0
	s_nop 0
	ds_read_b128 a[0:3], v86 offset:32768
	ds_read_b128 a[4:7], v86 offset:36864
	ds_read_b128 a[8:11], v85
	ds_read_b128 a[12:15], v85 offset:4096
	s_waitcnt lgkmcnt(5)
	v_mfma_f32_32x32x16_bf16 v[48:63], a[16:19], a[24:27], v[48:63]
	s_and_b32 m0, s32, 7
	s_lshl_b32 m0, m0, 12
	s_add_i32 m0, m0, 0x18800
	s_nop 0
	global_load_lds_dwordx4 v[174:175], off
	v_mfma_f32_32x32x16_bf16 v[32:47], a[20:23], a[24:27], v[32:47]
	s_waitcnt lgkmcnt(4)
	v_mfma_f32_32x32x16_bf16 v[16:31], a[16:19], a[28:31], v[16:31]
	v_mfma_f32_32x32x16_bf16 v[0:15], a[20:23], a[28:31], v[0:15]
	s_and_b32 m0, s32, 7
	s_lshl_b32 m0, m0, 12
	s_add_i32 m0, m0, 0x18c00
	s_nop 0
	global_load_lds_dwordx4 v[176:177], off
	s_nop 0
	s_nop 0
	s_nop 0
	s_nop 0
	ds_read_b128 a[16:19], v88 offset:32768
	ds_read_b128 a[20:23], v88 offset:36864
	ds_read_b128 a[24:27], v87
	ds_read_b128 a[28:31], v87 offset:4096
	s_waitcnt lgkmcnt(5)
	v_mfma_f32_32x32x16_bf16 v[48:63], a[0:3], a[8:11], v[48:63]
	v_mfma_f32_32x32x16_bf16 v[32:47], a[4:7], a[8:11], v[32:47]
	s_waitcnt lgkmcnt(4)
	v_mfma_f32_32x32x16_bf16 v[16:31], a[0:3], a[12:15], v[16:31]
	s_and_b32 m0, s32, 7
	s_lshl_b32 m0, m0, 11
	s_add_i32 m0, m0, 0x20000
	s_nop 0
	global_load_lds_dwordx4 v[178:179], off
	v_mfma_f32_32x32x16_bf16 v[0:15], a[4:7], a[12:15], v[0:15]
	s_nop 0
	s_nop 0
	s_nop 0
	s_nop 0
	s_waitcnt lgkmcnt(1)
	v_mfma_f32_32x32x16_bf16 v[48:63], a[16:19], a[24:27], v[48:63]
	s_and_b32 m0, s32, 7
	s_lshl_b32 m0, m0, 11
	s_add_i32 m0, m0, 0x20400
	s_nop 0
	global_load_lds_dwordx4 v[180:181], off
	v_mfma_f32_32x32x16_bf16 v[32:47], a[20:23], a[24:27], v[32:47]
	s_waitcnt vmcnt(6)
	s_waitcnt lgkmcnt(0)
	s_barrier
	ds_read_b128 a[12:15], v81 offset:53248
	ds_read_b128 a[8:11], v81 offset:49152
	ds_read_b128 a[4:7], v89
	ds_read_b128 a[0:3], v91
	s_nop 0
	v_lshl_add_u64 v[160:161], v[68:69], 0, s[30:31]
	s_nop 0
	v_mfma_f32_32x32x16_bf16 v[16:31], a[16:19], a[28:31], v[16:31]
	s_nop 0
	v_lshl_add_u64 v[162:163], v[70:71], 0, s[30:31]
	s_nop 0
	v_readlane_b32 s21, v214, 44
	s_nop 0
	v_lshl_add_u64 v[164:165], v[72:73], 0, s[30:31]
	s_nop 0
	v_mfma_f32_32x32x16_bf16 v[0:15], a[20:23], a[28:31], v[0:15]
	s_and_b32 m0, s32, 7
	s_lshl_b32 m0, m0, 12
	s_add_i32 m0, m0, 0x0
	s_nop 0
	global_load_lds_dwordx4 v[158:159], off
	s_nop 0
	v_lshl_add_u64 v[166:167], v[74:75], 0, s[30:31]
	s_nop 0
	s_lshl_b64 s[28:29], s[0:1], 21
	s_nop 0
	v_lshl_add_u64 v[168:169], v[76:77], 0, s[30:31]
	s_nop 0
	s_add_u32 s20, s20, s28
	s_nop 0
	s_nop 0
	s_nop 0
	s_nop 0
	s_nop 0
	ds_read_b128 a[16:19], v92
	ds_read_b128 a[20:23], v90
	ds_read_b128 a[24:27], v83 offset:49152
	ds_read_b128 a[28:31], v83 offset:53248
	s_waitcnt lgkmcnt(4)
	v_mfma_f32_32x32x16_bf16 v[48:63], a[0:3], a[8:11], v[48:63]
	s_addc_u32 s21, s21, s29
	v_readlane_b32 s23, v214, 41
	s_add_u32 s36, s23, s28
	v_readlane_b32 s23, v214, 42
	s_addc_u32 s37, s23, s29
	v_mfma_f32_32x32x16_bf16 v[32:47], a[4:7], a[8:11], v[32:47]
	v_mfma_f32_32x32x16_bf16 v[16:31], a[0:3], a[12:15], v[16:31]
	s_and_b32 m0, s32, 7
	s_lshl_b32 m0, m0, 12
	s_add_i32 m0, m0, 0x400
	s_nop 0
	global_load_lds_dwordx4 v[160:161], off
	v_mfma_f32_32x32x16_bf16 v[0:15], a[4:7], a[12:15], v[0:15]
	s_nop 0
	s_nop 0
	s_nop 0
	s_nop 0
	ds_read_b128 a[0:3], v94
	ds_read_b128 a[4:7], v93
	ds_read_b128 a[8:11], v85 offset:49152
	ds_read_b128 a[12:15], v85 offset:53248
	s_waitcnt lgkmcnt(5)
	v_mfma_f32_32x32x16_bf16 v[48:63], a[16:19], a[24:27], v[48:63]
	s_and_b32 m0, s32, 7
	s_lshl_b32 m0, m0, 12
	s_add_i32 m0, m0, 0x800
	s_nop 0
	global_load_lds_dwordx4 v[162:163], off
	v_mfma_f32_32x32x16_bf16 v[32:47], a[20:23], a[24:27], v[32:47]
	s_waitcnt lgkmcnt(4)
	v_mfma_f32_32x32x16_bf16 v[16:31], a[16:19], a[28:31], v[16:31]
	v_mfma_f32_32x32x16_bf16 v[0:15], a[20:23], a[28:31], v[0:15]
	s_and_b32 m0, s32, 7
	s_lshl_b32 m0, m0, 12
	s_add_i32 m0, m0, 0xc00
	s_nop 0
	global_load_lds_dwordx4 v[164:165], off
	s_nop 0
	s_nop 0
	s_nop 0
	s_nop 0
	ds_read_b128 a[16:19], v96
	ds_read_b128 a[20:23], v95
	ds_read_b128 a[24:27], v87 offset:49152
	ds_read_b128 a[28:31], v87 offset:53248
	s_waitcnt lgkmcnt(5)
	v_mfma_f32_32x32x16_bf16 v[48:63], a[0:3], a[8:11], v[48:63]
	v_mfma_f32_32x32x16_bf16 v[32:47], a[4:7], a[8:11], v[32:47]
	s_waitcnt lgkmcnt(4)
	v_mfma_f32_32x32x16_bf16 v[16:31], a[0:3], a[12:15], v[16:31]
	s_and_b32 m0, s32, 7
	s_lshl_b32 m0, m0, 11
	s_add_i32 m0, m0, 0x8000
	s_nop 0
	global_load_lds_dwordx4 v[166:167], off
	v_mfma_f32_32x32x16_bf16 v[0:15], a[4:7], a[12:15], v[0:15]
	s_nop 0
	s_nop 0
	s_nop 0
	s_nop 0
	s_waitcnt lgkmcnt(1)
	v_mfma_f32_32x32x16_bf16 v[48:63], a[16:19], a[24:27], v[48:63]
	s_and_b32 m0, s32, 7
	s_lshl_b32 m0, m0, 11
	s_add_i32 m0, m0, 0x8400
	s_nop 0
	global_load_lds_dwordx4 v[168:169], off
	v_mfma_f32_32x32x16_bf16 v[32:47], a[20:23], a[24:27], v[32:47]
	s_waitcnt vmcnt(6)
	s_waitcnt lgkmcnt(0)
	s_barrier
	ds_read_b128 a[12:15], v100
	ds_read_b128 a[8:11], v99
	ds_read_b128 a[4:7], v98
	ds_read_b128 a[0:3], v97
	v_mfma_f32_32x32x16_bf16 v[16:31], a[16:19], a[28:31], v[16:31]
	v_mfma_f32_32x32x16_bf16 v[0:15], a[20:23], a[28:31], v[0:15]
	s_nop 0
	s_nop 0
	s_nop 0
	s_nop 0
	ds_read_b128 a[16:19], v101
	ds_read_b128 a[20:23], v102
	ds_read_b128 a[24:27], v103
	ds_read_b128 a[28:31], v104
	s_waitcnt lgkmcnt(4)
	v_mfma_f32_32x32x16_bf16 v[48:63], a[0:3], a[8:11], v[48:63]
	v_mfma_f32_32x32x16_bf16 v[32:47], a[4:7], a[8:11], v[32:47]
	v_mfma_f32_32x32x16_bf16 v[16:31], a[0:3], a[12:15], v[16:31]
	v_mfma_f32_32x32x16_bf16 v[0:15], a[4:7], a[12:15], v[0:15]
	s_nop 0
	s_nop 0
	s_nop 0
	s_nop 0
	ds_read_b128 a[0:3], v105
	ds_read_b128 a[4:7], v106
	ds_read_b128 a[8:11], v107
	ds_read_b128 a[12:15], v108
	s_waitcnt lgkmcnt(5)
	v_mfma_f32_32x32x16_bf16 v[48:63], a[16:19], a[24:27], v[48:63]
	v_mfma_f32_32x32x16_bf16 v[32:47], a[20:23], a[24:27], v[32:47]
	s_waitcnt lgkmcnt(4)
	v_mfma_f32_32x32x16_bf16 v[16:31], a[16:19], a[28:31], v[16:31]
	v_mfma_f32_32x32x16_bf16 v[0:15], a[20:23], a[28:31], v[0:15]
	s_nop 0
	s_nop 0
	s_nop 0
	s_nop 0
	ds_read_b128 a[16:19], v109
	ds_read_b128 a[20:23], v110
	ds_read_b128 a[24:27], v111
	ds_read_b128 a[28:31], v112
	s_waitcnt lgkmcnt(5)
	v_mfma_f32_32x32x16_bf16 v[48:63], a[0:3], a[8:11], v[48:63]
	v_mfma_f32_32x32x16_bf16 v[32:47], a[4:7], a[8:11], v[32:47]
	s_waitcnt lgkmcnt(4)
	v_mfma_f32_32x32x16_bf16 v[16:31], a[0:3], a[12:15], v[16:31]
	v_mfma_f32_32x32x16_bf16 v[0:15], a[4:7], a[12:15], v[0:15]
	s_nop 0
	s_nop 0
	s_nop 0
	s_nop 0
	s_waitcnt lgkmcnt(1)
	v_mfma_f32_32x32x16_bf16 v[48:63], a[16:19], a[24:27], v[48:63]
	v_mfma_f32_32x32x16_bf16 v[32:47], a[20:23], a[24:27], v[32:47]
	s_waitcnt vmcnt(0)
	s_waitcnt lgkmcnt(0)
	s_barrier
	ds_read_b128 a[12:15], v81 offset:4096
	ds_read_b128 a[8:11], v81
	ds_read_b128 a[4:7], v82 offset:36864
	ds_read_b128 a[0:3], v82 offset:32768
	v_mfma_f32_32x32x16_bf16 v[16:31], a[16:19], a[28:31], v[16:31]
	v_mfma_f32_32x32x16_bf16 v[0:15], a[20:23], a[28:31], v[0:15]
	s_nop 0
	s_nop 0
	s_nop 0
	s_nop 0
	ds_read_b128 a[16:19], v84 offset:32768
	ds_read_b128 a[20:23], v84 offset:36864
	ds_read_b128 a[24:27], v83
	ds_read_b128 a[28:31], v83 offset:4096
	s_waitcnt lgkmcnt(4)
	v_mfma_f32_32x32x16_bf16 v[48:63], a[0:3], a[8:11], v[48:63]
	v_mfma_f32_32x32x16_bf16 v[32:47], a[4:7], a[8:11], v[32:47]
	v_mfma_f32_32x32x16_bf16 v[16:31], a[0:3], a[12:15], v[16:31]
	v_mfma_f32_32x32x16_bf16 v[0:15], a[4:7], a[12:15], v[0:15]
	s_nop 0
	s_nop 0
	s_nop 0
	s_nop 0
	ds_read_b128 a[0:3], v86 offset:32768
	ds_read_b128 a[4:7], v86 offset:36864
	ds_read_b128 a[8:11], v85
	ds_read_b128 a[12:15], v85 offset:4096
	s_waitcnt lgkmcnt(5)
	v_mfma_f32_32x32x16_bf16 v[48:63], a[16:19], a[24:27], v[48:63]
	v_mfma_f32_32x32x16_bf16 v[32:47], a[20:23], a[24:27], v[32:47]
	s_waitcnt lgkmcnt(4)
	v_mfma_f32_32x32x16_bf16 v[16:31], a[16:19], a[28:31], v[16:31]
	v_mfma_f32_32x32x16_bf16 v[0:15], a[20:23], a[28:31], v[0:15]
	s_nop 0
	s_nop 0
	s_nop 0
	s_nop 0
	s_waitcnt lgkmcnt(1)
	v_mfma_f32_32x32x16_bf16 v[48:63], a[0:3], a[8:11], v[48:63]
	v_mfma_f32_32x32x16_bf16 v[32:47], a[4:7], a[8:11], v[32:47]
	s_waitcnt lgkmcnt(0)
	v_mfma_f32_32x32x16_bf16 v[16:31], a[0:3], a[12:15], v[16:31]
	v_mfma_f32_32x32x16_bf16 v[0:15], a[4:7], a[12:15], v[0:15]
	ds_read_b128 v[66:69], v88 offset:32768
	ds_read_b128 v[70:73], v87
	ds_read_b128 v[74:77], v88 offset:36864
	ds_read_b128 v[82:85], v87 offset:4096
	s_waitcnt lgkmcnt(0)
	v_mfma_f32_32x32x16_bf16 v[48:63], v[66:69], v[70:73], v[48:63]
	v_mfma_f32_32x32x16_bf16 v[32:47], v[74:77], v[70:73], v[32:47]
	v_or_b32_e32 v70, s22, v80
	v_lshl_add_u32 v70, v78, 6, v70
	v_ashrrev_i32_e32 v71, 31, v70
	v_lshlrev_b64 v[72:73], 10, v[70:71]
	v_lshl_add_u64 v[86:87], s[36:37], 0, v[72:73]
	v_mfma_f32_32x32x16_bf16 v[16:31], v[66:69], v[82:85], v[16:31]
	v_lshlrev_b32_e32 v66, 6, v79
	v_or3_b32 v66, v66, v64, s2
	s_movk_i32 s2, 0xff
	v_cmp_lt_i32_e32 vcc, s2, v66
	v_mfma_f32_32x32x16_bf16 v[0:15], v[74:77], v[82:85], v[0:15]
	s_and_saveexec_b64 s[22:23], vcc
	s_xor_b64 s[28:29], exec, s[22:23]
	v_mov_b32_e32 v67, v65
	s_movk_i32 s22, 0xfc00
	v_lshl_add_u64 v[68:69], v[66:67], 2, v[86:87]
	s_mov_b32 s23, -1
	v_lshl_add_u64 v[68:69], v[68:69], 0, s[22:23]
	s_or_saveexec_b64 s[28:29], s[28:29]
	v_lshl_add_u64 v[90:91], s[20:21], 0, v[72:73]
	v_ashrrev_i32_e32 v67, 31, v66
	s_xor_b64 exec, exec, s[28:29]
	v_lshl_add_u64 v[68:69], v[66:67], 2, v[90:91]
	s_or_b64 exec, exec, s[28:29]
	s_lshl_b64 s[0:1], s[0:1], 19
	s_lshl_b64 s[22:23], s[0:1], 1
	v_readlane_b32 s0, v214, 37
	v_readlane_b32 s1, v214, 38
	s_add_u32 s0, s0, s22
	s_addc_u32 s1, s1, s23
	v_readlane_b32 s28, v214, 39
	v_readlane_b32 s29, v214, 40
	s_add_u32 s54, s28, s22
	v_and_b32_e32 v74, 0xdf, v70
	v_ashrrev_i32_e32 v71, 6, v70
	global_store_dwordx4 v[68:69], v[48:51], off
	v_add_u32_e32 v68, 0xffffff00, v66
	v_lshlrev_b32_e32 v69, 9, v66
	s_addc_u32 s55, s29, s23
	v_and_b32_e32 v71, -4, v71
	v_lshrrev_b32_e32 v92, 6, v68
	v_and_b32_e32 v72, 0x7800, v69
	v_lshlrev_b32_e32 v88, 1, v74
	s_and_saveexec_b64 s[22:23], vcc
	s_xor_b64 s[28:29], exec, s[22:23]
	s_cbranch_execz .LBB0_619
	v_add_u32_e32 v68, v92, v71
	v_ashrrev_i32_e32 v69, 31, v68
	v_lshlrev_b64 v[68:69], 15, v[68:69]
	v_lshl_add_u64 v[68:69], s[54:55], 0, v[68:69]
	v_mov_b32_e32 v73, v65
	v_lshl_add_u64 v[68:69], v[68:69], 0, v[72:73]
	v_mov_b32_e32 v89, v65
	v_bfe_u32 v73, v48, 16, 1
	v_lshl_add_u64 v[68:69], v[68:69], 0, v[88:89]
	v_add3_u32 v73, v48, v73, s27
	global_store_short_d16_hi v[68:69], v73, off
	v_bfe_u32 v73, v49, 16, 1
	v_add3_u32 v73, v49, v73, s27
	global_store_short_d16_hi v[68:69], v73, off offset:512
	v_bfe_u32 v73, v50, 16, 1
	v_add3_u32 v73, v50, v73, s27
	global_store_short_d16_hi v[68:69], v73, off offset:1024
	v_bfe_u32 v73, v51, 16, 1
	v_add3_u32 v73, v51, v73, s27
	global_store_short_d16_hi v[68:69], v73, off offset:1536

.LBB0_747:
	v_mov_b32_e32 v78, v133
	s_lshl_b32 s2, s2, 8
	v_ashrrev_i32_e32 v6, 6, v78
	v_bfe_u32 v7, v78, 3, 3
	v_lshl_or_b32 v8, v6, 5, v7
	v_add_u32_e32 v0, s2, v8
	s_waitcnt lgkmcnt(0)
	v_ashrrev_i32_e32 v1, 31, v0
	v_lshlrev_b64 v[2:3], 11, v[0:1]
	v_bfe_u32 v1, v78, 4, 2
	v_readlane_b32 s0, v215, 52
	v_xor_b32_e32 v1, v1, v78
	v_readlane_b32 s1, v215, 53
	v_lshlrev_b32_e32 v1, 4, v1
	v_and_b32_e32 v64, 0x70, v1
	v_lshl_add_u64 v[2:3], s[0:1], 0, v[2:3]
	v_or_b32_e32 v1, 8, v8
	v_lshl_add_u64 v[66:67], v[2:3], 0, v[64:65]
	v_add_u32_e32 v2, s2, v1
	v_lshrrev_b32_e32 v1, 1, v1
	v_xor_b32_e32 v1, v1, v78
	v_ashrrev_i32_e32 v3, 31, v2
	v_lshlrev_b32_e32 v1, 4, v1
	v_or_b32_e32 v0, 16, v0
	v_lshlrev_b64 v[2:3], 11, v[2:3]
	v_and_b32_e32 v4, 0x70, v1
	v_ashrrev_i32_e32 v1, 31, v0
	v_lshl_add_u64 v[2:3], s[0:1], 0, v[2:3]
	v_mov_b32_e32 v5, v65
	v_lshlrev_b64 v[0:1], 11, v[0:1]
	v_lshl_add_u64 v[68:69], v[2:3], 0, v[4:5]
	v_lshl_add_u64 v[0:1], s[0:1], 0, v[0:1]
	v_or_b32_e32 v2, 24, v8
	v_lshl_add_u64 v[70:71], v[0:1], 0, v[64:65]
	v_add_u32_e32 v0, s2, v2
	v_lshrrev_b32_e32 v2, 1, v2
	v_ashrrev_i32_e32 v1, 31, v0
	v_xor_b32_e32 v2, v2, v78
	v_lshlrev_b64 v[0:1], 11, v[0:1]
	v_lshlrev_b32_e32 v2, 4, v2
	v_lshl_add_u64 v[0:1], s[0:1], 0, v[0:1]
	v_and_b32_e32 v2, 0x70, v2
	v_mov_b32_e32 v3, v65
	v_lshl_add_u64 v[72:73], v[0:1], 0, v[2:3]
	v_lshl_or_b32 v2, v6, 4, v7
	v_add_u32_e32 v0, s20, v2
	v_lshlrev_b32_e32 v3, 12, v6
	v_ashrrev_i32_e32 v1, 31, v0
	v_add_u32_e32 v131, 0, v3
	v_lshlrev_b64 v[0:1], 11, v[0:1]
	s_waitcnt vmcnt(0)
	v_readfirstlane_b32 s40, v131
	v_add_u32_e32 v130, 0x400, v131
	v_lshl_add_u64 v[0:1], s[96:97], 0, v[0:1]
	v_or_b32_e32 v2, 8, v2
	s_waitcnt lgkmcnt(0)
	s_barrier
	s_mov_b32 m0, s40
	v_readfirstlane_b32 s41, v130
	v_add_u32_e32 v128, 0x800, v131
	v_lshlrev_b32_e32 v5, 11, v6
	v_and_b32_e32 v79, 1, v6
	v_lshl_add_u64 v[74:75], v[0:1], 0, v[64:65]
	v_add_u32_e32 v0, s20, v2
	v_lshrrev_b32_e32 v2, 1, v2
	global_load_lds_dwordx4 v[66:67], off
	s_mov_b32 m0, s41
	v_readfirstlane_b32 s42, v128
	v_add_u32_e32 v126, 0xc00, v131
	v_add_u32_e32 v6, 0, v5
	v_ashrrev_i32_e32 v1, 31, v0
	v_xor_b32_e32 v2, v2, v78
	global_load_lds_dwordx4 v[68:69], off
	s_mov_b32 m0, s42
	v_readfirstlane_b32 s43, v126
	v_add_u32_e32 v129, 0x8000, v6
	v_lshlrev_b64 v[0:1], 11, v[0:1]
	v_lshlrev_b32_e32 v2, 4, v2
	global_load_lds_dwordx4 v[70:71], off
	s_mov_b32 m0, s43
	v_readfirstlane_b32 s44, v129
	v_add_u32_e32 v127, 0x8400, v6
	v_lshl_add_u64 v[0:1], s[96:97], 0, v[0:1]
	v_and_b32_e32 v64, 0x70, v2
	global_load_lds_dwordx4 v[72:73], off
	s_mov_b32 m0, s44
	v_readfirstlane_b32 s45, v127
	v_add_u32_e32 v125, 0xc000, v131
	v_lshl_add_u64 v[76:77], v[0:1], 0, v[64:65]
	global_load_lds_dwordx4 v[74:75], off
	s_mov_b32 m0, s45
	s_mov_b64 s[0:1], 0x80
	v_readfirstlane_b32 s29, v125
	v_add_u32_e32 v120, 0xc400, v131
	global_load_lds_dwordx4 v[76:77], off
	v_lshl_add_u64 v[0:1], v[66:67], 0, s[0:1]
	s_mov_b32 m0, s29
	v_readfirstlane_b32 s33, v120
	v_add_u32_e32 v121, 0xc800, v131
	global_load_lds_dwordx4 v[0:1], off
	v_lshl_add_u64 v[0:1], v[68:69], 0, s[0:1]
	s_mov_b32 m0, s33
	v_readfirstlane_b32 s36, v121
	v_add_u32_e32 v122, 0xcc00, v131
	global_load_lds_dwordx4 v[0:1], off
	v_lshl_add_u64 v[0:1], v[70:71], 0, s[0:1]
	s_mov_b32 m0, s36
	v_readfirstlane_b32 s37, v122
	v_add_u32_e32 v123, s85, v5
	global_load_lds_dwordx4 v[0:1], off
	v_lshl_add_u64 v[0:1], v[72:73], 0, s[0:1]
	s_mov_b32 m0, s37
	v_readfirstlane_b32 s38, v123
	v_add_u32_e32 v124, 0x14400, v6
	global_load_lds_dwordx4 v[0:1], off
	v_lshl_add_u64 v[0:1], v[74:75], 0, s[0:1]
	s_mov_b32 m0, s38
	v_readfirstlane_b32 s39, v124
	global_load_lds_dwordx4 v[0:1], off
	v_lshl_add_u64 v[0:1], v[76:77], 0, s[0:1]
	s_mov_b32 m0, s39
	v_lshrrev_b32_e32 v2, 1, v78
	v_bfe_u32 v64, v78, 5, 1
	global_load_lds_dwordx4 v[0:1], off
	v_add_u32_e32 v119, s3, v3
	v_bitop3_b32 v0, v2, v64, 7 bitop3:0x6c
	s_waitcnt vmcnt(6)
	s_mov_b64 s[30:31], 0x100
	v_readfirstlane_b32 s0, v119
	v_add_u32_e32 v114, 0x400, v119
	v_lshlrev_b32_e32 v132, 4, v0
	s_waitcnt lgkmcnt(0)
	s_barrier
	v_lshl_add_u64 v[0:1], v[66:67], 0, s[30:31]
	s_mov_b32 m0, s0
	v_readfirstlane_b32 s1, v114
	v_add_u32_e32 v115, 0x800, v119
	global_load_lds_dwordx4 v[0:1], off
	v_lshl_add_u64 v[0:1], v[68:69], 0, s[30:31]
	s_mov_b32 m0, s1
	v_readfirstlane_b32 s21, v115
	v_add_u32_e32 v116, 0xc00, v119
	v_readlane_b32 s23, v212, 31
	v_and_b32_e32 v81, 31, v78
	global_load_lds_dwordx4 v[0:1], off
	v_lshl_add_u64 v[0:1], v[70:71], 0, s[30:31]
	s_mov_b32 m0, s21
	v_readfirstlane_b32 s22, v116
	v_add_u32_e32 v117, s23, v5
	v_add_u32_e32 v2, s3, v5
	v_lshlrev_b32_e32 v4, 7, v81
	global_load_lds_dwordx4 v[0:1], off
	v_lshl_add_u64 v[0:1], v[72:73], 0, s[30:31]
	s_mov_b32 m0, s22
	v_readfirstlane_b32 s23, v117
	v_add_u32_e32 v118, 0x8400, v2
	v_lshl_or_b32 v102, v79, 13, v4
	global_load_lds_dwordx4 v[0:1], off
	v_lshl_add_u64 v[0:1], v[74:75], 0, s[30:31]
	s_mov_b32 m0, s23
	v_readfirstlane_b32 s28, v118
	global_load_lds_dwordx4 v[0:1], off
	v_lshl_add_u64 v[0:1], v[76:77], 0, s[30:31]
	s_mov_b32 m0, s28
	v_add_u32_e32 v100, 0, v102
	global_load_lds_dwordx4 v[0:1], off
	v_add_u32_e32 v85, v100, v132
	v_ashrrev_i32_e32 v80, 7, v78
	ds_read_b128 v[0:3], v85 offset:32768
	ds_read_b128 v[86:89], v85 offset:36864
	v_lshl_or_b32 v134, v80, 13, v4
	v_add_u32_e32 v101, 0, v134
	v_add_u32_e32 v84, v101, v132
	ds_read_b128 v[4:7], v84
	v_bfe_u32 v103, v78, 1, 3
	s_waitcnt lgkmcnt(0)
	v_lshrrev_b32_e32 v182, 6, v133
	s_nop 0
	v_readfirstlane_b32 s32, v182
	v_mfma_f32_32x32x16_bf16 v[48:63], v[0:3], v[4:7], 0
	v_bitop3_b32 v8, v64, v103, 2 bitop3:0x36
	v_lshlrev_b32_e32 v135, 4, v8
	v_add_u32_e32 v83, v100, v135
	ds_read_b128 v[8:11], v83 offset:32768
	ds_read_b128 v[90:93], v83 offset:36864
	v_add_u32_e32 v82, v101, v135
	ds_read_b128 v[12:15], v82
	ds_read_b128 v[94:97], v82 offset:4096
	s_waitcnt vmcnt(12)
	v_mfma_f32_32x32x16_bf16 v[32:47], v[86:89], v[4:7], 0
	ds_read_b128 v[4:7], v84 offset:4096
	s_mov_b64 s[30:31], 0x180
	s_nop 0
	v_or_b32_e32 v143, 0x8000, v102
	v_or_b32_e32 v144, 0x9000, v102
	v_add_u32_e32 v145, s3, v134
	s_mov_b64 s[80:81], 0x200
	s_waitcnt lgkmcnt(0)
	v_mfma_f32_32x32x16_bf16 v[16:31], v[0:3], v[4:7], 0
	v_mfma_f32_32x32x16_bf16 v[48:63], v[8:11], v[12:15], v[48:63]
	v_mfma_f32_32x32x16_bf16 v[32:47], v[90:93], v[12:15], v[32:47]
	v_mfma_f32_32x32x16_bf16 v[16:31], v[8:11], v[94:97], v[16:31]
	v_mfma_f32_32x32x16_bf16 v[0:15], v[86:89], v[4:7], 0
	v_bitop3_b32 v86, v64, v103, 4 bitop3:0x36
	v_lshlrev_b32_e32 v138, 4, v86
	v_add_u32_e32 v87, v100, v138
	v_add_u32_e32 v86, v101, v138
	v_mfma_f32_32x32x16_bf16 v[0:15], v[90:93], v[94:97], v[0:15]
	ds_read_b128 v[88:91], v87 offset:32768
	ds_read_b128 v[92:95], v86
	ds_read_b128 v[96:99], v87 offset:36864
	s_waitcnt lgkmcnt(1)
	v_mfma_f32_32x32x16_bf16 v[48:63], v[88:91], v[92:95], v[48:63]
	s_waitcnt lgkmcnt(0)
	v_mfma_f32_32x32x16_bf16 v[32:47], v[96:99], v[92:95], v[32:47]
	ds_read_b128 v[92:95], v86 offset:4096
	s_waitcnt lgkmcnt(0)
	v_mfma_f32_32x32x16_bf16 v[16:31], v[88:91], v[92:95], v[16:31]
	v_bitop3_b32 v88, v64, v103, 6 bitop3:0x36
	v_lshlrev_b32_e32 v142, 4, v88
	v_add_u32_e32 v89, v100, v142
	v_add_u32_e32 v88, v101, v142
	v_mfma_f32_32x32x16_bf16 v[0:15], v[96:99], v[92:95], v[0:15]
	ds_read_b128 v[90:93], v89 offset:32768
	ds_read_b128 v[94:97], v88
	ds_read_b128 v[98:101], v89 offset:36864
	s_waitcnt lgkmcnt(1)
	v_mfma_f32_32x32x16_bf16 v[48:63], v[90:93], v[94:97], v[48:63]
	s_waitcnt lgkmcnt(0)
	v_mfma_f32_32x32x16_bf16 v[32:47], v[98:101], v[94:97], v[32:47]
	ds_read_b128 v[94:97], v88 offset:4096
	s_waitcnt vmcnt(6)
	s_waitcnt lgkmcnt(0)
	s_barrier
	s_waitcnt lgkmcnt(0)
	v_mfma_f32_32x32x16_bf16 v[16:31], v[90:93], v[94:97], v[16:31]
	v_lshl_add_u64 v[158:159], v[66:67], 0, s[30:31]
	s_nop 0
	v_lshl_add_u64 v[160:161], v[68:69], 0, s[30:31]
	s_nop 0
	s_nop 0
	s_nop 0
	v_lshl_add_u64 v[162:163], v[70:71], 0, s[30:31]
	s_nop 0
	v_mfma_f32_32x32x16_bf16 v[0:15], v[98:101], v[94:97], v[0:15]
	s_and_b32 m0, s32, 7
	s_lshl_b32 m0, m0, 12
	s_add_i32 m0, m0, 0x0
	s_nop 0
	global_load_lds_dwordx4 v[158:159], off
	s_nop 0
	v_lshl_add_u64 v[164:165], v[72:73], 0, s[30:31]
	s_nop 0
	s_nop 0
	s_nop 0
	v_lshl_add_u64 v[166:167], v[74:75], 0, s[30:31]
	s_nop 0
	s_nop 0
	s_nop 0
	v_lshl_add_u64 v[168:169], v[76:77], 0, s[30:31]
	s_nop 0
	s_add_i32 s30, 0, 0xc000
	s_nop 0
	v_add_u32_e32 v90, s30, v132
	v_add_u32_e32 v91, v90, v143
	v_add_u32_e32 v90, v90, v144
	ds_read_b128 v[92:95], v91
	ds_read_b128 v[96:99], v84 offset:49152
	ds_read_b128 v[100:103], v90
	ds_read_b128 v[150:153], v84 offset:53248
	s_waitcnt lgkmcnt(1)
	v_mfma_f32_32x32x16_bf16 v[48:63], v[92:95], v[96:99], v[48:63]
	s_nop 0
	v_mfma_f32_32x32x16_bf16 v[32:47], v[100:103], v[96:99], v[32:47]
	s_waitcnt lgkmcnt(0)
	v_mfma_f32_32x32x16_bf16 v[16:31], v[92:95], v[150:153], v[16:31]
	s_and_b32 m0, s32, 7
	s_lshl_b32 m0, m0, 12
	s_add_i32 m0, m0, 0x400
	s_nop 0
	global_load_lds_dwordx4 v[160:161], off
	v_add_u32_e32 v92, s30, v135
	v_add_u32_e32 v94, v92, v143
	v_add_u32_e32 v92, v92, v144
	v_add_u32_e32 v93, s30, v138
	v_add_u32_e32 v95, v93, v143
	v_add_u32_e32 v93, v93, v144
	v_mfma_f32_32x32x16_bf16 v[0:15], v[100:103], v[150:153], v[0:15]
	ds_read_b128 v[96:99], v94
	ds_read_b128 v[100:103], v82 offset:49152
	ds_read_b128 v[104:107], v92
	ds_read_b128 v[154:157], v82 offset:53248
	s_waitcnt lgkmcnt(1)
	v_mfma_f32_32x32x16_bf16 v[48:63], v[96:99], v[100:103], v[48:63]
	s_and_b32 m0, s32, 7
	s_lshl_b32 m0, m0, 12
	s_add_i32 m0, m0, 0x800
	s_nop 0
	global_load_lds_dwordx4 v[162:163], off
	v_mfma_f32_32x32x16_bf16 v[32:47], v[104:107], v[100:103], v[32:47]
	s_waitcnt lgkmcnt(0)
	v_mfma_f32_32x32x16_bf16 v[16:31], v[96:99], v[154:157], v[16:31]
	v_mfma_f32_32x32x16_bf16 v[0:15], v[104:107], v[154:157], v[0:15]
	s_and_b32 m0, s32, 7
	s_lshl_b32 m0, m0, 12
	s_add_i32 m0, m0, 0xc00
	s_nop 0
	global_load_lds_dwordx4 v[164:165], off
	ds_read_b128 v[96:99], v95
	ds_read_b128 v[100:103], v86 offset:49152
	ds_read_b128 v[104:107], v93
	ds_read_b128 v[150:153], v86 offset:53248
	s_waitcnt lgkmcnt(1)
	v_mfma_f32_32x32x16_bf16 v[48:63], v[96:99], v[100:103], v[48:63]
	v_mfma_f32_32x32x16_bf16 v[32:47], v[104:107], v[100:103], v[32:47]
	s_waitcnt lgkmcnt(0)
	v_mfma_f32_32x32x16_bf16 v[16:31], v[96:99], v[150:153], v[16:31]
	s_and_b32 m0, s32, 7
	s_lshl_b32 m0, m0, 11
	s_add_i32 m0, m0, 0x8000
	s_nop 0
	global_load_lds_dwordx4 v[166:167], off
	v_add_u32_e32 v96, s30, v142
	v_add_u32_e32 v97, v96, v143
	v_add_u32_e32 v96, v96, v144
	s_mov_b64 s[30:31], 0x200
	v_mfma_f32_32x32x16_bf16 v[0:15], v[104:107], v[150:153], v[0:15]
	ds_read_b128 v[98:101], v97
	ds_read_b128 v[102:105], v88 offset:49152
	ds_read_b128 v[106:109], v96
	ds_read_b128 v[154:157], v88 offset:53248
	s_waitcnt lgkmcnt(1)
	v_mfma_f32_32x32x16_bf16 v[48:63], v[98:101], v[102:105], v[48:63]
	s_and_b32 m0, s32, 7
	s_lshl_b32 m0, m0, 11
	s_add_i32 m0, m0, 0x8400
	s_nop 0
	global_load_lds_dwordx4 v[168:169], off
	v_mfma_f32_32x32x16_bf16 v[32:47], v[106:109], v[102:105], v[32:47]
	s_waitcnt vmcnt(6)
	s_waitcnt lgkmcnt(0)
	s_barrier
	s_waitcnt lgkmcnt(0)
	v_mfma_f32_32x32x16_bf16 v[16:31], v[98:101], v[154:157], v[16:31]
	v_lshl_add_u64 v[170:171], v[66:67], 0, s[30:31]
	s_nop 0
	v_lshl_add_u64 v[172:173], v[68:69], 0, s[30:31]
	s_nop 0
	v_add_u32_e32 v101, s3, v132
	s_nop 0
	v_lshl_add_u64 v[174:175], v[70:71], 0, s[30:31]
	s_nop 0
	v_mfma_f32_32x32x16_bf16 v[0:15], v[106:109], v[154:157], v[0:15]
	s_and_b32 m0, s32, 7
	s_lshl_b32 m0, m0, 12
	s_add_i32 m0, m0, 0xc000
	s_nop 0
	global_load_lds_dwordx4 v[170:171], off
	s_nop 0
	v_lshl_add_u64 v[176:177], v[72:73], 0, s[30:31]
	s_nop 0
	v_add_u32_e32 v100, v145, v132
	s_nop 0
	v_lshl_add_u64 v[178:179], v[74:75], 0, s[30:31]
	s_nop 0
	v_or_b32_e32 v132, 0x1000, v134
	s_nop 0
	v_lshl_add_u64 v[180:181], v[76:77], 0, s[30:31]
	s_nop 0
	s_mov_b64 s[30:31], 0x280
	s_nop 0
	v_add_u32_e32 v98, v101, v143
	v_add_u32_e32 v99, v101, v144
	ds_read_b128 v[110:113], v98
	ds_read_b128 v[106:109], v99
	ds_read_b128 v[102:105], v100
	v_add_u32_e32 v101, v101, v132
	ds_read_b128 v[150:153], v101
	s_waitcnt lgkmcnt(1)
	v_mfma_f32_32x32x16_bf16 v[48:63], v[110:113], v[102:105], v[48:63]
	s_nop 0
	v_mfma_f32_32x32x16_bf16 v[32:47], v[106:109], v[102:105], v[32:47]
	s_waitcnt lgkmcnt(0)
	v_mfma_f32_32x32x16_bf16 v[16:31], v[110:113], v[150:153], v[16:31]
	s_and_b32 m0, s32, 7
	s_lshl_b32 m0, m0, 12
	s_add_i32 m0, m0, 0xc400
	s_nop 0
	global_load_lds_dwordx4 v[172:173], off
	v_mfma_f32_32x32x16_bf16 v[0:15], v[106:109], v[150:153], v[0:15]
	v_add_u32_e32 v105, s3, v135
	v_add_u32_e32 v103, v105, v143
	v_add_u32_e32 v102, v105, v144
	ds_read_b128 v[106:109], v103
	v_add_u32_e32 v104, v145, v135
	ds_read_b128 v[134:137], v102
	ds_read_b128 v[110:113], v104
	v_add_u32_e32 v105, v105, v132
	ds_read_b128 v[154:157], v105
	s_waitcnt lgkmcnt(1)
	v_mfma_f32_32x32x16_bf16 v[48:63], v[106:109], v[110:113], v[48:63]
	s_and_b32 m0, s32, 7
	s_lshl_b32 m0, m0, 12
	s_add_i32 m0, m0, 0xc800
	s_nop 0
	global_load_lds_dwordx4 v[174:175], off
	v_mfma_f32_32x32x16_bf16 v[32:47], v[134:137], v[110:113], v[32:47]
	s_waitcnt lgkmcnt(0)
	v_mfma_f32_32x32x16_bf16 v[16:31], v[106:109], v[154:157], v[16:31]
	v_add_u32_e32 v109, s3, v138
	v_add_u32_e32 v107, v109, v143
	v_add_u32_e32 v106, v109, v144
	v_add_u32_e32 v108, v145, v138
	ds_read_b128 v[138:141], v106
	v_add_u32_e32 v109, v109, v132
	v_mfma_f32_32x32x16_bf16 v[0:15], v[134:137], v[154:157], v[0:15]
	s_and_b32 m0, s32, 7
	s_lshl_b32 m0, m0, 12
	s_add_i32 m0, m0, 0xcc00
	s_nop 0
	global_load_lds_dwordx4 v[176:177], off
	ds_read_b128 v[110:113], v107
	ds_read_b128 v[134:137], v108
	ds_read_b128 v[150:153], v109
	s_waitcnt lgkmcnt(1)
	v_mfma_f32_32x32x16_bf16 v[48:63], v[110:113], v[134:137], v[48:63]
	v_mfma_f32_32x32x16_bf16 v[32:47], v[138:141], v[134:137], v[32:47]
	s_waitcnt lgkmcnt(0)
	v_mfma_f32_32x32x16_bf16 v[16:31], v[110:113], v[150:153], v[16:31]
	s_and_b32 m0, s32, 7
	s_lshl_b32 m0, m0, 11
	s_add_i32 m0, m0, 0x14000
	s_nop 0
	global_load_lds_dwordx4 v[178:179], off
	v_add_u32_e32 v113, s3, v142
	v_add_u32_e32 v111, v113, v143
	v_add_u32_e32 v110, v113, v144
	v_add_u32_e32 v112, v145, v142
	ds_read_b128 v[142:145], v110
	v_add_u32_e32 v113, v113, v132
	v_mfma_f32_32x32x16_bf16 v[0:15], v[138:141], v[150:153], v[0:15]
	ds_read_b128 v[134:137], v111
	ds_read_b128 v[138:141], v112
	ds_read_b128 v[154:157], v113
	s_waitcnt lgkmcnt(1)
	v_mfma_f32_32x32x16_bf16 v[48:63], v[134:137], v[138:141], v[48:63]
	s_and_b32 m0, s32, 7
	s_lshl_b32 m0, m0, 11
	s_add_i32 m0, m0, 0x14400
	s_nop 0
	global_load_lds_dwordx4 v[180:181], off
	v_mfma_f32_32x32x16_bf16 v[32:47], v[142:145], v[138:141], v[32:47]
	s_waitcnt vmcnt(6)
	s_waitcnt lgkmcnt(0)
	s_barrier
	s_waitcnt lgkmcnt(0)
	v_mfma_f32_32x32x16_bf16 v[16:31], v[134:137], v[154:157], v[16:31]
	v_lshl_add_u64 v[158:159], v[66:67], 0, s[30:31]
	s_nop 0
	v_lshl_add_u64 v[160:161], v[68:69], 0, s[30:31]
	s_nop 0
	s_nop 0
	s_nop 0
	v_lshl_add_u64 v[162:163], v[70:71], 0, s[30:31]
	s_nop 0
	v_mfma_f32_32x32x16_bf16 v[0:15], v[142:145], v[154:157], v[0:15]
	s_and_b32 m0, s32, 7
	s_lshl_b32 m0, m0, 12
	s_add_i32 m0, m0, 0x18000
	s_nop 0
	global_load_lds_dwordx4 v[158:159], off
	s_nop 0
	v_lshl_add_u64 v[164:165], v[72:73], 0, s[30:31]
	s_nop 0
	s_nop 0
	s_nop 0
	v_lshl_add_u64 v[166:167], v[74:75], 0, s[30:31]
	s_nop 0
	s_nop 0
	s_nop 0
	v_lshl_add_u64 v[168:169], v[76:77], 0, s[30:31]
	s_nop 0
	s_mov_b64 s[30:31], 0x300
	s_nop 0
	ds_read_b128 v[134:137], v85 offset:32768
	ds_read_b128 v[138:141], v84
	ds_read_b128 v[142:145], v85 offset:36864
	ds_read_b128 v[150:153], v84 offset:4096
	s_waitcnt lgkmcnt(1)
	v_mfma_f32_32x32x16_bf16 v[48:63], v[134:137], v[138:141], v[48:63]
	s_nop 0
	v_readfirstlane_b32 s40, v119
	v_mfma_f32_32x32x16_bf16 v[32:47], v[142:145], v[138:141], v[32:47]
	s_waitcnt lgkmcnt(0)
	v_mfma_f32_32x32x16_bf16 v[16:31], v[134:137], v[150:153], v[16:31]
	s_and_b32 m0, s32, 7
	s_lshl_b32 m0, m0, 12
	s_add_i32 m0, m0, 0x18400
	s_nop 0
	global_load_lds_dwordx4 v[160:161], off
	v_mfma_f32_32x32x16_bf16 v[0:15], v[142:145], v[150:153], v[0:15]
	ds_read_b128 v[134:137], v83 offset:32768
	ds_read_b128 v[138:141], v82
	ds_read_b128 v[142:145], v83 offset:36864
	ds_read_b128 v[154:157], v82 offset:4096
	s_waitcnt lgkmcnt(1)
	v_mfma_f32_32x32x16_bf16 v[48:63], v[134:137], v[138:141], v[48:63]
	s_and_b32 m0, s32, 7
	s_lshl_b32 m0, m0, 12
	s_add_i32 m0, m0, 0x18800
	s_nop 0
	global_load_lds_dwordx4 v[162:163], off
	v_mfma_f32_32x32x16_bf16 v[32:47], v[142:145], v[138:141], v[32:47]
	s_waitcnt lgkmcnt(0)
	v_mfma_f32_32x32x16_bf16 v[16:31], v[134:137], v[154:157], v[16:31]
	v_mfma_f32_32x32x16_bf16 v[0:15], v[142:145], v[154:157], v[0:15]
	s_and_b32 m0, s32, 7
	s_lshl_b32 m0, m0, 12
	s_add_i32 m0, m0, 0x18c00
	s_nop 0
	global_load_lds_dwordx4 v[164:165], off
	ds_read_b128 v[134:137], v87 offset:32768
	ds_read_b128 v[138:141], v86
	ds_read_b128 v[142:145], v87 offset:36864
	ds_read_b128 v[150:153], v86 offset:4096
	s_waitcnt lgkmcnt(1)
	v_mfma_f32_32x32x16_bf16 v[48:63], v[134:137], v[138:141], v[48:63]
	v_mfma_f32_32x32x16_bf16 v[32:47], v[142:145], v[138:141], v[32:47]
	s_waitcnt lgkmcnt(0)
	v_mfma_f32_32x32x16_bf16 v[16:31], v[134:137], v[150:153], v[16:31]
	s_and_b32 m0, s32, 7
	s_lshl_b32 m0, m0, 11
	s_add_i32 m0, m0, 0x20000
	s_nop 0
	global_load_lds_dwordx4 v[166:167], off
	v_mfma_f32_32x32x16_bf16 v[0:15], v[142:145], v[150:153], v[0:15]
	ds_read_b128 v[134:137], v89 offset:32768
	ds_read_b128 v[138:141], v88
	ds_read_b128 v[142:145], v89 offset:36864
	ds_read_b128 v[154:157], v88 offset:4096
	s_waitcnt lgkmcnt(1)
	v_mfma_f32_32x32x16_bf16 v[48:63], v[134:137], v[138:141], v[48:63]
	s_and_b32 m0, s32, 7
	s_lshl_b32 m0, m0, 11
	s_add_i32 m0, m0, 0x20400
	s_nop 0
	global_load_lds_dwordx4 v[168:169], off
	v_mfma_f32_32x32x16_bf16 v[32:47], v[142:145], v[138:141], v[32:47]
	s_waitcnt vmcnt(6)
	s_waitcnt lgkmcnt(0)
	s_barrier
	s_waitcnt lgkmcnt(0)
	v_mfma_f32_32x32x16_bf16 v[16:31], v[134:137], v[154:157], v[16:31]
	v_lshl_add_u64 v[170:171], v[66:67], 0, s[30:31]
	s_nop 0
	v_lshl_add_u64 v[172:173], v[68:69], 0, s[30:31]
	s_nop 0
	v_readfirstlane_b32 s41, v114
	s_nop 0
	v_lshl_add_u64 v[174:175], v[70:71], 0, s[30:31]
	s_nop 0
	v_mfma_f32_32x32x16_bf16 v[0:15], v[142:145], v[154:157], v[0:15]
	s_and_b32 m0, s32, 7
	s_lshl_b32 m0, m0, 12
	s_add_i32 m0, m0, 0x0
	s_nop 0
	global_load_lds_dwordx4 v[170:171], off
	s_nop 0
	v_lshl_add_u64 v[176:177], v[72:73], 0, s[30:31]
	s_nop 0
	v_readfirstlane_b32 s42, v115
	s_nop 0
	v_lshl_add_u64 v[178:179], v[74:75], 0, s[30:31]
	s_nop 0
	v_readfirstlane_b32 s43, v116
	s_nop 0
	v_lshl_add_u64 v[180:181], v[76:77], 0, s[30:31]
	s_nop 0
	s_mov_b64 s[30:31], 0x380
	s_nop 0
	ds_read_b128 v[134:137], v91
	ds_read_b128 v[138:141], v84 offset:49152
	ds_read_b128 v[142:145], v90
	ds_read_b128 v[150:153], v84 offset:53248
	s_waitcnt lgkmcnt(1)
	v_mfma_f32_32x32x16_bf16 v[48:63], v[134:137], v[138:141], v[48:63]
	s_nop 0
	v_readfirstlane_b32 s29, v125
	v_readfirstlane_b32 s44, v117
	v_readfirstlane_b32 s45, v118
	v_mfma_f32_32x32x16_bf16 v[32:47], v[142:145], v[138:141], v[32:47]
	s_waitcnt lgkmcnt(0)
	v_mfma_f32_32x32x16_bf16 v[16:31], v[134:137], v[150:153], v[16:31]
	s_and_b32 m0, s32, 7
	s_lshl_b32 m0, m0, 12
	s_add_i32 m0, m0, 0x400
	s_nop 0
	global_load_lds_dwordx4 v[172:173], off
	v_mfma_f32_32x32x16_bf16 v[0:15], v[142:145], v[150:153], v[0:15]
	ds_read_b128 v[134:137], v94
	ds_read_b128 v[138:141], v82 offset:49152
	ds_read_b128 v[142:145], v92
	ds_read_b128 v[154:157], v82 offset:53248
	s_waitcnt lgkmcnt(1)
	v_mfma_f32_32x32x16_bf16 v[48:63], v[134:137], v[138:141], v[48:63]
	s_and_b32 m0, s32, 7
	s_lshl_b32 m0, m0, 12
	s_add_i32 m0, m0, 0x800
	s_nop 0
	global_load_lds_dwordx4 v[174:175], off
	v_mfma_f32_32x32x16_bf16 v[32:47], v[142:145], v[138:141], v[32:47]
	s_waitcnt lgkmcnt(0)
	v_mfma_f32_32x32x16_bf16 v[16:31], v[134:137], v[154:157], v[16:31]
	v_mfma_f32_32x32x16_bf16 v[0:15], v[142:145], v[154:157], v[0:15]
	s_and_b32 m0, s32, 7
	s_lshl_b32 m0, m0, 12
	s_add_i32 m0, m0, 0xc00
	s_nop 0
	global_load_lds_dwordx4 v[176:177], off
	ds_read_b128 v[134:137], v95
	ds_read_b128 v[138:141], v86 offset:49152
	ds_read_b128 v[142:145], v93
	ds_read_b128 v[150:153], v86 offset:53248
	s_waitcnt lgkmcnt(1)
	v_mfma_f32_32x32x16_bf16 v[48:63], v[134:137], v[138:141], v[48:63]
	v_mfma_f32_32x32x16_bf16 v[32:47], v[142:145], v[138:141], v[32:47]
	s_waitcnt lgkmcnt(0)
	v_mfma_f32_32x32x16_bf16 v[16:31], v[134:137], v[150:153], v[16:31]
	s_and_b32 m0, s32, 7
	s_lshl_b32 m0, m0, 11
	s_add_i32 m0, m0, 0x8000
	s_nop 0
	global_load_lds_dwordx4 v[178:179], off
	v_mfma_f32_32x32x16_bf16 v[0:15], v[142:145], v[150:153], v[0:15]
	ds_read_b128 v[134:137], v97
	ds_read_b128 v[138:141], v88 offset:49152
	ds_read_b128 v[142:145], v96
	ds_read_b128 v[154:157], v88 offset:53248
	s_waitcnt lgkmcnt(1)
	v_mfma_f32_32x32x16_bf16 v[48:63], v[134:137], v[138:141], v[48:63]
	s_and_b32 m0, s32, 7
	s_lshl_b32 m0, m0, 11
	s_add_i32 m0, m0, 0x8400
	s_nop 0
	global_load_lds_dwordx4 v[180:181], off
	v_mfma_f32_32x32x16_bf16 v[32:47], v[142:145], v[138:141], v[32:47]
	s_waitcnt vmcnt(6)
	s_waitcnt lgkmcnt(0)
	s_barrier
	s_waitcnt lgkmcnt(0)
	v_mfma_f32_32x32x16_bf16 v[16:31], v[134:137], v[154:157], v[16:31]
	v_lshl_add_u64 v[158:159], v[66:67], 0, s[30:31]
	s_nop 0
	v_lshl_add_u64 v[160:161], v[68:69], 0, s[30:31]
	s_nop 0
	v_readfirstlane_b32 s33, v120
	s_nop 0
	v_lshl_add_u64 v[162:163], v[70:71], 0, s[30:31]
	s_nop 0
	v_mfma_f32_32x32x16_bf16 v[0:15], v[142:145], v[154:157], v[0:15]
	s_and_b32 m0, s32, 7
	s_lshl_b32 m0, m0, 12
	s_add_i32 m0, m0, 0xc000
	s_nop 0
	global_load_lds_dwordx4 v[158:159], off
	s_nop 0
	v_lshl_add_u64 v[164:165], v[72:73], 0, s[30:31]
	s_nop 0
	v_readfirstlane_b32 s36, v121
	s_nop 0
	v_lshl_add_u64 v[166:167], v[74:75], 0, s[30:31]
	s_nop 0
	v_readfirstlane_b32 s37, v122
	s_nop 0
	v_lshl_add_u64 v[168:169], v[76:77], 0, s[30:31]
	s_nop 0
	s_mov_b64 s[30:31], 0x400
	s_nop 0
	ds_read_b128 v[134:137], v98
	ds_read_b128 v[138:141], v100
	ds_read_b128 v[142:145], v99
	ds_read_b128 v[150:153], v101
	s_waitcnt lgkmcnt(1)
	v_mfma_f32_32x32x16_bf16 v[48:63], v[134:137], v[138:141], v[48:63]
	s_nop 0
	v_readfirstlane_b32 s0, v131
	v_readfirstlane_b32 s38, v123
	v_readfirstlane_b32 s39, v124
	v_mfma_f32_32x32x16_bf16 v[32:47], v[142:145], v[138:141], v[32:47]
	s_waitcnt lgkmcnt(0)
	v_mfma_f32_32x32x16_bf16 v[16:31], v[134:137], v[150:153], v[16:31]
	s_and_b32 m0, s32, 7
	s_lshl_b32 m0, m0, 12
	s_add_i32 m0, m0, 0xc400
	s_nop 0
	global_load_lds_dwordx4 v[160:161], off
	v_mfma_f32_32x32x16_bf16 v[0:15], v[142:145], v[150:153], v[0:15]
	ds_read_b128 v[134:137], v103
	ds_read_b128 v[138:141], v104
	ds_read_b128 v[142:145], v102
	ds_read_b128 v[154:157], v105
	s_waitcnt lgkmcnt(1)
	v_mfma_f32_32x32x16_bf16 v[48:63], v[134:137], v[138:141], v[48:63]
	s_and_b32 m0, s32, 7
	s_lshl_b32 m0, m0, 12
	s_add_i32 m0, m0, 0xc800
	s_nop 0
	global_load_lds_dwordx4 v[162:163], off
	v_mfma_f32_32x32x16_bf16 v[32:47], v[142:145], v[138:141], v[32:47]
	s_waitcnt lgkmcnt(0)
	v_mfma_f32_32x32x16_bf16 v[16:31], v[134:137], v[154:157], v[16:31]
	v_mfma_f32_32x32x16_bf16 v[0:15], v[142:145], v[154:157], v[0:15]
	s_and_b32 m0, s32, 7
	s_lshl_b32 m0, m0, 12
	s_add_i32 m0, m0, 0xcc00
	s_nop 0
	global_load_lds_dwordx4 v[164:165], off
	ds_read_b128 v[134:137], v107
	ds_read_b128 v[138:141], v108
	ds_read_b128 v[142:145], v106
	ds_read_b128 v[150:153], v109
	s_waitcnt lgkmcnt(1)
	v_mfma_f32_32x32x16_bf16 v[48:63], v[134:137], v[138:141], v[48:63]
	v_mfma_f32_32x32x16_bf16 v[32:47], v[142:145], v[138:141], v[32:47]
	s_waitcnt lgkmcnt(0)
	v_mfma_f32_32x32x16_bf16 v[16:31], v[134:137], v[150:153], v[16:31]
	s_and_b32 m0, s32, 7
	s_lshl_b32 m0, m0, 11
	s_add_i32 m0, m0, 0x14000
	s_nop 0
	global_load_lds_dwordx4 v[166:167], off
	v_mfma_f32_32x32x16_bf16 v[0:15], v[142:145], v[150:153], v[0:15]
	ds_read_b128 v[134:137], v111
	ds_read_b128 v[138:141], v112
	ds_read_b128 v[142:145], v110
	ds_read_b128 v[154:157], v113
	s_waitcnt lgkmcnt(1)
	v_mfma_f32_32x32x16_bf16 v[48:63], v[134:137], v[138:141], v[48:63]
	s_and_b32 m0, s32, 7
	s_lshl_b32 m0, m0, 11
	s_add_i32 m0, m0, 0x14400
	s_nop 0
	global_load_lds_dwordx4 v[168:169], off
	v_mfma_f32_32x32x16_bf16 v[32:47], v[142:145], v[138:141], v[32:47]
	s_waitcnt vmcnt(6)
	s_waitcnt lgkmcnt(0)
	s_barrier
	s_waitcnt lgkmcnt(0)
	v_mfma_f32_32x32x16_bf16 v[16:31], v[134:137], v[154:157], v[16:31]
	v_lshl_add_u64 v[170:171], v[66:67], 0, s[30:31]
	s_nop 0
	v_lshl_add_u64 v[172:173], v[68:69], 0, s[30:31]
	s_nop 0
	v_readfirstlane_b32 s1, v130
	s_nop 0
	v_lshl_add_u64 v[174:175], v[70:71], 0, s[30:31]
	s_nop 0
	v_mfma_f32_32x32x16_bf16 v[0:15], v[142:145], v[154:157], v[0:15]
	s_and_b32 m0, s32, 7
	s_lshl_b32 m0, m0, 12
	s_add_i32 m0, m0, 0x18000
	s_nop 0
	global_load_lds_dwordx4 v[170:171], off
	s_nop 0
	v_lshl_add_u64 v[176:177], v[72:73], 0, s[30:31]
	s_nop 0
	v_readfirstlane_b32 s21, v128
	s_nop 0
	v_lshl_add_u64 v[178:179], v[74:75], 0, s[30:31]
	s_nop 0
	v_readfirstlane_b32 s22, v126
	s_nop 0
	v_lshl_add_u64 v[180:181], v[76:77], 0, s[30:31]
	s_nop 0
	s_mov_b64 s[30:31], 0x480
	s_nop 0
	ds_read_b128 v[134:137], v85 offset:32768
	ds_read_b128 v[138:141], v84
	ds_read_b128 v[142:145], v85 offset:36864
	ds_read_b128 v[150:153], v84 offset:4096
	s_waitcnt lgkmcnt(1)
	v_mfma_f32_32x32x16_bf16 v[48:63], v[134:137], v[138:141], v[48:63]
	s_nop 0
	v_lshl_add_u64 v[160:161], v[68:69], 0, s[30:31]
	v_readfirstlane_b32 s23, v129
	v_lshl_add_u64 v[166:167], v[74:75], 0, s[30:31]
	v_readfirstlane_b32 s28, v127
	v_lshl_add_u64 v[168:169], v[76:77], 0, s[30:31]
	v_mfma_f32_32x32x16_bf16 v[32:47], v[142:145], v[138:141], v[32:47]
	s_waitcnt lgkmcnt(0)
	v_mfma_f32_32x32x16_bf16 v[16:31], v[134:137], v[150:153], v[16:31]
	s_and_b32 m0, s32, 7
	s_lshl_b32 m0, m0, 12
	s_add_i32 m0, m0, 0x18400
	s_nop 0
	global_load_lds_dwordx4 v[172:173], off
	v_mfma_f32_32x32x16_bf16 v[0:15], v[142:145], v[150:153], v[0:15]
	ds_read_b128 v[134:137], v83 offset:32768
	ds_read_b128 v[138:141], v82
	ds_read_b128 v[142:145], v83 offset:36864
	ds_read_b128 v[154:157], v82 offset:4096
	s_waitcnt lgkmcnt(1)
	v_mfma_f32_32x32x16_bf16 v[48:63], v[134:137], v[138:141], v[48:63]
	s_and_b32 m0, s32, 7
	s_lshl_b32 m0, m0, 12
	s_add_i32 m0, m0, 0x18800
	s_nop 0
	global_load_lds_dwordx4 v[174:175], off
	v_mfma_f32_32x32x16_bf16 v[32:47], v[142:145], v[138:141], v[32:47]
	s_waitcnt lgkmcnt(0)
	v_mfma_f32_32x32x16_bf16 v[16:31], v[134:137], v[154:157], v[16:31]
	v_mfma_f32_32x32x16_bf16 v[0:15], v[142:145], v[154:157], v[0:15]
	s_and_b32 m0, s32, 7
	s_lshl_b32 m0, m0, 12
	s_add_i32 m0, m0, 0x18c00
	s_nop 0
	global_load_lds_dwordx4 v[176:177], off
	ds_read_b128 v[134:137], v87 offset:32768
	ds_read_b128 v[138:141], v86
	ds_read_b128 v[142:145], v87 offset:36864
	ds_read_b128 v[150:153], v86 offset:4096
	s_waitcnt lgkmcnt(1)
	v_mfma_f32_32x32x16_bf16 v[48:63], v[134:137], v[138:141], v[48:63]
	v_mfma_f32_32x32x16_bf16 v[32:47], v[142:145], v[138:141], v[32:47]
	s_waitcnt lgkmcnt(0)
	v_mfma_f32_32x32x16_bf16 v[16:31], v[134:137], v[150:153], v[16:31]
	s_and_b32 m0, s32, 7
	s_lshl_b32 m0, m0, 11
	s_add_i32 m0, m0, 0x20000
	s_nop 0
	global_load_lds_dwordx4 v[178:179], off
	v_mfma_f32_32x32x16_bf16 v[0:15], v[142:145], v[150:153], v[0:15]
	ds_read_b128 v[134:137], v89 offset:32768
	ds_read_b128 v[138:141], v88
	ds_read_b128 v[142:145], v89 offset:36864
	ds_read_b128 v[154:157], v88 offset:4096
	s_waitcnt lgkmcnt(1)
	v_mfma_f32_32x32x16_bf16 v[48:63], v[134:137], v[138:141], v[48:63]
	s_and_b32 m0, s32, 7
	s_lshl_b32 m0, m0, 11
	s_add_i32 m0, m0, 0x20400
	s_nop 0
	global_load_lds_dwordx4 v[180:181], off
	v_mfma_f32_32x32x16_bf16 v[32:47], v[142:145], v[138:141], v[32:47]
	s_waitcnt vmcnt(6)
	s_waitcnt lgkmcnt(0)
	s_barrier
	s_waitcnt lgkmcnt(0)
	v_mfma_f32_32x32x16_bf16 v[16:31], v[134:137], v[154:157], v[16:31]
	v_lshl_add_u64 v[158:159], v[66:67], 0, s[30:31]
	s_nop 0
	s_nop 0
	s_nop 0
	s_nop 0
	v_lshl_add_u64 v[162:163], v[70:71], 0, s[30:31]
	s_nop 0
	v_mfma_f32_32x32x16_bf16 v[0:15], v[142:145], v[154:157], v[0:15]
	s_and_b32 m0, s32, 7
	s_lshl_b32 m0, m0, 12
	s_add_i32 m0, m0, 0x0
	s_nop 0
	global_load_lds_dwordx4 v[158:159], off
	s_nop 0
	v_lshl_add_u64 v[164:165], v[72:73], 0, s[30:31]
	s_nop 0
	s_mov_b64 s[30:31], 0x500
	s_nop 0
	s_nop 0
	v_lshl_add_u64 v[174:175], v[70:71], 0, s[30:31]
	s_nop 0
	s_nop 0
	s_nop 0
	s_nop 0
	ds_read_b128 v[126:129], v91
	ds_read_b128 v[134:137], v84 offset:49152
	ds_read_b128 v[138:141], v90
	ds_read_b128 v[150:153], v84 offset:53248
	s_waitcnt lgkmcnt(1)
	v_mfma_f32_32x32x16_bf16 v[48:63], v[126:129], v[134:137], v[48:63]
	s_nop 0
	v_mfma_f32_32x32x16_bf16 v[32:47], v[138:141], v[134:137], v[32:47]
	s_waitcnt lgkmcnt(0)
	v_mfma_f32_32x32x16_bf16 v[16:31], v[126:129], v[150:153], v[16:31]
	s_and_b32 m0, s32, 7
	s_lshl_b32 m0, m0, 12
	s_add_i32 m0, m0, 0x400
	s_nop 0
	global_load_lds_dwordx4 v[160:161], off
	v_mfma_f32_32x32x16_bf16 v[0:15], v[138:141], v[150:153], v[0:15]
	ds_read_b128 v[126:129], v94
	ds_read_b128 v[134:137], v82 offset:49152
	ds_read_b128 v[138:141], v92
	ds_read_b128 v[154:157], v82 offset:53248
	s_waitcnt lgkmcnt(1)
	v_mfma_f32_32x32x16_bf16 v[48:63], v[126:129], v[134:137], v[48:63]
	s_and_b32 m0, s32, 7
	s_lshl_b32 m0, m0, 12
	s_add_i32 m0, m0, 0x800
	s_nop 0
	global_load_lds_dwordx4 v[162:163], off
	v_mfma_f32_32x32x16_bf16 v[32:47], v[138:141], v[134:137], v[32:47]
	s_waitcnt lgkmcnt(0)
	v_mfma_f32_32x32x16_bf16 v[16:31], v[126:129], v[154:157], v[16:31]
	v_mfma_f32_32x32x16_bf16 v[0:15], v[138:141], v[154:157], v[0:15]
	s_and_b32 m0, s32, 7
	s_lshl_b32 m0, m0, 12
	s_add_i32 m0, m0, 0xc00
	s_nop 0
	global_load_lds_dwordx4 v[164:165], off
	ds_read_b128 v[126:129], v95
	ds_read_b128 v[134:137], v86 offset:49152
	ds_read_b128 v[138:141], v93
	ds_read_b128 v[150:153], v86 offset:53248
	s_waitcnt lgkmcnt(1)
	v_mfma_f32_32x32x16_bf16 v[48:63], v[126:129], v[134:137], v[48:63]
	v_mfma_f32_32x32x16_bf16 v[32:47], v[138:141], v[134:137], v[32:47]
	s_waitcnt lgkmcnt(0)
	v_mfma_f32_32x32x16_bf16 v[16:31], v[126:129], v[150:153], v[16:31]
	s_and_b32 m0, s32, 7
	s_lshl_b32 m0, m0, 11
	s_add_i32 m0, m0, 0x8000
	s_nop 0
	global_load_lds_dwordx4 v[166:167], off
	v_mfma_f32_32x32x16_bf16 v[0:15], v[138:141], v[150:153], v[0:15]
	ds_read_b128 v[126:129], v97
	ds_read_b128 v[134:137], v88 offset:49152
	ds_read_b128 v[138:141], v96
	ds_read_b128 v[154:157], v88 offset:53248
	s_waitcnt lgkmcnt(1)
	v_mfma_f32_32x32x16_bf16 v[48:63], v[126:129], v[134:137], v[48:63]
	s_and_b32 m0, s32, 7
	s_lshl_b32 m0, m0, 11
	s_add_i32 m0, m0, 0x8400
	s_nop 0
	global_load_lds_dwordx4 v[168:169], off
	v_mfma_f32_32x32x16_bf16 v[32:47], v[138:141], v[134:137], v[32:47]
	s_waitcnt vmcnt(6)
	s_waitcnt lgkmcnt(0)
	s_barrier
	s_waitcnt lgkmcnt(0)
	v_mfma_f32_32x32x16_bf16 v[16:31], v[126:129], v[154:157], v[16:31]
	v_lshl_add_u64 v[170:171], v[66:67], 0, s[30:31]
	s_nop 0
	v_lshl_add_u64 v[172:173], v[68:69], 0, s[30:31]
	s_nop 0
	s_nop 0
	s_nop 0
	s_nop 0
	v_mfma_f32_32x32x16_bf16 v[0:15], v[138:141], v[154:157], v[0:15]
	s_and_b32 m0, s32, 7
	s_lshl_b32 m0, m0, 12
	s_add_i32 m0, m0, 0xc000
	s_nop 0
	global_load_lds_dwordx4 v[170:171], off
	s_nop 0
	v_lshl_add_u64 v[176:177], v[72:73], 0, s[30:31]
	s_nop 0
	s_nop 0
	s_nop 0
	v_lshl_add_u64 v[178:179], v[74:75], 0, s[30:31]
	s_nop 0
	s_nop 0
	s_nop 0
	v_lshl_add_u64 v[180:181], v[76:77], 0, s[30:31]
	s_nop 0
	s_mov_b64 s[30:31], 0x580
	s_nop 0
	ds_read_b128 v[120:123], v98
	ds_read_b128 v[124:127], v100
	ds_read_b128 v[128:131], v99
	ds_read_b128 v[150:153], v101
	s_waitcnt lgkmcnt(1)
	v_mfma_f32_32x32x16_bf16 v[48:63], v[120:123], v[124:127], v[48:63]
	s_nop 0
	v_lshl_add_u64 v[162:163], v[70:71], 0, s[30:31]
	v_mfma_f32_32x32x16_bf16 v[32:47], v[128:131], v[124:127], v[32:47]
	s_waitcnt lgkmcnt(0)
	v_mfma_f32_32x32x16_bf16 v[16:31], v[120:123], v[150:153], v[16:31]
	s_and_b32 m0, s32, 7
	s_lshl_b32 m0, m0, 12
	s_add_i32 m0, m0, 0xc400
	s_nop 0
	global_load_lds_dwordx4 v[172:173], off
	v_mfma_f32_32x32x16_bf16 v[0:15], v[128:131], v[150:153], v[0:15]
	ds_read_b128 v[120:123], v103
	ds_read_b128 v[124:127], v104
	ds_read_b128 v[128:131], v102
	ds_read_b128 v[154:157], v105
	s_waitcnt lgkmcnt(1)
	v_mfma_f32_32x32x16_bf16 v[48:63], v[120:123], v[124:127], v[48:63]
	s_and_b32 m0, s32, 7
	s_lshl_b32 m0, m0, 12
	s_add_i32 m0, m0, 0xc800
	s_nop 0
	global_load_lds_dwordx4 v[174:175], off
	v_mfma_f32_32x32x16_bf16 v[32:47], v[128:131], v[124:127], v[32:47]
	s_waitcnt lgkmcnt(0)
	v_mfma_f32_32x32x16_bf16 v[16:31], v[120:123], v[154:157], v[16:31]
	v_mfma_f32_32x32x16_bf16 v[0:15], v[128:131], v[154:157], v[0:15]
	s_and_b32 m0, s32, 7
	s_lshl_b32 m0, m0, 12
	s_add_i32 m0, m0, 0xcc00
	s_nop 0
	global_load_lds_dwordx4 v[176:177], off
	ds_read_b128 v[120:123], v107
	ds_read_b128 v[124:127], v108
	ds_read_b128 v[128:131], v106
	ds_read_b128 v[150:153], v109
	s_waitcnt lgkmcnt(1)
	v_mfma_f32_32x32x16_bf16 v[48:63], v[120:123], v[124:127], v[48:63]
	v_mfma_f32_32x32x16_bf16 v[32:47], v[128:131], v[124:127], v[32:47]
	s_waitcnt lgkmcnt(0)
	v_mfma_f32_32x32x16_bf16 v[16:31], v[120:123], v[150:153], v[16:31]
	s_and_b32 m0, s32, 7
	s_lshl_b32 m0, m0, 11
	s_add_i32 m0, m0, 0x14000
	s_nop 0
	global_load_lds_dwordx4 v[178:179], off
	v_mfma_f32_32x32x16_bf16 v[0:15], v[128:131], v[150:153], v[0:15]
	ds_read_b128 v[120:123], v111
	ds_read_b128 v[124:127], v112
	ds_read_b128 v[128:131], v110
	ds_read_b128 v[154:157], v113
	s_waitcnt lgkmcnt(1)
	v_mfma_f32_32x32x16_bf16 v[48:63], v[120:123], v[124:127], v[48:63]
	s_and_b32 m0, s32, 7
	s_lshl_b32 m0, m0, 11
	s_add_i32 m0, m0, 0x14400
	s_nop 0
	global_load_lds_dwordx4 v[180:181], off
	v_mfma_f32_32x32x16_bf16 v[32:47], v[128:131], v[124:127], v[32:47]
	s_waitcnt vmcnt(6)
	s_waitcnt lgkmcnt(0)
	s_barrier
	s_waitcnt lgkmcnt(0)
	v_mfma_f32_32x32x16_bf16 v[16:31], v[120:123], v[154:157], v[16:31]
	v_lshl_add_u64 v[158:159], v[66:67], 0, s[30:31]
	s_nop 0
	v_lshl_add_u64 v[160:161], v[68:69], 0, s[30:31]
	s_nop 0
	s_nop 0
	s_nop 0
	s_nop 0
	v_mfma_f32_32x32x16_bf16 v[0:15], v[128:131], v[154:157], v[0:15]
	s_and_b32 m0, s32, 7
	s_lshl_b32 m0, m0, 12
	s_add_i32 m0, m0, 0x18000
	s_nop 0
	global_load_lds_dwordx4 v[158:159], off
	s_nop 0
	v_lshl_add_u64 v[164:165], v[72:73], 0, s[30:31]
	s_nop 0
	s_nop 0
	s_nop 0
	v_lshl_add_u64 v[166:167], v[74:75], 0, s[30:31]
	s_nop 0
	s_nop 0
	s_nop 0
	v_lshl_add_u64 v[168:169], v[76:77], 0, s[30:31]
	s_nop 0
	s_mov_b64 s[30:31], 0x600
	s_nop 0
	ds_read_b128 v[114:117], v85 offset:32768
	ds_read_b128 v[118:121], v84
	ds_read_b128 v[122:125], v85 offset:36864
	ds_read_b128 v[150:153], v84 offset:4096
	s_waitcnt lgkmcnt(1)
	v_mfma_f32_32x32x16_bf16 v[48:63], v[114:117], v[118:121], v[48:63]
	s_nop 0
	v_mfma_f32_32x32x16_bf16 v[32:47], v[122:125], v[118:121], v[32:47]
	s_waitcnt lgkmcnt(0)
	v_mfma_f32_32x32x16_bf16 v[16:31], v[114:117], v[150:153], v[16:31]
	s_and_b32 m0, s32, 7
	s_lshl_b32 m0, m0, 12
	s_add_i32 m0, m0, 0x18400
	s_nop 0
	global_load_lds_dwordx4 v[160:161], off
	v_mfma_f32_32x32x16_bf16 v[0:15], v[122:125], v[150:153], v[0:15]
	ds_read_b128 v[114:117], v83 offset:32768
	ds_read_b128 v[118:121], v82
	ds_read_b128 v[122:125], v83 offset:36864
	ds_read_b128 v[154:157], v82 offset:4096
	s_waitcnt lgkmcnt(1)
	v_mfma_f32_32x32x16_bf16 v[48:63], v[114:117], v[118:121], v[48:63]
	s_and_b32 m0, s32, 7
	s_lshl_b32 m0, m0, 12
	s_add_i32 m0, m0, 0x18800
	s_nop 0
	global_load_lds_dwordx4 v[162:163], off
	v_mfma_f32_32x32x16_bf16 v[32:47], v[122:125], v[118:121], v[32:47]
	s_waitcnt lgkmcnt(0)
	v_mfma_f32_32x32x16_bf16 v[16:31], v[114:117], v[154:157], v[16:31]
	v_mfma_f32_32x32x16_bf16 v[0:15], v[122:125], v[154:157], v[0:15]
	s_and_b32 m0, s32, 7
	s_lshl_b32 m0, m0, 12
	s_add_i32 m0, m0, 0x18c00
	s_nop 0
	global_load_lds_dwordx4 v[164:165], off
	ds_read_b128 v[114:117], v87 offset:32768
	ds_read_b128 v[118:121], v86
	ds_read_b128 v[122:125], v87 offset:36864
	ds_read_b128 v[150:153], v86 offset:4096
	s_waitcnt lgkmcnt(1)
	v_mfma_f32_32x32x16_bf16 v[48:63], v[114:117], v[118:121], v[48:63]
	v_mfma_f32_32x32x16_bf16 v[32:47], v[122:125], v[118:121], v[32:47]
	s_waitcnt lgkmcnt(0)
	v_mfma_f32_32x32x16_bf16 v[16:31], v[114:117], v[150:153], v[16:31]
	s_and_b32 m0, s32, 7
	s_lshl_b32 m0, m0, 11
	s_add_i32 m0, m0, 0x20000
	s_nop 0
	global_load_lds_dwordx4 v[166:167], off
	v_mfma_f32_32x32x16_bf16 v[0:15], v[122:125], v[150:153], v[0:15]
	ds_read_b128 v[114:117], v89 offset:32768
	ds_read_b128 v[118:121], v88
	ds_read_b128 v[122:125], v89 offset:36864
	ds_read_b128 v[154:157], v88 offset:4096
	s_waitcnt lgkmcnt(1)
	v_mfma_f32_32x32x16_bf16 v[48:63], v[114:117], v[118:121], v[48:63]
	s_and_b32 m0, s32, 7
	s_lshl_b32 m0, m0, 11
	s_add_i32 m0, m0, 0x20400
	s_nop 0
	global_load_lds_dwordx4 v[168:169], off
	v_mfma_f32_32x32x16_bf16 v[32:47], v[122:125], v[118:121], v[32:47]
	s_waitcnt vmcnt(6)
	s_waitcnt lgkmcnt(0)
	s_barrier
	s_waitcnt lgkmcnt(0)
	v_mfma_f32_32x32x16_bf16 v[16:31], v[114:117], v[154:157], v[16:31]
	v_lshl_add_u64 v[170:171], v[66:67], 0, s[30:31]
	s_nop 0
	v_lshl_add_u64 v[172:173], v[68:69], 0, s[30:31]
	s_nop 0
	s_nop 0
	s_nop 0
	v_lshl_add_u64 v[174:175], v[70:71], 0, s[30:31]
	s_nop 0
	v_mfma_f32_32x32x16_bf16 v[0:15], v[122:125], v[154:157], v[0:15]
	s_and_b32 m0, s32, 7
	s_lshl_b32 m0, m0, 12
	s_add_i32 m0, m0, 0x0
	s_nop 0
	global_load_lds_dwordx4 v[170:171], off
	s_nop 0
	v_lshl_add_u64 v[176:177], v[72:73], 0, s[30:31]
	s_nop 0
	s_nop 0
	s_nop 0
	v_lshl_add_u64 v[178:179], v[74:75], 0, s[30:31]
	s_nop 0
	s_nop 0
	s_nop 0
	v_lshl_add_u64 v[180:181], v[76:77], 0, s[30:31]
	s_nop 0
	s_mov_b64 s[30:31], 0x680
	s_nop 0
	ds_read_b128 v[114:117], v91
	ds_read_b128 v[118:121], v84 offset:49152
	ds_read_b128 v[122:125], v90
	ds_read_b128 v[150:153], v84 offset:53248
	s_waitcnt lgkmcnt(1)
	v_mfma_f32_32x32x16_bf16 v[48:63], v[114:117], v[118:121], v[48:63]
	s_nop 0
	v_mfma_f32_32x32x16_bf16 v[32:47], v[122:125], v[118:121], v[32:47]
	s_waitcnt lgkmcnt(0)
	v_mfma_f32_32x32x16_bf16 v[16:31], v[114:117], v[150:153], v[16:31]
	s_and_b32 m0, s32, 7
	s_lshl_b32 m0, m0, 12
	s_add_i32 m0, m0, 0x400
	s_nop 0
	global_load_lds_dwordx4 v[172:173], off
	v_mfma_f32_32x32x16_bf16 v[0:15], v[122:125], v[150:153], v[0:15]
	ds_read_b128 v[114:117], v94
	ds_read_b128 v[118:121], v82 offset:49152
	ds_read_b128 v[122:125], v92
	ds_read_b128 v[154:157], v82 offset:53248
	s_waitcnt lgkmcnt(1)
	v_mfma_f32_32x32x16_bf16 v[48:63], v[114:117], v[118:121], v[48:63]
	s_and_b32 m0, s32, 7
	s_lshl_b32 m0, m0, 12
	s_add_i32 m0, m0, 0x800
	s_nop 0
	global_load_lds_dwordx4 v[174:175], off
	v_mfma_f32_32x32x16_bf16 v[32:47], v[122:125], v[118:121], v[32:47]
	s_waitcnt lgkmcnt(0)
	v_mfma_f32_32x32x16_bf16 v[16:31], v[114:117], v[154:157], v[16:31]
	v_mfma_f32_32x32x16_bf16 v[0:15], v[122:125], v[154:157], v[0:15]
	s_and_b32 m0, s32, 7
	s_lshl_b32 m0, m0, 12
	s_add_i32 m0, m0, 0xc00
	s_nop 0
	global_load_lds_dwordx4 v[176:177], off
	ds_read_b128 v[114:117], v95
	ds_read_b128 v[118:121], v86 offset:49152
	ds_read_b128 v[122:125], v93
	ds_read_b128 v[150:153], v86 offset:53248
	s_waitcnt lgkmcnt(1)
	v_mfma_f32_32x32x16_bf16 v[48:63], v[114:117], v[118:121], v[48:63]
	v_mfma_f32_32x32x16_bf16 v[32:47], v[122:125], v[118:121], v[32:47]
	s_waitcnt lgkmcnt(0)
	v_mfma_f32_32x32x16_bf16 v[16:31], v[114:117], v[150:153], v[16:31]
	s_and_b32 m0, s32, 7
	s_lshl_b32 m0, m0, 11
	s_add_i32 m0, m0, 0x8000
	s_nop 0
	global_load_lds_dwordx4 v[178:179], off
	v_mfma_f32_32x32x16_bf16 v[0:15], v[122:125], v[150:153], v[0:15]
	ds_read_b128 v[114:117], v97
	ds_read_b128 v[118:121], v88 offset:49152
	ds_read_b128 v[122:125], v96
	ds_read_b128 v[154:157], v88 offset:53248
	s_waitcnt lgkmcnt(1)
	v_mfma_f32_32x32x16_bf16 v[48:63], v[114:117], v[118:121], v[48:63]
	s_and_b32 m0, s32, 7
	s_lshl_b32 m0, m0, 11
	s_add_i32 m0, m0, 0x8400
	s_nop 0
	global_load_lds_dwordx4 v[180:181], off
	v_mfma_f32_32x32x16_bf16 v[32:47], v[122:125], v[118:121], v[32:47]
	s_waitcnt vmcnt(6)
	s_waitcnt lgkmcnt(0)
	s_barrier
	s_waitcnt lgkmcnt(0)
	v_mfma_f32_32x32x16_bf16 v[16:31], v[114:117], v[154:157], v[16:31]
	v_lshl_add_u64 v[158:159], v[66:67], 0, s[30:31]
	s_nop 0
	v_lshl_add_u64 v[160:161], v[68:69], 0, s[30:31]
	s_nop 0
	s_nop 0
	s_nop 0
	v_lshl_add_u64 v[162:163], v[70:71], 0, s[30:31]
	s_nop 0
	v_mfma_f32_32x32x16_bf16 v[0:15], v[122:125], v[154:157], v[0:15]
	s_and_b32 m0, s32, 7
	s_lshl_b32 m0, m0, 12
	s_add_i32 m0, m0, 0xc000
	s_nop 0
	global_load_lds_dwordx4 v[158:159], off
	s_nop 0
	v_lshl_add_u64 v[164:165], v[72:73], 0, s[30:31]
	s_nop 0
	s_nop 0
	s_nop 0
	v_lshl_add_u64 v[166:167], v[74:75], 0, s[30:31]
	s_nop 0
	s_nop 0
	s_nop 0
	v_lshl_add_u64 v[168:169], v[76:77], 0, s[30:31]
	s_nop 0
	s_mov_b64 s[30:31], 0x700
	s_nop 0
	ds_read_b128 v[114:117], v98
	ds_read_b128 v[118:121], v100
	ds_read_b128 v[122:125], v99
	ds_read_b128 v[150:153], v101
	s_waitcnt lgkmcnt(1)
	v_mfma_f32_32x32x16_bf16 v[48:63], v[114:117], v[118:121], v[48:63]
	s_nop 0
	v_mfma_f32_32x32x16_bf16 v[32:47], v[122:125], v[118:121], v[32:47]
	s_waitcnt lgkmcnt(0)
	v_mfma_f32_32x32x16_bf16 v[16:31], v[114:117], v[150:153], v[16:31]
	s_and_b32 m0, s32, 7
	s_lshl_b32 m0, m0, 12
	s_add_i32 m0, m0, 0xc400
	s_nop 0
	global_load_lds_dwordx4 v[160:161], off
	v_mfma_f32_32x32x16_bf16 v[0:15], v[122:125], v[150:153], v[0:15]
	ds_read_b128 v[114:117], v103
	ds_read_b128 v[118:121], v104
	ds_read_b128 v[122:125], v102
	ds_read_b128 v[154:157], v105
	s_waitcnt lgkmcnt(1)
	v_mfma_f32_32x32x16_bf16 v[48:63], v[114:117], v[118:121], v[48:63]
	s_and_b32 m0, s32, 7
	s_lshl_b32 m0, m0, 12
	s_add_i32 m0, m0, 0xc800
	s_nop 0
	global_load_lds_dwordx4 v[162:163], off
	v_mfma_f32_32x32x16_bf16 v[32:47], v[122:125], v[118:121], v[32:47]
	s_waitcnt lgkmcnt(0)
	v_mfma_f32_32x32x16_bf16 v[16:31], v[114:117], v[154:157], v[16:31]
	v_mfma_f32_32x32x16_bf16 v[0:15], v[122:125], v[154:157], v[0:15]
	s_and_b32 m0, s32, 7
	s_lshl_b32 m0, m0, 12
	s_add_i32 m0, m0, 0xcc00
	s_nop 0
	global_load_lds_dwordx4 v[164:165], off
	ds_read_b128 v[114:117], v107
	ds_read_b128 v[118:121], v108
	ds_read_b128 v[122:125], v106
	ds_read_b128 v[150:153], v109
	s_waitcnt lgkmcnt(1)
	v_mfma_f32_32x32x16_bf16 v[48:63], v[114:117], v[118:121], v[48:63]
	v_mfma_f32_32x32x16_bf16 v[32:47], v[122:125], v[118:121], v[32:47]
	s_waitcnt lgkmcnt(0)
	v_mfma_f32_32x32x16_bf16 v[16:31], v[114:117], v[150:153], v[16:31]
	s_and_b32 m0, s32, 7
	s_lshl_b32 m0, m0, 11
	s_add_i32 m0, m0, 0x14000
	s_nop 0
	global_load_lds_dwordx4 v[166:167], off
	v_mfma_f32_32x32x16_bf16 v[0:15], v[122:125], v[150:153], v[0:15]
	ds_read_b128 v[114:117], v111
	ds_read_b128 v[118:121], v112
	ds_read_b128 v[122:125], v110
	ds_read_b128 v[154:157], v113
	s_waitcnt lgkmcnt(1)
	v_mfma_f32_32x32x16_bf16 v[48:63], v[114:117], v[118:121], v[48:63]
	s_and_b32 m0, s32, 7
	s_lshl_b32 m0, m0, 11
	s_add_i32 m0, m0, 0x14400
	s_nop 0
	global_load_lds_dwordx4 v[168:169], off
	v_mfma_f32_32x32x16_bf16 v[32:47], v[122:125], v[118:121], v[32:47]
	s_waitcnt vmcnt(6)
	s_waitcnt lgkmcnt(0)
	s_barrier
	s_waitcnt lgkmcnt(0)
	v_mfma_f32_32x32x16_bf16 v[16:31], v[114:117], v[154:157], v[16:31]
	v_lshl_add_u64 v[170:171], v[66:67], 0, s[30:31]
	s_nop 0
	v_lshl_add_u64 v[172:173], v[68:69], 0, s[30:31]
	s_nop 0
	s_nop 0
	s_nop 0
	v_lshl_add_u64 v[174:175], v[70:71], 0, s[30:31]
	s_nop 0
	v_mfma_f32_32x32x16_bf16 v[0:15], v[122:125], v[154:157], v[0:15]
	s_and_b32 m0, s32, 7
	s_lshl_b32 m0, m0, 12
	s_add_i32 m0, m0, 0x18000
	s_nop 0
	global_load_lds_dwordx4 v[170:171], off
	s_nop 0
	v_lshl_add_u64 v[176:177], v[72:73], 0, s[30:31]
	s_nop 0
	s_nop 0
	s_nop 0
	v_lshl_add_u64 v[178:179], v[74:75], 0, s[30:31]
	s_nop 0
	s_nop 0
	s_nop 0
	v_lshl_add_u64 v[180:181], v[76:77], 0, s[30:31]
	s_nop 0
	s_mov_b64 s[30:31], 0x780
	s_nop 0
	ds_read_b128 v[114:117], v85 offset:32768
	ds_read_b128 v[118:121], v84
	ds_read_b128 v[122:125], v85 offset:36864
	ds_read_b128 v[150:153], v84 offset:4096
	s_waitcnt lgkmcnt(1)
	v_mfma_f32_32x32x16_bf16 v[48:63], v[114:117], v[118:121], v[48:63]
	v_lshl_add_u64 v[158:159], v[66:67], 0, s[30:31]
	s_nop 0
	v_mfma_f32_32x32x16_bf16 v[32:47], v[122:125], v[118:121], v[32:47]
	s_waitcnt lgkmcnt(0)
	v_mfma_f32_32x32x16_bf16 v[16:31], v[114:117], v[150:153], v[16:31]
	s_and_b32 m0, s32, 7
	s_lshl_b32 m0, m0, 12
	s_add_i32 m0, m0, 0x18400
	s_nop 0
	global_load_lds_dwordx4 v[172:173], off
	v_mfma_f32_32x32x16_bf16 v[0:15], v[122:125], v[150:153], v[0:15]
	ds_read_b128 v[114:117], v83 offset:32768
	ds_read_b128 v[118:121], v82
	ds_read_b128 v[122:125], v83 offset:36864
	ds_read_b128 v[154:157], v82 offset:4096
	s_waitcnt lgkmcnt(1)
	v_mfma_f32_32x32x16_bf16 v[48:63], v[114:117], v[118:121], v[48:63]
	s_and_b32 m0, s32, 7
	s_lshl_b32 m0, m0, 12
	s_add_i32 m0, m0, 0x18800
	s_nop 0
	global_load_lds_dwordx4 v[174:175], off
	v_mfma_f32_32x32x16_bf16 v[32:47], v[122:125], v[118:121], v[32:47]
	s_waitcnt lgkmcnt(0)
	v_mfma_f32_32x32x16_bf16 v[16:31], v[114:117], v[154:157], v[16:31]
	v_mfma_f32_32x32x16_bf16 v[0:15], v[122:125], v[154:157], v[0:15]
	s_and_b32 m0, s32, 7
	s_lshl_b32 m0, m0, 12
	s_add_i32 m0, m0, 0x18c00
	s_nop 0
	global_load_lds_dwordx4 v[176:177], off
	ds_read_b128 v[114:117], v87 offset:32768
	ds_read_b128 v[118:121], v86
	ds_read_b128 v[122:125], v87 offset:36864
	ds_read_b128 v[150:153], v86 offset:4096
	s_waitcnt lgkmcnt(1)
	v_mfma_f32_32x32x16_bf16 v[48:63], v[114:117], v[118:121], v[48:63]
	v_mfma_f32_32x32x16_bf16 v[32:47], v[122:125], v[118:121], v[32:47]
	s_waitcnt lgkmcnt(0)
	v_mfma_f32_32x32x16_bf16 v[16:31], v[114:117], v[150:153], v[16:31]
	s_and_b32 m0, s32, 7
	s_lshl_b32 m0, m0, 11
	s_add_i32 m0, m0, 0x20000
	s_nop 0
	global_load_lds_dwordx4 v[178:179], off
	v_mfma_f32_32x32x16_bf16 v[0:15], v[122:125], v[150:153], v[0:15]
	ds_read_b128 v[114:117], v89 offset:32768
	ds_read_b128 v[118:121], v88
	ds_read_b128 v[122:125], v89 offset:36864
	ds_read_b128 v[154:157], v88 offset:4096
	s_waitcnt lgkmcnt(1)
	v_mfma_f32_32x32x16_bf16 v[48:63], v[114:117], v[118:121], v[48:63]
	s_and_b32 m0, s32, 7
	s_lshl_b32 m0, m0, 11
	s_add_i32 m0, m0, 0x20400
	s_nop 0
	global_load_lds_dwordx4 v[180:181], off
	v_mfma_f32_32x32x16_bf16 v[32:47], v[122:125], v[118:121], v[32:47]
	s_waitcnt vmcnt(6)
	s_waitcnt lgkmcnt(0)
	s_barrier
	s_nop 0
	v_lshl_add_u64 v[160:161], v[68:69], 0, s[30:31]
	s_nop 0
	s_waitcnt lgkmcnt(0)
	v_mfma_f32_32x32x16_bf16 v[16:31], v[114:117], v[154:157], v[16:31]
	s_nop 0
	v_lshl_add_u64 v[162:163], v[70:71], 0, s[30:31]
	s_nop 0
	s_nop 0
	s_nop 0
	v_lshl_add_u64 v[164:165], v[72:73], 0, s[30:31]
	s_nop 0
	v_mfma_f32_32x32x16_bf16 v[0:15], v[122:125], v[154:157], v[0:15]
	s_and_b32 m0, s32, 7
	s_lshl_b32 m0, m0, 12
	s_add_i32 m0, m0, 0x0
	s_nop 0
	global_load_lds_dwordx4 v[158:159], off
	s_nop 0
	v_lshl_add_u64 v[166:167], v[74:75], 0, s[30:31]
	s_nop 0
	s_nop 0
	s_nop 0
	v_lshl_add_u64 v[168:169], v[76:77], 0, s[30:31]
	s_nop 0
	s_nop 0
	s_nop 0
	ds_read_b128 v[66:69], v91
	ds_read_b128 v[70:73], v84 offset:49152
	ds_read_b128 v[74:77], v90
	ds_read_b128 v[150:153], v84 offset:53248
	s_waitcnt lgkmcnt(1)
	v_mfma_f32_32x32x16_bf16 v[48:63], v[66:69], v[70:73], v[48:63]
	v_mfma_f32_32x32x16_bf16 v[32:47], v[74:77], v[70:73], v[32:47]
	s_waitcnt lgkmcnt(0)
	v_mfma_f32_32x32x16_bf16 v[16:31], v[66:69], v[150:153], v[16:31]
	s_and_b32 m0, s32, 7
	s_lshl_b32 m0, m0, 12
	s_add_i32 m0, m0, 0x400
	s_nop 0
	global_load_lds_dwordx4 v[160:161], off
	v_mfma_f32_32x32x16_bf16 v[0:15], v[74:77], v[150:153], v[0:15]
	ds_read_b128 v[66:69], v94
	ds_read_b128 v[70:73], v82 offset:49152
	ds_read_b128 v[74:77], v92
	ds_read_b128 v[154:157], v82 offset:53248
	s_waitcnt lgkmcnt(1)
	v_mfma_f32_32x32x16_bf16 v[48:63], v[66:69], v[70:73], v[48:63]
	s_and_b32 m0, s32, 7
	s_lshl_b32 m0, m0, 12
	s_add_i32 m0, m0, 0x800
	s_nop 0
	global_load_lds_dwordx4 v[162:163], off
	v_mfma_f32_32x32x16_bf16 v[32:47], v[74:77], v[70:73], v[32:47]
	s_waitcnt lgkmcnt(0)
	v_mfma_f32_32x32x16_bf16 v[16:31], v[66:69], v[154:157], v[16:31]
	v_mfma_f32_32x32x16_bf16 v[0:15], v[74:77], v[154:157], v[0:15]
	s_and_b32 m0, s32, 7
	s_lshl_b32 m0, m0, 12
	s_add_i32 m0, m0, 0xc00
	s_nop 0
	global_load_lds_dwordx4 v[164:165], off
	ds_read_b128 v[66:69], v95
	ds_read_b128 v[70:73], v86 offset:49152
	ds_read_b128 v[74:77], v93
	ds_read_b128 v[150:153], v86 offset:53248
	s_waitcnt lgkmcnt(1)
	v_mfma_f32_32x32x16_bf16 v[48:63], v[66:69], v[70:73], v[48:63]
	v_mfma_f32_32x32x16_bf16 v[32:47], v[74:77], v[70:73], v[32:47]
	s_waitcnt lgkmcnt(0)
	v_mfma_f32_32x32x16_bf16 v[16:31], v[66:69], v[150:153], v[16:31]
	s_and_b32 m0, s32, 7
	s_lshl_b32 m0, m0, 11
	s_add_i32 m0, m0, 0x8000
	s_nop 0
	global_load_lds_dwordx4 v[166:167], off
	v_mfma_f32_32x32x16_bf16 v[0:15], v[74:77], v[150:153], v[0:15]
	ds_read_b128 v[66:69], v97
	ds_read_b128 v[70:73], v88 offset:49152
	ds_read_b128 v[74:77], v96
	ds_read_b128 v[154:157], v88 offset:53248
	s_waitcnt lgkmcnt(1)
	v_mfma_f32_32x32x16_bf16 v[48:63], v[66:69], v[70:73], v[48:63]
	s_and_b32 m0, s32, 7
	s_lshl_b32 m0, m0, 11
	s_add_i32 m0, m0, 0x8400
	s_nop 0
	global_load_lds_dwordx4 v[168:169], off
	v_mfma_f32_32x32x16_bf16 v[32:47], v[74:77], v[70:73], v[32:47]
	s_waitcnt vmcnt(6)
	s_waitcnt lgkmcnt(0)
	s_barrier
	s_waitcnt lgkmcnt(0)
	v_mfma_f32_32x32x16_bf16 v[16:31], v[66:69], v[154:157], v[16:31]
	v_lshrrev_b32_e32 v183, 7, v133
	v_and_b32_e32 v184, 31, v133
	v_lshl_or_b32 v183, v183, 6, v184
	v_add_u32_e32 v183, s2, v183
	v_lshlrev_b32_e32 v183, 2, v183
	global_load_dword v184, v183, s[76:77]
	global_load_dword v185, v183, s[76:77] offset:128
	v_mfma_f32_32x32x16_bf16 v[0:15], v[74:77], v[154:157], v[0:15]
	ds_read_b128 v[66:69], v98
	ds_read_b128 v[70:73], v100
	ds_read_b128 v[74:77], v99
	ds_read_b128 v[150:153], v101
	s_waitcnt lgkmcnt(1)
	v_mfma_f32_32x32x16_bf16 v[48:63], v[66:69], v[70:73], v[48:63]
	v_mfma_f32_32x32x16_bf16 v[32:47], v[74:77], v[70:73], v[32:47]
	s_waitcnt lgkmcnt(0)
	v_mfma_f32_32x32x16_bf16 v[16:31], v[66:69], v[150:153], v[16:31]
	v_mfma_f32_32x32x16_bf16 v[0:15], v[74:77], v[150:153], v[0:15]
	ds_read_b128 v[66:69], v103
	ds_read_b128 v[70:73], v104
	ds_read_b128 v[74:77], v102
	ds_read_b128 v[154:157], v105
	s_waitcnt lgkmcnt(1)
	v_mfma_f32_32x32x16_bf16 v[48:63], v[66:69], v[70:73], v[48:63]
	v_mfma_f32_32x32x16_bf16 v[32:47], v[74:77], v[70:73], v[32:47]
	s_waitcnt lgkmcnt(0)
	v_mfma_f32_32x32x16_bf16 v[16:31], v[66:69], v[154:157], v[16:31]
	v_mfma_f32_32x32x16_bf16 v[0:15], v[74:77], v[154:157], v[0:15]
	ds_read_b128 v[66:69], v107
	ds_read_b128 v[70:73], v108
	ds_read_b128 v[74:77], v106
	ds_read_b128 v[150:153], v109
	s_waitcnt lgkmcnt(1)
	v_mfma_f32_32x32x16_bf16 v[48:63], v[66:69], v[70:73], v[48:63]
	v_mfma_f32_32x32x16_bf16 v[32:47], v[74:77], v[70:73], v[32:47]
	s_waitcnt lgkmcnt(0)
	v_mfma_f32_32x32x16_bf16 v[16:31], v[66:69], v[150:153], v[16:31]
	v_mfma_f32_32x32x16_bf16 v[0:15], v[74:77], v[150:153], v[0:15]
	ds_read_b128 v[66:69], v111
	ds_read_b128 v[70:73], v112
	ds_read_b128 v[74:77], v110
	ds_read_b128 v[154:157], v113
	s_waitcnt lgkmcnt(1)
	v_mfma_f32_32x32x16_bf16 v[48:63], v[66:69], v[70:73], v[48:63]
	v_mfma_f32_32x32x16_bf16 v[32:47], v[74:77], v[70:73], v[32:47]
	s_waitcnt vmcnt(0)
	s_waitcnt lgkmcnt(0)
	s_barrier
	s_waitcnt lgkmcnt(0)
	v_mfma_f32_32x32x16_bf16 v[16:31], v[66:69], v[154:157], v[16:31]
	v_mfma_f32_32x32x16_bf16 v[0:15], v[74:77], v[154:157], v[0:15]
	ds_read_b128 v[66:69], v85 offset:32768
	ds_read_b128 v[70:73], v84
	ds_read_b128 v[74:77], v85 offset:36864
	ds_read_b128 v[150:153], v84 offset:4096
	s_waitcnt lgkmcnt(1)
	v_mfma_f32_32x32x16_bf16 v[48:63], v[66:69], v[70:73], v[48:63]
	v_mfma_f32_32x32x16_bf16 v[32:47], v[74:77], v[70:73], v[32:47]
	s_waitcnt lgkmcnt(0)
	v_mfma_f32_32x32x16_bf16 v[16:31], v[66:69], v[150:153], v[16:31]
	v_mfma_f32_32x32x16_bf16 v[0:15], v[74:77], v[150:153], v[0:15]
	ds_read_b128 v[66:69], v83 offset:32768
	ds_read_b128 v[70:73], v82
	ds_read_b128 v[74:77], v83 offset:36864
	ds_read_b128 v[154:157], v82 offset:4096
	s_waitcnt lgkmcnt(1)
	v_mfma_f32_32x32x16_bf16 v[48:63], v[66:69], v[70:73], v[48:63]
	v_mfma_f32_32x32x16_bf16 v[32:47], v[74:77], v[70:73], v[32:47]
	s_waitcnt lgkmcnt(0)
	v_mfma_f32_32x32x16_bf16 v[16:31], v[66:69], v[154:157], v[16:31]
	v_mfma_f32_32x32x16_bf16 v[0:15], v[74:77], v[154:157], v[0:15]
	ds_read_b128 v[66:69], v87 offset:32768
	ds_read_b128 v[70:73], v86
	ds_read_b128 v[74:77], v87 offset:36864
	ds_read_b128 v[150:153], v86 offset:4096
	s_waitcnt lgkmcnt(1)
	v_mfma_f32_32x32x16_bf16 v[48:63], v[66:69], v[70:73], v[48:63]
	v_mfma_f32_32x32x16_bf16 v[32:47], v[74:77], v[70:73], v[32:47]
	s_waitcnt lgkmcnt(0)
	v_mfma_f32_32x32x16_bf16 v[16:31], v[66:69], v[150:153], v[16:31]
	v_mfma_f32_32x32x16_bf16 v[0:15], v[74:77], v[150:153], v[0:15]
	ds_read_b128 v[70:73], v89 offset:32768
	ds_read_b128 v[66:69], v88
	ds_read_b128 v[74:77], v89 offset:36864
	ds_read_b128 v[82:85], v88 offset:4096
	s_waitcnt lgkmcnt(0)
	s_barrier
	s_waitcnt lgkmcnt(0)
	v_mfma_f32_32x32x16_bf16 v[48:63], v[70:73], v[66:69], v[48:63]
	v_mfma_f32_32x32x16_bf16 v[32:47], v[74:77], v[66:69], v[32:47]
	v_lshl_or_b32 v69, v80, 6, v81
	v_add_u32_e32 v66, s2, v69
	v_cmp_gt_i32_e32 vcc, s69, v66
	v_ashrrev_i32_e32 v67, 31, v66
	v_mov_b32_e32 v68, 0
	v_mfma_f32_32x32x16_bf16 v[16:31], v[70:73], v[82:85], v[16:31]
	v_mov_b32_e32 v70, 0
	v_mfma_f32_32x32x16_bf16 v[0:15], v[74:77], v[82:85], v[0:15]
	s_and_saveexec_b64 s[0:1], vcc
	s_cbranch_execz .LBB0_749
	v_lshl_add_u64 v[70:71], v[66:67], 2, s[76:77]
	v_mov_b32_e32 v70, v184
	v_fmamk_f32 v70, v70, 0x3a800000, v188
	v_mul_f32_e32 v71, 0x4b800000, v70
	v_cmp_gt_f32_e32 vcc, s82, v70
	s_nop 1
	v_cndmask_b32_e32 v70, v70, v71, vcc
	v_rsq_f32_e32 v70, v70
	s_nop 0
	v_mul_f32_e32 v71, 0x45800000, v70
	v_cndmask_b32_e32 v70, v70, v71, vcc
